# all 16-byte stores made write-through (sc1) so the barrier's L2 writeback has less dirty data; otherwise same as v45
# baseline (speedup 1.0000x reference)
.LBB0_22:
	v_add_co_u32_e32 v14, vcc, 0xfffffc00, v4
	v_add_u32_e32 v180, s30, v180
	s_nop 0
	v_addc_co_u32_e32 v15, vcc, -1, v5, vcc
	flat_load_dwordx4 v[14:17], v[14:15]
	s_nop 0
	flat_load_dwordx4 v[18:21], v[4:5]
	global_load_dwordx4 v[22:25], v[2:3], off
	v_lshl_add_u64 v[4:5], v[4:5], 0, s[4:5]
	s_waitcnt vmcnt(0) lgkmcnt(0)
	v_lshlrev_b32_e32 v30, 16, v14
	v_and_b32_e32 v31, 0xffff0000, v14
	v_lshlrev_b32_e32 v14, 16, v15
	v_and_b32_e32 v15, 0xffff0000, v15
	v_pk_mul_f32 v[42:43], v[30:31], v[30:31]
	v_pk_mul_f32 v[44:45], v[14:15], v[14:15]
	v_add_f32_e32 v0, v42, v43
	v_lshlrev_b32_e32 v32, 16, v16
	v_and_b32_e32 v33, 0xffff0000, v16
	v_add_f32_e32 v0, v44, v0
	v_pk_mul_f32 v[46:47], v[32:33], v[32:33]
	v_add_f32_e32 v0, v45, v0
	v_lshlrev_b32_e32 v34, 16, v17
	v_and_b32_e32 v35, 0xffff0000, v17
	v_add_f32_e32 v0, v46, v0
	v_pk_mul_f32 v[48:49], v[34:35], v[34:35]
	v_add_f32_e32 v0, v47, v0
	v_lshlrev_b32_e32 v26, 16, v18
	v_and_b32_e32 v27, 0xffff0000, v18
	v_add_f32_e32 v0, v48, v0
	v_pk_mul_f32 v[16:17], v[26:27], v[26:27]
	v_add_f32_e32 v0, v49, v0
	v_lshlrev_b32_e32 v18, 16, v19
	v_and_b32_e32 v19, 0xffff0000, v19
	v_add_f32_e32 v0, v16, v0
	v_pk_mul_f32 v[36:37], v[18:19], v[18:19]
	v_add_f32_e32 v0, v17, v0
	v_lshlrev_b32_e32 v28, 16, v20
	v_and_b32_e32 v29, 0xffff0000, v20
	v_add_f32_e32 v0, v36, v0
	v_pk_mul_f32 v[38:39], v[28:29], v[28:29]
	v_add_f32_e32 v0, v37, v0
	v_lshlrev_b32_e32 v20, 16, v21
	v_and_b32_e32 v21, 0xffff0000, v21
	v_add_f32_e32 v0, v38, v0
	v_pk_mul_f32 v[40:41], v[20:21], v[20:21]
	v_add_f32_e32 v0, v39, v0
	v_add_f32_e32 v0, v40, v0
	v_add_f32_e32 v0, v41, v0
	ds_bpermute_b32 v16, v8, v0
	s_waitcnt lgkmcnt(0)
	v_add_f32_e32 v0, v0, v16
	ds_bpermute_b32 v16, v9, v0
	s_waitcnt lgkmcnt(0)
	v_add_f32_e32 v0, v0, v16
	ds_bpermute_b32 v16, v10, v0
	s_waitcnt lgkmcnt(0)
	v_add_f32_e32 v0, v0, v16
	ds_bpermute_b32 v16, v11, v0
	s_waitcnt lgkmcnt(0)
	v_add_f32_e32 v0, v0, v16
	ds_bpermute_b32 v16, v12, v0
	s_waitcnt lgkmcnt(0)
	v_add_f32_e32 v0, v0, v16
	ds_bpermute_b32 v16, v13, v0
	s_waitcnt lgkmcnt(0)
	v_add_f32_e32 v0, v0, v16
	v_fmamk_f32 v0, v0, 0x3a800000, v196
	v_mul_f32_e32 v16, 0x4b800000, v0
	v_cmp_gt_f32_e32 vcc, s84, v0
	s_nop 1
	v_cndmask_b32_e32 v0, v0, v16, vcc
	v_rsq_f32_e32 v0, v0
	s_nop 0
	v_mul_f32_e32 v16, 0x45800000, v0
	v_cndmask_b32_e32 v0, v0, v16, vcc
	v_pk_mul_f32 v[30:31], v[0:1], v[30:31] op_sel_hi:[0,1]
	v_pk_mul_f32 v[14:15], v[0:1], v[14:15] op_sel_hi:[0,1]
	v_pk_mul_f32 v[16:17], v[24:25], v[14:15]
	v_pk_mul_f32 v[14:15], v[22:23], v[30:31]
	global_store_dwordx4 v[6:7], v[14:17], off sc1
	global_load_dwordx4 v[14:17], v[2:3], off offset:16
	v_pk_mul_f32 v[22:23], v[0:1], v[34:35] op_sel_hi:[0,1]
	v_pk_mul_f32 v[24:25], v[0:1], v[32:33] op_sel_hi:[0,1]
	v_pk_mul_f32 v[18:19], v[0:1], v[18:19] op_sel_hi:[0,1]
	v_cmp_lt_i32_e32 vcc, s90, v180
	s_or_b64 s[10:11], vcc, s[10:11]
	s_waitcnt vmcnt(0)
	v_pk_mul_f32 v[14:15], v[14:15], v[24:25]
	v_pk_mul_f32 v[16:17], v[16:17], v[22:23]
	global_store_dwordx4 v[6:7], v[14:17], off offset:16 sc1
	global_load_dwordx4 v[14:17], v[2:3], off offset:2048
	v_pk_mul_f32 v[22:23], v[0:1], v[26:27] op_sel_hi:[0,1]
	s_waitcnt vmcnt(0)
	v_pk_mul_f32 v[14:15], v[14:15], v[22:23]
	v_pk_mul_f32 v[16:17], v[16:17], v[18:19]
	global_store_dwordx4 v[6:7], v[14:17], off offset:2048 sc1
	global_load_dwordx4 v[14:17], v[2:3], off offset:2064
	v_pk_mul_f32 v[18:19], v[0:1], v[20:21] op_sel_hi:[0,1]
	v_pk_mul_f32 v[20:21], v[0:1], v[28:29] op_sel_hi:[0,1]
	s_waitcnt vmcnt(0)
	v_pk_mul_f32 v[14:15], v[14:15], v[20:21]
	v_pk_mul_f32 v[16:17], v[16:17], v[18:19]
	global_store_dwordx4 v[6:7], v[14:17], off offset:2064 sc1
	v_lshl_add_u64 v[6:7], v[6:7], 0, s[6:7]
	s_andn2_b64 exec, exec, s[10:11]
	s_cbranch_execnz .LBB0_22

.LBB0_55:
	s_add_u32 s9, s0, s15
	s_addc_u32 s19, s1, 0
	s_add_u32 s18, s9, 0x80
	s_addc_u32 s19, s19, 0
	s_lshl_b32 s53, s53, 8
	v_lshl_or_b32 v132, s52, 8, v213
	v_add_u32_e32 v130, s53, v212
	v_ashrrev_i32_e32 v133, 31, v132
	v_lshlrev_b64 v[182:183], 1, v[132:133]
	v_ashrrev_i32_e32 v131, 31, v130
	s_mov_b32 m0, s93
	s_nop 0
	global_load_lds_dwordx4 v159, s[18:19]
	v_lshl_add_u64 v[184:185], s[16:17], 0, v[182:183]
	v_lshlrev_b64 v[186:187], 11, v[130:131]
	s_mov_b32 m0, s8
	s_nop 0
	global_load_lds_dwordx4 v210, s[18:19]
	v_lshl_add_u64 v[132:133], v[184:185], 0, v[186:187]
	global_load_dwordx4 v[220:223], v[132:133], off
	global_load_dwordx4 v[154:157], v[132:133], off offset:256
	v_or_b32_e32 v132, 16, v130
	v_ashrrev_i32_e32 v133, 31, v132
	v_lshlrev_b64 v[192:193], 11, v[132:133]
	v_lshl_add_u64 v[132:133], v[184:185], 0, v[192:193]
	global_load_dwordx4 v[150:153], v[132:133], off
	global_load_dwordx4 v[146:149], v[132:133], off offset:256
	v_or_b32_e32 v132, 32, v130
	v_ashrrev_i32_e32 v133, 31, v132
	v_lshlrev_b64 v[190:191], 11, v[132:133]
	v_lshl_add_u64 v[132:133], v[184:185], 0, v[190:191]
	global_load_dwordx4 v[142:145], v[132:133], off
	global_load_dwordx4 v[138:141], v[132:133], off offset:256
	v_or_b32_e32 v130, 48, v130
	v_ashrrev_i32_e32 v131, 31, v130
	v_lshlrev_b64 v[188:189], 11, v[130:131]
	v_lshl_add_u64 v[130:131], v[184:185], 0, v[188:189]
	global_load_dwordx4 v[134:137], v[130:131], off
	s_nop 0
	global_load_dwordx4 v[130:133], v[130:131], off offset:256
	s_mov_b64 s[60:61], 0x40000
	s_mov_b64 s[8:9], 0x48000
	s_waitcnt vmcnt(0)
	v_lshlrev_b32_e32 v224, 16, v221
	v_lshlrev_b32_e32 v219, 16, v220
	v_and_b32_e32 v220, 0xffff0000, v220
	v_fmac_f32_e32 v224, v0, v128
	v_and_b32_e32 v128, 0xffff0000, v221
	v_fmac_f32_e32 v219, v0, v126
	v_fmac_f32_e32 v220, v0, v127
	v_fmac_f32_e32 v128, v0, v129
	v_lshlrev_b32_e32 v129, 16, v222
	v_and_b32_e32 v221, 0xffff0000, v222
	v_lshl_add_u64 v[126:127], s[46:47], 0, v[186:187]
	v_fmac_f32_e32 v129, v0, v122
	v_fmac_f32_e32 v221, v0, v123
	v_lshlrev_b32_e32 v222, 16, v223
	v_and_b32_e32 v223, 0xffff0000, v223
	v_cvt_pk_bf16_f32 v122, v219, v220
	v_cvt_pk_bf16_f32 v123, v224, v128
	v_lshl_add_u64 v[126:127], v[126:127], 0, v[182:183]
	v_fmac_f32_e32 v222, v0, v124
	v_fmac_f32_e32 v223, v0, v125
	v_cvt_pk_bf16_f32 v124, v129, v221
	v_cvt_pk_bf16_f32 v125, v222, v223
	global_store_dwordx4 v[126:127], v[122:125], off sc1
	s_nop 1
	v_mul_f32_e32 v122, v220, v220
	v_mul_f32_e32 v123, v128, v128
	v_fmac_f32_e32 v122, v219, v219
	v_fmac_f32_e32 v123, v224, v224
	v_add_f32_e32 v122, v122, v123
	v_mul_f32_e32 v123, v221, v221
	v_mul_f32_e32 v124, v223, v223
	v_fmac_f32_e32 v123, v129, v129
	v_fmac_f32_e32 v124, v222, v222
	v_add_f32_e32 v123, v123, v124
	v_add_f32_e32 v122, v122, v123
	s_waitcnt vmcnt(7)
	v_lshlrev_b32_e32 v123, 16, v154
	v_fmac_f32_e32 v123, v0, v118
	v_and_b32_e32 v118, 0xffff0000, v154
	v_fmac_f32_e32 v118, v0, v119
	v_lshlrev_b32_e32 v119, 16, v155
	v_fmac_f32_e32 v119, v0, v120
	v_and_b32_e32 v120, 0xffff0000, v155
	v_fmac_f32_e32 v120, v0, v121
	v_lshlrev_b32_e32 v121, 16, v156
	v_and_b32_e32 v124, 0xffff0000, v156
	v_fmac_f32_e32 v121, v0, v114
	v_fmac_f32_e32 v124, v0, v115
	v_lshlrev_b32_e32 v125, 16, v157
	v_and_b32_e32 v128, 0xffff0000, v157
	v_cvt_pk_bf16_f32 v114, v123, v118
	v_cvt_pk_bf16_f32 v115, v119, v120
	v_fmac_f32_e32 v125, v0, v116
	v_fmac_f32_e32 v128, v0, v117
	v_cvt_pk_bf16_f32 v116, v121, v124
	v_cvt_pk_bf16_f32 v117, v125, v128
	global_store_dwordx4 v[126:127], v[114:117], off offset:256 sc1
	s_nop 1
	v_mul_f32_e32 v114, v118, v118
	v_mul_f32_e32 v115, v120, v120
	v_fmac_f32_e32 v114, v123, v123
	v_fmac_f32_e32 v115, v119, v119
	v_add_f32_e32 v114, v114, v115
	v_mul_f32_e32 v115, v124, v124
	v_mul_f32_e32 v116, v128, v128
	v_fmac_f32_e32 v115, v121, v121
	v_fmac_f32_e32 v116, v125, v125
	v_add_f32_e32 v115, v115, v116
	s_waitcnt vmcnt(7)
	v_lshlrev_b32_e32 v117, 16, v151
	v_add_f32_e32 v114, v114, v115
	v_lshlrev_b32_e32 v115, 16, v150
	v_and_b32_e32 v116, 0xffff0000, v150
	v_fmac_f32_e32 v117, v0, v112
	v_and_b32_e32 v112, 0xffff0000, v151
	v_fmac_f32_e32 v115, v0, v110
	v_fmac_f32_e32 v116, v0, v111
	v_fmac_f32_e32 v112, v0, v113
	v_lshlrev_b32_e32 v113, 16, v152
	v_and_b32_e32 v118, 0xffff0000, v152
	v_lshl_add_u64 v[110:111], s[46:47], 0, v[192:193]
	v_fmac_f32_e32 v113, v0, v106
	v_fmac_f32_e32 v118, v0, v107
	v_lshlrev_b32_e32 v119, 16, v153
	v_and_b32_e32 v120, 0xffff0000, v153
	v_cvt_pk_bf16_f32 v106, v115, v116
	v_cvt_pk_bf16_f32 v107, v117, v112
	v_lshl_add_u64 v[110:111], v[110:111], 0, v[182:183]
	v_fmac_f32_e32 v119, v0, v108
	v_fmac_f32_e32 v120, v0, v109
	v_cvt_pk_bf16_f32 v108, v113, v118
	v_cvt_pk_bf16_f32 v109, v119, v120
	global_store_dwordx4 v[110:111], v[106:109], off sc1
	v_add_f32_e32 v114, v122, v114
	s_nop 0
	v_mul_f32_e32 v106, v116, v116
	v_mul_f32_e32 v107, v112, v112
	v_fmac_f32_e32 v106, v115, v115
	v_fmac_f32_e32 v107, v117, v117
	v_add_f32_e32 v106, v106, v107
	v_mul_f32_e32 v107, v118, v118
	v_mul_f32_e32 v108, v120, v120
	v_fmac_f32_e32 v107, v113, v113
	v_fmac_f32_e32 v108, v119, v119
	v_add_f32_e32 v107, v107, v108
	v_add_f32_e32 v106, v106, v107
	s_waitcnt vmcnt(7)
	v_lshlrev_b32_e32 v107, 16, v146
	v_fmac_f32_e32 v107, v0, v102
	v_and_b32_e32 v102, 0xffff0000, v146
	v_fmac_f32_e32 v102, v0, v103
	v_lshlrev_b32_e32 v103, 16, v147
	v_fmac_f32_e32 v103, v0, v104
	v_and_b32_e32 v104, 0xffff0000, v147
	v_fmac_f32_e32 v104, v0, v105
	v_lshlrev_b32_e32 v105, 16, v148
	v_and_b32_e32 v108, 0xffff0000, v148
	v_fmac_f32_e32 v105, v0, v98
	v_fmac_f32_e32 v108, v0, v99
	v_lshlrev_b32_e32 v109, 16, v149
	v_and_b32_e32 v112, 0xffff0000, v149
	v_cvt_pk_bf16_f32 v98, v107, v102
	v_cvt_pk_bf16_f32 v99, v103, v104
	v_fmac_f32_e32 v109, v0, v100
	v_fmac_f32_e32 v112, v0, v101
	v_cvt_pk_bf16_f32 v100, v105, v108
	v_cvt_pk_bf16_f32 v101, v109, v112
	global_store_dwordx4 v[110:111], v[98:101], off offset:256 sc1
	s_nop 1
	v_mul_f32_e32 v98, v102, v102
	v_mul_f32_e32 v99, v104, v104
	v_fmac_f32_e32 v98, v107, v107
	v_fmac_f32_e32 v99, v103, v103
	v_add_f32_e32 v98, v98, v99
	v_mul_f32_e32 v99, v108, v108
	v_mul_f32_e32 v100, v112, v112
	v_fmac_f32_e32 v99, v105, v105
	v_fmac_f32_e32 v100, v109, v109
	v_add_f32_e32 v99, v99, v100
	s_waitcnt vmcnt(7)
	v_lshlrev_b32_e32 v101, 16, v143
	v_add_f32_e32 v98, v98, v99
	v_lshlrev_b32_e32 v99, 16, v142
	v_and_b32_e32 v100, 0xffff0000, v142
	v_fmac_f32_e32 v101, v0, v96
	v_and_b32_e32 v96, 0xffff0000, v143
	v_fmac_f32_e32 v99, v0, v94
	v_fmac_f32_e32 v100, v0, v95
	v_fmac_f32_e32 v96, v0, v97
	v_lshlrev_b32_e32 v97, 16, v144
	v_and_b32_e32 v102, 0xffff0000, v144
	v_lshl_add_u64 v[94:95], s[46:47], 0, v[190:191]
	v_fmac_f32_e32 v97, v0, v90
	v_fmac_f32_e32 v102, v0, v91
	v_lshlrev_b32_e32 v103, 16, v145
	v_and_b32_e32 v104, 0xffff0000, v145
	v_cvt_pk_bf16_f32 v90, v99, v100
	v_cvt_pk_bf16_f32 v91, v101, v96
	v_lshl_add_u64 v[94:95], v[94:95], 0, v[182:183]
	v_fmac_f32_e32 v103, v0, v92
	v_fmac_f32_e32 v104, v0, v93
	v_cvt_pk_bf16_f32 v92, v97, v102
	v_cvt_pk_bf16_f32 v93, v103, v104
	global_store_dwordx4 v[94:95], v[90:93], off sc1
	v_add_f32_e32 v98, v106, v98
	s_nop 0
	v_mul_f32_e32 v90, v100, v100
	v_mul_f32_e32 v91, v96, v96
	v_fmac_f32_e32 v90, v99, v99
	v_fmac_f32_e32 v91, v101, v101
	v_add_f32_e32 v90, v90, v91
	v_mul_f32_e32 v91, v102, v102
	v_mul_f32_e32 v92, v104, v104
	v_fmac_f32_e32 v91, v97, v97
	v_fmac_f32_e32 v92, v103, v103
	v_add_f32_e32 v91, v91, v92
	v_add_f32_e32 v90, v90, v91
	s_waitcnt vmcnt(7)
	v_lshlrev_b32_e32 v91, 16, v138
	v_fmac_f32_e32 v91, v0, v86
	v_and_b32_e32 v86, 0xffff0000, v138
	v_fmac_f32_e32 v86, v0, v87
	v_lshlrev_b32_e32 v87, 16, v139
	v_fmac_f32_e32 v87, v0, v88
	v_and_b32_e32 v88, 0xffff0000, v139
	v_fmac_f32_e32 v88, v0, v89
	v_lshlrev_b32_e32 v89, 16, v140
	v_and_b32_e32 v92, 0xffff0000, v140
	v_fmac_f32_e32 v89, v0, v82
	v_fmac_f32_e32 v92, v0, v83
	v_lshlrev_b32_e32 v93, 16, v141
	v_and_b32_e32 v96, 0xffff0000, v141
	v_cvt_pk_bf16_f32 v82, v91, v86
	v_cvt_pk_bf16_f32 v83, v87, v88
	v_fmac_f32_e32 v93, v0, v84
	v_fmac_f32_e32 v96, v0, v85
	v_cvt_pk_bf16_f32 v84, v89, v92
	v_cvt_pk_bf16_f32 v85, v93, v96
	global_store_dwordx4 v[94:95], v[82:85], off offset:256 sc1
	s_nop 1
	v_mul_f32_e32 v82, v86, v86
	v_mul_f32_e32 v83, v88, v88
	v_fmac_f32_e32 v82, v91, v91
	v_fmac_f32_e32 v83, v87, v87
	v_add_f32_e32 v82, v82, v83
	v_mul_f32_e32 v83, v92, v92
	v_mul_f32_e32 v84, v96, v96
	v_fmac_f32_e32 v83, v89, v89
	v_fmac_f32_e32 v84, v93, v93
	v_add_f32_e32 v83, v83, v84
	v_add_f32_e32 v82, v82, v83
	s_waitcnt vmcnt(7)
	v_lshlrev_b32_e32 v84, 16, v135
	v_add_f32_e32 v86, v90, v82
	v_lshlrev_b32_e32 v82, 16, v134
	v_and_b32_e32 v83, 0xffff0000, v134
	v_fmac_f32_e32 v84, v0, v80
	v_and_b32_e32 v80, 0xffff0000, v135
	v_fmac_f32_e32 v82, v0, v78
	v_fmac_f32_e32 v83, v0, v79
	v_fmac_f32_e32 v80, v0, v81
	v_lshlrev_b32_e32 v81, 16, v136
	v_and_b32_e32 v85, 0xffff0000, v136
	v_lshl_add_u64 v[78:79], s[46:47], 0, v[188:189]
	v_fmac_f32_e32 v81, v0, v74
	v_fmac_f32_e32 v85, v0, v75
	v_lshlrev_b32_e32 v87, 16, v137
	v_and_b32_e32 v88, 0xffff0000, v137
	v_cvt_pk_bf16_f32 v74, v82, v83
	v_cvt_pk_bf16_f32 v75, v84, v80
	v_lshl_add_u64 v[78:79], v[78:79], 0, v[182:183]
	v_fmac_f32_e32 v87, v0, v76
	v_fmac_f32_e32 v88, v0, v77
	v_cvt_pk_bf16_f32 v76, v81, v85
	v_cvt_pk_bf16_f32 v77, v87, v88
	global_store_dwordx4 v[78:79], v[74:77], off sc1
	v_lshl_add_u64 v[96:97], v[186:187], 0, s[8:9]
	s_mov_b64 s[8:9], 0x50000
	v_mul_f32_e32 v74, v83, v83
	v_mul_f32_e32 v75, v80, v80
	v_fmac_f32_e32 v74, v82, v82
	v_fmac_f32_e32 v75, v84, v84
	v_add_f32_e32 v74, v74, v75
	v_mul_f32_e32 v75, v85, v85
	v_mul_f32_e32 v76, v88, v88
	v_fmac_f32_e32 v75, v81, v81
	v_fmac_f32_e32 v76, v87, v87
	v_add_f32_e32 v75, v75, v76
	v_add_f32_e32 v74, v74, v75
	s_waitcnt vmcnt(7)
	v_lshlrev_b32_e32 v75, 16, v130
	v_fmac_f32_e32 v75, v0, v70
	v_and_b32_e32 v70, 0xffff0000, v130
	v_fmac_f32_e32 v70, v0, v71
	v_lshlrev_b32_e32 v71, 16, v131
	v_fmac_f32_e32 v71, v0, v72
	v_and_b32_e32 v72, 0xffff0000, v131
	v_fmac_f32_e32 v72, v0, v73
	v_lshlrev_b32_e32 v73, 16, v132
	v_and_b32_e32 v76, 0xffff0000, v132
	v_fmac_f32_e32 v73, v0, v66
	v_fmac_f32_e32 v76, v0, v67
	v_lshlrev_b32_e32 v77, 16, v133
	v_and_b32_e32 v80, 0xffff0000, v133
	v_cvt_pk_bf16_f32 v66, v75, v70
	v_cvt_pk_bf16_f32 v67, v71, v72
	v_fmac_f32_e32 v77, v0, v68
	v_fmac_f32_e32 v80, v0, v69
	v_cvt_pk_bf16_f32 v68, v73, v76
	v_cvt_pk_bf16_f32 v69, v77, v80
	global_store_dwordx4 v[78:79], v[66:69], off offset:256 sc1
	v_lshl_add_u64 v[84:85], v[186:187], 0, s[60:61]
	v_lshl_add_u64 v[108:109], v[186:187], 0, s[8:9]
	v_mul_f32_e32 v66, v70, v70
	v_mul_f32_e32 v67, v72, v72
	v_fmac_f32_e32 v66, v75, v75
	v_fmac_f32_e32 v67, v71, v71
	v_add_f32_e32 v66, v66, v67
	v_mul_f32_e32 v67, v76, v76
	v_mul_f32_e32 v68, v80, v80
	v_fmac_f32_e32 v67, v73, v73
	v_fmac_f32_e32 v68, v77, v77
	v_add_f32_e32 v67, v67, v68
	v_add_f32_e32 v66, v66, v67
	v_add_f32_e32 v87, v74, v66
	v_lshl_add_u64 v[66:67], v[184:185], 0, v[84:85]
	global_load_dwordx4 v[74:77], v[66:67], off
	global_load_dwordx4 v[88:91], v[66:67], off offset:256
	v_lshl_add_u64 v[66:67], v[184:185], 0, v[96:97]
	global_load_dwordx4 v[92:95], v[66:67], off
	global_load_dwordx4 v[100:103], v[66:67], off offset:256
	v_lshl_add_u64 v[66:67], v[184:185], 0, v[108:109]
	global_load_dwordx4 v[104:107], v[66:67], off
	global_load_dwordx4 v[78:81], v[66:67], off offset:256
	s_mov_b64 s[8:9], 0x58000
	v_lshl_add_u64 v[82:83], v[186:187], 0, s[8:9]
	v_lshl_add_u64 v[66:67], v[184:185], 0, v[82:83]
	global_load_dwordx4 v[70:73], v[66:67], off
	s_nop 0
	global_load_dwordx4 v[66:69], v[66:67], off offset:256
	s_waitcnt vmcnt(7)
	v_lshlrev_b32_e32 v110, 16, v75
	v_lshlrev_b32_e32 v99, 16, v74
	v_and_b32_e32 v74, 0xffff0000, v74
	v_fmac_f32_e32 v110, v0, v64
	v_and_b32_e32 v64, 0xffff0000, v75
	v_fmac_f32_e32 v99, v0, v62
	v_fmac_f32_e32 v74, v0, v63
	v_fmac_f32_e32 v64, v0, v65
	v_lshlrev_b32_e32 v65, 16, v76
	v_and_b32_e32 v75, 0xffff0000, v76
	v_lshl_add_u64 v[62:63], s[46:47], 0, v[84:85]
	v_fmac_f32_e32 v65, v0, v58
	v_fmac_f32_e32 v75, v0, v59
	v_lshlrev_b32_e32 v76, 16, v77
	v_and_b32_e32 v77, 0xffff0000, v77
	v_cvt_pk_bf16_f32 v58, v99, v74
	v_cvt_pk_bf16_f32 v59, v110, v64
	v_lshl_add_u64 v[62:63], v[62:63], 0, v[182:183]
	v_fmac_f32_e32 v76, v0, v60
	v_fmac_f32_e32 v77, v0, v61
	v_cvt_pk_bf16_f32 v60, v65, v75
	v_cvt_pk_bf16_f32 v61, v76, v77
	global_store_dwordx4 v[62:63], v[58:61], off sc1
	s_nop 1
	v_mul_f32_e32 v58, v74, v74
	v_mul_f32_e32 v59, v64, v64
	v_fmac_f32_e32 v58, v99, v99
	v_fmac_f32_e32 v59, v110, v110
	v_add_f32_e32 v58, v58, v59
	v_mul_f32_e32 v59, v75, v75
	v_mul_f32_e32 v60, v77, v77
	v_fmac_f32_e32 v59, v65, v65
	v_fmac_f32_e32 v60, v76, v76
	v_add_f32_e32 v59, v59, v60
	v_add_f32_e32 v58, v58, v59
	s_waitcnt vmcnt(7)
	v_lshlrev_b32_e32 v59, 16, v88
	v_fmac_f32_e32 v59, v0, v54
	v_and_b32_e32 v54, 0xffff0000, v88
	v_fmac_f32_e32 v54, v0, v55
	v_lshlrev_b32_e32 v55, 16, v89
	v_fmac_f32_e32 v55, v0, v56
	v_and_b32_e32 v56, 0xffff0000, v89
	v_fmac_f32_e32 v56, v0, v57
	v_lshlrev_b32_e32 v57, 16, v90
	v_and_b32_e32 v60, 0xffff0000, v90
	v_fmac_f32_e32 v57, v0, v50
	v_fmac_f32_e32 v60, v0, v51
	v_lshlrev_b32_e32 v61, 16, v91
	v_and_b32_e32 v64, 0xffff0000, v91
	v_cvt_pk_bf16_f32 v50, v59, v54
	v_cvt_pk_bf16_f32 v51, v55, v56
	v_fmac_f32_e32 v61, v0, v52
	v_fmac_f32_e32 v64, v0, v53
	v_cvt_pk_bf16_f32 v52, v57, v60
	v_cvt_pk_bf16_f32 v53, v61, v64
	global_store_dwordx4 v[62:63], v[50:53], off offset:256 sc1
	s_nop 1
	v_mul_f32_e32 v50, v54, v54
	v_mul_f32_e32 v51, v56, v56
	v_fmac_f32_e32 v50, v59, v59
	v_fmac_f32_e32 v51, v55, v55
	v_add_f32_e32 v50, v50, v51
	v_mul_f32_e32 v51, v60, v60
	v_mul_f32_e32 v52, v64, v64
	v_fmac_f32_e32 v51, v57, v57
	v_fmac_f32_e32 v52, v61, v61
	v_add_f32_e32 v51, v51, v52
	s_waitcnt vmcnt(7)
	v_lshlrev_b32_e32 v53, 16, v93
	v_add_f32_e32 v50, v50, v51
	v_lshlrev_b32_e32 v51, 16, v92
	v_and_b32_e32 v52, 0xffff0000, v92
	v_fmac_f32_e32 v53, v0, v48
	v_and_b32_e32 v48, 0xffff0000, v93
	v_fmac_f32_e32 v51, v0, v46
	v_fmac_f32_e32 v52, v0, v47
	v_fmac_f32_e32 v48, v0, v49
	v_lshlrev_b32_e32 v49, 16, v94
	v_and_b32_e32 v54, 0xffff0000, v94
	v_lshl_add_u64 v[46:47], s[46:47], 0, v[96:97]
	v_fmac_f32_e32 v49, v0, v42
	v_fmac_f32_e32 v54, v0, v43
	v_lshlrev_b32_e32 v55, 16, v95
	v_and_b32_e32 v56, 0xffff0000, v95
	v_cvt_pk_bf16_f32 v42, v51, v52
	v_cvt_pk_bf16_f32 v43, v53, v48
	v_lshl_add_u64 v[46:47], v[46:47], 0, v[182:183]
	v_fmac_f32_e32 v55, v0, v44
	v_fmac_f32_e32 v56, v0, v45
	v_cvt_pk_bf16_f32 v44, v49, v54
	v_cvt_pk_bf16_f32 v45, v55, v56
	global_store_dwordx4 v[46:47], v[42:45], off sc1
	v_add_f32_e32 v50, v58, v50
	s_nop 0
	v_mul_f32_e32 v42, v52, v52
	v_mul_f32_e32 v43, v48, v48
	v_fmac_f32_e32 v42, v51, v51
	v_fmac_f32_e32 v43, v53, v53
	v_add_f32_e32 v42, v42, v43
	v_mul_f32_e32 v43, v54, v54
	v_mul_f32_e32 v44, v56, v56
	v_fmac_f32_e32 v43, v49, v49
	v_fmac_f32_e32 v44, v55, v55
	v_add_f32_e32 v43, v43, v44
	v_add_f32_e32 v42, v42, v43
	s_waitcnt vmcnt(7)
	v_lshlrev_b32_e32 v43, 16, v100
	v_fmac_f32_e32 v43, v0, v38
	v_and_b32_e32 v38, 0xffff0000, v100
	v_fmac_f32_e32 v38, v0, v39
	v_lshlrev_b32_e32 v39, 16, v101
	v_fmac_f32_e32 v39, v0, v40
	v_and_b32_e32 v40, 0xffff0000, v101
	v_fmac_f32_e32 v40, v0, v41
	v_lshlrev_b32_e32 v41, 16, v102
	v_and_b32_e32 v44, 0xffff0000, v102
	v_fmac_f32_e32 v41, v0, v34
	v_fmac_f32_e32 v44, v0, v35
	v_lshlrev_b32_e32 v45, 16, v103
	v_and_b32_e32 v48, 0xffff0000, v103
	v_cvt_pk_bf16_f32 v34, v43, v38
	v_cvt_pk_bf16_f32 v35, v39, v40
	v_fmac_f32_e32 v45, v0, v36
	v_fmac_f32_e32 v48, v0, v37
	v_cvt_pk_bf16_f32 v36, v41, v44
	v_cvt_pk_bf16_f32 v37, v45, v48
	global_store_dwordx4 v[46:47], v[34:37], off offset:256 sc1
	s_nop 1
	v_mul_f32_e32 v34, v38, v38
	v_mul_f32_e32 v35, v40, v40
	v_fmac_f32_e32 v34, v43, v43
	v_fmac_f32_e32 v35, v39, v39
	v_add_f32_e32 v34, v34, v35
	v_mul_f32_e32 v35, v44, v44
	v_mul_f32_e32 v36, v48, v48
	v_fmac_f32_e32 v35, v41, v41
	v_fmac_f32_e32 v36, v45, v45
	v_add_f32_e32 v35, v35, v36
	s_waitcnt vmcnt(7)
	v_lshlrev_b32_e32 v37, 16, v105
	v_add_f32_e32 v34, v34, v35
	v_lshlrev_b32_e32 v35, 16, v104
	v_and_b32_e32 v36, 0xffff0000, v104
	v_fmac_f32_e32 v37, v0, v32
	v_and_b32_e32 v32, 0xffff0000, v105
	v_fmac_f32_e32 v35, v0, v30
	v_fmac_f32_e32 v36, v0, v31
	v_fmac_f32_e32 v32, v0, v33
	v_lshlrev_b32_e32 v33, 16, v106
	v_and_b32_e32 v38, 0xffff0000, v106
	v_lshl_add_u64 v[30:31], s[46:47], 0, v[108:109]
	v_fmac_f32_e32 v33, v0, v26
	v_fmac_f32_e32 v38, v0, v27
	v_lshlrev_b32_e32 v39, 16, v107
	v_and_b32_e32 v40, 0xffff0000, v107
	v_cvt_pk_bf16_f32 v26, v35, v36
	v_cvt_pk_bf16_f32 v27, v37, v32
	v_lshl_add_u64 v[30:31], v[30:31], 0, v[182:183]
	v_fmac_f32_e32 v39, v0, v28
	v_fmac_f32_e32 v40, v0, v29
	v_cvt_pk_bf16_f32 v28, v33, v38
	v_cvt_pk_bf16_f32 v29, v39, v40
	global_store_dwordx4 v[30:31], v[26:29], off sc1
	v_add_f32_e32 v34, v42, v34
	s_nop 0
	v_mul_f32_e32 v26, v36, v36
	v_mul_f32_e32 v27, v32, v32
	v_fmac_f32_e32 v26, v35, v35
	v_fmac_f32_e32 v27, v37, v37
	v_add_f32_e32 v26, v26, v27
	v_mul_f32_e32 v27, v38, v38
	v_mul_f32_e32 v28, v40, v40
	v_fmac_f32_e32 v27, v33, v33
	v_fmac_f32_e32 v28, v39, v39
	v_add_f32_e32 v27, v27, v28
	v_add_f32_e32 v26, v26, v27
	s_waitcnt vmcnt(7)
	v_lshlrev_b32_e32 v27, 16, v78
	v_fmac_f32_e32 v27, v0, v22
	v_and_b32_e32 v22, 0xffff0000, v78
	v_fmac_f32_e32 v22, v0, v23
	v_lshlrev_b32_e32 v23, 16, v79
	v_fmac_f32_e32 v23, v0, v24
	v_and_b32_e32 v24, 0xffff0000, v79
	v_fmac_f32_e32 v24, v0, v25
	v_lshlrev_b32_e32 v25, 16, v80
	v_and_b32_e32 v28, 0xffff0000, v80
	v_fmac_f32_e32 v25, v0, v18
	v_fmac_f32_e32 v28, v0, v19
	v_lshlrev_b32_e32 v29, 16, v81
	v_and_b32_e32 v32, 0xffff0000, v81
	v_cvt_pk_bf16_f32 v18, v27, v22
	v_cvt_pk_bf16_f32 v19, v23, v24
	v_fmac_f32_e32 v29, v0, v20
	v_fmac_f32_e32 v32, v0, v21
	v_cvt_pk_bf16_f32 v20, v25, v28
	v_cvt_pk_bf16_f32 v21, v29, v32
	global_store_dwordx4 v[30:31], v[18:21], off offset:256 sc1
	s_nop 1
	v_mul_f32_e32 v18, v22, v22
	v_mul_f32_e32 v19, v24, v24
	v_fmac_f32_e32 v18, v27, v27
	v_fmac_f32_e32 v19, v23, v23
	v_add_f32_e32 v18, v18, v19
	v_mul_f32_e32 v19, v28, v28
	v_mul_f32_e32 v20, v32, v32
	v_fmac_f32_e32 v19, v25, v25
	v_fmac_f32_e32 v20, v29, v29
	v_add_f32_e32 v19, v19, v20
	s_waitcnt vmcnt(7)
	v_lshlrev_b32_e32 v21, 16, v71
	v_add_f32_e32 v18, v18, v19
	v_lshlrev_b32_e32 v19, 16, v70
	v_and_b32_e32 v20, 0xffff0000, v70
	v_fmac_f32_e32 v21, v0, v16
	v_and_b32_e32 v16, 0xffff0000, v71
	v_fmac_f32_e32 v19, v0, v14
	v_fmac_f32_e32 v20, v0, v15
	v_fmac_f32_e32 v16, v0, v17
	v_lshlrev_b32_e32 v17, 16, v72
	v_and_b32_e32 v22, 0xffff0000, v72
	v_lshl_add_u64 v[14:15], s[46:47], 0, v[82:83]
	v_fmac_f32_e32 v17, v0, v10
	v_fmac_f32_e32 v22, v0, v11
	v_lshlrev_b32_e32 v23, 16, v73
	v_and_b32_e32 v24, 0xffff0000, v73
	v_cvt_pk_bf16_f32 v10, v19, v20
	v_cvt_pk_bf16_f32 v11, v21, v16
	v_lshl_add_u64 v[14:15], v[14:15], 0, v[182:183]
	v_fmac_f32_e32 v23, v0, v12
	v_fmac_f32_e32 v24, v0, v13
	v_cvt_pk_bf16_f32 v12, v17, v22
	v_cvt_pk_bf16_f32 v13, v23, v24
	global_store_dwordx4 v[14:15], v[10:13], off sc1
	v_add_f32_e32 v18, v26, v18
	s_nop 0
	v_mul_f32_e32 v10, v20, v20
	v_mul_f32_e32 v11, v16, v16
	v_fmac_f32_e32 v10, v19, v19
	v_fmac_f32_e32 v11, v21, v21
	v_add_f32_e32 v10, v10, v11
	v_mul_f32_e32 v11, v22, v22
	v_mul_f32_e32 v12, v24, v24
	v_fmac_f32_e32 v11, v17, v17
	v_fmac_f32_e32 v12, v23, v23
	v_add_f32_e32 v11, v11, v12
	v_add_f32_e32 v10, v10, v11
	s_waitcnt vmcnt(7)
	v_lshlrev_b32_e32 v11, 16, v66
	v_fmac_f32_e32 v11, v0, v6
	v_and_b32_e32 v6, 0xffff0000, v66
	v_fmac_f32_e32 v6, v0, v7
	v_lshlrev_b32_e32 v7, 16, v67
	v_fmac_f32_e32 v7, v0, v8
	v_and_b32_e32 v8, 0xffff0000, v67
	v_fmac_f32_e32 v8, v0, v9
	v_lshlrev_b32_e32 v9, 16, v68
	v_and_b32_e32 v12, 0xffff0000, v68
	v_fmac_f32_e32 v9, v0, v2
	v_fmac_f32_e32 v12, v0, v3
	v_lshlrev_b32_e32 v13, 16, v69
	v_and_b32_e32 v16, 0xffff0000, v69
	v_cvt_pk_bf16_f32 v2, v11, v6
	v_cvt_pk_bf16_f32 v3, v7, v8
	v_fmac_f32_e32 v13, v0, v4
	v_fmac_f32_e32 v16, v0, v5
	v_cvt_pk_bf16_f32 v4, v9, v12
	v_cvt_pk_bf16_f32 v5, v13, v16
	global_store_dwordx4 v[14:15], v[2:5], off offset:256 sc1
	s_nop 1
	v_mul_f32_e32 v2, v6, v6
	v_mul_f32_e32 v3, v8, v8
	v_fmac_f32_e32 v2, v11, v11
	v_fmac_f32_e32 v3, v7, v7
	v_add_f32_e32 v2, v2, v3
	v_mul_f32_e32 v3, v12, v12
	v_mul_f32_e32 v4, v16, v16
	v_fmac_f32_e32 v3, v9, v9
	v_fmac_f32_e32 v4, v13, v13
	v_add_f32_e32 v3, v3, v4
	v_add_f32_e32 v2, v2, v3
	v_and_b32_e32 v4, 64, v195
	v_add_f32_e32 v3, v10, v2
	v_xor_b32_e32 v2, 16, v195
	v_add_u32_e32 v10, 64, v4
	v_cmp_lt_i32_e32 vcc, v2, v10
	s_nop 1
	v_cndmask_b32_e32 v2, v195, v2, vcc
	v_lshlrev_b32_e32 v2, 2, v2
	ds_bpermute_b32 v4, v2, v114
	ds_bpermute_b32 v11, v2, v50
	ds_bpermute_b32 v5, v2, v98
	ds_bpermute_b32 v6, v2, v86
	ds_bpermute_b32 v7, v2, v87
	ds_bpermute_b32 v12, v2, v34
	ds_bpermute_b32 v13, v2, v18
	ds_bpermute_b32 v14, v2, v3
	s_waitcnt lgkmcnt(7)
	v_add_f32_e32 v8, v114, v4
	s_waitcnt lgkmcnt(6)
	v_add_f32_e32 v4, v50, v11
	v_xor_b32_e32 v11, 32, v195
	v_cmp_lt_i32_e32 vcc, v11, v10
	s_waitcnt lgkmcnt(5)
	v_add_f32_e32 v9, v98, v5
	s_waitcnt lgkmcnt(4)
	v_add_f32_e32 v6, v86, v6
	v_cndmask_b32_e32 v10, v195, v11, vcc
	s_waitcnt lgkmcnt(3)
	v_add_f32_e32 v7, v87, v7
	s_waitcnt lgkmcnt(2)
	v_add_f32_e32 v5, v34, v12
	s_waitcnt lgkmcnt(1)
	v_add_f32_e32 v2, v18, v13
	s_waitcnt lgkmcnt(0)
	v_add_f32_e32 v3, v3, v14
	v_lshlrev_b32_e32 v11, 2, v10
	ds_bpermute_b32 v16, v11, v8
	ds_bpermute_b32 v17, v11, v9
	ds_bpermute_b32 v14, v11, v6
	ds_bpermute_b32 v15, v11, v7
	ds_bpermute_b32 v12, v11, v4
	ds_bpermute_b32 v13, v11, v5
	ds_bpermute_b32 v10, v11, v2
	ds_bpermute_b32 v11, v11, v3
	s_and_saveexec_b64 s[34:35], s[38:39]
	s_cbranch_execz .LBB0_57
	s_waitcnt lgkmcnt(7)
	v_add_f32_e32 v8, v8, v16
	s_waitcnt lgkmcnt(6)
	v_add_f32_e32 v9, v9, v17
	s_waitcnt lgkmcnt(5)
	v_add_f32_e32 v6, v6, v14
	s_waitcnt lgkmcnt(4)
	v_add_f32_e32 v7, v7, v15
	s_waitcnt lgkmcnt(3)
	v_add_f32_e32 v4, v4, v12
	s_waitcnt lgkmcnt(2)
	v_add_f32_e32 v5, v5, v13
	s_waitcnt lgkmcnt(1)
	v_add_f32_e32 v2, v2, v10
	s_waitcnt lgkmcnt(0)
	v_add_f32_e32 v3, v3, v11
	ds_write2st64_b32 v217, v8, v9 offset1:1
	ds_write2st64_b32 v217, v6, v7 offset0:2 offset1:3
	ds_write2st64_b32 v217, v4, v5 offset0:8 offset1:9
	ds_write2st64_b32 v217, v2, v3 offset0:10 offset1:11

.LBB0_149:
	s_or_b64 exec, exec, s[38:39]
	s_waitcnt vmcnt(0) lgkmcnt(0)
	ds_write_b128 v83, v[2:5]
	v_add_u32_e32 v2, v69, v49
	ds_write_b16 v2, v6 offset:36864
	ds_write_b16_d16_hi v70, v6 offset:37392
	ds_write_b16 v2, v7 offset:37920
	ds_write_b16_d16_hi v70, v7 offset:38448
	v_add_u32_e32 v2, v69, v55
	ds_write_b16 v2, v8 offset:36864
	ds_write_b16_d16_hi v71, v8 offset:37392
	v_add_u32_e32 v2, v69, v57
	ds_write_b16 v2, v9 offset:36864
	ds_write_b16_d16_hi v72, v9 offset:37392
	v_lshl_add_u32 v2, s15, 3, v181
	v_ashrrev_i32_e32 v3, 31, v2
	v_lshl_add_u64 v[4:5], v[2:3], 2, s[20:21]
	s_waitcnt lgkmcnt(0)
	s_barrier
	global_load_dword v85, v[4:5], off
	v_lshlrev_b32_e32 v22, 6, v2
	v_or_b32_e32 v4, s78, v44
	v_mov_b64_e32 v[2:3], s[26:27]
	s_mul_i32 s15, s79, 0x4200
	v_mad_u64_u32 v[2:3], s[8:9], v4, s83, v[2:3]
	v_ashrrev_i32_e32 v23, 31, v22
	v_add_u32_e32 v3, s15, v3
	v_lshl_add_u64 v[2:3], v[22:23], 1, v[2:3]
	v_lshl_add_u64 v[2:3], v[2:3], 0, v[0:1]
	s_mov_b64 s[18:19], 0x1800
	s_movk_i32 s8, 0x1000
	v_lshl_add_u64 v[24:25], v[2:3], 0, s[18:19]
	v_add_u32_e32 v118, v35, v73
	v_and_b32_e32 v248, 15, v195
	v_bfe_u32 v249, v195, 4, 2
	v_mul_u32_u24_e32 v245, 0x210, v248
	v_lshl_add_u32 v245, v249, 3, v245
	v_add_u32_e32 v245, 0x9000, v245
	v_lshlrev_b32_e32 v249, 2, v249
	v_mov_b64_e32 v[246:247], v[24:25]
	s_mov_b64 s[8:9], 0x42000
	global_load_dwordx4 v[90:93], v[246:247], off
	global_load_dwordx4 v[94:97], v[246:247], off offset:64
	s_waitcnt vmcnt(0)
	ds_read_b128 v[106:109], v118
	ds_read_b128 v[110:113], v118 offset:64
	ds_read_b128 v[114:117], v118 offset:2304
	ds_read_b128 v[128:131], v118 offset:2368
	ds_read_b128 v[132:135], v118 offset:4608
	ds_read_b128 v[120:123], v118 offset:4672
	s_waitcnt lgkmcnt(5)
	v_mfma_f32_16x16x32_bf16 v[2:5], v[106:109], v[90:93], 0
	ds_read_b128 v[106:109], v118 offset:6912
	s_waitcnt lgkmcnt(5)
	v_mfma_f32_16x16x32_bf16 v[2:5], v[110:113], v[94:97], v[2:5]
	ds_read_b128 v[110:113], v118 offset:6976
	s_waitcnt lgkmcnt(5)
	v_mfma_f32_16x16x32_bf16 v[6:9], v[114:117], v[90:93], 0
	ds_read_b128 v[114:117], v118 offset:9216
	s_waitcnt lgkmcnt(5)
	v_mfma_f32_16x16x32_bf16 v[6:9], v[128:131], v[94:97], v[6:9]
	ds_read_b128 v[128:131], v118 offset:9280
	s_waitcnt lgkmcnt(5)
	v_mfma_f32_16x16x32_bf16 v[10:13], v[132:135], v[90:93], 0
	ds_read_b128 v[132:135], v118 offset:11520
	s_waitcnt lgkmcnt(5)
	v_mfma_f32_16x16x32_bf16 v[10:13], v[120:123], v[94:97], v[10:13]
	ds_read_b128 v[120:123], v118 offset:11584
	s_waitcnt lgkmcnt(5)
	v_mfma_f32_16x16x32_bf16 v[14:17], v[106:109], v[90:93], 0
	ds_read_b128 v[106:109], v118 offset:13824
	s_waitcnt lgkmcnt(5)
	v_mfma_f32_16x16x32_bf16 v[14:17], v[110:113], v[94:97], v[14:17]
	ds_read_b128 v[110:113], v118 offset:13888
	s_waitcnt lgkmcnt(5)
	v_mfma_f32_16x16x32_bf16 v[18:21], v[114:117], v[90:93], 0
	ds_read_b128 v[114:117], v118 offset:16128
	s_waitcnt lgkmcnt(5)
	v_mfma_f32_16x16x32_bf16 v[18:21], v[128:131], v[94:97], v[18:21]
	ds_read_b128 v[128:131], v118 offset:16192
	s_waitcnt lgkmcnt(5)
	v_mfma_f32_16x16x32_bf16 v[22:25], v[132:135], v[90:93], 0
	ds_read_b128 v[132:135], v118 offset:18432
	s_waitcnt lgkmcnt(5)
	v_mfma_f32_16x16x32_bf16 v[22:25], v[120:123], v[94:97], v[22:25]
	ds_read_b128 v[120:123], v118 offset:18496
	s_waitcnt lgkmcnt(5)
	v_mfma_f32_16x16x32_bf16 v[26:29], v[106:109], v[90:93], 0
	s_waitcnt lgkmcnt(4)
	v_mfma_f32_16x16x32_bf16 v[26:29], v[110:113], v[94:97], v[26:29]
	s_waitcnt lgkmcnt(3)
	v_mfma_f32_16x16x32_bf16 v[30:33], v[114:117], v[90:93], 0
	s_waitcnt lgkmcnt(2)
	v_mfma_f32_16x16x32_bf16 v[30:33], v[128:131], v[94:97], v[30:33]
	s_waitcnt lgkmcnt(1)
	v_mfma_f32_16x16x32_bf16 v[86:89], v[132:135], v[90:93], 0
	s_waitcnt lgkmcnt(0)
	v_mfma_f32_16x16x32_bf16 v[86:89], v[120:123], v[94:97], v[86:89]
	v_lshl_add_u64 v[240:241], v[246:247], 0, s[8:9]
	global_load_dwordx4 v[98:101], v[240:241], off
	global_load_dwordx4 v[102:105], v[240:241], off offset:64
	v_add_u32_e32 v242, 0, v249
	v_cmp_gt_u32_e32 vcc, v242, v248
	s_nop 1
	s_and_b64 vcc, vcc, s[66:67]
	s_nop 0
	v_cndmask_b32_e32 v2, v205, v2, vcc
	v_add_u32_e32 v242, 1, v249
	v_cmp_gt_u32_e32 vcc, v242, v248
	s_nop 1
	s_and_b64 vcc, vcc, s[66:67]
	s_nop 0
	v_cndmask_b32_e32 v3, v205, v3, vcc
	v_add_u32_e32 v242, 2, v249
	v_cmp_gt_u32_e32 vcc, v242, v248
	s_nop 1
	s_and_b64 vcc, vcc, s[66:67]
	s_nop 0
	v_cndmask_b32_e32 v4, v205, v4, vcc
	v_add_u32_e32 v242, 3, v249
	v_cmp_gt_u32_e32 vcc, v242, v248
	s_nop 1
	s_and_b64 vcc, vcc, s[66:67]
	s_nop 0
	v_cndmask_b32_e32 v5, v205, v5, vcc
	v_cndmask_b32_e64 v6, v205, v6, s[66:67]
	v_cndmask_b32_e64 v7, v205, v7, s[66:67]
	v_cndmask_b32_e64 v8, v205, v8, s[66:67]
	v_cndmask_b32_e64 v9, v205, v9, s[66:67]
	v_cndmask_b32_e64 v10, v205, v10, s[66:67]
	v_cndmask_b32_e64 v11, v205, v11, s[66:67]
	v_cndmask_b32_e64 v12, v205, v12, s[66:67]
	v_cndmask_b32_e64 v13, v205, v13, s[66:67]
	v_cndmask_b32_e64 v14, v205, v14, s[66:67]
	v_cndmask_b32_e64 v15, v205, v15, s[66:67]
	v_cndmask_b32_e64 v16, v205, v16, s[66:67]
	v_cndmask_b32_e64 v17, v205, v17, s[66:67]
	v_cndmask_b32_e64 v18, v205, v18, s[66:67]
	v_cndmask_b32_e64 v19, v205, v19, s[66:67]
	v_cndmask_b32_e64 v20, v205, v20, s[66:67]
	v_cndmask_b32_e64 v21, v205, v21, s[66:67]
	v_cndmask_b32_e64 v22, v205, v22, s[66:67]
	v_cndmask_b32_e64 v23, v205, v23, s[66:67]
	v_cndmask_b32_e64 v24, v205, v24, s[66:67]
	v_cndmask_b32_e64 v25, v205, v25, s[66:67]
	v_cndmask_b32_e64 v26, v205, v26, s[66:67]
	v_cndmask_b32_e64 v27, v205, v27, s[66:67]
	v_cndmask_b32_e64 v28, v205, v28, s[66:67]
	v_cndmask_b32_e64 v29, v205, v29, s[66:67]
	v_cndmask_b32_e64 v30, v205, v30, s[66:67]
	v_cndmask_b32_e64 v31, v205, v31, s[66:67]
	v_cndmask_b32_e64 v32, v205, v32, s[66:67]
	v_cndmask_b32_e64 v33, v205, v33, s[66:67]
	v_add_u32_e32 v242, 0, v249
	v_cmp_le_u32_e32 vcc, v242, v248
	s_nop 1
	v_cndmask_b32_e32 v86, v205, v86, vcc
	v_add_u32_e32 v242, 1, v249
	v_cmp_le_u32_e32 vcc, v242, v248
	s_nop 1
	v_cndmask_b32_e32 v87, v205, v87, vcc
	v_add_u32_e32 v242, 2, v249
	v_cmp_le_u32_e32 vcc, v242, v248
	s_nop 1
	v_cndmask_b32_e32 v88, v205, v88, vcc
	v_add_u32_e32 v242, 3, v249
	v_cmp_le_u32_e32 vcc, v242, v248
	s_nop 1
	v_cndmask_b32_e32 v89, v205, v89, vcc
	v_max3_f32 v238, v2, v3, v205
	v_max3_f32 v238, v238, v4, v5
	v_max3_f32 v238, v238, v6, v7
	v_max3_f32 v238, v238, v8, v9
	v_max3_f32 v238, v238, v10, v11
	v_max3_f32 v238, v238, v12, v13
	v_max3_f32 v238, v238, v14, v15
	v_max3_f32 v238, v238, v16, v17
	v_max3_f32 v238, v238, v18, v19
	v_max3_f32 v238, v238, v20, v21
	v_max3_f32 v238, v238, v22, v23
	v_max3_f32 v238, v238, v24, v25
	v_max3_f32 v238, v238, v26, v27
	v_max3_f32 v238, v238, v28, v29
	v_max3_f32 v238, v238, v30, v31
	v_max3_f32 v238, v238, v32, v33
	v_max3_f32 v238, v238, v86, v87
	v_max3_f32 v238, v238, v88, v89
	v_xor_b32_e32 v242, 16, v195
	v_lshlrev_b32_e32 v242, 2, v242
	ds_bpermute_b32 v242, v242, v238
	s_waitcnt lgkmcnt(0)
	v_max_f32_e32 v238, v238, v242
	v_xor_b32_e32 v242, 32, v195
	v_lshlrev_b32_e32 v242, 2, v242
	ds_bpermute_b32 v242, v242, v238
	s_waitcnt lgkmcnt(0)
	v_max_f32_e32 v238, v238, v242
	v_mul_f32_e32 v238, 0x3e000000, v238
	v_max_f32_e32 v238, v238, v85
	v_mul_f32_e32 v243, 0xbfb8aa3b, v238
	v_fmamk_f32 v2, v2, 0x3e38aa3b, v243
	v_fmamk_f32 v3, v3, 0x3e38aa3b, v243
	v_fmamk_f32 v4, v4, 0x3e38aa3b, v243
	v_fmamk_f32 v5, v5, 0x3e38aa3b, v243
	v_exp_f32_e32 v2, v2
	v_exp_f32_e32 v3, v3
	v_exp_f32_e32 v4, v4
	v_exp_f32_e32 v5, v5
	v_fmamk_f32 v6, v6, 0x3e38aa3b, v243
	v_fmamk_f32 v7, v7, 0x3e38aa3b, v243
	v_fmamk_f32 v8, v8, 0x3e38aa3b, v243
	v_fmamk_f32 v9, v9, 0x3e38aa3b, v243
	v_exp_f32_e32 v6, v6
	v_exp_f32_e32 v7, v7
	v_exp_f32_e32 v8, v8
	v_exp_f32_e32 v9, v9
	v_add_f32_e32 v239, 0, v2
	v_add_f32_e32 v239, v239, v3
	v_add_f32_e32 v239, v239, v4
	v_add_f32_e32 v239, v239, v5
	v_fmamk_f32 v10, v10, 0x3e38aa3b, v243
	v_fmamk_f32 v11, v11, 0x3e38aa3b, v243
	v_fmamk_f32 v12, v12, 0x3e38aa3b, v243
	v_fmamk_f32 v13, v13, 0x3e38aa3b, v243
	v_exp_f32_e32 v10, v10
	v_exp_f32_e32 v11, v11
	v_exp_f32_e32 v12, v12
	v_exp_f32_e32 v13, v13
	v_add_f32_e32 v239, v239, v6
	v_add_f32_e32 v239, v239, v7
	v_add_f32_e32 v239, v239, v8
	v_add_f32_e32 v239, v239, v9
	v_fmamk_f32 v14, v14, 0x3e38aa3b, v243
	v_fmamk_f32 v15, v15, 0x3e38aa3b, v243
	v_fmamk_f32 v16, v16, 0x3e38aa3b, v243
	v_fmamk_f32 v17, v17, 0x3e38aa3b, v243
	v_exp_f32_e32 v14, v14
	v_exp_f32_e32 v15, v15
	v_exp_f32_e32 v16, v16
	v_exp_f32_e32 v17, v17
	v_add_f32_e32 v239, v239, v10
	v_add_f32_e32 v239, v239, v11
	v_add_f32_e32 v239, v239, v12
	v_add_f32_e32 v239, v239, v13
	v_fmamk_f32 v18, v18, 0x3e38aa3b, v243
	v_fmamk_f32 v19, v19, 0x3e38aa3b, v243
	v_fmamk_f32 v20, v20, 0x3e38aa3b, v243
	v_fmamk_f32 v21, v21, 0x3e38aa3b, v243
	v_exp_f32_e32 v18, v18
	v_exp_f32_e32 v19, v19
	v_exp_f32_e32 v20, v20
	v_exp_f32_e32 v21, v21
	v_add_f32_e32 v239, v239, v14
	v_add_f32_e32 v239, v239, v15
	v_add_f32_e32 v239, v239, v16
	v_add_f32_e32 v239, v239, v17
	v_fmamk_f32 v22, v22, 0x3e38aa3b, v243
	v_fmamk_f32 v23, v23, 0x3e38aa3b, v243
	v_fmamk_f32 v24, v24, 0x3e38aa3b, v243
	v_fmamk_f32 v25, v25, 0x3e38aa3b, v243
	v_exp_f32_e32 v22, v22
	v_exp_f32_e32 v23, v23
	v_exp_f32_e32 v24, v24
	v_exp_f32_e32 v25, v25
	v_add_f32_e32 v239, v239, v18
	v_add_f32_e32 v239, v239, v19
	v_add_f32_e32 v239, v239, v20
	v_add_f32_e32 v239, v239, v21
	v_fmamk_f32 v26, v26, 0x3e38aa3b, v243
	v_fmamk_f32 v27, v27, 0x3e38aa3b, v243
	v_fmamk_f32 v28, v28, 0x3e38aa3b, v243
	v_fmamk_f32 v29, v29, 0x3e38aa3b, v243
	v_exp_f32_e32 v26, v26
	v_exp_f32_e32 v27, v27
	v_exp_f32_e32 v28, v28
	v_exp_f32_e32 v29, v29
	v_add_f32_e32 v239, v239, v22
	v_add_f32_e32 v239, v239, v23
	v_add_f32_e32 v239, v239, v24
	v_add_f32_e32 v239, v239, v25
	v_fmamk_f32 v30, v30, 0x3e38aa3b, v243
	v_fmamk_f32 v31, v31, 0x3e38aa3b, v243
	v_fmamk_f32 v32, v32, 0x3e38aa3b, v243
	v_fmamk_f32 v33, v33, 0x3e38aa3b, v243
	v_exp_f32_e32 v30, v30
	v_exp_f32_e32 v31, v31
	v_exp_f32_e32 v32, v32
	v_exp_f32_e32 v33, v33
	v_add_f32_e32 v239, v239, v26
	v_add_f32_e32 v239, v239, v27
	v_add_f32_e32 v239, v239, v28
	v_add_f32_e32 v239, v239, v29
	v_fmamk_f32 v86, v86, 0x3e38aa3b, v243
	v_fmamk_f32 v87, v87, 0x3e38aa3b, v243
	v_fmamk_f32 v88, v88, 0x3e38aa3b, v243
	v_fmamk_f32 v89, v89, 0x3e38aa3b, v243
	v_exp_f32_e32 v86, v86
	v_exp_f32_e32 v87, v87
	v_exp_f32_e32 v88, v88
	v_exp_f32_e32 v89, v89
	v_add_f32_e32 v239, v239, v30
	v_add_f32_e32 v239, v239, v31
	v_add_f32_e32 v239, v239, v32
	v_add_f32_e32 v239, v239, v33
	s_nop 0
	v_add_f32_e32 v239, v239, v86
	v_add_f32_e32 v239, v239, v87
	v_add_f32_e32 v239, v239, v88
	v_add_f32_e32 v239, v239, v89
	v_xor_b32_e32 v242, 16, v195
	v_lshlrev_b32_e32 v242, 2, v242
	ds_bpermute_b32 v242, v242, v239
	s_waitcnt lgkmcnt(0)
	v_add_f32_e32 v239, v239, v242
	v_xor_b32_e32 v242, 32, v195
	v_lshlrev_b32_e32 v242, 2, v242
	ds_bpermute_b32 v242, v242, v239
	s_waitcnt lgkmcnt(0)
	v_add_f32_e32 v239, v239, v242
	v_sub_f32_e32 v242, v85, v238
	v_mul_f32_e32 v242, 0x3fb8aa3b, v242
	v_exp_f32_e32 v242, v242
	s_nop 0
	v_add_f32_e32 v239, v239, v242
	v_rcp_f32_e32 v244, v239
	v_cvt_pk_bf16_f32 v218, v2, v3
	v_cvt_pk_bf16_f32 v219, v4, v5
	v_cvt_pk_bf16_f32 v220, v6, v7
	v_cvt_pk_bf16_f32 v221, v8, v9
	v_cvt_pk_bf16_f32 v222, v10, v11
	v_cvt_pk_bf16_f32 v223, v12, v13
	v_cvt_pk_bf16_f32 v224, v14, v15
	v_cvt_pk_bf16_f32 v225, v16, v17
	v_cvt_pk_bf16_f32 v226, v18, v19
	v_cvt_pk_bf16_f32 v227, v20, v21
	v_cvt_pk_bf16_f32 v228, v22, v23
	v_cvt_pk_bf16_f32 v229, v24, v25
	v_cvt_pk_bf16_f32 v230, v26, v27
	v_cvt_pk_bf16_f32 v231, v28, v29
	v_cvt_pk_bf16_f32 v232, v30, v31
	v_cvt_pk_bf16_f32 v233, v32, v33
	v_cvt_pk_bf16_f32 v234, v86, v87
	v_cvt_pk_bf16_f32 v235, v88, v89
	v_mov_b32_e32 v236, 0
	v_mov_b32_e32 v237, 0
	ds_read_b64 v[182:183], v245
	ds_read_b64 v[184:185], v245 offset:32
	ds_read_b64 v[186:187], v245 offset:8448
	ds_read_b64 v[188:189], v245 offset:8480
	ds_read_b64 v[190:191], v245 offset:16896
	ds_read_b64 v[192:193], v245 offset:16928
	ds_read_b64 v[210:211], v245 offset:25344
	ds_read_b64 v[212:213], v245 offset:25376
	ds_read_b64 v[214:215], v245 offset:64
	ds_read_b64 v[216:217], v245 offset:96
	s_waitcnt lgkmcnt(8)
	v_mfma_f32_16x16x32_bf16 v[142:145], v[182:185], v[218:221], 0
	ds_read_b64 v[182:183], v245 offset:8512
	ds_read_b64 v[184:185], v245 offset:8544
	s_waitcnt lgkmcnt(8)
	v_mfma_f32_16x16x32_bf16 v[146:149], v[186:189], v[218:221], 0
	ds_read_b64 v[186:187], v245 offset:16960
	ds_read_b64 v[188:189], v245 offset:16992
	s_waitcnt lgkmcnt(8)
	v_mfma_f32_16x16x32_bf16 v[150:153], v[190:193], v[218:221], 0
	ds_read_b64 v[190:191], v245 offset:25408
	ds_read_b64 v[192:193], v245 offset:25440
	s_waitcnt lgkmcnt(8)
	v_mfma_f32_16x16x32_bf16 v[154:157], v[210:213], v[218:221], 0
	ds_read_b64 v[210:211], v245 offset:128
	ds_read_b64 v[212:213], v245 offset:160
	s_waitcnt lgkmcnt(8)
	v_mfma_f32_16x16x32_bf16 v[142:145], v[214:217], v[222:225], v[142:145]
	ds_read_b64 v[214:215], v245 offset:8576
	ds_read_b64 v[216:217], v245 offset:8608
	s_waitcnt lgkmcnt(8)
	v_mfma_f32_16x16x32_bf16 v[146:149], v[182:185], v[222:225], v[146:149]
	ds_read_b64 v[182:183], v245 offset:17024
	ds_read_b64 v[184:185], v245 offset:17056
	s_waitcnt lgkmcnt(8)
	v_mfma_f32_16x16x32_bf16 v[150:153], v[186:189], v[222:225], v[150:153]
	ds_read_b64 v[186:187], v245 offset:25472
	ds_read_b64 v[188:189], v245 offset:25504
	s_waitcnt lgkmcnt(8)
	v_mfma_f32_16x16x32_bf16 v[154:157], v[190:193], v[222:225], v[154:157]
	ds_read_b64 v[190:191], v245 offset:192
	ds_read_b64 v[192:193], v245 offset:224
	s_waitcnt lgkmcnt(8)
	v_mfma_f32_16x16x32_bf16 v[142:145], v[210:213], v[226:229], v[142:145]
	ds_read_b64 v[210:211], v245 offset:8640
	ds_read_b64 v[212:213], v245 offset:8672
	s_waitcnt lgkmcnt(8)
	v_mfma_f32_16x16x32_bf16 v[146:149], v[214:217], v[226:229], v[146:149]
	ds_read_b64 v[214:215], v245 offset:17088
	ds_read_b64 v[216:217], v245 offset:17120
	s_waitcnt lgkmcnt(8)
	v_mfma_f32_16x16x32_bf16 v[150:153], v[182:185], v[226:229], v[150:153]
	ds_read_b64 v[182:183], v245 offset:25536
	ds_read_b64 v[184:185], v245 offset:25568
	s_waitcnt lgkmcnt(8)
	v_mfma_f32_16x16x32_bf16 v[154:157], v[186:189], v[226:229], v[154:157]
	ds_read_b64 v[186:187], v245 offset:256
	ds_read_b64 v[188:189], v245 offset:256
	s_waitcnt lgkmcnt(8)
	v_mfma_f32_16x16x32_bf16 v[142:145], v[190:193], v[230:233], v[142:145]
	ds_read_b64 v[190:191], v245 offset:8704
	ds_read_b64 v[192:193], v245 offset:8704
	s_waitcnt lgkmcnt(8)
	v_mfma_f32_16x16x32_bf16 v[146:149], v[210:213], v[230:233], v[146:149]
	ds_read_b64 v[210:211], v245 offset:17152
	ds_read_b64 v[212:213], v245 offset:17152
	s_waitcnt lgkmcnt(8)
	v_mfma_f32_16x16x32_bf16 v[150:153], v[214:217], v[230:233], v[150:153]
	ds_read_b64 v[214:215], v245 offset:25600
	ds_read_b64 v[216:217], v245 offset:25600
	s_waitcnt lgkmcnt(8)
	v_mfma_f32_16x16x32_bf16 v[154:157], v[182:185], v[230:233], v[154:157]
	s_waitcnt lgkmcnt(6)
	v_mfma_f32_16x16x32_bf16 v[142:145], v[186:189], v[234:237], v[142:145]
	s_waitcnt lgkmcnt(4)
	v_mfma_f32_16x16x32_bf16 v[146:149], v[190:193], v[234:237], v[146:149]
	s_waitcnt lgkmcnt(2)
	v_mfma_f32_16x16x32_bf16 v[150:153], v[210:213], v[234:237], v[150:153]
	s_waitcnt lgkmcnt(0)
	v_mfma_f32_16x16x32_bf16 v[154:157], v[214:217], v[234:237], v[154:157]
	s_nop 7
	s_nop 1
	v_mul_f32_e32 v142, v244, v142
	v_mul_f32_e32 v143, v244, v143
	v_mul_f32_e32 v144, v244, v144
	v_mul_f32_e32 v145, v244, v145
	v_mul_f32_e32 v146, v244, v146
	v_mul_f32_e32 v147, v244, v147
	v_mul_f32_e32 v148, v244, v148
	v_mul_f32_e32 v149, v244, v149
	v_cvt_pk_bf16_f32 v240, v142, v143
	v_cvt_pk_bf16_f32 v241, v144, v145
	v_cvt_pk_bf16_f32 v242, v146, v147
	v_cvt_pk_bf16_f32 v243, v148, v149
	global_store_dwordx4 v[246:247], v[240:243], off sc1
	s_nop 1
	v_mul_f32_e32 v150, v244, v150
	v_mul_f32_e32 v151, v244, v151
	v_mul_f32_e32 v152, v244, v152
	v_mul_f32_e32 v153, v244, v153
	v_mul_f32_e32 v154, v244, v154
	v_mul_f32_e32 v155, v244, v155
	v_mul_f32_e32 v156, v244, v156
	v_mul_f32_e32 v157, v244, v157
	v_cvt_pk_bf16_f32 v240, v150, v151
	v_cvt_pk_bf16_f32 v241, v152, v153
	v_cvt_pk_bf16_f32 v242, v154, v155
	v_cvt_pk_bf16_f32 v243, v156, v157
	global_store_dwordx4 v[246:247], v[240:243], off offset:64 sc1
	v_lshl_add_u64 v[246:247], v[246:247], 0, s[8:9]
	s_waitcnt vmcnt(2)
	ds_read_b128 v[106:109], v118 offset:2304
	ds_read_b128 v[110:113], v118 offset:2368
	ds_read_b128 v[114:117], v118 offset:4608
	ds_read_b128 v[128:131], v118 offset:4672
	ds_read_b128 v[132:135], v118 offset:6912
	ds_read_b128 v[120:123], v118 offset:6976
	s_waitcnt lgkmcnt(5)
	v_mfma_f32_16x16x32_bf16 v[2:5], v[106:109], v[98:101], 0
	ds_read_b128 v[106:109], v118 offset:9216
	s_waitcnt lgkmcnt(5)
	v_mfma_f32_16x16x32_bf16 v[2:5], v[110:113], v[102:105], v[2:5]
	ds_read_b128 v[110:113], v118 offset:9280
	s_waitcnt lgkmcnt(5)
	v_mfma_f32_16x16x32_bf16 v[6:9], v[114:117], v[98:101], 0
	ds_read_b128 v[114:117], v118 offset:11520
	s_waitcnt lgkmcnt(5)
	v_mfma_f32_16x16x32_bf16 v[6:9], v[128:131], v[102:105], v[6:9]
	ds_read_b128 v[128:131], v118 offset:11584
	s_waitcnt lgkmcnt(5)
	v_mfma_f32_16x16x32_bf16 v[10:13], v[132:135], v[98:101], 0
	ds_read_b128 v[132:135], v118 offset:13824
	s_waitcnt lgkmcnt(5)
	v_mfma_f32_16x16x32_bf16 v[10:13], v[120:123], v[102:105], v[10:13]
	ds_read_b128 v[120:123], v118 offset:13888
	s_waitcnt lgkmcnt(5)
	v_mfma_f32_16x16x32_bf16 v[14:17], v[106:109], v[98:101], 0
	ds_read_b128 v[106:109], v118 offset:16128
	s_waitcnt lgkmcnt(5)
	v_mfma_f32_16x16x32_bf16 v[14:17], v[110:113], v[102:105], v[14:17]
	ds_read_b128 v[110:113], v118 offset:16192
	s_waitcnt lgkmcnt(5)
	v_mfma_f32_16x16x32_bf16 v[18:21], v[114:117], v[98:101], 0
	ds_read_b128 v[114:117], v118 offset:18432
	s_waitcnt lgkmcnt(5)
	v_mfma_f32_16x16x32_bf16 v[18:21], v[128:131], v[102:105], v[18:21]
	ds_read_b128 v[128:131], v118 offset:18496
	s_waitcnt lgkmcnt(5)
	v_mfma_f32_16x16x32_bf16 v[22:25], v[132:135], v[98:101], 0
	ds_read_b128 v[132:135], v118 offset:20736
	s_waitcnt lgkmcnt(5)
	v_mfma_f32_16x16x32_bf16 v[22:25], v[120:123], v[102:105], v[22:25]
	ds_read_b128 v[120:123], v118 offset:20800
	s_waitcnt lgkmcnt(5)
	v_mfma_f32_16x16x32_bf16 v[26:29], v[106:109], v[98:101], 0
	s_waitcnt lgkmcnt(4)
	v_mfma_f32_16x16x32_bf16 v[26:29], v[110:113], v[102:105], v[26:29]
	s_waitcnt lgkmcnt(3)
	v_mfma_f32_16x16x32_bf16 v[30:33], v[114:117], v[98:101], 0
	s_waitcnt lgkmcnt(2)
	v_mfma_f32_16x16x32_bf16 v[30:33], v[128:131], v[102:105], v[30:33]
	s_waitcnt lgkmcnt(1)
	v_mfma_f32_16x16x32_bf16 v[86:89], v[132:135], v[98:101], 0
	s_waitcnt lgkmcnt(0)
	v_mfma_f32_16x16x32_bf16 v[86:89], v[120:123], v[102:105], v[86:89]
	v_lshl_add_u64 v[240:241], v[246:247], 0, s[8:9]
	global_load_dwordx4 v[90:93], v[240:241], off
	global_load_dwordx4 v[94:97], v[240:241], off offset:64
	v_add_u32_e32 v242, 0, v249
	v_cmp_gt_u32_e32 vcc, v242, v248
	s_nop 1
	s_and_b64 vcc, vcc, s[66:67]
	s_nop 0
	v_cndmask_b32_e32 v2, v205, v2, vcc
	v_add_u32_e32 v242, 1, v249
	v_cmp_gt_u32_e32 vcc, v242, v248
	s_nop 1
	s_and_b64 vcc, vcc, s[66:67]
	s_nop 0
	v_cndmask_b32_e32 v3, v205, v3, vcc
	v_add_u32_e32 v242, 2, v249
	v_cmp_gt_u32_e32 vcc, v242, v248
	s_nop 1
	s_and_b64 vcc, vcc, s[66:67]
	s_nop 0
	v_cndmask_b32_e32 v4, v205, v4, vcc
	v_add_u32_e32 v242, 3, v249
	v_cmp_gt_u32_e32 vcc, v242, v248
	s_nop 1
	s_and_b64 vcc, vcc, s[66:67]
	s_nop 0
	v_cndmask_b32_e32 v5, v205, v5, vcc
	v_cndmask_b32_e64 v6, v205, v6, s[66:67]
	v_cndmask_b32_e64 v7, v205, v7, s[66:67]
	v_cndmask_b32_e64 v8, v205, v8, s[66:67]
	v_cndmask_b32_e64 v9, v205, v9, s[66:67]
	v_cndmask_b32_e64 v10, v205, v10, s[66:67]
	v_cndmask_b32_e64 v11, v205, v11, s[66:67]
	v_cndmask_b32_e64 v12, v205, v12, s[66:67]
	v_cndmask_b32_e64 v13, v205, v13, s[66:67]
	v_cndmask_b32_e64 v14, v205, v14, s[66:67]
	v_cndmask_b32_e64 v15, v205, v15, s[66:67]
	v_cndmask_b32_e64 v16, v205, v16, s[66:67]
	v_cndmask_b32_e64 v17, v205, v17, s[66:67]
	v_cndmask_b32_e64 v18, v205, v18, s[66:67]
	v_cndmask_b32_e64 v19, v205, v19, s[66:67]
	v_cndmask_b32_e64 v20, v205, v20, s[66:67]
	v_cndmask_b32_e64 v21, v205, v21, s[66:67]
	v_cndmask_b32_e64 v22, v205, v22, s[66:67]
	v_cndmask_b32_e64 v23, v205, v23, s[66:67]
	v_cndmask_b32_e64 v24, v205, v24, s[66:67]
	v_cndmask_b32_e64 v25, v205, v25, s[66:67]
	v_cndmask_b32_e64 v26, v205, v26, s[66:67]
	v_cndmask_b32_e64 v27, v205, v27, s[66:67]
	v_cndmask_b32_e64 v28, v205, v28, s[66:67]
	v_cndmask_b32_e64 v29, v205, v29, s[66:67]
	v_add_u32_e32 v242, 0, v249
	v_cmp_le_u32_e32 vcc, v242, v248
	s_nop 1
	v_cndmask_b32_e32 v86, v205, v86, vcc
	v_add_u32_e32 v242, 1, v249
	v_cmp_le_u32_e32 vcc, v242, v248
	s_nop 1
	v_cndmask_b32_e32 v87, v205, v87, vcc
	v_add_u32_e32 v242, 2, v249
	v_cmp_le_u32_e32 vcc, v242, v248
	s_nop 1
	v_cndmask_b32_e32 v88, v205, v88, vcc
	v_add_u32_e32 v242, 3, v249
	v_cmp_le_u32_e32 vcc, v242, v248
	s_nop 1
	v_cndmask_b32_e32 v89, v205, v89, vcc
	v_max3_f32 v238, v2, v3, v205
	v_max3_f32 v238, v238, v4, v5
	v_max3_f32 v238, v238, v6, v7
	v_max3_f32 v238, v238, v8, v9
	v_max3_f32 v238, v238, v10, v11
	v_max3_f32 v238, v238, v12, v13
	v_max3_f32 v238, v238, v14, v15
	v_max3_f32 v238, v238, v16, v17
	v_max3_f32 v238, v238, v18, v19
	v_max3_f32 v238, v238, v20, v21
	v_max3_f32 v238, v238, v22, v23
	v_max3_f32 v238, v238, v24, v25
	v_max3_f32 v238, v238, v26, v27
	v_max3_f32 v238, v238, v28, v29
	v_max3_f32 v238, v238, v30, v31
	v_max3_f32 v238, v238, v32, v33
	v_max3_f32 v238, v238, v86, v87
	v_max3_f32 v238, v238, v88, v89
	v_xor_b32_e32 v242, 16, v195
	v_lshlrev_b32_e32 v242, 2, v242
	ds_bpermute_b32 v242, v242, v238
	s_waitcnt lgkmcnt(0)
	v_max_f32_e32 v238, v238, v242
	v_xor_b32_e32 v242, 32, v195
	v_lshlrev_b32_e32 v242, 2, v242
	ds_bpermute_b32 v242, v242, v238
	s_waitcnt lgkmcnt(0)
	v_max_f32_e32 v238, v238, v242
	v_mul_f32_e32 v238, 0x3e000000, v238
	v_max_f32_e32 v238, v238, v85
	v_mul_f32_e32 v243, 0xbfb8aa3b, v238
	v_fmamk_f32 v2, v2, 0x3e38aa3b, v243
	v_fmamk_f32 v3, v3, 0x3e38aa3b, v243
	v_fmamk_f32 v4, v4, 0x3e38aa3b, v243
	v_fmamk_f32 v5, v5, 0x3e38aa3b, v243
	v_exp_f32_e32 v2, v2
	v_exp_f32_e32 v3, v3
	v_exp_f32_e32 v4, v4
	v_exp_f32_e32 v5, v5
	v_fmamk_f32 v6, v6, 0x3e38aa3b, v243
	v_fmamk_f32 v7, v7, 0x3e38aa3b, v243
	v_fmamk_f32 v8, v8, 0x3e38aa3b, v243
	v_fmamk_f32 v9, v9, 0x3e38aa3b, v243
	v_exp_f32_e32 v6, v6
	v_exp_f32_e32 v7, v7
	v_exp_f32_e32 v8, v8
	v_exp_f32_e32 v9, v9
	v_add_f32_e32 v239, 0, v2
	v_add_f32_e32 v239, v239, v3
	v_add_f32_e32 v239, v239, v4
	v_add_f32_e32 v239, v239, v5
	v_fmamk_f32 v10, v10, 0x3e38aa3b, v243
	v_fmamk_f32 v11, v11, 0x3e38aa3b, v243
	v_fmamk_f32 v12, v12, 0x3e38aa3b, v243
	v_fmamk_f32 v13, v13, 0x3e38aa3b, v243
	v_exp_f32_e32 v10, v10
	v_exp_f32_e32 v11, v11
	v_exp_f32_e32 v12, v12
	v_exp_f32_e32 v13, v13
	v_add_f32_e32 v239, v239, v6
	v_add_f32_e32 v239, v239, v7
	v_add_f32_e32 v239, v239, v8
	v_add_f32_e32 v239, v239, v9
	v_fmamk_f32 v14, v14, 0x3e38aa3b, v243
	v_fmamk_f32 v15, v15, 0x3e38aa3b, v243
	v_fmamk_f32 v16, v16, 0x3e38aa3b, v243
	v_fmamk_f32 v17, v17, 0x3e38aa3b, v243
	v_exp_f32_e32 v14, v14
	v_exp_f32_e32 v15, v15
	v_exp_f32_e32 v16, v16
	v_exp_f32_e32 v17, v17
	v_add_f32_e32 v239, v239, v10
	v_add_f32_e32 v239, v239, v11
	v_add_f32_e32 v239, v239, v12
	v_add_f32_e32 v239, v239, v13
	v_fmamk_f32 v18, v18, 0x3e38aa3b, v243
	v_fmamk_f32 v19, v19, 0x3e38aa3b, v243
	v_fmamk_f32 v20, v20, 0x3e38aa3b, v243
	v_fmamk_f32 v21, v21, 0x3e38aa3b, v243
	v_exp_f32_e32 v18, v18
	v_exp_f32_e32 v19, v19
	v_exp_f32_e32 v20, v20
	v_exp_f32_e32 v21, v21
	v_add_f32_e32 v239, v239, v14
	v_add_f32_e32 v239, v239, v15
	v_add_f32_e32 v239, v239, v16
	v_add_f32_e32 v239, v239, v17
	v_fmamk_f32 v22, v22, 0x3e38aa3b, v243
	v_fmamk_f32 v23, v23, 0x3e38aa3b, v243
	v_fmamk_f32 v24, v24, 0x3e38aa3b, v243
	v_fmamk_f32 v25, v25, 0x3e38aa3b, v243
	v_exp_f32_e32 v22, v22
	v_exp_f32_e32 v23, v23
	v_exp_f32_e32 v24, v24
	v_exp_f32_e32 v25, v25
	v_add_f32_e32 v239, v239, v18
	v_add_f32_e32 v239, v239, v19
	v_add_f32_e32 v239, v239, v20
	v_add_f32_e32 v239, v239, v21
	v_fmamk_f32 v26, v26, 0x3e38aa3b, v243
	v_fmamk_f32 v27, v27, 0x3e38aa3b, v243
	v_fmamk_f32 v28, v28, 0x3e38aa3b, v243
	v_fmamk_f32 v29, v29, 0x3e38aa3b, v243
	v_exp_f32_e32 v26, v26
	v_exp_f32_e32 v27, v27
	v_exp_f32_e32 v28, v28
	v_exp_f32_e32 v29, v29
	v_add_f32_e32 v239, v239, v22
	v_add_f32_e32 v239, v239, v23
	v_add_f32_e32 v239, v239, v24
	v_add_f32_e32 v239, v239, v25
	v_fmamk_f32 v30, v30, 0x3e38aa3b, v243
	v_fmamk_f32 v31, v31, 0x3e38aa3b, v243
	v_fmamk_f32 v32, v32, 0x3e38aa3b, v243
	v_fmamk_f32 v33, v33, 0x3e38aa3b, v243
	v_exp_f32_e32 v30, v30
	v_exp_f32_e32 v31, v31
	v_exp_f32_e32 v32, v32
	v_exp_f32_e32 v33, v33
	v_add_f32_e32 v239, v239, v26
	v_add_f32_e32 v239, v239, v27
	v_add_f32_e32 v239, v239, v28
	v_add_f32_e32 v239, v239, v29
	v_fmamk_f32 v86, v86, 0x3e38aa3b, v243
	v_fmamk_f32 v87, v87, 0x3e38aa3b, v243
	v_fmamk_f32 v88, v88, 0x3e38aa3b, v243
	v_fmamk_f32 v89, v89, 0x3e38aa3b, v243
	v_exp_f32_e32 v86, v86
	v_exp_f32_e32 v87, v87
	v_exp_f32_e32 v88, v88
	v_exp_f32_e32 v89, v89
	v_add_f32_e32 v239, v239, v30
	v_add_f32_e32 v239, v239, v31
	v_add_f32_e32 v239, v239, v32
	v_add_f32_e32 v239, v239, v33
	s_nop 0
	v_add_f32_e32 v239, v239, v86
	v_add_f32_e32 v239, v239, v87
	v_add_f32_e32 v239, v239, v88
	v_add_f32_e32 v239, v239, v89
	v_xor_b32_e32 v242, 16, v195
	v_lshlrev_b32_e32 v242, 2, v242
	ds_bpermute_b32 v242, v242, v239
	s_waitcnt lgkmcnt(0)
	v_add_f32_e32 v239, v239, v242
	v_xor_b32_e32 v242, 32, v195
	v_lshlrev_b32_e32 v242, 2, v242
	ds_bpermute_b32 v242, v242, v239
	s_waitcnt lgkmcnt(0)
	v_add_f32_e32 v239, v239, v242
	v_sub_f32_e32 v242, v85, v238
	v_mul_f32_e32 v242, 0x3fb8aa3b, v242
	v_exp_f32_e32 v242, v242
	s_nop 0
	v_add_f32_e32 v239, v239, v242
	v_rcp_f32_e32 v244, v239
	v_cvt_pk_bf16_f32 v218, v2, v3
	v_cvt_pk_bf16_f32 v219, v4, v5
	v_cvt_pk_bf16_f32 v220, v6, v7
	v_cvt_pk_bf16_f32 v221, v8, v9
	v_cvt_pk_bf16_f32 v222, v10, v11
	v_cvt_pk_bf16_f32 v223, v12, v13
	v_cvt_pk_bf16_f32 v224, v14, v15
	v_cvt_pk_bf16_f32 v225, v16, v17
	v_cvt_pk_bf16_f32 v226, v18, v19
	v_cvt_pk_bf16_f32 v227, v20, v21
	v_cvt_pk_bf16_f32 v228, v22, v23
	v_cvt_pk_bf16_f32 v229, v24, v25
	v_cvt_pk_bf16_f32 v230, v26, v27
	v_cvt_pk_bf16_f32 v231, v28, v29
	v_cvt_pk_bf16_f32 v232, v30, v31
	v_cvt_pk_bf16_f32 v233, v32, v33
	v_cvt_pk_bf16_f32 v234, v86, v87
	v_cvt_pk_bf16_f32 v235, v88, v89
	v_mov_b32_e32 v236, 0
	v_mov_b32_e32 v237, 0
	ds_read_b64 v[182:183], v245 offset:32
	ds_read_b64 v[184:185], v245 offset:64
	ds_read_b64 v[186:187], v245 offset:8480
	ds_read_b64 v[188:189], v245 offset:8512
	ds_read_b64 v[190:191], v245 offset:16928
	ds_read_b64 v[192:193], v245 offset:16960
	ds_read_b64 v[210:211], v245 offset:25376
	ds_read_b64 v[212:213], v245 offset:25408
	ds_read_b64 v[214:215], v245 offset:96
	ds_read_b64 v[216:217], v245 offset:128
	s_waitcnt lgkmcnt(8)
	v_mfma_f32_16x16x32_bf16 v[142:145], v[182:185], v[218:221], 0
	ds_read_b64 v[182:183], v245 offset:8544
	ds_read_b64 v[184:185], v245 offset:8576
	s_waitcnt lgkmcnt(8)
	v_mfma_f32_16x16x32_bf16 v[146:149], v[186:189], v[218:221], 0
	ds_read_b64 v[186:187], v245 offset:16992
	ds_read_b64 v[188:189], v245 offset:17024
	s_waitcnt lgkmcnt(8)
	v_mfma_f32_16x16x32_bf16 v[150:153], v[190:193], v[218:221], 0
	ds_read_b64 v[190:191], v245 offset:25440
	ds_read_b64 v[192:193], v245 offset:25472
	s_waitcnt lgkmcnt(8)
	v_mfma_f32_16x16x32_bf16 v[154:157], v[210:213], v[218:221], 0
	ds_read_b64 v[210:211], v245 offset:160
	ds_read_b64 v[212:213], v245 offset:192
	s_waitcnt lgkmcnt(8)
	v_mfma_f32_16x16x32_bf16 v[142:145], v[214:217], v[222:225], v[142:145]
	ds_read_b64 v[214:215], v245 offset:8608
	ds_read_b64 v[216:217], v245 offset:8640
	s_waitcnt lgkmcnt(8)
	v_mfma_f32_16x16x32_bf16 v[146:149], v[182:185], v[222:225], v[146:149]
	ds_read_b64 v[182:183], v245 offset:17056
	ds_read_b64 v[184:185], v245 offset:17088
	s_waitcnt lgkmcnt(8)
	v_mfma_f32_16x16x32_bf16 v[150:153], v[186:189], v[222:225], v[150:153]
	ds_read_b64 v[186:187], v245 offset:25504
	ds_read_b64 v[188:189], v245 offset:25536
	s_waitcnt lgkmcnt(8)
	v_mfma_f32_16x16x32_bf16 v[154:157], v[190:193], v[222:225], v[154:157]
	ds_read_b64 v[190:191], v245 offset:224
	ds_read_b64 v[192:193], v245 offset:256
	s_waitcnt lgkmcnt(8)
	v_mfma_f32_16x16x32_bf16 v[142:145], v[210:213], v[226:229], v[142:145]
	ds_read_b64 v[210:211], v245 offset:8672
	ds_read_b64 v[212:213], v245 offset:8704
	s_waitcnt lgkmcnt(8)
	v_mfma_f32_16x16x32_bf16 v[146:149], v[214:217], v[226:229], v[146:149]
	ds_read_b64 v[214:215], v245 offset:17120
	ds_read_b64 v[216:217], v245 offset:17152
	s_waitcnt lgkmcnt(8)
	v_mfma_f32_16x16x32_bf16 v[150:153], v[182:185], v[226:229], v[150:153]
	ds_read_b64 v[182:183], v245 offset:25568
	ds_read_b64 v[184:185], v245 offset:25600
	s_waitcnt lgkmcnt(8)
	v_mfma_f32_16x16x32_bf16 v[154:157], v[186:189], v[226:229], v[154:157]
	ds_read_b64 v[186:187], v245 offset:288
	ds_read_b64 v[188:189], v245 offset:288
	s_waitcnt lgkmcnt(8)
	v_mfma_f32_16x16x32_bf16 v[142:145], v[190:193], v[230:233], v[142:145]
	ds_read_b64 v[190:191], v245 offset:8736
	ds_read_b64 v[192:193], v245 offset:8736
	s_waitcnt lgkmcnt(8)
	v_mfma_f32_16x16x32_bf16 v[146:149], v[210:213], v[230:233], v[146:149]
	ds_read_b64 v[210:211], v245 offset:17184
	ds_read_b64 v[212:213], v245 offset:17184
	s_waitcnt lgkmcnt(8)
	v_mfma_f32_16x16x32_bf16 v[150:153], v[214:217], v[230:233], v[150:153]
	ds_read_b64 v[214:215], v245 offset:25632
	ds_read_b64 v[216:217], v245 offset:25632
	s_waitcnt lgkmcnt(8)
	v_mfma_f32_16x16x32_bf16 v[154:157], v[182:185], v[230:233], v[154:157]
	s_waitcnt lgkmcnt(6)
	v_mfma_f32_16x16x32_bf16 v[142:145], v[186:189], v[234:237], v[142:145]
	s_waitcnt lgkmcnt(4)
	v_mfma_f32_16x16x32_bf16 v[146:149], v[190:193], v[234:237], v[146:149]
	s_waitcnt lgkmcnt(2)
	v_mfma_f32_16x16x32_bf16 v[150:153], v[210:213], v[234:237], v[150:153]
	s_waitcnt lgkmcnt(0)
	v_mfma_f32_16x16x32_bf16 v[154:157], v[214:217], v[234:237], v[154:157]
	s_nop 7
	s_nop 1
	v_mul_f32_e32 v142, v244, v142
	v_mul_f32_e32 v143, v244, v143
	v_mul_f32_e32 v144, v244, v144
	v_mul_f32_e32 v145, v244, v145
	v_mul_f32_e32 v146, v244, v146
	v_mul_f32_e32 v147, v244, v147
	v_mul_f32_e32 v148, v244, v148
	v_mul_f32_e32 v149, v244, v149
	v_cvt_pk_bf16_f32 v240, v142, v143
	v_cvt_pk_bf16_f32 v241, v144, v145
	v_cvt_pk_bf16_f32 v242, v146, v147
	v_cvt_pk_bf16_f32 v243, v148, v149
	global_store_dwordx4 v[246:247], v[240:243], off sc1
	s_nop 1
	v_mul_f32_e32 v150, v244, v150
	v_mul_f32_e32 v151, v244, v151
	v_mul_f32_e32 v152, v244, v152
	v_mul_f32_e32 v153, v244, v153
	v_mul_f32_e32 v154, v244, v154
	v_mul_f32_e32 v155, v244, v155
	v_mul_f32_e32 v156, v244, v156
	v_mul_f32_e32 v157, v244, v157
	v_cvt_pk_bf16_f32 v240, v150, v151
	v_cvt_pk_bf16_f32 v241, v152, v153
	v_cvt_pk_bf16_f32 v242, v154, v155
	v_cvt_pk_bf16_f32 v243, v156, v157
	global_store_dwordx4 v[246:247], v[240:243], off offset:64 sc1
	v_lshl_add_u64 v[246:247], v[246:247], 0, s[8:9]
	s_waitcnt vmcnt(2)
	ds_read_b128 v[106:109], v118 offset:4608
	ds_read_b128 v[110:113], v118 offset:4672
	ds_read_b128 v[114:117], v118 offset:6912
	ds_read_b128 v[128:131], v118 offset:6976
	ds_read_b128 v[132:135], v118 offset:9216
	ds_read_b128 v[120:123], v118 offset:9280
	s_waitcnt lgkmcnt(5)
	v_mfma_f32_16x16x32_bf16 v[2:5], v[106:109], v[90:93], 0
	ds_read_b128 v[106:109], v118 offset:11520
	s_waitcnt lgkmcnt(5)
	v_mfma_f32_16x16x32_bf16 v[2:5], v[110:113], v[94:97], v[2:5]
	ds_read_b128 v[110:113], v118 offset:11584
	s_waitcnt lgkmcnt(5)
	v_mfma_f32_16x16x32_bf16 v[6:9], v[114:117], v[90:93], 0
	ds_read_b128 v[114:117], v118 offset:13824
	s_waitcnt lgkmcnt(5)
	v_mfma_f32_16x16x32_bf16 v[6:9], v[128:131], v[94:97], v[6:9]
	ds_read_b128 v[128:131], v118 offset:13888
	s_waitcnt lgkmcnt(5)
	v_mfma_f32_16x16x32_bf16 v[10:13], v[132:135], v[90:93], 0
	ds_read_b128 v[132:135], v118 offset:16128
	s_waitcnt lgkmcnt(5)
	v_mfma_f32_16x16x32_bf16 v[10:13], v[120:123], v[94:97], v[10:13]
	ds_read_b128 v[120:123], v118 offset:16192
	s_waitcnt lgkmcnt(5)
	v_mfma_f32_16x16x32_bf16 v[14:17], v[106:109], v[90:93], 0
	ds_read_b128 v[106:109], v118 offset:18432
	s_waitcnt lgkmcnt(5)
	v_mfma_f32_16x16x32_bf16 v[14:17], v[110:113], v[94:97], v[14:17]
	ds_read_b128 v[110:113], v118 offset:18496
	s_waitcnt lgkmcnt(5)
	v_mfma_f32_16x16x32_bf16 v[18:21], v[114:117], v[90:93], 0
	ds_read_b128 v[114:117], v118 offset:20736
	s_waitcnt lgkmcnt(5)
	v_mfma_f32_16x16x32_bf16 v[18:21], v[128:131], v[94:97], v[18:21]
	ds_read_b128 v[128:131], v118 offset:20800
	s_waitcnt lgkmcnt(5)
	v_mfma_f32_16x16x32_bf16 v[22:25], v[132:135], v[90:93], 0
	ds_read_b128 v[132:135], v118 offset:23040
	s_waitcnt lgkmcnt(5)
	v_mfma_f32_16x16x32_bf16 v[22:25], v[120:123], v[94:97], v[22:25]
	ds_read_b128 v[120:123], v118 offset:23104
	s_waitcnt lgkmcnt(5)
	v_mfma_f32_16x16x32_bf16 v[26:29], v[106:109], v[90:93], 0
	s_waitcnt lgkmcnt(4)
	v_mfma_f32_16x16x32_bf16 v[26:29], v[110:113], v[94:97], v[26:29]
	s_waitcnt lgkmcnt(3)
	v_mfma_f32_16x16x32_bf16 v[30:33], v[114:117], v[90:93], 0
	s_waitcnt lgkmcnt(2)
	v_mfma_f32_16x16x32_bf16 v[30:33], v[128:131], v[94:97], v[30:33]
	s_waitcnt lgkmcnt(1)
	v_mfma_f32_16x16x32_bf16 v[86:89], v[132:135], v[90:93], 0
	s_waitcnt lgkmcnt(0)
	v_mfma_f32_16x16x32_bf16 v[86:89], v[120:123], v[94:97], v[86:89]
	v_lshl_add_u64 v[240:241], v[246:247], 0, s[8:9]
	global_load_dwordx4 v[98:101], v[240:241], off
	global_load_dwordx4 v[102:105], v[240:241], off offset:64
	v_add_u32_e32 v242, 0, v249
	v_cmp_gt_u32_e32 vcc, v242, v248
	s_nop 1
	s_and_b64 vcc, vcc, s[66:67]
	s_nop 0
	v_cndmask_b32_e32 v2, v205, v2, vcc
	v_add_u32_e32 v242, 1, v249
	v_cmp_gt_u32_e32 vcc, v242, v248
	s_nop 1
	s_and_b64 vcc, vcc, s[66:67]
	s_nop 0
	v_cndmask_b32_e32 v3, v205, v3, vcc
	v_add_u32_e32 v242, 2, v249
	v_cmp_gt_u32_e32 vcc, v242, v248
	s_nop 1
	s_and_b64 vcc, vcc, s[66:67]
	s_nop 0
	v_cndmask_b32_e32 v4, v205, v4, vcc
	v_add_u32_e32 v242, 3, v249
	v_cmp_gt_u32_e32 vcc, v242, v248
	s_nop 1
	s_and_b64 vcc, vcc, s[66:67]
	s_nop 0
	v_cndmask_b32_e32 v5, v205, v5, vcc
	v_cndmask_b32_e64 v6, v205, v6, s[66:67]
	v_cndmask_b32_e64 v7, v205, v7, s[66:67]
	v_cndmask_b32_e64 v8, v205, v8, s[66:67]
	v_cndmask_b32_e64 v9, v205, v9, s[66:67]
	v_cndmask_b32_e64 v10, v205, v10, s[66:67]
	v_cndmask_b32_e64 v11, v205, v11, s[66:67]
	v_cndmask_b32_e64 v12, v205, v12, s[66:67]
	v_cndmask_b32_e64 v13, v205, v13, s[66:67]
	v_cndmask_b32_e64 v14, v205, v14, s[66:67]
	v_cndmask_b32_e64 v15, v205, v15, s[66:67]
	v_cndmask_b32_e64 v16, v205, v16, s[66:67]
	v_cndmask_b32_e64 v17, v205, v17, s[66:67]
	v_cndmask_b32_e64 v18, v205, v18, s[66:67]
	v_cndmask_b32_e64 v19, v205, v19, s[66:67]
	v_cndmask_b32_e64 v20, v205, v20, s[66:67]
	v_cndmask_b32_e64 v21, v205, v21, s[66:67]
	v_cndmask_b32_e64 v22, v205, v22, s[66:67]
	v_cndmask_b32_e64 v23, v205, v23, s[66:67]
	v_cndmask_b32_e64 v24, v205, v24, s[66:67]
	v_cndmask_b32_e64 v25, v205, v25, s[66:67]
	v_add_u32_e32 v242, 0, v249
	v_cmp_le_u32_e32 vcc, v242, v248
	s_nop 1
	v_cndmask_b32_e32 v86, v205, v86, vcc
	v_add_u32_e32 v242, 1, v249
	v_cmp_le_u32_e32 vcc, v242, v248
	s_nop 1
	v_cndmask_b32_e32 v87, v205, v87, vcc
	v_add_u32_e32 v242, 2, v249
	v_cmp_le_u32_e32 vcc, v242, v248
	s_nop 1
	v_cndmask_b32_e32 v88, v205, v88, vcc
	v_add_u32_e32 v242, 3, v249
	v_cmp_le_u32_e32 vcc, v242, v248
	s_nop 1
	v_cndmask_b32_e32 v89, v205, v89, vcc
	v_max3_f32 v238, v2, v3, v205
	v_max3_f32 v238, v238, v4, v5
	v_max3_f32 v238, v238, v6, v7
	v_max3_f32 v238, v238, v8, v9
	v_max3_f32 v238, v238, v10, v11
	v_max3_f32 v238, v238, v12, v13
	v_max3_f32 v238, v238, v14, v15
	v_max3_f32 v238, v238, v16, v17
	v_max3_f32 v238, v238, v18, v19
	v_max3_f32 v238, v238, v20, v21
	v_max3_f32 v238, v238, v22, v23
	v_max3_f32 v238, v238, v24, v25
	v_max3_f32 v238, v238, v26, v27
	v_max3_f32 v238, v238, v28, v29
	v_max3_f32 v238, v238, v30, v31
	v_max3_f32 v238, v238, v32, v33
	v_max3_f32 v238, v238, v86, v87
	v_max3_f32 v238, v238, v88, v89
	v_xor_b32_e32 v242, 16, v195
	v_lshlrev_b32_e32 v242, 2, v242
	ds_bpermute_b32 v242, v242, v238
	s_waitcnt lgkmcnt(0)
	v_max_f32_e32 v238, v238, v242
	v_xor_b32_e32 v242, 32, v195
	v_lshlrev_b32_e32 v242, 2, v242
	ds_bpermute_b32 v242, v242, v238
	s_waitcnt lgkmcnt(0)
	v_max_f32_e32 v238, v238, v242
	v_mul_f32_e32 v238, 0x3e000000, v238
	v_max_f32_e32 v238, v238, v85
	v_mul_f32_e32 v243, 0xbfb8aa3b, v238
	v_fmamk_f32 v2, v2, 0x3e38aa3b, v243
	v_fmamk_f32 v3, v3, 0x3e38aa3b, v243
	v_fmamk_f32 v4, v4, 0x3e38aa3b, v243
	v_fmamk_f32 v5, v5, 0x3e38aa3b, v243
	v_exp_f32_e32 v2, v2
	v_exp_f32_e32 v3, v3
	v_exp_f32_e32 v4, v4
	v_exp_f32_e32 v5, v5
	v_fmamk_f32 v6, v6, 0x3e38aa3b, v243
	v_fmamk_f32 v7, v7, 0x3e38aa3b, v243
	v_fmamk_f32 v8, v8, 0x3e38aa3b, v243
	v_fmamk_f32 v9, v9, 0x3e38aa3b, v243
	v_exp_f32_e32 v6, v6
	v_exp_f32_e32 v7, v7
	v_exp_f32_e32 v8, v8
	v_exp_f32_e32 v9, v9
	v_add_f32_e32 v239, 0, v2
	v_add_f32_e32 v239, v239, v3
	v_add_f32_e32 v239, v239, v4
	v_add_f32_e32 v239, v239, v5
	v_fmamk_f32 v10, v10, 0x3e38aa3b, v243
	v_fmamk_f32 v11, v11, 0x3e38aa3b, v243
	v_fmamk_f32 v12, v12, 0x3e38aa3b, v243
	v_fmamk_f32 v13, v13, 0x3e38aa3b, v243
	v_exp_f32_e32 v10, v10
	v_exp_f32_e32 v11, v11
	v_exp_f32_e32 v12, v12
	v_exp_f32_e32 v13, v13
	v_add_f32_e32 v239, v239, v6
	v_add_f32_e32 v239, v239, v7
	v_add_f32_e32 v239, v239, v8
	v_add_f32_e32 v239, v239, v9
	v_fmamk_f32 v14, v14, 0x3e38aa3b, v243
	v_fmamk_f32 v15, v15, 0x3e38aa3b, v243
	v_fmamk_f32 v16, v16, 0x3e38aa3b, v243
	v_fmamk_f32 v17, v17, 0x3e38aa3b, v243
	v_exp_f32_e32 v14, v14
	v_exp_f32_e32 v15, v15
	v_exp_f32_e32 v16, v16
	v_exp_f32_e32 v17, v17
	v_add_f32_e32 v239, v239, v10
	v_add_f32_e32 v239, v239, v11
	v_add_f32_e32 v239, v239, v12
	v_add_f32_e32 v239, v239, v13
	v_fmamk_f32 v18, v18, 0x3e38aa3b, v243
	v_fmamk_f32 v19, v19, 0x3e38aa3b, v243
	v_fmamk_f32 v20, v20, 0x3e38aa3b, v243
	v_fmamk_f32 v21, v21, 0x3e38aa3b, v243
	v_exp_f32_e32 v18, v18
	v_exp_f32_e32 v19, v19
	v_exp_f32_e32 v20, v20
	v_exp_f32_e32 v21, v21
	v_add_f32_e32 v239, v239, v14
	v_add_f32_e32 v239, v239, v15
	v_add_f32_e32 v239, v239, v16
	v_add_f32_e32 v239, v239, v17
	v_fmamk_f32 v22, v22, 0x3e38aa3b, v243
	v_fmamk_f32 v23, v23, 0x3e38aa3b, v243
	v_fmamk_f32 v24, v24, 0x3e38aa3b, v243
	v_fmamk_f32 v25, v25, 0x3e38aa3b, v243
	v_exp_f32_e32 v22, v22
	v_exp_f32_e32 v23, v23
	v_exp_f32_e32 v24, v24
	v_exp_f32_e32 v25, v25
	v_add_f32_e32 v239, v239, v18
	v_add_f32_e32 v239, v239, v19
	v_add_f32_e32 v239, v239, v20
	v_add_f32_e32 v239, v239, v21
	v_fmamk_f32 v26, v26, 0x3e38aa3b, v243
	v_fmamk_f32 v27, v27, 0x3e38aa3b, v243
	v_fmamk_f32 v28, v28, 0x3e38aa3b, v243
	v_fmamk_f32 v29, v29, 0x3e38aa3b, v243
	v_exp_f32_e32 v26, v26
	v_exp_f32_e32 v27, v27
	v_exp_f32_e32 v28, v28
	v_exp_f32_e32 v29, v29
	v_add_f32_e32 v239, v239, v22
	v_add_f32_e32 v239, v239, v23
	v_add_f32_e32 v239, v239, v24
	v_add_f32_e32 v239, v239, v25
	v_fmamk_f32 v30, v30, 0x3e38aa3b, v243
	v_fmamk_f32 v31, v31, 0x3e38aa3b, v243
	v_fmamk_f32 v32, v32, 0x3e38aa3b, v243
	v_fmamk_f32 v33, v33, 0x3e38aa3b, v243
	v_exp_f32_e32 v30, v30
	v_exp_f32_e32 v31, v31
	v_exp_f32_e32 v32, v32
	v_exp_f32_e32 v33, v33
	v_add_f32_e32 v239, v239, v26
	v_add_f32_e32 v239, v239, v27
	v_add_f32_e32 v239, v239, v28
	v_add_f32_e32 v239, v239, v29
	v_fmamk_f32 v86, v86, 0x3e38aa3b, v243
	v_fmamk_f32 v87, v87, 0x3e38aa3b, v243
	v_fmamk_f32 v88, v88, 0x3e38aa3b, v243
	v_fmamk_f32 v89, v89, 0x3e38aa3b, v243
	v_exp_f32_e32 v86, v86
	v_exp_f32_e32 v87, v87
	v_exp_f32_e32 v88, v88
	v_exp_f32_e32 v89, v89
	v_add_f32_e32 v239, v239, v30
	v_add_f32_e32 v239, v239, v31
	v_add_f32_e32 v239, v239, v32
	v_add_f32_e32 v239, v239, v33
	s_nop 0
	v_add_f32_e32 v239, v239, v86
	v_add_f32_e32 v239, v239, v87
	v_add_f32_e32 v239, v239, v88
	v_add_f32_e32 v239, v239, v89
	v_xor_b32_e32 v242, 16, v195
	v_lshlrev_b32_e32 v242, 2, v242
	ds_bpermute_b32 v242, v242, v239
	s_waitcnt lgkmcnt(0)
	v_add_f32_e32 v239, v239, v242
	v_xor_b32_e32 v242, 32, v195
	v_lshlrev_b32_e32 v242, 2, v242
	ds_bpermute_b32 v242, v242, v239
	s_waitcnt lgkmcnt(0)
	v_add_f32_e32 v239, v239, v242
	v_sub_f32_e32 v242, v85, v238
	v_mul_f32_e32 v242, 0x3fb8aa3b, v242
	v_exp_f32_e32 v242, v242
	s_nop 0
	v_add_f32_e32 v239, v239, v242
	v_rcp_f32_e32 v244, v239
	v_cvt_pk_bf16_f32 v218, v2, v3
	v_cvt_pk_bf16_f32 v219, v4, v5
	v_cvt_pk_bf16_f32 v220, v6, v7
	v_cvt_pk_bf16_f32 v221, v8, v9
	v_cvt_pk_bf16_f32 v222, v10, v11
	v_cvt_pk_bf16_f32 v223, v12, v13
	v_cvt_pk_bf16_f32 v224, v14, v15
	v_cvt_pk_bf16_f32 v225, v16, v17
	v_cvt_pk_bf16_f32 v226, v18, v19
	v_cvt_pk_bf16_f32 v227, v20, v21
	v_cvt_pk_bf16_f32 v228, v22, v23
	v_cvt_pk_bf16_f32 v229, v24, v25
	v_cvt_pk_bf16_f32 v230, v26, v27
	v_cvt_pk_bf16_f32 v231, v28, v29
	v_cvt_pk_bf16_f32 v232, v30, v31
	v_cvt_pk_bf16_f32 v233, v32, v33
	v_cvt_pk_bf16_f32 v234, v86, v87
	v_cvt_pk_bf16_f32 v235, v88, v89
	v_mov_b32_e32 v236, 0
	v_mov_b32_e32 v237, 0
	ds_read_b64 v[182:183], v245 offset:64
	ds_read_b64 v[184:185], v245 offset:96
	ds_read_b64 v[186:187], v245 offset:8512
	ds_read_b64 v[188:189], v245 offset:8544
	ds_read_b64 v[190:191], v245 offset:16960
	ds_read_b64 v[192:193], v245 offset:16992
	ds_read_b64 v[210:211], v245 offset:25408
	ds_read_b64 v[212:213], v245 offset:25440
	ds_read_b64 v[214:215], v245 offset:128
	ds_read_b64 v[216:217], v245 offset:160
	s_waitcnt lgkmcnt(8)
	v_mfma_f32_16x16x32_bf16 v[142:145], v[182:185], v[218:221], 0
	ds_read_b64 v[182:183], v245 offset:8576
	ds_read_b64 v[184:185], v245 offset:8608
	s_waitcnt lgkmcnt(8)
	v_mfma_f32_16x16x32_bf16 v[146:149], v[186:189], v[218:221], 0
	ds_read_b64 v[186:187], v245 offset:17024
	ds_read_b64 v[188:189], v245 offset:17056
	s_waitcnt lgkmcnt(8)
	v_mfma_f32_16x16x32_bf16 v[150:153], v[190:193], v[218:221], 0
	ds_read_b64 v[190:191], v245 offset:25472
	ds_read_b64 v[192:193], v245 offset:25504
	s_waitcnt lgkmcnt(8)
	v_mfma_f32_16x16x32_bf16 v[154:157], v[210:213], v[218:221], 0
	ds_read_b64 v[210:211], v245 offset:192
	ds_read_b64 v[212:213], v245 offset:224
	s_waitcnt lgkmcnt(8)
	v_mfma_f32_16x16x32_bf16 v[142:145], v[214:217], v[222:225], v[142:145]
	ds_read_b64 v[214:215], v245 offset:8640
	ds_read_b64 v[216:217], v245 offset:8672
	s_waitcnt lgkmcnt(8)
	v_mfma_f32_16x16x32_bf16 v[146:149], v[182:185], v[222:225], v[146:149]
	ds_read_b64 v[182:183], v245 offset:17088
	ds_read_b64 v[184:185], v245 offset:17120
	s_waitcnt lgkmcnt(8)
	v_mfma_f32_16x16x32_bf16 v[150:153], v[186:189], v[222:225], v[150:153]
	ds_read_b64 v[186:187], v245 offset:25536
	ds_read_b64 v[188:189], v245 offset:25568
	s_waitcnt lgkmcnt(8)
	v_mfma_f32_16x16x32_bf16 v[154:157], v[190:193], v[222:225], v[154:157]
	ds_read_b64 v[190:191], v245 offset:256
	ds_read_b64 v[192:193], v245 offset:288
	s_waitcnt lgkmcnt(8)
	v_mfma_f32_16x16x32_bf16 v[142:145], v[210:213], v[226:229], v[142:145]
	ds_read_b64 v[210:211], v245 offset:8704
	ds_read_b64 v[212:213], v245 offset:8736
	s_waitcnt lgkmcnt(8)
	v_mfma_f32_16x16x32_bf16 v[146:149], v[214:217], v[226:229], v[146:149]
	ds_read_b64 v[214:215], v245 offset:17152
	ds_read_b64 v[216:217], v245 offset:17184
	s_waitcnt lgkmcnt(8)
	v_mfma_f32_16x16x32_bf16 v[150:153], v[182:185], v[226:229], v[150:153]
	ds_read_b64 v[182:183], v245 offset:25600
	ds_read_b64 v[184:185], v245 offset:25632
	s_waitcnt lgkmcnt(8)
	v_mfma_f32_16x16x32_bf16 v[154:157], v[186:189], v[226:229], v[154:157]
	ds_read_b64 v[186:187], v245 offset:320
	ds_read_b64 v[188:189], v245 offset:320
	s_waitcnt lgkmcnt(8)
	v_mfma_f32_16x16x32_bf16 v[142:145], v[190:193], v[230:233], v[142:145]
	ds_read_b64 v[190:191], v245 offset:8768
	ds_read_b64 v[192:193], v245 offset:8768
	s_waitcnt lgkmcnt(8)
	v_mfma_f32_16x16x32_bf16 v[146:149], v[210:213], v[230:233], v[146:149]
	ds_read_b64 v[210:211], v245 offset:17216
	ds_read_b64 v[212:213], v245 offset:17216
	s_waitcnt lgkmcnt(8)
	v_mfma_f32_16x16x32_bf16 v[150:153], v[214:217], v[230:233], v[150:153]
	ds_read_b64 v[214:215], v245 offset:25664
	ds_read_b64 v[216:217], v245 offset:25664
	s_waitcnt lgkmcnt(8)
	v_mfma_f32_16x16x32_bf16 v[154:157], v[182:185], v[230:233], v[154:157]
	s_waitcnt lgkmcnt(6)
	v_mfma_f32_16x16x32_bf16 v[142:145], v[186:189], v[234:237], v[142:145]
	s_waitcnt lgkmcnt(4)
	v_mfma_f32_16x16x32_bf16 v[146:149], v[190:193], v[234:237], v[146:149]
	s_waitcnt lgkmcnt(2)
	v_mfma_f32_16x16x32_bf16 v[150:153], v[210:213], v[234:237], v[150:153]
	s_waitcnt lgkmcnt(0)
	v_mfma_f32_16x16x32_bf16 v[154:157], v[214:217], v[234:237], v[154:157]
	s_nop 7
	s_nop 1
	v_mul_f32_e32 v142, v244, v142
	v_mul_f32_e32 v143, v244, v143
	v_mul_f32_e32 v144, v244, v144
	v_mul_f32_e32 v145, v244, v145
	v_mul_f32_e32 v146, v244, v146
	v_mul_f32_e32 v147, v244, v147
	v_mul_f32_e32 v148, v244, v148
	v_mul_f32_e32 v149, v244, v149
	v_cvt_pk_bf16_f32 v240, v142, v143
	v_cvt_pk_bf16_f32 v241, v144, v145
	v_cvt_pk_bf16_f32 v242, v146, v147
	v_cvt_pk_bf16_f32 v243, v148, v149
	global_store_dwordx4 v[246:247], v[240:243], off sc1
	s_nop 1
	v_mul_f32_e32 v150, v244, v150
	v_mul_f32_e32 v151, v244, v151
	v_mul_f32_e32 v152, v244, v152
	v_mul_f32_e32 v153, v244, v153
	v_mul_f32_e32 v154, v244, v154
	v_mul_f32_e32 v155, v244, v155
	v_mul_f32_e32 v156, v244, v156
	v_mul_f32_e32 v157, v244, v157
	v_cvt_pk_bf16_f32 v240, v150, v151
	v_cvt_pk_bf16_f32 v241, v152, v153
	v_cvt_pk_bf16_f32 v242, v154, v155
	v_cvt_pk_bf16_f32 v243, v156, v157
	global_store_dwordx4 v[246:247], v[240:243], off offset:64 sc1
	v_lshl_add_u64 v[246:247], v[246:247], 0, s[8:9]
	s_waitcnt vmcnt(2)
	ds_read_b128 v[106:109], v118 offset:6912
	ds_read_b128 v[110:113], v118 offset:6976
	ds_read_b128 v[114:117], v118 offset:9216
	ds_read_b128 v[128:131], v118 offset:9280
	ds_read_b128 v[132:135], v118 offset:11520
	ds_read_b128 v[120:123], v118 offset:11584
	s_waitcnt lgkmcnt(5)
	v_mfma_f32_16x16x32_bf16 v[2:5], v[106:109], v[98:101], 0
	ds_read_b128 v[106:109], v118 offset:13824
	s_waitcnt lgkmcnt(5)
	v_mfma_f32_16x16x32_bf16 v[2:5], v[110:113], v[102:105], v[2:5]
	ds_read_b128 v[110:113], v118 offset:13888
	s_waitcnt lgkmcnt(5)
	v_mfma_f32_16x16x32_bf16 v[6:9], v[114:117], v[98:101], 0
	ds_read_b128 v[114:117], v118 offset:16128
	s_waitcnt lgkmcnt(5)
	v_mfma_f32_16x16x32_bf16 v[6:9], v[128:131], v[102:105], v[6:9]
	ds_read_b128 v[128:131], v118 offset:16192
	s_waitcnt lgkmcnt(5)
	v_mfma_f32_16x16x32_bf16 v[10:13], v[132:135], v[98:101], 0
	ds_read_b128 v[132:135], v118 offset:18432
	s_waitcnt lgkmcnt(5)
	v_mfma_f32_16x16x32_bf16 v[10:13], v[120:123], v[102:105], v[10:13]
	ds_read_b128 v[120:123], v118 offset:18496
	s_waitcnt lgkmcnt(5)
	v_mfma_f32_16x16x32_bf16 v[14:17], v[106:109], v[98:101], 0
	ds_read_b128 v[106:109], v118 offset:20736
	s_waitcnt lgkmcnt(5)
	v_mfma_f32_16x16x32_bf16 v[14:17], v[110:113], v[102:105], v[14:17]
	ds_read_b128 v[110:113], v118 offset:20800
	s_waitcnt lgkmcnt(5)
	v_mfma_f32_16x16x32_bf16 v[18:21], v[114:117], v[98:101], 0
	ds_read_b128 v[114:117], v118 offset:23040
	s_waitcnt lgkmcnt(5)
	v_mfma_f32_16x16x32_bf16 v[18:21], v[128:131], v[102:105], v[18:21]
	ds_read_b128 v[128:131], v118 offset:23104
	s_waitcnt lgkmcnt(5)
	v_mfma_f32_16x16x32_bf16 v[22:25], v[132:135], v[98:101], 0
	ds_read_b128 v[132:135], v118 offset:25344
	s_waitcnt lgkmcnt(5)
	v_mfma_f32_16x16x32_bf16 v[22:25], v[120:123], v[102:105], v[22:25]
	ds_read_b128 v[120:123], v118 offset:25408
	s_waitcnt lgkmcnt(5)
	v_mfma_f32_16x16x32_bf16 v[26:29], v[106:109], v[98:101], 0
	s_waitcnt lgkmcnt(4)
	v_mfma_f32_16x16x32_bf16 v[26:29], v[110:113], v[102:105], v[26:29]
	s_waitcnt lgkmcnt(3)
	v_mfma_f32_16x16x32_bf16 v[30:33], v[114:117], v[98:101], 0
	s_waitcnt lgkmcnt(2)
	v_mfma_f32_16x16x32_bf16 v[30:33], v[128:131], v[102:105], v[30:33]
	s_waitcnt lgkmcnt(1)
	v_mfma_f32_16x16x32_bf16 v[86:89], v[132:135], v[98:101], 0
	s_waitcnt lgkmcnt(0)
	v_mfma_f32_16x16x32_bf16 v[86:89], v[120:123], v[102:105], v[86:89]
	v_lshl_add_u64 v[240:241], v[246:247], 0, s[8:9]
	global_load_dwordx4 v[90:93], v[240:241], off
	global_load_dwordx4 v[94:97], v[240:241], off offset:64
	v_add_u32_e32 v242, 0, v249
	v_cmp_gt_u32_e32 vcc, v242, v248
	s_nop 1
	s_and_b64 vcc, vcc, s[66:67]
	s_nop 0
	v_cndmask_b32_e32 v2, v205, v2, vcc
	v_add_u32_e32 v242, 1, v249
	v_cmp_gt_u32_e32 vcc, v242, v248
	s_nop 1
	s_and_b64 vcc, vcc, s[66:67]
	s_nop 0
	v_cndmask_b32_e32 v3, v205, v3, vcc
	v_add_u32_e32 v242, 2, v249
	v_cmp_gt_u32_e32 vcc, v242, v248
	s_nop 1
	s_and_b64 vcc, vcc, s[66:67]
	s_nop 0
	v_cndmask_b32_e32 v4, v205, v4, vcc
	v_add_u32_e32 v242, 3, v249
	v_cmp_gt_u32_e32 vcc, v242, v248
	s_nop 1
	s_and_b64 vcc, vcc, s[66:67]
	s_nop 0
	v_cndmask_b32_e32 v5, v205, v5, vcc
	v_cndmask_b32_e64 v6, v205, v6, s[66:67]
	v_cndmask_b32_e64 v7, v205, v7, s[66:67]
	v_cndmask_b32_e64 v8, v205, v8, s[66:67]
	v_cndmask_b32_e64 v9, v205, v9, s[66:67]
	v_cndmask_b32_e64 v10, v205, v10, s[66:67]
	v_cndmask_b32_e64 v11, v205, v11, s[66:67]
	v_cndmask_b32_e64 v12, v205, v12, s[66:67]
	v_cndmask_b32_e64 v13, v205, v13, s[66:67]
	v_cndmask_b32_e64 v14, v205, v14, s[66:67]
	v_cndmask_b32_e64 v15, v205, v15, s[66:67]
	v_cndmask_b32_e64 v16, v205, v16, s[66:67]
	v_cndmask_b32_e64 v17, v205, v17, s[66:67]
	v_cndmask_b32_e64 v18, v205, v18, s[66:67]
	v_cndmask_b32_e64 v19, v205, v19, s[66:67]
	v_cndmask_b32_e64 v20, v205, v20, s[66:67]
	v_cndmask_b32_e64 v21, v205, v21, s[66:67]
	v_add_u32_e32 v242, 0, v249
	v_cmp_le_u32_e32 vcc, v242, v248
	s_nop 1
	v_cndmask_b32_e32 v86, v205, v86, vcc
	v_add_u32_e32 v242, 1, v249
	v_cmp_le_u32_e32 vcc, v242, v248
	s_nop 1
	v_cndmask_b32_e32 v87, v205, v87, vcc
	v_add_u32_e32 v242, 2, v249
	v_cmp_le_u32_e32 vcc, v242, v248
	s_nop 1
	v_cndmask_b32_e32 v88, v205, v88, vcc
	v_add_u32_e32 v242, 3, v249
	v_cmp_le_u32_e32 vcc, v242, v248
	s_nop 1
	v_cndmask_b32_e32 v89, v205, v89, vcc
	v_max3_f32 v238, v2, v3, v205
	v_max3_f32 v238, v238, v4, v5
	v_max3_f32 v238, v238, v6, v7
	v_max3_f32 v238, v238, v8, v9
	v_max3_f32 v238, v238, v10, v11
	v_max3_f32 v238, v238, v12, v13
	v_max3_f32 v238, v238, v14, v15
	v_max3_f32 v238, v238, v16, v17
	v_max3_f32 v238, v238, v18, v19
	v_max3_f32 v238, v238, v20, v21
	v_max3_f32 v238, v238, v22, v23
	v_max3_f32 v238, v238, v24, v25
	v_max3_f32 v238, v238, v26, v27
	v_max3_f32 v238, v238, v28, v29
	v_max3_f32 v238, v238, v30, v31
	v_max3_f32 v238, v238, v32, v33
	v_max3_f32 v238, v238, v86, v87
	v_max3_f32 v238, v238, v88, v89
	v_xor_b32_e32 v242, 16, v195
	v_lshlrev_b32_e32 v242, 2, v242
	ds_bpermute_b32 v242, v242, v238
	s_waitcnt lgkmcnt(0)
	v_max_f32_e32 v238, v238, v242
	v_xor_b32_e32 v242, 32, v195
	v_lshlrev_b32_e32 v242, 2, v242
	ds_bpermute_b32 v242, v242, v238
	s_waitcnt lgkmcnt(0)
	v_max_f32_e32 v238, v238, v242
	v_mul_f32_e32 v238, 0x3e000000, v238
	v_max_f32_e32 v238, v238, v85
	v_mul_f32_e32 v243, 0xbfb8aa3b, v238
	v_fmamk_f32 v2, v2, 0x3e38aa3b, v243
	v_fmamk_f32 v3, v3, 0x3e38aa3b, v243
	v_fmamk_f32 v4, v4, 0x3e38aa3b, v243
	v_fmamk_f32 v5, v5, 0x3e38aa3b, v243
	v_exp_f32_e32 v2, v2
	v_exp_f32_e32 v3, v3
	v_exp_f32_e32 v4, v4
	v_exp_f32_e32 v5, v5
	v_fmamk_f32 v6, v6, 0x3e38aa3b, v243
	v_fmamk_f32 v7, v7, 0x3e38aa3b, v243
	v_fmamk_f32 v8, v8, 0x3e38aa3b, v243
	v_fmamk_f32 v9, v9, 0x3e38aa3b, v243
	v_exp_f32_e32 v6, v6
	v_exp_f32_e32 v7, v7
	v_exp_f32_e32 v8, v8
	v_exp_f32_e32 v9, v9
	v_add_f32_e32 v239, 0, v2
	v_add_f32_e32 v239, v239, v3
	v_add_f32_e32 v239, v239, v4
	v_add_f32_e32 v239, v239, v5
	v_fmamk_f32 v10, v10, 0x3e38aa3b, v243
	v_fmamk_f32 v11, v11, 0x3e38aa3b, v243
	v_fmamk_f32 v12, v12, 0x3e38aa3b, v243
	v_fmamk_f32 v13, v13, 0x3e38aa3b, v243
	v_exp_f32_e32 v10, v10
	v_exp_f32_e32 v11, v11
	v_exp_f32_e32 v12, v12
	v_exp_f32_e32 v13, v13
	v_add_f32_e32 v239, v239, v6
	v_add_f32_e32 v239, v239, v7
	v_add_f32_e32 v239, v239, v8
	v_add_f32_e32 v239, v239, v9
	v_fmamk_f32 v14, v14, 0x3e38aa3b, v243
	v_fmamk_f32 v15, v15, 0x3e38aa3b, v243
	v_fmamk_f32 v16, v16, 0x3e38aa3b, v243
	v_fmamk_f32 v17, v17, 0x3e38aa3b, v243
	v_exp_f32_e32 v14, v14
	v_exp_f32_e32 v15, v15
	v_exp_f32_e32 v16, v16
	v_exp_f32_e32 v17, v17
	v_add_f32_e32 v239, v239, v10
	v_add_f32_e32 v239, v239, v11
	v_add_f32_e32 v239, v239, v12
	v_add_f32_e32 v239, v239, v13
	v_fmamk_f32 v18, v18, 0x3e38aa3b, v243
	v_fmamk_f32 v19, v19, 0x3e38aa3b, v243
	v_fmamk_f32 v20, v20, 0x3e38aa3b, v243
	v_fmamk_f32 v21, v21, 0x3e38aa3b, v243
	v_exp_f32_e32 v18, v18
	v_exp_f32_e32 v19, v19
	v_exp_f32_e32 v20, v20
	v_exp_f32_e32 v21, v21
	v_add_f32_e32 v239, v239, v14
	v_add_f32_e32 v239, v239, v15
	v_add_f32_e32 v239, v239, v16
	v_add_f32_e32 v239, v239, v17
	v_fmamk_f32 v22, v22, 0x3e38aa3b, v243
	v_fmamk_f32 v23, v23, 0x3e38aa3b, v243
	v_fmamk_f32 v24, v24, 0x3e38aa3b, v243
	v_fmamk_f32 v25, v25, 0x3e38aa3b, v243
	v_exp_f32_e32 v22, v22
	v_exp_f32_e32 v23, v23
	v_exp_f32_e32 v24, v24
	v_exp_f32_e32 v25, v25
	v_add_f32_e32 v239, v239, v18
	v_add_f32_e32 v239, v239, v19
	v_add_f32_e32 v239, v239, v20
	v_add_f32_e32 v239, v239, v21
	v_fmamk_f32 v26, v26, 0x3e38aa3b, v243
	v_fmamk_f32 v27, v27, 0x3e38aa3b, v243
	v_fmamk_f32 v28, v28, 0x3e38aa3b, v243
	v_fmamk_f32 v29, v29, 0x3e38aa3b, v243
	v_exp_f32_e32 v26, v26
	v_exp_f32_e32 v27, v27
	v_exp_f32_e32 v28, v28
	v_exp_f32_e32 v29, v29
	v_add_f32_e32 v239, v239, v22
	v_add_f32_e32 v239, v239, v23
	v_add_f32_e32 v239, v239, v24
	v_add_f32_e32 v239, v239, v25
	v_fmamk_f32 v30, v30, 0x3e38aa3b, v243
	v_fmamk_f32 v31, v31, 0x3e38aa3b, v243
	v_fmamk_f32 v32, v32, 0x3e38aa3b, v243
	v_fmamk_f32 v33, v33, 0x3e38aa3b, v243
	v_exp_f32_e32 v30, v30
	v_exp_f32_e32 v31, v31
	v_exp_f32_e32 v32, v32
	v_exp_f32_e32 v33, v33
	v_add_f32_e32 v239, v239, v26
	v_add_f32_e32 v239, v239, v27
	v_add_f32_e32 v239, v239, v28
	v_add_f32_e32 v239, v239, v29
	v_fmamk_f32 v86, v86, 0x3e38aa3b, v243
	v_fmamk_f32 v87, v87, 0x3e38aa3b, v243
	v_fmamk_f32 v88, v88, 0x3e38aa3b, v243
	v_fmamk_f32 v89, v89, 0x3e38aa3b, v243
	v_exp_f32_e32 v86, v86
	v_exp_f32_e32 v87, v87
	v_exp_f32_e32 v88, v88
	v_exp_f32_e32 v89, v89
	v_add_f32_e32 v239, v239, v30
	v_add_f32_e32 v239, v239, v31
	v_add_f32_e32 v239, v239, v32
	v_add_f32_e32 v239, v239, v33
	s_nop 0
	v_add_f32_e32 v239, v239, v86
	v_add_f32_e32 v239, v239, v87
	v_add_f32_e32 v239, v239, v88
	v_add_f32_e32 v239, v239, v89
	v_xor_b32_e32 v242, 16, v195
	v_lshlrev_b32_e32 v242, 2, v242
	ds_bpermute_b32 v242, v242, v239
	s_waitcnt lgkmcnt(0)
	v_add_f32_e32 v239, v239, v242
	v_xor_b32_e32 v242, 32, v195
	v_lshlrev_b32_e32 v242, 2, v242
	ds_bpermute_b32 v242, v242, v239
	s_waitcnt lgkmcnt(0)
	v_add_f32_e32 v239, v239, v242
	v_sub_f32_e32 v242, v85, v238
	v_mul_f32_e32 v242, 0x3fb8aa3b, v242
	v_exp_f32_e32 v242, v242
	s_nop 0
	v_add_f32_e32 v239, v239, v242
	v_rcp_f32_e32 v244, v239
	v_cvt_pk_bf16_f32 v218, v2, v3
	v_cvt_pk_bf16_f32 v219, v4, v5
	v_cvt_pk_bf16_f32 v220, v6, v7
	v_cvt_pk_bf16_f32 v221, v8, v9
	v_cvt_pk_bf16_f32 v222, v10, v11
	v_cvt_pk_bf16_f32 v223, v12, v13
	v_cvt_pk_bf16_f32 v224, v14, v15
	v_cvt_pk_bf16_f32 v225, v16, v17
	v_cvt_pk_bf16_f32 v226, v18, v19
	v_cvt_pk_bf16_f32 v227, v20, v21
	v_cvt_pk_bf16_f32 v228, v22, v23
	v_cvt_pk_bf16_f32 v229, v24, v25
	v_cvt_pk_bf16_f32 v230, v26, v27
	v_cvt_pk_bf16_f32 v231, v28, v29
	v_cvt_pk_bf16_f32 v232, v30, v31
	v_cvt_pk_bf16_f32 v233, v32, v33
	v_cvt_pk_bf16_f32 v234, v86, v87
	v_cvt_pk_bf16_f32 v235, v88, v89
	v_mov_b32_e32 v236, 0
	v_mov_b32_e32 v237, 0
	ds_read_b64 v[182:183], v245 offset:96
	ds_read_b64 v[184:185], v245 offset:128
	ds_read_b64 v[186:187], v245 offset:8544
	ds_read_b64 v[188:189], v245 offset:8576
	ds_read_b64 v[190:191], v245 offset:16992
	ds_read_b64 v[192:193], v245 offset:17024
	ds_read_b64 v[210:211], v245 offset:25440
	ds_read_b64 v[212:213], v245 offset:25472
	ds_read_b64 v[214:215], v245 offset:160
	ds_read_b64 v[216:217], v245 offset:192
	s_waitcnt lgkmcnt(8)
	v_mfma_f32_16x16x32_bf16 v[142:145], v[182:185], v[218:221], 0
	ds_read_b64 v[182:183], v245 offset:8608
	ds_read_b64 v[184:185], v245 offset:8640
	s_waitcnt lgkmcnt(8)
	v_mfma_f32_16x16x32_bf16 v[146:149], v[186:189], v[218:221], 0
	ds_read_b64 v[186:187], v245 offset:17056
	ds_read_b64 v[188:189], v245 offset:17088
	s_waitcnt lgkmcnt(8)
	v_mfma_f32_16x16x32_bf16 v[150:153], v[190:193], v[218:221], 0
	ds_read_b64 v[190:191], v245 offset:25504
	ds_read_b64 v[192:193], v245 offset:25536
	s_waitcnt lgkmcnt(8)
	v_mfma_f32_16x16x32_bf16 v[154:157], v[210:213], v[218:221], 0
	ds_read_b64 v[210:211], v245 offset:224
	ds_read_b64 v[212:213], v245 offset:256
	s_waitcnt lgkmcnt(8)
	v_mfma_f32_16x16x32_bf16 v[142:145], v[214:217], v[222:225], v[142:145]
	ds_read_b64 v[214:215], v245 offset:8672
	ds_read_b64 v[216:217], v245 offset:8704
	s_waitcnt lgkmcnt(8)
	v_mfma_f32_16x16x32_bf16 v[146:149], v[182:185], v[222:225], v[146:149]
	ds_read_b64 v[182:183], v245 offset:17120
	ds_read_b64 v[184:185], v245 offset:17152
	s_waitcnt lgkmcnt(8)
	v_mfma_f32_16x16x32_bf16 v[150:153], v[186:189], v[222:225], v[150:153]
	ds_read_b64 v[186:187], v245 offset:25568
	ds_read_b64 v[188:189], v245 offset:25600
	s_waitcnt lgkmcnt(8)
	v_mfma_f32_16x16x32_bf16 v[154:157], v[190:193], v[222:225], v[154:157]
	ds_read_b64 v[190:191], v245 offset:288
	ds_read_b64 v[192:193], v245 offset:320
	s_waitcnt lgkmcnt(8)
	v_mfma_f32_16x16x32_bf16 v[142:145], v[210:213], v[226:229], v[142:145]
	ds_read_b64 v[210:211], v245 offset:8736
	ds_read_b64 v[212:213], v245 offset:8768
	s_waitcnt lgkmcnt(8)
	v_mfma_f32_16x16x32_bf16 v[146:149], v[214:217], v[226:229], v[146:149]
	ds_read_b64 v[214:215], v245 offset:17184
	ds_read_b64 v[216:217], v245 offset:17216
	s_waitcnt lgkmcnt(8)
	v_mfma_f32_16x16x32_bf16 v[150:153], v[182:185], v[226:229], v[150:153]
	ds_read_b64 v[182:183], v245 offset:25632
	ds_read_b64 v[184:185], v245 offset:25664
	s_waitcnt lgkmcnt(8)
	v_mfma_f32_16x16x32_bf16 v[154:157], v[186:189], v[226:229], v[154:157]
	ds_read_b64 v[186:187], v245 offset:352
	ds_read_b64 v[188:189], v245 offset:352
	s_waitcnt lgkmcnt(8)
	v_mfma_f32_16x16x32_bf16 v[142:145], v[190:193], v[230:233], v[142:145]
	ds_read_b64 v[190:191], v245 offset:8800
	ds_read_b64 v[192:193], v245 offset:8800
	s_waitcnt lgkmcnt(8)
	v_mfma_f32_16x16x32_bf16 v[146:149], v[210:213], v[230:233], v[146:149]
	ds_read_b64 v[210:211], v245 offset:17248
	ds_read_b64 v[212:213], v245 offset:17248
	s_waitcnt lgkmcnt(8)
	v_mfma_f32_16x16x32_bf16 v[150:153], v[214:217], v[230:233], v[150:153]
	ds_read_b64 v[214:215], v245 offset:25696
	ds_read_b64 v[216:217], v245 offset:25696
	s_waitcnt lgkmcnt(8)
	v_mfma_f32_16x16x32_bf16 v[154:157], v[182:185], v[230:233], v[154:157]
	s_waitcnt lgkmcnt(6)
	v_mfma_f32_16x16x32_bf16 v[142:145], v[186:189], v[234:237], v[142:145]
	s_waitcnt lgkmcnt(4)
	v_mfma_f32_16x16x32_bf16 v[146:149], v[190:193], v[234:237], v[146:149]
	s_waitcnt lgkmcnt(2)
	v_mfma_f32_16x16x32_bf16 v[150:153], v[210:213], v[234:237], v[150:153]
	s_waitcnt lgkmcnt(0)
	v_mfma_f32_16x16x32_bf16 v[154:157], v[214:217], v[234:237], v[154:157]
	s_nop 7
	s_nop 1
	v_mul_f32_e32 v142, v244, v142
	v_mul_f32_e32 v143, v244, v143
	v_mul_f32_e32 v144, v244, v144
	v_mul_f32_e32 v145, v244, v145
	v_mul_f32_e32 v146, v244, v146
	v_mul_f32_e32 v147, v244, v147
	v_mul_f32_e32 v148, v244, v148
	v_mul_f32_e32 v149, v244, v149
	v_cvt_pk_bf16_f32 v240, v142, v143
	v_cvt_pk_bf16_f32 v241, v144, v145
	v_cvt_pk_bf16_f32 v242, v146, v147
	v_cvt_pk_bf16_f32 v243, v148, v149
	global_store_dwordx4 v[246:247], v[240:243], off sc1
	s_nop 1
	v_mul_f32_e32 v150, v244, v150
	v_mul_f32_e32 v151, v244, v151
	v_mul_f32_e32 v152, v244, v152
	v_mul_f32_e32 v153, v244, v153
	v_mul_f32_e32 v154, v244, v154
	v_mul_f32_e32 v155, v244, v155
	v_mul_f32_e32 v156, v244, v156
	v_mul_f32_e32 v157, v244, v157
	v_cvt_pk_bf16_f32 v240, v150, v151
	v_cvt_pk_bf16_f32 v241, v152, v153
	v_cvt_pk_bf16_f32 v242, v154, v155
	v_cvt_pk_bf16_f32 v243, v156, v157
	global_store_dwordx4 v[246:247], v[240:243], off offset:64 sc1
	v_lshl_add_u64 v[246:247], v[246:247], 0, s[8:9]
	s_waitcnt vmcnt(2)
	ds_read_b128 v[106:109], v118 offset:9216
	ds_read_b128 v[110:113], v118 offset:9280
	ds_read_b128 v[114:117], v118 offset:11520
	ds_read_b128 v[128:131], v118 offset:11584
	ds_read_b128 v[132:135], v118 offset:13824
	ds_read_b128 v[120:123], v118 offset:13888
	s_waitcnt lgkmcnt(5)
	v_mfma_f32_16x16x32_bf16 v[2:5], v[106:109], v[90:93], 0
	ds_read_b128 v[106:109], v118 offset:16128
	s_waitcnt lgkmcnt(5)
	v_mfma_f32_16x16x32_bf16 v[2:5], v[110:113], v[94:97], v[2:5]
	ds_read_b128 v[110:113], v118 offset:16192
	s_waitcnt lgkmcnt(5)
	v_mfma_f32_16x16x32_bf16 v[6:9], v[114:117], v[90:93], 0
	ds_read_b128 v[114:117], v118 offset:18432
	s_waitcnt lgkmcnt(5)
	v_mfma_f32_16x16x32_bf16 v[6:9], v[128:131], v[94:97], v[6:9]
	ds_read_b128 v[128:131], v118 offset:18496
	s_waitcnt lgkmcnt(5)
	v_mfma_f32_16x16x32_bf16 v[10:13], v[132:135], v[90:93], 0
	ds_read_b128 v[132:135], v118 offset:20736
	s_waitcnt lgkmcnt(5)
	v_mfma_f32_16x16x32_bf16 v[10:13], v[120:123], v[94:97], v[10:13]
	ds_read_b128 v[120:123], v118 offset:20800
	s_waitcnt lgkmcnt(5)
	v_mfma_f32_16x16x32_bf16 v[14:17], v[106:109], v[90:93], 0
	ds_read_b128 v[106:109], v118 offset:23040
	s_waitcnt lgkmcnt(5)
	v_mfma_f32_16x16x32_bf16 v[14:17], v[110:113], v[94:97], v[14:17]
	ds_read_b128 v[110:113], v118 offset:23104
	s_waitcnt lgkmcnt(5)
	v_mfma_f32_16x16x32_bf16 v[18:21], v[114:117], v[90:93], 0
	ds_read_b128 v[114:117], v118 offset:25344
	s_waitcnt lgkmcnt(5)
	v_mfma_f32_16x16x32_bf16 v[18:21], v[128:131], v[94:97], v[18:21]
	ds_read_b128 v[128:131], v118 offset:25408
	s_waitcnt lgkmcnt(5)
	v_mfma_f32_16x16x32_bf16 v[22:25], v[132:135], v[90:93], 0
	ds_read_b128 v[132:135], v118 offset:27648
	s_waitcnt lgkmcnt(5)
	v_mfma_f32_16x16x32_bf16 v[22:25], v[120:123], v[94:97], v[22:25]
	ds_read_b128 v[120:123], v118 offset:27712
	s_waitcnt lgkmcnt(5)
	v_mfma_f32_16x16x32_bf16 v[26:29], v[106:109], v[90:93], 0
	s_waitcnt lgkmcnt(4)
	v_mfma_f32_16x16x32_bf16 v[26:29], v[110:113], v[94:97], v[26:29]
	s_waitcnt lgkmcnt(3)
	v_mfma_f32_16x16x32_bf16 v[30:33], v[114:117], v[90:93], 0
	s_waitcnt lgkmcnt(2)
	v_mfma_f32_16x16x32_bf16 v[30:33], v[128:131], v[94:97], v[30:33]
	s_waitcnt lgkmcnt(1)
	v_mfma_f32_16x16x32_bf16 v[86:89], v[132:135], v[90:93], 0
	s_waitcnt lgkmcnt(0)
	v_mfma_f32_16x16x32_bf16 v[86:89], v[120:123], v[94:97], v[86:89]
	v_lshl_add_u64 v[240:241], v[246:247], 0, s[8:9]
	global_load_dwordx4 v[98:101], v[240:241], off
	global_load_dwordx4 v[102:105], v[240:241], off offset:64
	v_add_u32_e32 v242, 0, v249
	v_cmp_gt_u32_e32 vcc, v242, v248
	s_nop 1
	s_and_b64 vcc, vcc, s[66:67]
	s_nop 0
	v_cndmask_b32_e32 v2, v205, v2, vcc
	v_add_u32_e32 v242, 1, v249
	v_cmp_gt_u32_e32 vcc, v242, v248
	s_nop 1
	s_and_b64 vcc, vcc, s[66:67]
	s_nop 0
	v_cndmask_b32_e32 v3, v205, v3, vcc
	v_add_u32_e32 v242, 2, v249
	v_cmp_gt_u32_e32 vcc, v242, v248
	s_nop 1
	s_and_b64 vcc, vcc, s[66:67]
	s_nop 0
	v_cndmask_b32_e32 v4, v205, v4, vcc
	v_add_u32_e32 v242, 3, v249
	v_cmp_gt_u32_e32 vcc, v242, v248
	s_nop 1
	s_and_b64 vcc, vcc, s[66:67]
	s_nop 0
	v_cndmask_b32_e32 v5, v205, v5, vcc
	v_cndmask_b32_e64 v6, v205, v6, s[66:67]
	v_cndmask_b32_e64 v7, v205, v7, s[66:67]
	v_cndmask_b32_e64 v8, v205, v8, s[66:67]
	v_cndmask_b32_e64 v9, v205, v9, s[66:67]
	v_cndmask_b32_e64 v10, v205, v10, s[66:67]
	v_cndmask_b32_e64 v11, v205, v11, s[66:67]
	v_cndmask_b32_e64 v12, v205, v12, s[66:67]
	v_cndmask_b32_e64 v13, v205, v13, s[66:67]
	v_cndmask_b32_e64 v14, v205, v14, s[66:67]
	v_cndmask_b32_e64 v15, v205, v15, s[66:67]
	v_cndmask_b32_e64 v16, v205, v16, s[66:67]
	v_cndmask_b32_e64 v17, v205, v17, s[66:67]
	v_add_u32_e32 v242, 0, v249
	v_cmp_le_u32_e32 vcc, v242, v248
	s_nop 1
	v_cndmask_b32_e32 v86, v205, v86, vcc
	v_add_u32_e32 v242, 1, v249
	v_cmp_le_u32_e32 vcc, v242, v248
	s_nop 1
	v_cndmask_b32_e32 v87, v205, v87, vcc
	v_add_u32_e32 v242, 2, v249
	v_cmp_le_u32_e32 vcc, v242, v248
	s_nop 1
	v_cndmask_b32_e32 v88, v205, v88, vcc
	v_add_u32_e32 v242, 3, v249
	v_cmp_le_u32_e32 vcc, v242, v248
	s_nop 1
	v_cndmask_b32_e32 v89, v205, v89, vcc
	v_max3_f32 v238, v2, v3, v205
	v_max3_f32 v238, v238, v4, v5
	v_max3_f32 v238, v238, v6, v7
	v_max3_f32 v238, v238, v8, v9
	v_max3_f32 v238, v238, v10, v11
	v_max3_f32 v238, v238, v12, v13
	v_max3_f32 v238, v238, v14, v15
	v_max3_f32 v238, v238, v16, v17
	v_max3_f32 v238, v238, v18, v19
	v_max3_f32 v238, v238, v20, v21
	v_max3_f32 v238, v238, v22, v23
	v_max3_f32 v238, v238, v24, v25
	v_max3_f32 v238, v238, v26, v27
	v_max3_f32 v238, v238, v28, v29
	v_max3_f32 v238, v238, v30, v31
	v_max3_f32 v238, v238, v32, v33
	v_max3_f32 v238, v238, v86, v87
	v_max3_f32 v238, v238, v88, v89
	v_xor_b32_e32 v242, 16, v195
	v_lshlrev_b32_e32 v242, 2, v242
	ds_bpermute_b32 v242, v242, v238
	s_waitcnt lgkmcnt(0)
	v_max_f32_e32 v238, v238, v242
	v_xor_b32_e32 v242, 32, v195
	v_lshlrev_b32_e32 v242, 2, v242
	ds_bpermute_b32 v242, v242, v238
	s_waitcnt lgkmcnt(0)
	v_max_f32_e32 v238, v238, v242
	v_mul_f32_e32 v238, 0x3e000000, v238
	v_max_f32_e32 v238, v238, v85
	v_mul_f32_e32 v243, 0xbfb8aa3b, v238
	v_fmamk_f32 v2, v2, 0x3e38aa3b, v243
	v_fmamk_f32 v3, v3, 0x3e38aa3b, v243
	v_fmamk_f32 v4, v4, 0x3e38aa3b, v243
	v_fmamk_f32 v5, v5, 0x3e38aa3b, v243
	v_exp_f32_e32 v2, v2
	v_exp_f32_e32 v3, v3
	v_exp_f32_e32 v4, v4
	v_exp_f32_e32 v5, v5
	v_fmamk_f32 v6, v6, 0x3e38aa3b, v243
	v_fmamk_f32 v7, v7, 0x3e38aa3b, v243
	v_fmamk_f32 v8, v8, 0x3e38aa3b, v243
	v_fmamk_f32 v9, v9, 0x3e38aa3b, v243
	v_exp_f32_e32 v6, v6
	v_exp_f32_e32 v7, v7
	v_exp_f32_e32 v8, v8
	v_exp_f32_e32 v9, v9
	v_add_f32_e32 v239, 0, v2
	v_add_f32_e32 v239, v239, v3
	v_add_f32_e32 v239, v239, v4
	v_add_f32_e32 v239, v239, v5
	v_fmamk_f32 v10, v10, 0x3e38aa3b, v243
	v_fmamk_f32 v11, v11, 0x3e38aa3b, v243
	v_fmamk_f32 v12, v12, 0x3e38aa3b, v243
	v_fmamk_f32 v13, v13, 0x3e38aa3b, v243
	v_exp_f32_e32 v10, v10
	v_exp_f32_e32 v11, v11
	v_exp_f32_e32 v12, v12
	v_exp_f32_e32 v13, v13
	v_add_f32_e32 v239, v239, v6
	v_add_f32_e32 v239, v239, v7
	v_add_f32_e32 v239, v239, v8
	v_add_f32_e32 v239, v239, v9
	v_fmamk_f32 v14, v14, 0x3e38aa3b, v243
	v_fmamk_f32 v15, v15, 0x3e38aa3b, v243
	v_fmamk_f32 v16, v16, 0x3e38aa3b, v243
	v_fmamk_f32 v17, v17, 0x3e38aa3b, v243
	v_exp_f32_e32 v14, v14
	v_exp_f32_e32 v15, v15
	v_exp_f32_e32 v16, v16
	v_exp_f32_e32 v17, v17
	v_add_f32_e32 v239, v239, v10
	v_add_f32_e32 v239, v239, v11
	v_add_f32_e32 v239, v239, v12
	v_add_f32_e32 v239, v239, v13
	v_fmamk_f32 v18, v18, 0x3e38aa3b, v243
	v_fmamk_f32 v19, v19, 0x3e38aa3b, v243
	v_fmamk_f32 v20, v20, 0x3e38aa3b, v243
	v_fmamk_f32 v21, v21, 0x3e38aa3b, v243
	v_exp_f32_e32 v18, v18
	v_exp_f32_e32 v19, v19
	v_exp_f32_e32 v20, v20
	v_exp_f32_e32 v21, v21
	v_add_f32_e32 v239, v239, v14
	v_add_f32_e32 v239, v239, v15
	v_add_f32_e32 v239, v239, v16
	v_add_f32_e32 v239, v239, v17
	v_fmamk_f32 v22, v22, 0x3e38aa3b, v243
	v_fmamk_f32 v23, v23, 0x3e38aa3b, v243
	v_fmamk_f32 v24, v24, 0x3e38aa3b, v243
	v_fmamk_f32 v25, v25, 0x3e38aa3b, v243
	v_exp_f32_e32 v22, v22
	v_exp_f32_e32 v23, v23
	v_exp_f32_e32 v24, v24
	v_exp_f32_e32 v25, v25
	v_add_f32_e32 v239, v239, v18
	v_add_f32_e32 v239, v239, v19
	v_add_f32_e32 v239, v239, v20
	v_add_f32_e32 v239, v239, v21
	v_fmamk_f32 v26, v26, 0x3e38aa3b, v243
	v_fmamk_f32 v27, v27, 0x3e38aa3b, v243
	v_fmamk_f32 v28, v28, 0x3e38aa3b, v243
	v_fmamk_f32 v29, v29, 0x3e38aa3b, v243
	v_exp_f32_e32 v26, v26
	v_exp_f32_e32 v27, v27
	v_exp_f32_e32 v28, v28
	v_exp_f32_e32 v29, v29
	v_add_f32_e32 v239, v239, v22
	v_add_f32_e32 v239, v239, v23
	v_add_f32_e32 v239, v239, v24
	v_add_f32_e32 v239, v239, v25
	v_fmamk_f32 v30, v30, 0x3e38aa3b, v243
	v_fmamk_f32 v31, v31, 0x3e38aa3b, v243
	v_fmamk_f32 v32, v32, 0x3e38aa3b, v243
	v_fmamk_f32 v33, v33, 0x3e38aa3b, v243
	v_exp_f32_e32 v30, v30
	v_exp_f32_e32 v31, v31
	v_exp_f32_e32 v32, v32
	v_exp_f32_e32 v33, v33
	v_add_f32_e32 v239, v239, v26
	v_add_f32_e32 v239, v239, v27
	v_add_f32_e32 v239, v239, v28
	v_add_f32_e32 v239, v239, v29
	v_fmamk_f32 v86, v86, 0x3e38aa3b, v243
	v_fmamk_f32 v87, v87, 0x3e38aa3b, v243
	v_fmamk_f32 v88, v88, 0x3e38aa3b, v243
	v_fmamk_f32 v89, v89, 0x3e38aa3b, v243
	v_exp_f32_e32 v86, v86
	v_exp_f32_e32 v87, v87
	v_exp_f32_e32 v88, v88
	v_exp_f32_e32 v89, v89
	v_add_f32_e32 v239, v239, v30
	v_add_f32_e32 v239, v239, v31
	v_add_f32_e32 v239, v239, v32
	v_add_f32_e32 v239, v239, v33
	s_nop 0
	v_add_f32_e32 v239, v239, v86
	v_add_f32_e32 v239, v239, v87
	v_add_f32_e32 v239, v239, v88
	v_add_f32_e32 v239, v239, v89
	v_xor_b32_e32 v242, 16, v195
	v_lshlrev_b32_e32 v242, 2, v242
	ds_bpermute_b32 v242, v242, v239
	s_waitcnt lgkmcnt(0)
	v_add_f32_e32 v239, v239, v242
	v_xor_b32_e32 v242, 32, v195
	v_lshlrev_b32_e32 v242, 2, v242
	ds_bpermute_b32 v242, v242, v239
	s_waitcnt lgkmcnt(0)
	v_add_f32_e32 v239, v239, v242
	v_sub_f32_e32 v242, v85, v238
	v_mul_f32_e32 v242, 0x3fb8aa3b, v242
	v_exp_f32_e32 v242, v242
	s_nop 0
	v_add_f32_e32 v239, v239, v242
	v_rcp_f32_e32 v244, v239
	v_cvt_pk_bf16_f32 v218, v2, v3
	v_cvt_pk_bf16_f32 v219, v4, v5
	v_cvt_pk_bf16_f32 v220, v6, v7
	v_cvt_pk_bf16_f32 v221, v8, v9
	v_cvt_pk_bf16_f32 v222, v10, v11
	v_cvt_pk_bf16_f32 v223, v12, v13
	v_cvt_pk_bf16_f32 v224, v14, v15
	v_cvt_pk_bf16_f32 v225, v16, v17
	v_cvt_pk_bf16_f32 v226, v18, v19
	v_cvt_pk_bf16_f32 v227, v20, v21
	v_cvt_pk_bf16_f32 v228, v22, v23
	v_cvt_pk_bf16_f32 v229, v24, v25
	v_cvt_pk_bf16_f32 v230, v26, v27
	v_cvt_pk_bf16_f32 v231, v28, v29
	v_cvt_pk_bf16_f32 v232, v30, v31
	v_cvt_pk_bf16_f32 v233, v32, v33
	v_cvt_pk_bf16_f32 v234, v86, v87
	v_cvt_pk_bf16_f32 v235, v88, v89
	v_mov_b32_e32 v236, 0
	v_mov_b32_e32 v237, 0
	ds_read_b64 v[182:183], v245 offset:128
	ds_read_b64 v[184:185], v245 offset:160
	ds_read_b64 v[186:187], v245 offset:8576
	ds_read_b64 v[188:189], v245 offset:8608
	ds_read_b64 v[190:191], v245 offset:17024
	ds_read_b64 v[192:193], v245 offset:17056
	ds_read_b64 v[210:211], v245 offset:25472
	ds_read_b64 v[212:213], v245 offset:25504
	ds_read_b64 v[214:215], v245 offset:192
	ds_read_b64 v[216:217], v245 offset:224
	s_waitcnt lgkmcnt(8)
	v_mfma_f32_16x16x32_bf16 v[142:145], v[182:185], v[218:221], 0
	ds_read_b64 v[182:183], v245 offset:8640
	ds_read_b64 v[184:185], v245 offset:8672
	s_waitcnt lgkmcnt(8)
	v_mfma_f32_16x16x32_bf16 v[146:149], v[186:189], v[218:221], 0
	ds_read_b64 v[186:187], v245 offset:17088
	ds_read_b64 v[188:189], v245 offset:17120
	s_waitcnt lgkmcnt(8)
	v_mfma_f32_16x16x32_bf16 v[150:153], v[190:193], v[218:221], 0
	ds_read_b64 v[190:191], v245 offset:25536
	ds_read_b64 v[192:193], v245 offset:25568
	s_waitcnt lgkmcnt(8)
	v_mfma_f32_16x16x32_bf16 v[154:157], v[210:213], v[218:221], 0
	ds_read_b64 v[210:211], v245 offset:256
	ds_read_b64 v[212:213], v245 offset:288
	s_waitcnt lgkmcnt(8)
	v_mfma_f32_16x16x32_bf16 v[142:145], v[214:217], v[222:225], v[142:145]
	ds_read_b64 v[214:215], v245 offset:8704
	ds_read_b64 v[216:217], v245 offset:8736
	s_waitcnt lgkmcnt(8)
	v_mfma_f32_16x16x32_bf16 v[146:149], v[182:185], v[222:225], v[146:149]
	ds_read_b64 v[182:183], v245 offset:17152
	ds_read_b64 v[184:185], v245 offset:17184
	s_waitcnt lgkmcnt(8)
	v_mfma_f32_16x16x32_bf16 v[150:153], v[186:189], v[222:225], v[150:153]
	ds_read_b64 v[186:187], v245 offset:25600
	ds_read_b64 v[188:189], v245 offset:25632
	s_waitcnt lgkmcnt(8)
	v_mfma_f32_16x16x32_bf16 v[154:157], v[190:193], v[222:225], v[154:157]
	ds_read_b64 v[190:191], v245 offset:320
	ds_read_b64 v[192:193], v245 offset:352
	s_waitcnt lgkmcnt(8)
	v_mfma_f32_16x16x32_bf16 v[142:145], v[210:213], v[226:229], v[142:145]
	ds_read_b64 v[210:211], v245 offset:8768
	ds_read_b64 v[212:213], v245 offset:8800
	s_waitcnt lgkmcnt(8)
	v_mfma_f32_16x16x32_bf16 v[146:149], v[214:217], v[226:229], v[146:149]
	ds_read_b64 v[214:215], v245 offset:17216
	ds_read_b64 v[216:217], v245 offset:17248
	s_waitcnt lgkmcnt(8)
	v_mfma_f32_16x16x32_bf16 v[150:153], v[182:185], v[226:229], v[150:153]
	ds_read_b64 v[182:183], v245 offset:25664
	ds_read_b64 v[184:185], v245 offset:25696
	s_waitcnt lgkmcnt(8)
	v_mfma_f32_16x16x32_bf16 v[154:157], v[186:189], v[226:229], v[154:157]
	ds_read_b64 v[186:187], v245 offset:384
	ds_read_b64 v[188:189], v245 offset:384
	s_waitcnt lgkmcnt(8)
	v_mfma_f32_16x16x32_bf16 v[142:145], v[190:193], v[230:233], v[142:145]
	ds_read_b64 v[190:191], v245 offset:8832
	ds_read_b64 v[192:193], v245 offset:8832
	s_waitcnt lgkmcnt(8)
	v_mfma_f32_16x16x32_bf16 v[146:149], v[210:213], v[230:233], v[146:149]
	ds_read_b64 v[210:211], v245 offset:17280
	ds_read_b64 v[212:213], v245 offset:17280
	s_waitcnt lgkmcnt(8)
	v_mfma_f32_16x16x32_bf16 v[150:153], v[214:217], v[230:233], v[150:153]
	ds_read_b64 v[214:215], v245 offset:25728
	ds_read_b64 v[216:217], v245 offset:25728
	s_waitcnt lgkmcnt(8)
	v_mfma_f32_16x16x32_bf16 v[154:157], v[182:185], v[230:233], v[154:157]
	s_waitcnt lgkmcnt(6)
	v_mfma_f32_16x16x32_bf16 v[142:145], v[186:189], v[234:237], v[142:145]
	s_waitcnt lgkmcnt(4)
	v_mfma_f32_16x16x32_bf16 v[146:149], v[190:193], v[234:237], v[146:149]
	s_waitcnt lgkmcnt(2)
	v_mfma_f32_16x16x32_bf16 v[150:153], v[210:213], v[234:237], v[150:153]
	s_waitcnt lgkmcnt(0)
	v_mfma_f32_16x16x32_bf16 v[154:157], v[214:217], v[234:237], v[154:157]
	s_nop 7
	s_nop 1
	v_mul_f32_e32 v142, v244, v142
	v_mul_f32_e32 v143, v244, v143
	v_mul_f32_e32 v144, v244, v144
	v_mul_f32_e32 v145, v244, v145
	v_mul_f32_e32 v146, v244, v146
	v_mul_f32_e32 v147, v244, v147
	v_mul_f32_e32 v148, v244, v148
	v_mul_f32_e32 v149, v244, v149
	v_cvt_pk_bf16_f32 v240, v142, v143
	v_cvt_pk_bf16_f32 v241, v144, v145
	v_cvt_pk_bf16_f32 v242, v146, v147
	v_cvt_pk_bf16_f32 v243, v148, v149
	global_store_dwordx4 v[246:247], v[240:243], off sc1
	s_nop 1
	v_mul_f32_e32 v150, v244, v150
	v_mul_f32_e32 v151, v244, v151
	v_mul_f32_e32 v152, v244, v152
	v_mul_f32_e32 v153, v244, v153
	v_mul_f32_e32 v154, v244, v154
	v_mul_f32_e32 v155, v244, v155
	v_mul_f32_e32 v156, v244, v156
	v_mul_f32_e32 v157, v244, v157
	v_cvt_pk_bf16_f32 v240, v150, v151
	v_cvt_pk_bf16_f32 v241, v152, v153
	v_cvt_pk_bf16_f32 v242, v154, v155
	v_cvt_pk_bf16_f32 v243, v156, v157
	global_store_dwordx4 v[246:247], v[240:243], off offset:64 sc1
	v_lshl_add_u64 v[246:247], v[246:247], 0, s[8:9]
	s_waitcnt vmcnt(2)
	ds_read_b128 v[106:109], v118 offset:11520
	ds_read_b128 v[110:113], v118 offset:11584
	ds_read_b128 v[114:117], v118 offset:13824
	ds_read_b128 v[128:131], v118 offset:13888
	ds_read_b128 v[132:135], v118 offset:16128
	ds_read_b128 v[120:123], v118 offset:16192
	s_waitcnt lgkmcnt(5)
	v_mfma_f32_16x16x32_bf16 v[2:5], v[106:109], v[98:101], 0
	ds_read_b128 v[106:109], v118 offset:18432
	s_waitcnt lgkmcnt(5)
	v_mfma_f32_16x16x32_bf16 v[2:5], v[110:113], v[102:105], v[2:5]
	ds_read_b128 v[110:113], v118 offset:18496
	s_waitcnt lgkmcnt(5)
	v_mfma_f32_16x16x32_bf16 v[6:9], v[114:117], v[98:101], 0
	ds_read_b128 v[114:117], v118 offset:20736
	s_waitcnt lgkmcnt(5)
	v_mfma_f32_16x16x32_bf16 v[6:9], v[128:131], v[102:105], v[6:9]
	ds_read_b128 v[128:131], v118 offset:20800
	s_waitcnt lgkmcnt(5)
	v_mfma_f32_16x16x32_bf16 v[10:13], v[132:135], v[98:101], 0
	ds_read_b128 v[132:135], v118 offset:23040
	s_waitcnt lgkmcnt(5)
	v_mfma_f32_16x16x32_bf16 v[10:13], v[120:123], v[102:105], v[10:13]
	ds_read_b128 v[120:123], v118 offset:23104
	s_waitcnt lgkmcnt(5)
	v_mfma_f32_16x16x32_bf16 v[14:17], v[106:109], v[98:101], 0
	ds_read_b128 v[106:109], v118 offset:25344
	s_waitcnt lgkmcnt(5)
	v_mfma_f32_16x16x32_bf16 v[14:17], v[110:113], v[102:105], v[14:17]
	ds_read_b128 v[110:113], v118 offset:25408
	s_waitcnt lgkmcnt(5)
	v_mfma_f32_16x16x32_bf16 v[18:21], v[114:117], v[98:101], 0
	ds_read_b128 v[114:117], v118 offset:27648
	s_waitcnt lgkmcnt(5)
	v_mfma_f32_16x16x32_bf16 v[18:21], v[128:131], v[102:105], v[18:21]
	ds_read_b128 v[128:131], v118 offset:27712
	s_waitcnt lgkmcnt(5)
	v_mfma_f32_16x16x32_bf16 v[22:25], v[132:135], v[98:101], 0
	ds_read_b128 v[132:135], v118 offset:29952
	s_waitcnt lgkmcnt(5)
	v_mfma_f32_16x16x32_bf16 v[22:25], v[120:123], v[102:105], v[22:25]
	ds_read_b128 v[120:123], v118 offset:30016
	s_waitcnt lgkmcnt(5)
	v_mfma_f32_16x16x32_bf16 v[26:29], v[106:109], v[98:101], 0
	s_waitcnt lgkmcnt(4)
	v_mfma_f32_16x16x32_bf16 v[26:29], v[110:113], v[102:105], v[26:29]
	s_waitcnt lgkmcnt(3)
	v_mfma_f32_16x16x32_bf16 v[30:33], v[114:117], v[98:101], 0
	s_waitcnt lgkmcnt(2)
	v_mfma_f32_16x16x32_bf16 v[30:33], v[128:131], v[102:105], v[30:33]
	s_waitcnt lgkmcnt(1)
	v_mfma_f32_16x16x32_bf16 v[86:89], v[132:135], v[98:101], 0
	s_waitcnt lgkmcnt(0)
	v_mfma_f32_16x16x32_bf16 v[86:89], v[120:123], v[102:105], v[86:89]
	v_lshl_add_u64 v[240:241], v[246:247], 0, s[8:9]
	global_load_dwordx4 v[90:93], v[240:241], off
	global_load_dwordx4 v[94:97], v[240:241], off offset:64
	v_add_u32_e32 v242, 0, v249
	v_cmp_gt_u32_e32 vcc, v242, v248
	s_nop 1
	s_and_b64 vcc, vcc, s[66:67]
	s_nop 0
	v_cndmask_b32_e32 v2, v205, v2, vcc
	v_add_u32_e32 v242, 1, v249
	v_cmp_gt_u32_e32 vcc, v242, v248
	s_nop 1
	s_and_b64 vcc, vcc, s[66:67]
	s_nop 0
	v_cndmask_b32_e32 v3, v205, v3, vcc
	v_add_u32_e32 v242, 2, v249
	v_cmp_gt_u32_e32 vcc, v242, v248
	s_nop 1
	s_and_b64 vcc, vcc, s[66:67]
	s_nop 0
	v_cndmask_b32_e32 v4, v205, v4, vcc
	v_add_u32_e32 v242, 3, v249
	v_cmp_gt_u32_e32 vcc, v242, v248
	s_nop 1
	s_and_b64 vcc, vcc, s[66:67]
	s_nop 0
	v_cndmask_b32_e32 v5, v205, v5, vcc
	v_cndmask_b32_e64 v6, v205, v6, s[66:67]
	v_cndmask_b32_e64 v7, v205, v7, s[66:67]
	v_cndmask_b32_e64 v8, v205, v8, s[66:67]
	v_cndmask_b32_e64 v9, v205, v9, s[66:67]
	v_cndmask_b32_e64 v10, v205, v10, s[66:67]
	v_cndmask_b32_e64 v11, v205, v11, s[66:67]
	v_cndmask_b32_e64 v12, v205, v12, s[66:67]
	v_cndmask_b32_e64 v13, v205, v13, s[66:67]
	v_add_u32_e32 v242, 0, v249
	v_cmp_le_u32_e32 vcc, v242, v248
	s_nop 1
	v_cndmask_b32_e32 v86, v205, v86, vcc
	v_add_u32_e32 v242, 1, v249
	v_cmp_le_u32_e32 vcc, v242, v248
	s_nop 1
	v_cndmask_b32_e32 v87, v205, v87, vcc
	v_add_u32_e32 v242, 2, v249
	v_cmp_le_u32_e32 vcc, v242, v248
	s_nop 1
	v_cndmask_b32_e32 v88, v205, v88, vcc
	v_add_u32_e32 v242, 3, v249
	v_cmp_le_u32_e32 vcc, v242, v248
	s_nop 1
	v_cndmask_b32_e32 v89, v205, v89, vcc
	v_max3_f32 v238, v2, v3, v205
	v_max3_f32 v238, v238, v4, v5
	v_max3_f32 v238, v238, v6, v7
	v_max3_f32 v238, v238, v8, v9
	v_max3_f32 v238, v238, v10, v11
	v_max3_f32 v238, v238, v12, v13
	v_max3_f32 v238, v238, v14, v15
	v_max3_f32 v238, v238, v16, v17
	v_max3_f32 v238, v238, v18, v19
	v_max3_f32 v238, v238, v20, v21
	v_max3_f32 v238, v238, v22, v23
	v_max3_f32 v238, v238, v24, v25
	v_max3_f32 v238, v238, v26, v27
	v_max3_f32 v238, v238, v28, v29
	v_max3_f32 v238, v238, v30, v31
	v_max3_f32 v238, v238, v32, v33
	v_max3_f32 v238, v238, v86, v87
	v_max3_f32 v238, v238, v88, v89
	v_xor_b32_e32 v242, 16, v195
	v_lshlrev_b32_e32 v242, 2, v242
	ds_bpermute_b32 v242, v242, v238
	s_waitcnt lgkmcnt(0)
	v_max_f32_e32 v238, v238, v242
	v_xor_b32_e32 v242, 32, v195
	v_lshlrev_b32_e32 v242, 2, v242
	ds_bpermute_b32 v242, v242, v238
	s_waitcnt lgkmcnt(0)
	v_max_f32_e32 v238, v238, v242
	v_mul_f32_e32 v238, 0x3e000000, v238
	v_max_f32_e32 v238, v238, v85
	v_mul_f32_e32 v243, 0xbfb8aa3b, v238
	v_fmamk_f32 v2, v2, 0x3e38aa3b, v243
	v_fmamk_f32 v3, v3, 0x3e38aa3b, v243
	v_fmamk_f32 v4, v4, 0x3e38aa3b, v243
	v_fmamk_f32 v5, v5, 0x3e38aa3b, v243
	v_exp_f32_e32 v2, v2
	v_exp_f32_e32 v3, v3
	v_exp_f32_e32 v4, v4
	v_exp_f32_e32 v5, v5
	v_fmamk_f32 v6, v6, 0x3e38aa3b, v243
	v_fmamk_f32 v7, v7, 0x3e38aa3b, v243
	v_fmamk_f32 v8, v8, 0x3e38aa3b, v243
	v_fmamk_f32 v9, v9, 0x3e38aa3b, v243
	v_exp_f32_e32 v6, v6
	v_exp_f32_e32 v7, v7
	v_exp_f32_e32 v8, v8
	v_exp_f32_e32 v9, v9
	v_add_f32_e32 v239, 0, v2
	v_add_f32_e32 v239, v239, v3
	v_add_f32_e32 v239, v239, v4
	v_add_f32_e32 v239, v239, v5
	v_fmamk_f32 v10, v10, 0x3e38aa3b, v243
	v_fmamk_f32 v11, v11, 0x3e38aa3b, v243
	v_fmamk_f32 v12, v12, 0x3e38aa3b, v243
	v_fmamk_f32 v13, v13, 0x3e38aa3b, v243
	v_exp_f32_e32 v10, v10
	v_exp_f32_e32 v11, v11
	v_exp_f32_e32 v12, v12
	v_exp_f32_e32 v13, v13
	v_add_f32_e32 v239, v239, v6
	v_add_f32_e32 v239, v239, v7
	v_add_f32_e32 v239, v239, v8
	v_add_f32_e32 v239, v239, v9
	v_fmamk_f32 v14, v14, 0x3e38aa3b, v243
	v_fmamk_f32 v15, v15, 0x3e38aa3b, v243
	v_fmamk_f32 v16, v16, 0x3e38aa3b, v243
	v_fmamk_f32 v17, v17, 0x3e38aa3b, v243
	v_exp_f32_e32 v14, v14
	v_exp_f32_e32 v15, v15
	v_exp_f32_e32 v16, v16
	v_exp_f32_e32 v17, v17
	v_add_f32_e32 v239, v239, v10
	v_add_f32_e32 v239, v239, v11
	v_add_f32_e32 v239, v239, v12
	v_add_f32_e32 v239, v239, v13
	v_fmamk_f32 v18, v18, 0x3e38aa3b, v243
	v_fmamk_f32 v19, v19, 0x3e38aa3b, v243
	v_fmamk_f32 v20, v20, 0x3e38aa3b, v243
	v_fmamk_f32 v21, v21, 0x3e38aa3b, v243
	v_exp_f32_e32 v18, v18
	v_exp_f32_e32 v19, v19
	v_exp_f32_e32 v20, v20
	v_exp_f32_e32 v21, v21
	v_add_f32_e32 v239, v239, v14
	v_add_f32_e32 v239, v239, v15
	v_add_f32_e32 v239, v239, v16
	v_add_f32_e32 v239, v239, v17
	v_fmamk_f32 v22, v22, 0x3e38aa3b, v243
	v_fmamk_f32 v23, v23, 0x3e38aa3b, v243
	v_fmamk_f32 v24, v24, 0x3e38aa3b, v243
	v_fmamk_f32 v25, v25, 0x3e38aa3b, v243
	v_exp_f32_e32 v22, v22
	v_exp_f32_e32 v23, v23
	v_exp_f32_e32 v24, v24
	v_exp_f32_e32 v25, v25
	v_add_f32_e32 v239, v239, v18
	v_add_f32_e32 v239, v239, v19
	v_add_f32_e32 v239, v239, v20
	v_add_f32_e32 v239, v239, v21
	v_fmamk_f32 v26, v26, 0x3e38aa3b, v243
	v_fmamk_f32 v27, v27, 0x3e38aa3b, v243
	v_fmamk_f32 v28, v28, 0x3e38aa3b, v243
	v_fmamk_f32 v29, v29, 0x3e38aa3b, v243
	v_exp_f32_e32 v26, v26
	v_exp_f32_e32 v27, v27
	v_exp_f32_e32 v28, v28
	v_exp_f32_e32 v29, v29
	v_add_f32_e32 v239, v239, v22
	v_add_f32_e32 v239, v239, v23
	v_add_f32_e32 v239, v239, v24
	v_add_f32_e32 v239, v239, v25
	v_fmamk_f32 v30, v30, 0x3e38aa3b, v243
	v_fmamk_f32 v31, v31, 0x3e38aa3b, v243
	v_fmamk_f32 v32, v32, 0x3e38aa3b, v243
	v_fmamk_f32 v33, v33, 0x3e38aa3b, v243
	v_exp_f32_e32 v30, v30
	v_exp_f32_e32 v31, v31
	v_exp_f32_e32 v32, v32
	v_exp_f32_e32 v33, v33
	v_add_f32_e32 v239, v239, v26
	v_add_f32_e32 v239, v239, v27
	v_add_f32_e32 v239, v239, v28
	v_add_f32_e32 v239, v239, v29
	v_fmamk_f32 v86, v86, 0x3e38aa3b, v243
	v_fmamk_f32 v87, v87, 0x3e38aa3b, v243
	v_fmamk_f32 v88, v88, 0x3e38aa3b, v243
	v_fmamk_f32 v89, v89, 0x3e38aa3b, v243
	v_exp_f32_e32 v86, v86
	v_exp_f32_e32 v87, v87
	v_exp_f32_e32 v88, v88
	v_exp_f32_e32 v89, v89
	v_add_f32_e32 v239, v239, v30
	v_add_f32_e32 v239, v239, v31
	v_add_f32_e32 v239, v239, v32
	v_add_f32_e32 v239, v239, v33
	s_nop 0
	v_add_f32_e32 v239, v239, v86
	v_add_f32_e32 v239, v239, v87
	v_add_f32_e32 v239, v239, v88
	v_add_f32_e32 v239, v239, v89
	v_xor_b32_e32 v242, 16, v195
	v_lshlrev_b32_e32 v242, 2, v242
	ds_bpermute_b32 v242, v242, v239
	s_waitcnt lgkmcnt(0)
	v_add_f32_e32 v239, v239, v242
	v_xor_b32_e32 v242, 32, v195
	v_lshlrev_b32_e32 v242, 2, v242
	ds_bpermute_b32 v242, v242, v239
	s_waitcnt lgkmcnt(0)
	v_add_f32_e32 v239, v239, v242
	v_sub_f32_e32 v242, v85, v238
	v_mul_f32_e32 v242, 0x3fb8aa3b, v242
	v_exp_f32_e32 v242, v242
	s_nop 0
	v_add_f32_e32 v239, v239, v242
	v_rcp_f32_e32 v244, v239
	v_cvt_pk_bf16_f32 v218, v2, v3
	v_cvt_pk_bf16_f32 v219, v4, v5
	v_cvt_pk_bf16_f32 v220, v6, v7
	v_cvt_pk_bf16_f32 v221, v8, v9
	v_cvt_pk_bf16_f32 v222, v10, v11
	v_cvt_pk_bf16_f32 v223, v12, v13
	v_cvt_pk_bf16_f32 v224, v14, v15
	v_cvt_pk_bf16_f32 v225, v16, v17
	v_cvt_pk_bf16_f32 v226, v18, v19
	v_cvt_pk_bf16_f32 v227, v20, v21
	v_cvt_pk_bf16_f32 v228, v22, v23
	v_cvt_pk_bf16_f32 v229, v24, v25
	v_cvt_pk_bf16_f32 v230, v26, v27
	v_cvt_pk_bf16_f32 v231, v28, v29
	v_cvt_pk_bf16_f32 v232, v30, v31
	v_cvt_pk_bf16_f32 v233, v32, v33
	v_cvt_pk_bf16_f32 v234, v86, v87
	v_cvt_pk_bf16_f32 v235, v88, v89
	v_mov_b32_e32 v236, 0
	v_mov_b32_e32 v237, 0
	ds_read_b64 v[182:183], v245 offset:160
	ds_read_b64 v[184:185], v245 offset:192
	ds_read_b64 v[186:187], v245 offset:8608
	ds_read_b64 v[188:189], v245 offset:8640
	ds_read_b64 v[190:191], v245 offset:17056
	ds_read_b64 v[192:193], v245 offset:17088
	ds_read_b64 v[210:211], v245 offset:25504
	ds_read_b64 v[212:213], v245 offset:25536
	ds_read_b64 v[214:215], v245 offset:224
	ds_read_b64 v[216:217], v245 offset:256
	s_waitcnt lgkmcnt(8)
	v_mfma_f32_16x16x32_bf16 v[142:145], v[182:185], v[218:221], 0
	ds_read_b64 v[182:183], v245 offset:8672
	ds_read_b64 v[184:185], v245 offset:8704
	s_waitcnt lgkmcnt(8)
	v_mfma_f32_16x16x32_bf16 v[146:149], v[186:189], v[218:221], 0
	ds_read_b64 v[186:187], v245 offset:17120
	ds_read_b64 v[188:189], v245 offset:17152
	s_waitcnt lgkmcnt(8)
	v_mfma_f32_16x16x32_bf16 v[150:153], v[190:193], v[218:221], 0
	ds_read_b64 v[190:191], v245 offset:25568
	ds_read_b64 v[192:193], v245 offset:25600
	s_waitcnt lgkmcnt(8)
	v_mfma_f32_16x16x32_bf16 v[154:157], v[210:213], v[218:221], 0
	ds_read_b64 v[210:211], v245 offset:288
	ds_read_b64 v[212:213], v245 offset:320
	s_waitcnt lgkmcnt(8)
	v_mfma_f32_16x16x32_bf16 v[142:145], v[214:217], v[222:225], v[142:145]
	ds_read_b64 v[214:215], v245 offset:8736
	ds_read_b64 v[216:217], v245 offset:8768
	s_waitcnt lgkmcnt(8)
	v_mfma_f32_16x16x32_bf16 v[146:149], v[182:185], v[222:225], v[146:149]
	ds_read_b64 v[182:183], v245 offset:17184
	ds_read_b64 v[184:185], v245 offset:17216
	s_waitcnt lgkmcnt(8)
	v_mfma_f32_16x16x32_bf16 v[150:153], v[186:189], v[222:225], v[150:153]
	ds_read_b64 v[186:187], v245 offset:25632
	ds_read_b64 v[188:189], v245 offset:25664
	s_waitcnt lgkmcnt(8)
	v_mfma_f32_16x16x32_bf16 v[154:157], v[190:193], v[222:225], v[154:157]
	ds_read_b64 v[190:191], v245 offset:352
	ds_read_b64 v[192:193], v245 offset:384
	s_waitcnt lgkmcnt(8)
	v_mfma_f32_16x16x32_bf16 v[142:145], v[210:213], v[226:229], v[142:145]
	ds_read_b64 v[210:211], v245 offset:8800
	ds_read_b64 v[212:213], v245 offset:8832
	s_waitcnt lgkmcnt(8)
	v_mfma_f32_16x16x32_bf16 v[146:149], v[214:217], v[226:229], v[146:149]
	ds_read_b64 v[214:215], v245 offset:17248
	ds_read_b64 v[216:217], v245 offset:17280
	s_waitcnt lgkmcnt(8)
	v_mfma_f32_16x16x32_bf16 v[150:153], v[182:185], v[226:229], v[150:153]
	ds_read_b64 v[182:183], v245 offset:25696
	ds_read_b64 v[184:185], v245 offset:25728
	s_waitcnt lgkmcnt(8)
	v_mfma_f32_16x16x32_bf16 v[154:157], v[186:189], v[226:229], v[154:157]
	ds_read_b64 v[186:187], v245 offset:416
	ds_read_b64 v[188:189], v245 offset:416
	s_waitcnt lgkmcnt(8)
	v_mfma_f32_16x16x32_bf16 v[142:145], v[190:193], v[230:233], v[142:145]
	ds_read_b64 v[190:191], v245 offset:8864
	ds_read_b64 v[192:193], v245 offset:8864
	s_waitcnt lgkmcnt(8)
	v_mfma_f32_16x16x32_bf16 v[146:149], v[210:213], v[230:233], v[146:149]
	ds_read_b64 v[210:211], v245 offset:17312
	ds_read_b64 v[212:213], v245 offset:17312
	s_waitcnt lgkmcnt(8)
	v_mfma_f32_16x16x32_bf16 v[150:153], v[214:217], v[230:233], v[150:153]
	ds_read_b64 v[214:215], v245 offset:25760
	ds_read_b64 v[216:217], v245 offset:25760
	s_waitcnt lgkmcnt(8)
	v_mfma_f32_16x16x32_bf16 v[154:157], v[182:185], v[230:233], v[154:157]
	s_waitcnt lgkmcnt(6)
	v_mfma_f32_16x16x32_bf16 v[142:145], v[186:189], v[234:237], v[142:145]
	s_waitcnt lgkmcnt(4)
	v_mfma_f32_16x16x32_bf16 v[146:149], v[190:193], v[234:237], v[146:149]
	s_waitcnt lgkmcnt(2)
	v_mfma_f32_16x16x32_bf16 v[150:153], v[210:213], v[234:237], v[150:153]
	s_waitcnt lgkmcnt(0)
	v_mfma_f32_16x16x32_bf16 v[154:157], v[214:217], v[234:237], v[154:157]
	s_nop 7
	s_nop 1
	v_mul_f32_e32 v142, v244, v142
	v_mul_f32_e32 v143, v244, v143
	v_mul_f32_e32 v144, v244, v144
	v_mul_f32_e32 v145, v244, v145
	v_mul_f32_e32 v146, v244, v146
	v_mul_f32_e32 v147, v244, v147
	v_mul_f32_e32 v148, v244, v148
	v_mul_f32_e32 v149, v244, v149
	v_cvt_pk_bf16_f32 v240, v142, v143
	v_cvt_pk_bf16_f32 v241, v144, v145
	v_cvt_pk_bf16_f32 v242, v146, v147
	v_cvt_pk_bf16_f32 v243, v148, v149
	global_store_dwordx4 v[246:247], v[240:243], off sc1
	s_nop 1
	v_mul_f32_e32 v150, v244, v150
	v_mul_f32_e32 v151, v244, v151
	v_mul_f32_e32 v152, v244, v152
	v_mul_f32_e32 v153, v244, v153
	v_mul_f32_e32 v154, v244, v154
	v_mul_f32_e32 v155, v244, v155
	v_mul_f32_e32 v156, v244, v156
	v_mul_f32_e32 v157, v244, v157
	v_cvt_pk_bf16_f32 v240, v150, v151
	v_cvt_pk_bf16_f32 v241, v152, v153
	v_cvt_pk_bf16_f32 v242, v154, v155
	v_cvt_pk_bf16_f32 v243, v156, v157
	global_store_dwordx4 v[246:247], v[240:243], off offset:64 sc1
	v_lshl_add_u64 v[246:247], v[246:247], 0, s[8:9]
	s_waitcnt vmcnt(2)
	ds_read_b128 v[106:109], v118 offset:13824
	ds_read_b128 v[110:113], v118 offset:13888
	ds_read_b128 v[114:117], v118 offset:16128
	ds_read_b128 v[128:131], v118 offset:16192
	ds_read_b128 v[132:135], v118 offset:18432
	ds_read_b128 v[120:123], v118 offset:18496
	s_waitcnt lgkmcnt(5)
	v_mfma_f32_16x16x32_bf16 v[2:5], v[106:109], v[90:93], 0
	ds_read_b128 v[106:109], v118 offset:20736
	s_waitcnt lgkmcnt(5)
	v_mfma_f32_16x16x32_bf16 v[2:5], v[110:113], v[94:97], v[2:5]
	ds_read_b128 v[110:113], v118 offset:20800
	s_waitcnt lgkmcnt(5)
	v_mfma_f32_16x16x32_bf16 v[6:9], v[114:117], v[90:93], 0
	ds_read_b128 v[114:117], v118 offset:23040
	s_waitcnt lgkmcnt(5)
	v_mfma_f32_16x16x32_bf16 v[6:9], v[128:131], v[94:97], v[6:9]
	ds_read_b128 v[128:131], v118 offset:23104
	s_waitcnt lgkmcnt(5)
	v_mfma_f32_16x16x32_bf16 v[10:13], v[132:135], v[90:93], 0
	ds_read_b128 v[132:135], v118 offset:25344
	s_waitcnt lgkmcnt(5)
	v_mfma_f32_16x16x32_bf16 v[10:13], v[120:123], v[94:97], v[10:13]
	ds_read_b128 v[120:123], v118 offset:25408
	s_waitcnt lgkmcnt(5)
	v_mfma_f32_16x16x32_bf16 v[14:17], v[106:109], v[90:93], 0
	ds_read_b128 v[106:109], v118 offset:27648
	s_waitcnt lgkmcnt(5)
	v_mfma_f32_16x16x32_bf16 v[14:17], v[110:113], v[94:97], v[14:17]
	ds_read_b128 v[110:113], v118 offset:27712
	s_waitcnt lgkmcnt(5)
	v_mfma_f32_16x16x32_bf16 v[18:21], v[114:117], v[90:93], 0
	ds_read_b128 v[114:117], v118 offset:29952
	s_waitcnt lgkmcnt(5)
	v_mfma_f32_16x16x32_bf16 v[18:21], v[128:131], v[94:97], v[18:21]
	ds_read_b128 v[128:131], v118 offset:30016
	s_waitcnt lgkmcnt(5)
	v_mfma_f32_16x16x32_bf16 v[22:25], v[132:135], v[90:93], 0
	ds_read_b128 v[132:135], v118 offset:32256
	s_waitcnt lgkmcnt(5)
	v_mfma_f32_16x16x32_bf16 v[22:25], v[120:123], v[94:97], v[22:25]
	ds_read_b128 v[120:123], v118 offset:32320
	s_waitcnt lgkmcnt(5)
	v_mfma_f32_16x16x32_bf16 v[26:29], v[106:109], v[90:93], 0
	s_waitcnt lgkmcnt(4)
	v_mfma_f32_16x16x32_bf16 v[26:29], v[110:113], v[94:97], v[26:29]
	s_waitcnt lgkmcnt(3)
	v_mfma_f32_16x16x32_bf16 v[30:33], v[114:117], v[90:93], 0
	s_waitcnt lgkmcnt(2)
	v_mfma_f32_16x16x32_bf16 v[30:33], v[128:131], v[94:97], v[30:33]
	s_waitcnt lgkmcnt(1)
	v_mfma_f32_16x16x32_bf16 v[86:89], v[132:135], v[90:93], 0
	s_waitcnt lgkmcnt(0)
	v_mfma_f32_16x16x32_bf16 v[86:89], v[120:123], v[94:97], v[86:89]
	v_lshl_add_u64 v[240:241], v[246:247], 0, s[8:9]
	global_load_dwordx4 v[98:101], v[240:241], off
	global_load_dwordx4 v[102:105], v[240:241], off offset:64
	v_add_u32_e32 v242, 0, v249
	v_cmp_gt_u32_e32 vcc, v242, v248
	s_nop 1
	s_and_b64 vcc, vcc, s[66:67]
	s_nop 0
	v_cndmask_b32_e32 v2, v205, v2, vcc
	v_add_u32_e32 v242, 1, v249
	v_cmp_gt_u32_e32 vcc, v242, v248
	s_nop 1
	s_and_b64 vcc, vcc, s[66:67]
	s_nop 0
	v_cndmask_b32_e32 v3, v205, v3, vcc
	v_add_u32_e32 v242, 2, v249
	v_cmp_gt_u32_e32 vcc, v242, v248
	s_nop 1
	s_and_b64 vcc, vcc, s[66:67]
	s_nop 0
	v_cndmask_b32_e32 v4, v205, v4, vcc
	v_add_u32_e32 v242, 3, v249
	v_cmp_gt_u32_e32 vcc, v242, v248
	s_nop 1
	s_and_b64 vcc, vcc, s[66:67]
	s_nop 0
	v_cndmask_b32_e32 v5, v205, v5, vcc
	v_cndmask_b32_e64 v6, v205, v6, s[66:67]
	v_cndmask_b32_e64 v7, v205, v7, s[66:67]
	v_cndmask_b32_e64 v8, v205, v8, s[66:67]
	v_cndmask_b32_e64 v9, v205, v9, s[66:67]
	v_add_u32_e32 v242, 0, v249
	v_cmp_le_u32_e32 vcc, v242, v248
	s_nop 1
	v_cndmask_b32_e32 v86, v205, v86, vcc
	v_add_u32_e32 v242, 1, v249
	v_cmp_le_u32_e32 vcc, v242, v248
	s_nop 1
	v_cndmask_b32_e32 v87, v205, v87, vcc
	v_add_u32_e32 v242, 2, v249
	v_cmp_le_u32_e32 vcc, v242, v248
	s_nop 1
	v_cndmask_b32_e32 v88, v205, v88, vcc
	v_add_u32_e32 v242, 3, v249
	v_cmp_le_u32_e32 vcc, v242, v248
	s_nop 1
	v_cndmask_b32_e32 v89, v205, v89, vcc
	v_max3_f32 v238, v2, v3, v205
	v_max3_f32 v238, v238, v4, v5
	v_max3_f32 v238, v238, v6, v7
	v_max3_f32 v238, v238, v8, v9
	v_max3_f32 v238, v238, v10, v11
	v_max3_f32 v238, v238, v12, v13
	v_max3_f32 v238, v238, v14, v15
	v_max3_f32 v238, v238, v16, v17
	v_max3_f32 v238, v238, v18, v19
	v_max3_f32 v238, v238, v20, v21
	v_max3_f32 v238, v238, v22, v23
	v_max3_f32 v238, v238, v24, v25
	v_max3_f32 v238, v238, v26, v27
	v_max3_f32 v238, v238, v28, v29
	v_max3_f32 v238, v238, v30, v31
	v_max3_f32 v238, v238, v32, v33
	v_max3_f32 v238, v238, v86, v87
	v_max3_f32 v238, v238, v88, v89
	v_xor_b32_e32 v242, 16, v195
	v_lshlrev_b32_e32 v242, 2, v242
	ds_bpermute_b32 v242, v242, v238
	s_waitcnt lgkmcnt(0)
	v_max_f32_e32 v238, v238, v242
	v_xor_b32_e32 v242, 32, v195
	v_lshlrev_b32_e32 v242, 2, v242
	ds_bpermute_b32 v242, v242, v238
	s_waitcnt lgkmcnt(0)
	v_max_f32_e32 v238, v238, v242
	v_mul_f32_e32 v238, 0x3e000000, v238
	v_max_f32_e32 v238, v238, v85
	v_mul_f32_e32 v243, 0xbfb8aa3b, v238
	v_fmamk_f32 v2, v2, 0x3e38aa3b, v243
	v_fmamk_f32 v3, v3, 0x3e38aa3b, v243
	v_fmamk_f32 v4, v4, 0x3e38aa3b, v243
	v_fmamk_f32 v5, v5, 0x3e38aa3b, v243
	v_exp_f32_e32 v2, v2
	v_exp_f32_e32 v3, v3
	v_exp_f32_e32 v4, v4
	v_exp_f32_e32 v5, v5
	v_fmamk_f32 v6, v6, 0x3e38aa3b, v243
	v_fmamk_f32 v7, v7, 0x3e38aa3b, v243
	v_fmamk_f32 v8, v8, 0x3e38aa3b, v243
	v_fmamk_f32 v9, v9, 0x3e38aa3b, v243
	v_exp_f32_e32 v6, v6
	v_exp_f32_e32 v7, v7
	v_exp_f32_e32 v8, v8
	v_exp_f32_e32 v9, v9
	v_add_f32_e32 v239, 0, v2
	v_add_f32_e32 v239, v239, v3
	v_add_f32_e32 v239, v239, v4
	v_add_f32_e32 v239, v239, v5
	v_fmamk_f32 v10, v10, 0x3e38aa3b, v243
	v_fmamk_f32 v11, v11, 0x3e38aa3b, v243
	v_fmamk_f32 v12, v12, 0x3e38aa3b, v243
	v_fmamk_f32 v13, v13, 0x3e38aa3b, v243
	v_exp_f32_e32 v10, v10
	v_exp_f32_e32 v11, v11
	v_exp_f32_e32 v12, v12
	v_exp_f32_e32 v13, v13
	v_add_f32_e32 v239, v239, v6
	v_add_f32_e32 v239, v239, v7
	v_add_f32_e32 v239, v239, v8
	v_add_f32_e32 v239, v239, v9
	v_fmamk_f32 v14, v14, 0x3e38aa3b, v243
	v_fmamk_f32 v15, v15, 0x3e38aa3b, v243
	v_fmamk_f32 v16, v16, 0x3e38aa3b, v243
	v_fmamk_f32 v17, v17, 0x3e38aa3b, v243
	v_exp_f32_e32 v14, v14
	v_exp_f32_e32 v15, v15
	v_exp_f32_e32 v16, v16
	v_exp_f32_e32 v17, v17
	v_add_f32_e32 v239, v239, v10
	v_add_f32_e32 v239, v239, v11
	v_add_f32_e32 v239, v239, v12
	v_add_f32_e32 v239, v239, v13
	v_fmamk_f32 v18, v18, 0x3e38aa3b, v243
	v_fmamk_f32 v19, v19, 0x3e38aa3b, v243
	v_fmamk_f32 v20, v20, 0x3e38aa3b, v243
	v_fmamk_f32 v21, v21, 0x3e38aa3b, v243
	v_exp_f32_e32 v18, v18
	v_exp_f32_e32 v19, v19
	v_exp_f32_e32 v20, v20
	v_exp_f32_e32 v21, v21
	v_add_f32_e32 v239, v239, v14
	v_add_f32_e32 v239, v239, v15
	v_add_f32_e32 v239, v239, v16
	v_add_f32_e32 v239, v239, v17
	v_fmamk_f32 v22, v22, 0x3e38aa3b, v243
	v_fmamk_f32 v23, v23, 0x3e38aa3b, v243
	v_fmamk_f32 v24, v24, 0x3e38aa3b, v243
	v_fmamk_f32 v25, v25, 0x3e38aa3b, v243
	v_exp_f32_e32 v22, v22
	v_exp_f32_e32 v23, v23
	v_exp_f32_e32 v24, v24
	v_exp_f32_e32 v25, v25
	v_add_f32_e32 v239, v239, v18
	v_add_f32_e32 v239, v239, v19
	v_add_f32_e32 v239, v239, v20
	v_add_f32_e32 v239, v239, v21
	v_fmamk_f32 v26, v26, 0x3e38aa3b, v243
	v_fmamk_f32 v27, v27, 0x3e38aa3b, v243
	v_fmamk_f32 v28, v28, 0x3e38aa3b, v243
	v_fmamk_f32 v29, v29, 0x3e38aa3b, v243
	v_exp_f32_e32 v26, v26
	v_exp_f32_e32 v27, v27
	v_exp_f32_e32 v28, v28
	v_exp_f32_e32 v29, v29
	v_add_f32_e32 v239, v239, v22
	v_add_f32_e32 v239, v239, v23
	v_add_f32_e32 v239, v239, v24
	v_add_f32_e32 v239, v239, v25
	v_fmamk_f32 v30, v30, 0x3e38aa3b, v243
	v_fmamk_f32 v31, v31, 0x3e38aa3b, v243
	v_fmamk_f32 v32, v32, 0x3e38aa3b, v243
	v_fmamk_f32 v33, v33, 0x3e38aa3b, v243
	v_exp_f32_e32 v30, v30
	v_exp_f32_e32 v31, v31
	v_exp_f32_e32 v32, v32
	v_exp_f32_e32 v33, v33
	v_add_f32_e32 v239, v239, v26
	v_add_f32_e32 v239, v239, v27
	v_add_f32_e32 v239, v239, v28
	v_add_f32_e32 v239, v239, v29
	v_fmamk_f32 v86, v86, 0x3e38aa3b, v243
	v_fmamk_f32 v87, v87, 0x3e38aa3b, v243
	v_fmamk_f32 v88, v88, 0x3e38aa3b, v243
	v_fmamk_f32 v89, v89, 0x3e38aa3b, v243
	v_exp_f32_e32 v86, v86
	v_exp_f32_e32 v87, v87
	v_exp_f32_e32 v88, v88
	v_exp_f32_e32 v89, v89
	v_add_f32_e32 v239, v239, v30
	v_add_f32_e32 v239, v239, v31
	v_add_f32_e32 v239, v239, v32
	v_add_f32_e32 v239, v239, v33
	s_nop 0
	v_add_f32_e32 v239, v239, v86
	v_add_f32_e32 v239, v239, v87
	v_add_f32_e32 v239, v239, v88
	v_add_f32_e32 v239, v239, v89
	v_xor_b32_e32 v242, 16, v195
	v_lshlrev_b32_e32 v242, 2, v242
	ds_bpermute_b32 v242, v242, v239
	s_waitcnt lgkmcnt(0)
	v_add_f32_e32 v239, v239, v242
	v_xor_b32_e32 v242, 32, v195
	v_lshlrev_b32_e32 v242, 2, v242
	ds_bpermute_b32 v242, v242, v239
	s_waitcnt lgkmcnt(0)
	v_add_f32_e32 v239, v239, v242
	v_sub_f32_e32 v242, v85, v238
	v_mul_f32_e32 v242, 0x3fb8aa3b, v242
	v_exp_f32_e32 v242, v242
	s_nop 0
	v_add_f32_e32 v239, v239, v242
	v_rcp_f32_e32 v244, v239
	v_cvt_pk_bf16_f32 v218, v2, v3
	v_cvt_pk_bf16_f32 v219, v4, v5
	v_cvt_pk_bf16_f32 v220, v6, v7
	v_cvt_pk_bf16_f32 v221, v8, v9
	v_cvt_pk_bf16_f32 v222, v10, v11
	v_cvt_pk_bf16_f32 v223, v12, v13
	v_cvt_pk_bf16_f32 v224, v14, v15
	v_cvt_pk_bf16_f32 v225, v16, v17
	v_cvt_pk_bf16_f32 v226, v18, v19
	v_cvt_pk_bf16_f32 v227, v20, v21
	v_cvt_pk_bf16_f32 v228, v22, v23
	v_cvt_pk_bf16_f32 v229, v24, v25
	v_cvt_pk_bf16_f32 v230, v26, v27
	v_cvt_pk_bf16_f32 v231, v28, v29
	v_cvt_pk_bf16_f32 v232, v30, v31
	v_cvt_pk_bf16_f32 v233, v32, v33
	v_cvt_pk_bf16_f32 v234, v86, v87
	v_cvt_pk_bf16_f32 v235, v88, v89
	v_mov_b32_e32 v236, 0
	v_mov_b32_e32 v237, 0
	ds_read_b64 v[182:183], v245 offset:192
	ds_read_b64 v[184:185], v245 offset:224
	ds_read_b64 v[186:187], v245 offset:8640
	ds_read_b64 v[188:189], v245 offset:8672
	ds_read_b64 v[190:191], v245 offset:17088
	ds_read_b64 v[192:193], v245 offset:17120
	ds_read_b64 v[210:211], v245 offset:25536
	ds_read_b64 v[212:213], v245 offset:25568
	ds_read_b64 v[214:215], v245 offset:256
	ds_read_b64 v[216:217], v245 offset:288
	s_waitcnt lgkmcnt(8)
	v_mfma_f32_16x16x32_bf16 v[142:145], v[182:185], v[218:221], 0
	ds_read_b64 v[182:183], v245 offset:8704
	ds_read_b64 v[184:185], v245 offset:8736
	s_waitcnt lgkmcnt(8)
	v_mfma_f32_16x16x32_bf16 v[146:149], v[186:189], v[218:221], 0
	ds_read_b64 v[186:187], v245 offset:17152
	ds_read_b64 v[188:189], v245 offset:17184
	s_waitcnt lgkmcnt(8)
	v_mfma_f32_16x16x32_bf16 v[150:153], v[190:193], v[218:221], 0
	ds_read_b64 v[190:191], v245 offset:25600
	ds_read_b64 v[192:193], v245 offset:25632
	s_waitcnt lgkmcnt(8)
	v_mfma_f32_16x16x32_bf16 v[154:157], v[210:213], v[218:221], 0
	ds_read_b64 v[210:211], v245 offset:320
	ds_read_b64 v[212:213], v245 offset:352
	s_waitcnt lgkmcnt(8)
	v_mfma_f32_16x16x32_bf16 v[142:145], v[214:217], v[222:225], v[142:145]
	ds_read_b64 v[214:215], v245 offset:8768
	ds_read_b64 v[216:217], v245 offset:8800
	s_waitcnt lgkmcnt(8)
	v_mfma_f32_16x16x32_bf16 v[146:149], v[182:185], v[222:225], v[146:149]
	ds_read_b64 v[182:183], v245 offset:17216
	ds_read_b64 v[184:185], v245 offset:17248
	s_waitcnt lgkmcnt(8)
	v_mfma_f32_16x16x32_bf16 v[150:153], v[186:189], v[222:225], v[150:153]
	ds_read_b64 v[186:187], v245 offset:25664
	ds_read_b64 v[188:189], v245 offset:25696
	s_waitcnt lgkmcnt(8)
	v_mfma_f32_16x16x32_bf16 v[154:157], v[190:193], v[222:225], v[154:157]
	ds_read_b64 v[190:191], v245 offset:384
	ds_read_b64 v[192:193], v245 offset:416
	s_waitcnt lgkmcnt(8)
	v_mfma_f32_16x16x32_bf16 v[142:145], v[210:213], v[226:229], v[142:145]
	ds_read_b64 v[210:211], v245 offset:8832
	ds_read_b64 v[212:213], v245 offset:8864
	s_waitcnt lgkmcnt(8)
	v_mfma_f32_16x16x32_bf16 v[146:149], v[214:217], v[226:229], v[146:149]
	ds_read_b64 v[214:215], v245 offset:17280
	ds_read_b64 v[216:217], v245 offset:17312
	s_waitcnt lgkmcnt(8)
	v_mfma_f32_16x16x32_bf16 v[150:153], v[182:185], v[226:229], v[150:153]
	ds_read_b64 v[182:183], v245 offset:25728
	ds_read_b64 v[184:185], v245 offset:25760
	s_waitcnt lgkmcnt(8)
	v_mfma_f32_16x16x32_bf16 v[154:157], v[186:189], v[226:229], v[154:157]
	ds_read_b64 v[186:187], v245 offset:448
	ds_read_b64 v[188:189], v245 offset:448
	s_waitcnt lgkmcnt(8)
	v_mfma_f32_16x16x32_bf16 v[142:145], v[190:193], v[230:233], v[142:145]
	ds_read_b64 v[190:191], v245 offset:8896
	ds_read_b64 v[192:193], v245 offset:8896
	s_waitcnt lgkmcnt(8)
	v_mfma_f32_16x16x32_bf16 v[146:149], v[210:213], v[230:233], v[146:149]
	ds_read_b64 v[210:211], v245 offset:17344
	ds_read_b64 v[212:213], v245 offset:17344
	s_waitcnt lgkmcnt(8)
	v_mfma_f32_16x16x32_bf16 v[150:153], v[214:217], v[230:233], v[150:153]
	ds_read_b64 v[214:215], v245 offset:25792
	ds_read_b64 v[216:217], v245 offset:25792
	s_waitcnt lgkmcnt(8)
	v_mfma_f32_16x16x32_bf16 v[154:157], v[182:185], v[230:233], v[154:157]
	s_waitcnt lgkmcnt(6)
	v_mfma_f32_16x16x32_bf16 v[142:145], v[186:189], v[234:237], v[142:145]
	s_waitcnt lgkmcnt(4)
	v_mfma_f32_16x16x32_bf16 v[146:149], v[190:193], v[234:237], v[146:149]
	s_waitcnt lgkmcnt(2)
	v_mfma_f32_16x16x32_bf16 v[150:153], v[210:213], v[234:237], v[150:153]
	s_waitcnt lgkmcnt(0)
	v_mfma_f32_16x16x32_bf16 v[154:157], v[214:217], v[234:237], v[154:157]
	s_nop 7
	s_nop 1
	v_mul_f32_e32 v142, v244, v142
	v_mul_f32_e32 v143, v244, v143
	v_mul_f32_e32 v144, v244, v144
	v_mul_f32_e32 v145, v244, v145
	v_mul_f32_e32 v146, v244, v146
	v_mul_f32_e32 v147, v244, v147
	v_mul_f32_e32 v148, v244, v148
	v_mul_f32_e32 v149, v244, v149
	v_cvt_pk_bf16_f32 v240, v142, v143
	v_cvt_pk_bf16_f32 v241, v144, v145
	v_cvt_pk_bf16_f32 v242, v146, v147
	v_cvt_pk_bf16_f32 v243, v148, v149
	global_store_dwordx4 v[246:247], v[240:243], off sc1
	s_nop 1
	v_mul_f32_e32 v150, v244, v150
	v_mul_f32_e32 v151, v244, v151
	v_mul_f32_e32 v152, v244, v152
	v_mul_f32_e32 v153, v244, v153
	v_mul_f32_e32 v154, v244, v154
	v_mul_f32_e32 v155, v244, v155
	v_mul_f32_e32 v156, v244, v156
	v_mul_f32_e32 v157, v244, v157
	v_cvt_pk_bf16_f32 v240, v150, v151
	v_cvt_pk_bf16_f32 v241, v152, v153
	v_cvt_pk_bf16_f32 v242, v154, v155
	v_cvt_pk_bf16_f32 v243, v156, v157
	global_store_dwordx4 v[246:247], v[240:243], off offset:64 sc1
	v_lshl_add_u64 v[246:247], v[246:247], 0, s[8:9]
	s_waitcnt vmcnt(2)
	ds_read_b128 v[106:109], v118 offset:16128
	ds_read_b128 v[110:113], v118 offset:16192
	ds_read_b128 v[114:117], v118 offset:18432
	ds_read_b128 v[128:131], v118 offset:18496
	ds_read_b128 v[132:135], v118 offset:20736
	ds_read_b128 v[120:123], v118 offset:20800
	s_waitcnt lgkmcnt(5)
	v_mfma_f32_16x16x32_bf16 v[2:5], v[106:109], v[98:101], 0
	ds_read_b128 v[106:109], v118 offset:23040
	s_waitcnt lgkmcnt(5)
	v_mfma_f32_16x16x32_bf16 v[2:5], v[110:113], v[102:105], v[2:5]
	ds_read_b128 v[110:113], v118 offset:23104
	s_waitcnt lgkmcnt(5)
	v_mfma_f32_16x16x32_bf16 v[6:9], v[114:117], v[98:101], 0
	ds_read_b128 v[114:117], v118 offset:25344
	s_waitcnt lgkmcnt(5)
	v_mfma_f32_16x16x32_bf16 v[6:9], v[128:131], v[102:105], v[6:9]
	ds_read_b128 v[128:131], v118 offset:25408
	s_waitcnt lgkmcnt(5)
	v_mfma_f32_16x16x32_bf16 v[10:13], v[132:135], v[98:101], 0
	ds_read_b128 v[132:135], v118 offset:27648
	s_waitcnt lgkmcnt(5)
	v_mfma_f32_16x16x32_bf16 v[10:13], v[120:123], v[102:105], v[10:13]
	ds_read_b128 v[120:123], v118 offset:27712
	s_waitcnt lgkmcnt(5)
	v_mfma_f32_16x16x32_bf16 v[14:17], v[106:109], v[98:101], 0
	ds_read_b128 v[106:109], v118 offset:29952
	s_waitcnt lgkmcnt(5)
	v_mfma_f32_16x16x32_bf16 v[14:17], v[110:113], v[102:105], v[14:17]
	ds_read_b128 v[110:113], v118 offset:30016
	s_waitcnt lgkmcnt(5)
	v_mfma_f32_16x16x32_bf16 v[18:21], v[114:117], v[98:101], 0
	ds_read_b128 v[114:117], v118 offset:32256
	s_waitcnt lgkmcnt(5)
	v_mfma_f32_16x16x32_bf16 v[18:21], v[128:131], v[102:105], v[18:21]
	ds_read_b128 v[128:131], v118 offset:32320
	s_waitcnt lgkmcnt(5)
	v_mfma_f32_16x16x32_bf16 v[22:25], v[132:135], v[98:101], 0
	ds_read_b128 v[132:135], v118 offset:34560
	s_waitcnt lgkmcnt(5)
	v_mfma_f32_16x16x32_bf16 v[22:25], v[120:123], v[102:105], v[22:25]
	ds_read_b128 v[120:123], v118 offset:34624
	s_waitcnt lgkmcnt(5)
	v_mfma_f32_16x16x32_bf16 v[26:29], v[106:109], v[98:101], 0
	s_waitcnt lgkmcnt(4)
	v_mfma_f32_16x16x32_bf16 v[26:29], v[110:113], v[102:105], v[26:29]
	s_waitcnt lgkmcnt(3)
	v_mfma_f32_16x16x32_bf16 v[30:33], v[114:117], v[98:101], 0
	s_waitcnt lgkmcnt(2)
	v_mfma_f32_16x16x32_bf16 v[30:33], v[128:131], v[102:105], v[30:33]
	s_waitcnt lgkmcnt(1)
	v_mfma_f32_16x16x32_bf16 v[86:89], v[132:135], v[98:101], 0
	s_waitcnt lgkmcnt(0)
	v_mfma_f32_16x16x32_bf16 v[86:89], v[120:123], v[102:105], v[86:89]
	v_add_u32_e32 v242, 0, v249
	v_cmp_gt_u32_e32 vcc, v242, v248
	s_nop 1
	s_and_b64 vcc, vcc, s[66:67]
	s_nop 0
	v_cndmask_b32_e32 v2, v205, v2, vcc
	v_add_u32_e32 v242, 1, v249
	v_cmp_gt_u32_e32 vcc, v242, v248
	s_nop 1
	s_and_b64 vcc, vcc, s[66:67]
	s_nop 0
	v_cndmask_b32_e32 v3, v205, v3, vcc
	v_add_u32_e32 v242, 2, v249
	v_cmp_gt_u32_e32 vcc, v242, v248
	s_nop 1
	s_and_b64 vcc, vcc, s[66:67]
	s_nop 0
	v_cndmask_b32_e32 v4, v205, v4, vcc
	v_add_u32_e32 v242, 3, v249
	v_cmp_gt_u32_e32 vcc, v242, v248
	s_nop 1
	s_and_b64 vcc, vcc, s[66:67]
	s_nop 0
	v_cndmask_b32_e32 v5, v205, v5, vcc
	v_add_u32_e32 v242, 0, v249
	v_cmp_le_u32_e32 vcc, v242, v248
	s_nop 1
	v_cndmask_b32_e32 v86, v205, v86, vcc
	v_add_u32_e32 v242, 1, v249
	v_cmp_le_u32_e32 vcc, v242, v248
	s_nop 1
	v_cndmask_b32_e32 v87, v205, v87, vcc
	v_add_u32_e32 v242, 2, v249
	v_cmp_le_u32_e32 vcc, v242, v248
	s_nop 1
	v_cndmask_b32_e32 v88, v205, v88, vcc
	v_add_u32_e32 v242, 3, v249
	v_cmp_le_u32_e32 vcc, v242, v248
	s_nop 1
	v_cndmask_b32_e32 v89, v205, v89, vcc
	v_max3_f32 v238, v2, v3, v205
	v_max3_f32 v238, v238, v4, v5
	v_max3_f32 v238, v238, v6, v7
	v_max3_f32 v238, v238, v8, v9
	v_max3_f32 v238, v238, v10, v11
	v_max3_f32 v238, v238, v12, v13
	v_max3_f32 v238, v238, v14, v15
	v_max3_f32 v238, v238, v16, v17
	v_max3_f32 v238, v238, v18, v19
	v_max3_f32 v238, v238, v20, v21
	v_max3_f32 v238, v238, v22, v23
	v_max3_f32 v238, v238, v24, v25
	v_max3_f32 v238, v238, v26, v27
	v_max3_f32 v238, v238, v28, v29
	v_max3_f32 v238, v238, v30, v31
	v_max3_f32 v238, v238, v32, v33
	v_max3_f32 v238, v238, v86, v87
	v_max3_f32 v238, v238, v88, v89
	v_xor_b32_e32 v242, 16, v195
	v_lshlrev_b32_e32 v242, 2, v242
	ds_bpermute_b32 v242, v242, v238
	s_waitcnt lgkmcnt(0)
	v_max_f32_e32 v238, v238, v242
	v_xor_b32_e32 v242, 32, v195
	v_lshlrev_b32_e32 v242, 2, v242
	ds_bpermute_b32 v242, v242, v238
	s_waitcnt lgkmcnt(0)
	v_max_f32_e32 v238, v238, v242
	v_mul_f32_e32 v238, 0x3e000000, v238
	v_max_f32_e32 v238, v238, v85
	v_mul_f32_e32 v243, 0xbfb8aa3b, v238
	v_fmamk_f32 v2, v2, 0x3e38aa3b, v243
	v_fmamk_f32 v3, v3, 0x3e38aa3b, v243
	v_fmamk_f32 v4, v4, 0x3e38aa3b, v243
	v_fmamk_f32 v5, v5, 0x3e38aa3b, v243
	v_exp_f32_e32 v2, v2
	v_exp_f32_e32 v3, v3
	v_exp_f32_e32 v4, v4
	v_exp_f32_e32 v5, v5
	v_fmamk_f32 v6, v6, 0x3e38aa3b, v243
	v_fmamk_f32 v7, v7, 0x3e38aa3b, v243
	v_fmamk_f32 v8, v8, 0x3e38aa3b, v243
	v_fmamk_f32 v9, v9, 0x3e38aa3b, v243
	v_exp_f32_e32 v6, v6
	v_exp_f32_e32 v7, v7
	v_exp_f32_e32 v8, v8
	v_exp_f32_e32 v9, v9
	v_add_f32_e32 v239, 0, v2
	v_add_f32_e32 v239, v239, v3
	v_add_f32_e32 v239, v239, v4
	v_add_f32_e32 v239, v239, v5
	v_fmamk_f32 v10, v10, 0x3e38aa3b, v243
	v_fmamk_f32 v11, v11, 0x3e38aa3b, v243
	v_fmamk_f32 v12, v12, 0x3e38aa3b, v243
	v_fmamk_f32 v13, v13, 0x3e38aa3b, v243
	v_exp_f32_e32 v10, v10
	v_exp_f32_e32 v11, v11
	v_exp_f32_e32 v12, v12
	v_exp_f32_e32 v13, v13
	v_add_f32_e32 v239, v239, v6
	v_add_f32_e32 v239, v239, v7
	v_add_f32_e32 v239, v239, v8
	v_add_f32_e32 v239, v239, v9
	v_fmamk_f32 v14, v14, 0x3e38aa3b, v243
	v_fmamk_f32 v15, v15, 0x3e38aa3b, v243
	v_fmamk_f32 v16, v16, 0x3e38aa3b, v243
	v_fmamk_f32 v17, v17, 0x3e38aa3b, v243
	v_exp_f32_e32 v14, v14
	v_exp_f32_e32 v15, v15
	v_exp_f32_e32 v16, v16
	v_exp_f32_e32 v17, v17
	v_add_f32_e32 v239, v239, v10
	v_add_f32_e32 v239, v239, v11
	v_add_f32_e32 v239, v239, v12
	v_add_f32_e32 v239, v239, v13
	v_fmamk_f32 v18, v18, 0x3e38aa3b, v243
	v_fmamk_f32 v19, v19, 0x3e38aa3b, v243
	v_fmamk_f32 v20, v20, 0x3e38aa3b, v243
	v_fmamk_f32 v21, v21, 0x3e38aa3b, v243
	v_exp_f32_e32 v18, v18
	v_exp_f32_e32 v19, v19
	v_exp_f32_e32 v20, v20
	v_exp_f32_e32 v21, v21
	v_add_f32_e32 v239, v239, v14
	v_add_f32_e32 v239, v239, v15
	v_add_f32_e32 v239, v239, v16
	v_add_f32_e32 v239, v239, v17
	v_fmamk_f32 v22, v22, 0x3e38aa3b, v243
	v_fmamk_f32 v23, v23, 0x3e38aa3b, v243
	v_fmamk_f32 v24, v24, 0x3e38aa3b, v243
	v_fmamk_f32 v25, v25, 0x3e38aa3b, v243
	v_exp_f32_e32 v22, v22
	v_exp_f32_e32 v23, v23
	v_exp_f32_e32 v24, v24
	v_exp_f32_e32 v25, v25
	v_add_f32_e32 v239, v239, v18
	v_add_f32_e32 v239, v239, v19
	v_add_f32_e32 v239, v239, v20
	v_add_f32_e32 v239, v239, v21
	v_fmamk_f32 v26, v26, 0x3e38aa3b, v243
	v_fmamk_f32 v27, v27, 0x3e38aa3b, v243
	v_fmamk_f32 v28, v28, 0x3e38aa3b, v243
	v_fmamk_f32 v29, v29, 0x3e38aa3b, v243
	v_exp_f32_e32 v26, v26
	v_exp_f32_e32 v27, v27
	v_exp_f32_e32 v28, v28
	v_exp_f32_e32 v29, v29
	v_add_f32_e32 v239, v239, v22
	v_add_f32_e32 v239, v239, v23
	v_add_f32_e32 v239, v239, v24
	v_add_f32_e32 v239, v239, v25
	v_fmamk_f32 v30, v30, 0x3e38aa3b, v243
	v_fmamk_f32 v31, v31, 0x3e38aa3b, v243
	v_fmamk_f32 v32, v32, 0x3e38aa3b, v243
	v_fmamk_f32 v33, v33, 0x3e38aa3b, v243
	v_exp_f32_e32 v30, v30
	v_exp_f32_e32 v31, v31
	v_exp_f32_e32 v32, v32
	v_exp_f32_e32 v33, v33
	v_add_f32_e32 v239, v239, v26
	v_add_f32_e32 v239, v239, v27
	v_add_f32_e32 v239, v239, v28
	v_add_f32_e32 v239, v239, v29
	v_fmamk_f32 v86, v86, 0x3e38aa3b, v243
	v_fmamk_f32 v87, v87, 0x3e38aa3b, v243
	v_fmamk_f32 v88, v88, 0x3e38aa3b, v243
	v_fmamk_f32 v89, v89, 0x3e38aa3b, v243
	v_exp_f32_e32 v86, v86
	v_exp_f32_e32 v87, v87
	v_exp_f32_e32 v88, v88
	v_exp_f32_e32 v89, v89
	v_add_f32_e32 v239, v239, v30
	v_add_f32_e32 v239, v239, v31
	v_add_f32_e32 v239, v239, v32
	v_add_f32_e32 v239, v239, v33
	s_nop 0
	v_add_f32_e32 v239, v239, v86
	v_add_f32_e32 v239, v239, v87
	v_add_f32_e32 v239, v239, v88
	v_add_f32_e32 v239, v239, v89
	v_xor_b32_e32 v242, 16, v195
	v_lshlrev_b32_e32 v242, 2, v242
	ds_bpermute_b32 v242, v242, v239
	s_waitcnt lgkmcnt(0)
	v_add_f32_e32 v239, v239, v242
	v_xor_b32_e32 v242, 32, v195
	v_lshlrev_b32_e32 v242, 2, v242
	ds_bpermute_b32 v242, v242, v239
	s_waitcnt lgkmcnt(0)
	v_add_f32_e32 v239, v239, v242
	v_sub_f32_e32 v242, v85, v238
	v_mul_f32_e32 v242, 0x3fb8aa3b, v242
	v_exp_f32_e32 v242, v242
	s_nop 0
	v_add_f32_e32 v239, v239, v242
	v_rcp_f32_e32 v244, v239
	v_cvt_pk_bf16_f32 v218, v2, v3
	v_cvt_pk_bf16_f32 v219, v4, v5
	v_cvt_pk_bf16_f32 v220, v6, v7
	v_cvt_pk_bf16_f32 v221, v8, v9
	v_cvt_pk_bf16_f32 v222, v10, v11
	v_cvt_pk_bf16_f32 v223, v12, v13
	v_cvt_pk_bf16_f32 v224, v14, v15
	v_cvt_pk_bf16_f32 v225, v16, v17
	v_cvt_pk_bf16_f32 v226, v18, v19
	v_cvt_pk_bf16_f32 v227, v20, v21
	v_cvt_pk_bf16_f32 v228, v22, v23
	v_cvt_pk_bf16_f32 v229, v24, v25
	v_cvt_pk_bf16_f32 v230, v26, v27
	v_cvt_pk_bf16_f32 v231, v28, v29
	v_cvt_pk_bf16_f32 v232, v30, v31
	v_cvt_pk_bf16_f32 v233, v32, v33
	v_cvt_pk_bf16_f32 v234, v86, v87
	v_cvt_pk_bf16_f32 v235, v88, v89
	v_mov_b32_e32 v236, 0
	v_mov_b32_e32 v237, 0
	ds_read_b64 v[182:183], v245 offset:224
	ds_read_b64 v[184:185], v245 offset:256
	ds_read_b64 v[186:187], v245 offset:8672
	ds_read_b64 v[188:189], v245 offset:8704
	ds_read_b64 v[190:191], v245 offset:17120
	ds_read_b64 v[192:193], v245 offset:17152
	ds_read_b64 v[210:211], v245 offset:25568
	ds_read_b64 v[212:213], v245 offset:25600
	ds_read_b64 v[214:215], v245 offset:288
	ds_read_b64 v[216:217], v245 offset:320
	s_waitcnt lgkmcnt(8)
	v_mfma_f32_16x16x32_bf16 v[142:145], v[182:185], v[218:221], 0
	ds_read_b64 v[182:183], v245 offset:8736
	ds_read_b64 v[184:185], v245 offset:8768
	s_waitcnt lgkmcnt(8)
	v_mfma_f32_16x16x32_bf16 v[146:149], v[186:189], v[218:221], 0
	ds_read_b64 v[186:187], v245 offset:17184
	ds_read_b64 v[188:189], v245 offset:17216
	s_waitcnt lgkmcnt(8)
	v_mfma_f32_16x16x32_bf16 v[150:153], v[190:193], v[218:221], 0
	ds_read_b64 v[190:191], v245 offset:25632
	ds_read_b64 v[192:193], v245 offset:25664
	s_waitcnt lgkmcnt(8)
	v_mfma_f32_16x16x32_bf16 v[154:157], v[210:213], v[218:221], 0
	ds_read_b64 v[210:211], v245 offset:352
	ds_read_b64 v[212:213], v245 offset:384
	s_waitcnt lgkmcnt(8)
	v_mfma_f32_16x16x32_bf16 v[142:145], v[214:217], v[222:225], v[142:145]
	ds_read_b64 v[214:215], v245 offset:8800
	ds_read_b64 v[216:217], v245 offset:8832
	s_waitcnt lgkmcnt(8)
	v_mfma_f32_16x16x32_bf16 v[146:149], v[182:185], v[222:225], v[146:149]
	ds_read_b64 v[182:183], v245 offset:17248
	ds_read_b64 v[184:185], v245 offset:17280
	s_waitcnt lgkmcnt(8)
	v_mfma_f32_16x16x32_bf16 v[150:153], v[186:189], v[222:225], v[150:153]
	ds_read_b64 v[186:187], v245 offset:25696
	ds_read_b64 v[188:189], v245 offset:25728
	s_waitcnt lgkmcnt(8)
	v_mfma_f32_16x16x32_bf16 v[154:157], v[190:193], v[222:225], v[154:157]
	ds_read_b64 v[190:191], v245 offset:416
	ds_read_b64 v[192:193], v245 offset:448
	s_waitcnt lgkmcnt(8)
	v_mfma_f32_16x16x32_bf16 v[142:145], v[210:213], v[226:229], v[142:145]
	ds_read_b64 v[210:211], v245 offset:8864
	ds_read_b64 v[212:213], v245 offset:8896
	s_waitcnt lgkmcnt(8)
	v_mfma_f32_16x16x32_bf16 v[146:149], v[214:217], v[226:229], v[146:149]
	ds_read_b64 v[214:215], v245 offset:17312
	ds_read_b64 v[216:217], v245 offset:17344
	s_waitcnt lgkmcnt(8)
	v_mfma_f32_16x16x32_bf16 v[150:153], v[182:185], v[226:229], v[150:153]
	ds_read_b64 v[182:183], v245 offset:25760
	ds_read_b64 v[184:185], v245 offset:25792
	s_waitcnt lgkmcnt(8)
	v_mfma_f32_16x16x32_bf16 v[154:157], v[186:189], v[226:229], v[154:157]
	ds_read_b64 v[186:187], v245 offset:480
	ds_read_b64 v[188:189], v245 offset:480
	s_waitcnt lgkmcnt(8)
	v_mfma_f32_16x16x32_bf16 v[142:145], v[190:193], v[230:233], v[142:145]
	ds_read_b64 v[190:191], v245 offset:8928
	ds_read_b64 v[192:193], v245 offset:8928
	s_waitcnt lgkmcnt(8)
	v_mfma_f32_16x16x32_bf16 v[146:149], v[210:213], v[230:233], v[146:149]
	ds_read_b64 v[210:211], v245 offset:17376
	ds_read_b64 v[212:213], v245 offset:17376
	s_waitcnt lgkmcnt(8)
	v_mfma_f32_16x16x32_bf16 v[150:153], v[214:217], v[230:233], v[150:153]
	ds_read_b64 v[214:215], v245 offset:25824
	ds_read_b64 v[216:217], v245 offset:25824
	s_waitcnt lgkmcnt(8)
	v_mfma_f32_16x16x32_bf16 v[154:157], v[182:185], v[230:233], v[154:157]
	s_waitcnt lgkmcnt(6)
	v_mfma_f32_16x16x32_bf16 v[142:145], v[186:189], v[234:237], v[142:145]
	s_waitcnt lgkmcnt(4)
	v_mfma_f32_16x16x32_bf16 v[146:149], v[190:193], v[234:237], v[146:149]
	s_waitcnt lgkmcnt(2)
	v_mfma_f32_16x16x32_bf16 v[150:153], v[210:213], v[234:237], v[150:153]
	s_waitcnt lgkmcnt(0)
	v_mfma_f32_16x16x32_bf16 v[154:157], v[214:217], v[234:237], v[154:157]
	s_nop 7
	s_nop 1
	v_mul_f32_e32 v142, v244, v142
	v_mul_f32_e32 v143, v244, v143
	v_mul_f32_e32 v144, v244, v144
	v_mul_f32_e32 v145, v244, v145
	v_mul_f32_e32 v146, v244, v146
	v_mul_f32_e32 v147, v244, v147
	v_mul_f32_e32 v148, v244, v148
	v_mul_f32_e32 v149, v244, v149
	v_cvt_pk_bf16_f32 v240, v142, v143
	v_cvt_pk_bf16_f32 v241, v144, v145
	v_cvt_pk_bf16_f32 v242, v146, v147
	v_cvt_pk_bf16_f32 v243, v148, v149
	global_store_dwordx4 v[246:247], v[240:243], off sc1
	s_nop 1
	v_mul_f32_e32 v150, v244, v150
	v_mul_f32_e32 v151, v244, v151
	v_mul_f32_e32 v152, v244, v152
	v_mul_f32_e32 v153, v244, v153
	v_mul_f32_e32 v154, v244, v154
	v_mul_f32_e32 v155, v244, v155
	v_mul_f32_e32 v156, v244, v156
	v_mul_f32_e32 v157, v244, v157
	v_cvt_pk_bf16_f32 v240, v150, v151
	v_cvt_pk_bf16_f32 v241, v152, v153
	v_cvt_pk_bf16_f32 v242, v154, v155
	v_cvt_pk_bf16_f32 v243, v156, v157
	global_store_dwordx4 v[246:247], v[240:243], off offset:64 sc1
	v_cndmask_b32_e64 v30, 0, 1, s[74:75]
	v_cmp_ne_u32_e64 s[38:39], 1, v30
	s_branch .LBB0_140

.LBB0_162:
	v_cndmask_b32_e64 v66, 0, 1, s[0:1]
	v_cmp_ne_u32_e32 vcc, 1, v66
	v_add_u32_e32 v66, s5, v208
	v_ashrrev_i32_e32 v88, 5, v66
	v_ashrrev_i32_e32 v89, 31, v88
	v_lshlrev_b64 v[66:67], 9, v[88:89]
	v_lshl_add_u64 v[66:67], v[86:87], 0, v[66:67]
	v_add_u32_e32 v70, s5, v127
	flat_load_dwordx4 v[66:69], v[66:67]
	v_ashrrev_i32_e32 v90, 5, v70
	v_ashrrev_i32_e32 v91, 31, v90
	v_lshlrev_b64 v[70:71], 9, v[90:91]
	v_lshl_add_u64 v[70:71], v[86:87], 0, v[70:71]
	v_add_u32_e32 v74, s5, v136
	flat_load_dwordx4 v[70:73], v[70:71]
	v_ashrrev_i32_e32 v92, 5, v74
	v_ashrrev_i32_e32 v93, 31, v92
	v_lshlrev_b64 v[74:75], 9, v[92:93]
	v_lshl_add_u64 v[74:75], v[86:87], 0, v[74:75]
	v_add_u32_e32 v78, s5, v137
	flat_load_dwordx4 v[74:77], v[74:75]
	v_ashrrev_i32_e32 v94, 5, v78
	v_ashrrev_i32_e32 v95, 31, v94
	v_lshlrev_b64 v[78:79], 9, v[94:95]
	v_lshl_add_u64 v[78:79], v[86:87], 0, v[78:79]
	v_add_u32_e32 v82, s5, v141
	flat_load_dwordx4 v[78:81], v[78:79]
	v_ashrrev_i32_e32 v96, 5, v82
	v_ashrrev_i32_e32 v97, 31, v96
	v_lshlrev_b64 v[82:83], 9, v[96:97]
	v_lshl_add_u64 v[82:83], v[86:87], 0, v[82:83]
	v_add_u32_e32 v89, s5, v142
	flat_load_dwordx4 v[82:85], v[82:83]
	v_ashrrev_i32_e32 v112, 5, v89
	v_ashrrev_i32_e32 v113, 31, v112
	v_lshlrev_b64 v[100:101], 9, v[112:113]
	v_lshl_add_u64 v[100:101], v[86:87], 0, v[100:101]
	v_add_u32_e32 v89, s5, v143
	flat_load_dwordx4 v[100:103], v[100:101]
	v_ashrrev_i32_e32 v114, 5, v89
	v_ashrrev_i32_e32 v115, 31, v114
	v_lshlrev_b64 v[104:105], 9, v[114:115]
	v_lshl_add_u64 v[104:105], v[86:87], 0, v[104:105]
	flat_load_dwordx4 v[104:107], v[104:105]
	v_add_u32_e32 v89, s5, v144
	v_ashrrev_i32_e32 v116, 5, v89
	v_ashrrev_i32_e32 v117, 31, v116
	v_lshlrev_b64 v[108:109], 9, v[116:117]
	v_lshl_add_u64 v[108:109], v[86:87], 0, v[108:109]
	flat_load_dwordx4 v[108:111], v[108:109]
	v_lshlrev_b32_e32 v89, 2, v88
	v_lshrrev_b32_e32 v91, 1, v88
	v_and_b32_e32 v89, 16, v89
	v_and_b32_e32 v91, 12, v91
	v_and_b32_e32 v88, 0xfffffe3, v88
	v_or3_b32 v88, v88, v89, v91
	v_mad_u64_u32 v[88:89], s[0:1], v88, s85, v[126:127]
	s_movk_i32 s5, 0x1000
	s_and_b64 vcc, exec, vcc
	s_waitcnt vmcnt(0) lgkmcnt(0)
	ds_write_b128 v88, v[66:69]
	v_lshlrev_b32_e32 v66, 2, v90
	v_lshrrev_b32_e32 v67, 1, v90
	v_and_b32_e32 v66, 16, v66
	v_and_b32_e32 v67, 12, v67
	v_and_b32_e32 v68, 0xfffffe3, v90
	v_or3_b32 v66, v68, v66, v67
	v_mad_u64_u32 v[66:67], s[0:1], v66, s85, v[126:127]
	ds_write_b128 v66, v[70:73]
	v_lshlrev_b32_e32 v66, 2, v92
	v_lshrrev_b32_e32 v67, 1, v92
	v_and_b32_e32 v66, 16, v66
	v_and_b32_e32 v67, 12, v67
	v_and_b32_e32 v68, 0xfffffe3, v92
	v_or3_b32 v66, v68, v66, v67
	v_mad_u64_u32 v[66:67], s[0:1], v66, s85, v[126:127]
	ds_write_b128 v66, v[74:77]
	v_lshlrev_b32_e32 v66, 2, v94
	v_lshrrev_b32_e32 v67, 1, v94
	v_and_b32_e32 v66, 16, v66
	v_and_b32_e32 v67, 12, v67
	v_and_b32_e32 v68, 0xfffffe3, v94
	v_or3_b32 v66, v68, v66, v67
	v_mad_u64_u32 v[66:67], s[0:1], v66, s85, v[126:127]
	ds_write_b128 v66, v[78:81]
	v_lshlrev_b32_e32 v66, 2, v96
	v_lshrrev_b32_e32 v67, 1, v96
	v_and_b32_e32 v66, 16, v66
	v_and_b32_e32 v67, 12, v67
	v_and_b32_e32 v68, 0xfffffe3, v96
	v_or3_b32 v66, v68, v66, v67
	v_mad_u64_u32 v[66:67], s[0:1], v66, s85, v[126:127]
	ds_write_b128 v66, v[82:85]
	v_lshlrev_b32_e32 v66, 2, v112
	v_lshrrev_b32_e32 v67, 1, v112
	v_and_b32_e32 v66, 16, v66
	v_and_b32_e32 v67, 12, v67
	v_and_b32_e32 v68, 0xfffffe3, v112
	v_or3_b32 v66, v68, v66, v67
	v_mad_u64_u32 v[66:67], s[0:1], v66, s85, v[126:127]
	ds_write_b128 v66, v[100:103]
	v_lshlrev_b32_e32 v66, 2, v114
	v_lshrrev_b32_e32 v67, 1, v114
	v_and_b32_e32 v66, 16, v66
	v_and_b32_e32 v67, 12, v67
	v_and_b32_e32 v68, 0xfffffe3, v114
	v_or3_b32 v66, v68, v66, v67
	v_mad_u64_u32 v[66:67], s[0:1], v66, s85, v[126:127]
	ds_write_b128 v66, v[104:107]
	v_lshlrev_b32_e32 v66, 2, v116
	v_lshrrev_b32_e32 v67, 1, v116
	v_and_b32_e32 v66, 16, v66
	v_and_b32_e32 v67, 12, v67
	v_and_b32_e32 v68, 0xfffffe3, v116
	v_or3_b32 v66, v68, v66, v67
	v_mad_u64_u32 v[66:67], s[0:1], v66, s85, v[126:127]
	s_mov_b64 s[0:1], 0
	ds_write_b128 v66, v[108:111]
	s_cbranch_vccz .LBB0_162
	s_waitcnt lgkmcnt(0)
	s_barrier
	v_and_b32_e32 v114, 15, v195
	v_lshrrev_b32_e32 v115, 4, v195
	v_and_b32_e32 v115, 3, v115
	v_mul_u32_u24_e32 v114, 0x210, v114
	v_lshl_add_u32 v114, v115, 3, v114
	v_add_u32_e32 v115, 0x10800, v114
	ds_read_b64 v[82:83], v114
	ds_read_b64 v[84:85], v114 offset:32
	ds_read_b64 v[86:87], v114 offset:8448
	ds_read_b64 v[88:89], v114 offset:8480
	ds_read_b64 v[90:91], v114 offset:64
	ds_read_b64 v[92:93], v114 offset:96
	ds_read_b64 v[94:95], v114 offset:8512
	ds_read_b64 v[96:97], v114 offset:8544
	ds_read_b64 v[98:99], v114 offset:128
	ds_read_b64 v[100:101], v114 offset:160
	ds_read_b64 v[102:103], v114 offset:8576
	ds_read_b64 v[104:105], v114 offset:8608
	ds_read_b64 v[106:107], v114 offset:192
	ds_read_b64 v[108:109], v114 offset:224
	ds_read_b64 v[110:111], v114 offset:8640
	ds_read_b64 v[112:113], v114 offset:8672
	s_waitcnt lgkmcnt(12)
	v_mfma_f32_16x16x32_bf16 v[66:69], v[82:85], v[2:5], 0
	v_mfma_f32_16x16x32_bf16 v[70:73], v[82:85], v[34:37], 0
	v_mfma_f32_16x16x32_bf16 v[74:77], v[86:89], v[2:5], 0
	v_mfma_f32_16x16x32_bf16 v[78:81], v[86:89], v[34:37], 0
	ds_read_b64 v[82:83], v114 offset:256
	ds_read_b64 v[84:85], v114 offset:288
	ds_read_b64 v[86:87], v114 offset:8704
	ds_read_b64 v[88:89], v114 offset:8736
	s_waitcnt lgkmcnt(12)
	v_mfma_f32_16x16x32_bf16 v[66:69], v[90:93], v[6:9], v[66:69]
	v_mfma_f32_16x16x32_bf16 v[70:73], v[90:93], v[38:41], v[70:73]
	v_mfma_f32_16x16x32_bf16 v[74:77], v[94:97], v[6:9], v[74:77]
	v_mfma_f32_16x16x32_bf16 v[78:81], v[94:97], v[38:41], v[78:81]
	ds_read_b64 v[90:91], v114 offset:320
	ds_read_b64 v[92:93], v114 offset:352
	ds_read_b64 v[94:95], v114 offset:8768
	ds_read_b64 v[96:97], v114 offset:8800
	s_waitcnt lgkmcnt(12)
	v_mfma_f32_16x16x32_bf16 v[66:69], v[98:101], v[10:13], v[66:69]
	v_mfma_f32_16x16x32_bf16 v[70:73], v[98:101], v[42:45], v[70:73]
	v_mfma_f32_16x16x32_bf16 v[74:77], v[102:105], v[10:13], v[74:77]
	v_mfma_f32_16x16x32_bf16 v[78:81], v[102:105], v[42:45], v[78:81]
	ds_read_b64 v[98:99], v114 offset:384
	ds_read_b64 v[100:101], v114 offset:416
	ds_read_b64 v[102:103], v114 offset:8832
	ds_read_b64 v[104:105], v114 offset:8864
	s_waitcnt lgkmcnt(12)
	v_mfma_f32_16x16x32_bf16 v[66:69], v[106:109], v[14:17], v[66:69]
	v_mfma_f32_16x16x32_bf16 v[70:73], v[106:109], v[46:49], v[70:73]
	v_mfma_f32_16x16x32_bf16 v[74:77], v[110:113], v[14:17], v[74:77]
	v_mfma_f32_16x16x32_bf16 v[78:81], v[110:113], v[46:49], v[78:81]
	ds_read_b64 v[106:107], v114 offset:448
	ds_read_b64 v[108:109], v114 offset:480
	ds_read_b64 v[110:111], v114 offset:8896
	ds_read_b64 v[112:113], v114 offset:8928
	s_waitcnt lgkmcnt(12)
	v_mfma_f32_16x16x32_bf16 v[66:69], v[82:85], v[18:21], v[66:69]
	v_mfma_f32_16x16x32_bf16 v[70:73], v[82:85], v[50:53], v[70:73]
	v_mfma_f32_16x16x32_bf16 v[74:77], v[86:89], v[18:21], v[74:77]
	v_mfma_f32_16x16x32_bf16 v[78:81], v[86:89], v[50:53], v[78:81]
	ds_read_b64 v[82:83], v114 offset:16896
	ds_read_b64 v[84:85], v114 offset:16928
	ds_read_b64 v[86:87], v114 offset:25344
	ds_read_b64 v[88:89], v114 offset:25376
	s_waitcnt lgkmcnt(12)
	v_mfma_f32_16x16x32_bf16 v[66:69], v[90:93], v[22:25], v[66:69]
	v_mfma_f32_16x16x32_bf16 v[70:73], v[90:93], v[54:57], v[70:73]
	v_mfma_f32_16x16x32_bf16 v[74:77], v[94:97], v[22:25], v[74:77]
	v_mfma_f32_16x16x32_bf16 v[78:81], v[94:97], v[54:57], v[78:81]
	ds_read_b64 v[90:91], v114 offset:16960
	ds_read_b64 v[92:93], v114 offset:16992
	ds_read_b64 v[94:95], v114 offset:25408
	ds_read_b64 v[96:97], v114 offset:25440
	s_waitcnt lgkmcnt(12)
	v_mfma_f32_16x16x32_bf16 v[66:69], v[98:101], v[26:29], v[66:69]
	v_mfma_f32_16x16x32_bf16 v[70:73], v[98:101], v[58:61], v[70:73]
	v_mfma_f32_16x16x32_bf16 v[74:77], v[102:105], v[26:29], v[74:77]
	v_mfma_f32_16x16x32_bf16 v[78:81], v[102:105], v[58:61], v[78:81]
	ds_read_b64 v[98:99], v114 offset:17024
	ds_read_b64 v[100:101], v114 offset:17056
	ds_read_b64 v[102:103], v114 offset:25472
	ds_read_b64 v[104:105], v114 offset:25504
	s_waitcnt lgkmcnt(12)
	v_mfma_f32_16x16x32_bf16 v[66:69], v[106:109], v[30:33], v[66:69]
	v_mfma_f32_16x16x32_bf16 v[70:73], v[106:109], v[62:65], v[70:73]
	v_mfma_f32_16x16x32_bf16 v[74:77], v[110:113], v[30:33], v[74:77]
	v_mfma_f32_16x16x32_bf16 v[78:81], v[110:113], v[62:65], v[78:81]
	ds_read_b64 v[106:107], v114 offset:17088
	ds_read_b64 v[108:109], v114 offset:17120
	ds_read_b64 v[110:111], v114 offset:25536
	ds_read_b64 v[112:113], v114 offset:25568
	s_waitcnt lgkmcnt(12)
	v_mfma_f32_16x16x32_bf16 v[224:227], v[82:85], v[2:5], 0
	v_mfma_f32_16x16x32_bf16 v[228:231], v[82:85], v[34:37], 0
	v_mfma_f32_16x16x32_bf16 v[232:235], v[86:89], v[2:5], 0
	v_mfma_f32_16x16x32_bf16 v[236:239], v[86:89], v[34:37], 0
	ds_read_b64 v[82:83], v114 offset:17152
	ds_read_b64 v[84:85], v114 offset:17184
	ds_read_b64 v[86:87], v114 offset:25600
	ds_read_b64 v[88:89], v114 offset:25632
	s_waitcnt lgkmcnt(12)
	v_mfma_f32_16x16x32_bf16 v[224:227], v[90:93], v[6:9], v[224:227]
	v_mfma_f32_16x16x32_bf16 v[228:231], v[90:93], v[38:41], v[228:231]
	v_mfma_f32_16x16x32_bf16 v[232:235], v[94:97], v[6:9], v[232:235]
	v_mfma_f32_16x16x32_bf16 v[236:239], v[94:97], v[38:41], v[236:239]
	ds_read_b64 v[90:91], v114 offset:17216
	ds_read_b64 v[92:93], v114 offset:17248
	ds_read_b64 v[94:95], v114 offset:25664
	ds_read_b64 v[96:97], v114 offset:25696
	s_waitcnt lgkmcnt(12)
	v_mfma_f32_16x16x32_bf16 v[224:227], v[98:101], v[10:13], v[224:227]
	v_mfma_f32_16x16x32_bf16 v[228:231], v[98:101], v[42:45], v[228:231]
	v_mfma_f32_16x16x32_bf16 v[232:235], v[102:105], v[10:13], v[232:235]
	v_mfma_f32_16x16x32_bf16 v[236:239], v[102:105], v[42:45], v[236:239]
	v_mul_f32_e32 v66, v134, v66
	v_mul_f32_e32 v67, v134, v67
	v_mul_f32_e32 v68, v134, v68
	v_mul_f32_e32 v69, v134, v69
	v_mul_f32_e32 v74, v134, v74
	v_mul_f32_e32 v75, v134, v75
	v_mul_f32_e32 v76, v134, v76
	v_mul_f32_e32 v77, v134, v77
	v_cvt_pk_bf16_f32 v116, v66, v67
	v_cvt_pk_bf16_f32 v117, v68, v69
	v_cvt_pk_bf16_f32 v118, v74, v75
	v_cvt_pk_bf16_f32 v119, v76, v77
	global_store_dwordx4 v[132:133], v[116:119], off sc1
	v_mul_f32_e32 v70, v135, v70
	v_mul_f32_e32 v71, v135, v71
	v_mul_f32_e32 v72, v135, v72
	v_mul_f32_e32 v73, v135, v73
	v_mul_f32_e32 v78, v135, v78
	v_mul_f32_e32 v79, v135, v79
	v_mul_f32_e32 v80, v135, v80
	v_mul_f32_e32 v81, v135, v81
	v_cvt_pk_bf16_f32 v120, v70, v71
	v_cvt_pk_bf16_f32 v121, v72, v73
	v_cvt_pk_bf16_f32 v122, v78, v79
	v_cvt_pk_bf16_f32 v123, v80, v81
	global_store_dwordx4 v[246:247], v[120:123], off sc1
	ds_read_b64 v[98:99], v114 offset:17280
	ds_read_b64 v[100:101], v114 offset:17312
	ds_read_b64 v[102:103], v114 offset:25728
	ds_read_b64 v[104:105], v114 offset:25760
	s_waitcnt lgkmcnt(12)
	v_mfma_f32_16x16x32_bf16 v[224:227], v[106:109], v[14:17], v[224:227]
	v_mfma_f32_16x16x32_bf16 v[228:231], v[106:109], v[46:49], v[228:231]
	v_mfma_f32_16x16x32_bf16 v[232:235], v[110:113], v[14:17], v[232:235]
	v_mfma_f32_16x16x32_bf16 v[236:239], v[110:113], v[46:49], v[236:239]
	ds_read_b64 v[106:107], v114 offset:17344
	ds_read_b64 v[108:109], v114 offset:17376
	ds_read_b64 v[110:111], v114 offset:25792
	ds_read_b64 v[112:113], v114 offset:25824
	s_waitcnt lgkmcnt(12)
	v_mfma_f32_16x16x32_bf16 v[224:227], v[82:85], v[18:21], v[224:227]
	v_mfma_f32_16x16x32_bf16 v[228:231], v[82:85], v[50:53], v[228:231]
	v_mfma_f32_16x16x32_bf16 v[232:235], v[86:89], v[18:21], v[232:235]
	v_mfma_f32_16x16x32_bf16 v[236:239], v[86:89], v[50:53], v[236:239]
	ds_read_b64 v[82:83], v114 offset:33792
	ds_read_b64 v[84:85], v114 offset:33824
	ds_read_b64 v[86:87], v114 offset:42240
	ds_read_b64 v[88:89], v114 offset:42272
	s_waitcnt lgkmcnt(12)
	v_mfma_f32_16x16x32_bf16 v[224:227], v[90:93], v[22:25], v[224:227]
	v_mfma_f32_16x16x32_bf16 v[228:231], v[90:93], v[54:57], v[228:231]
	v_mfma_f32_16x16x32_bf16 v[232:235], v[94:97], v[22:25], v[232:235]
	v_mfma_f32_16x16x32_bf16 v[236:239], v[94:97], v[54:57], v[236:239]
	ds_read_b64 v[90:91], v114 offset:33856
	ds_read_b64 v[92:93], v114 offset:33888
	ds_read_b64 v[94:95], v114 offset:42304
	ds_read_b64 v[96:97], v114 offset:42336
	s_waitcnt lgkmcnt(12)
	v_mfma_f32_16x16x32_bf16 v[224:227], v[98:101], v[26:29], v[224:227]
	v_mfma_f32_16x16x32_bf16 v[228:231], v[98:101], v[58:61], v[228:231]
	v_mfma_f32_16x16x32_bf16 v[232:235], v[102:105], v[26:29], v[232:235]
	v_mfma_f32_16x16x32_bf16 v[236:239], v[102:105], v[58:61], v[236:239]
	ds_read_b64 v[98:99], v114 offset:33920
	ds_read_b64 v[100:101], v114 offset:33952
	ds_read_b64 v[102:103], v114 offset:42368
	ds_read_b64 v[104:105], v114 offset:42400
	s_waitcnt lgkmcnt(12)
	v_mfma_f32_16x16x32_bf16 v[224:227], v[106:109], v[30:33], v[224:227]
	v_mfma_f32_16x16x32_bf16 v[228:231], v[106:109], v[62:65], v[228:231]
	v_mfma_f32_16x16x32_bf16 v[232:235], v[110:113], v[30:33], v[232:235]
	v_mfma_f32_16x16x32_bf16 v[236:239], v[110:113], v[62:65], v[236:239]
	ds_read_b64 v[106:107], v114 offset:33984
	ds_read_b64 v[108:109], v114 offset:34016
	ds_read_b64 v[110:111], v114 offset:42432
	ds_read_b64 v[112:113], v114 offset:42464
	s_waitcnt lgkmcnt(12)
	v_mfma_f32_16x16x32_bf16 v[66:69], v[82:85], v[2:5], 0
	v_mfma_f32_16x16x32_bf16 v[70:73], v[82:85], v[34:37], 0
	v_mfma_f32_16x16x32_bf16 v[74:77], v[86:89], v[2:5], 0
	v_mfma_f32_16x16x32_bf16 v[78:81], v[86:89], v[34:37], 0
	ds_read_b64 v[82:83], v114 offset:34048
	ds_read_b64 v[84:85], v114 offset:34080
	ds_read_b64 v[86:87], v114 offset:42496
	ds_read_b64 v[88:89], v114 offset:42528
	s_waitcnt lgkmcnt(12)
	v_mfma_f32_16x16x32_bf16 v[66:69], v[90:93], v[6:9], v[66:69]
	v_mfma_f32_16x16x32_bf16 v[70:73], v[90:93], v[38:41], v[70:73]
	v_mfma_f32_16x16x32_bf16 v[74:77], v[94:97], v[6:9], v[74:77]
	v_mfma_f32_16x16x32_bf16 v[78:81], v[94:97], v[38:41], v[78:81]
	ds_read_b64 v[90:91], v114 offset:34112
	ds_read_b64 v[92:93], v114 offset:34144
	ds_read_b64 v[94:95], v114 offset:42560
	ds_read_b64 v[96:97], v114 offset:42592
	s_waitcnt lgkmcnt(12)
	v_mfma_f32_16x16x32_bf16 v[66:69], v[98:101], v[10:13], v[66:69]
	v_mfma_f32_16x16x32_bf16 v[70:73], v[98:101], v[42:45], v[70:73]
	v_mfma_f32_16x16x32_bf16 v[74:77], v[102:105], v[10:13], v[74:77]
	v_mfma_f32_16x16x32_bf16 v[78:81], v[102:105], v[42:45], v[78:81]
	v_mul_f32_e32 v224, v134, v224
	v_mul_f32_e32 v225, v134, v225
	v_mul_f32_e32 v226, v134, v226
	v_mul_f32_e32 v227, v134, v227
	v_mul_f32_e32 v232, v134, v232
	v_mul_f32_e32 v233, v134, v233
	v_mul_f32_e32 v234, v134, v234
	v_mul_f32_e32 v235, v134, v235
	v_cvt_pk_bf16_f32 v116, v224, v225
	v_cvt_pk_bf16_f32 v117, v226, v227
	v_cvt_pk_bf16_f32 v118, v232, v233
	v_cvt_pk_bf16_f32 v119, v234, v235
	global_store_dwordx4 v[132:133], v[116:119], off offset:64 sc1
	v_mul_f32_e32 v228, v135, v228
	v_mul_f32_e32 v229, v135, v229
	v_mul_f32_e32 v230, v135, v230
	v_mul_f32_e32 v231, v135, v231
	v_mul_f32_e32 v236, v135, v236
	v_mul_f32_e32 v237, v135, v237
	v_mul_f32_e32 v238, v135, v238
	v_mul_f32_e32 v239, v135, v239
	v_cvt_pk_bf16_f32 v120, v228, v229
	v_cvt_pk_bf16_f32 v121, v230, v231
	v_cvt_pk_bf16_f32 v122, v236, v237
	v_cvt_pk_bf16_f32 v123, v238, v239
	global_store_dwordx4 v[246:247], v[120:123], off offset:64 sc1
	ds_read_b64 v[98:99], v114 offset:34176
	ds_read_b64 v[100:101], v114 offset:34208
	ds_read_b64 v[102:103], v114 offset:42624
	ds_read_b64 v[104:105], v114 offset:42656
	s_waitcnt lgkmcnt(12)
	v_mfma_f32_16x16x32_bf16 v[66:69], v[106:109], v[14:17], v[66:69]
	v_mfma_f32_16x16x32_bf16 v[70:73], v[106:109], v[46:49], v[70:73]
	v_mfma_f32_16x16x32_bf16 v[74:77], v[110:113], v[14:17], v[74:77]
	v_mfma_f32_16x16x32_bf16 v[78:81], v[110:113], v[46:49], v[78:81]
	ds_read_b64 v[106:107], v114 offset:34240
	ds_read_b64 v[108:109], v114 offset:34272
	ds_read_b64 v[110:111], v114 offset:42688
	ds_read_b64 v[112:113], v114 offset:42720
	s_waitcnt lgkmcnt(12)
	v_mfma_f32_16x16x32_bf16 v[66:69], v[82:85], v[18:21], v[66:69]
	v_mfma_f32_16x16x32_bf16 v[70:73], v[82:85], v[50:53], v[70:73]
	v_mfma_f32_16x16x32_bf16 v[74:77], v[86:89], v[18:21], v[74:77]
	v_mfma_f32_16x16x32_bf16 v[78:81], v[86:89], v[50:53], v[78:81]
	ds_read_b64 v[82:83], v114 offset:50688
	ds_read_b64 v[84:85], v114 offset:50720
	ds_read_b64 v[86:87], v114 offset:59136
	ds_read_b64 v[88:89], v114 offset:59168
	s_waitcnt lgkmcnt(12)
	v_mfma_f32_16x16x32_bf16 v[66:69], v[90:93], v[22:25], v[66:69]
	v_mfma_f32_16x16x32_bf16 v[70:73], v[90:93], v[54:57], v[70:73]
	v_mfma_f32_16x16x32_bf16 v[74:77], v[94:97], v[22:25], v[74:77]
	v_mfma_f32_16x16x32_bf16 v[78:81], v[94:97], v[54:57], v[78:81]
	ds_read_b64 v[90:91], v114 offset:50752
	ds_read_b64 v[92:93], v114 offset:50784
	ds_read_b64 v[94:95], v114 offset:59200
	ds_read_b64 v[96:97], v114 offset:59232
	s_waitcnt lgkmcnt(12)
	v_mfma_f32_16x16x32_bf16 v[66:69], v[98:101], v[26:29], v[66:69]
	v_mfma_f32_16x16x32_bf16 v[70:73], v[98:101], v[58:61], v[70:73]
	v_mfma_f32_16x16x32_bf16 v[74:77], v[102:105], v[26:29], v[74:77]
	v_mfma_f32_16x16x32_bf16 v[78:81], v[102:105], v[58:61], v[78:81]
	ds_read_b64 v[98:99], v114 offset:50816
	ds_read_b64 v[100:101], v114 offset:50848
	ds_read_b64 v[102:103], v114 offset:59264
	ds_read_b64 v[104:105], v114 offset:59296
	s_waitcnt lgkmcnt(12)
	v_mfma_f32_16x16x32_bf16 v[66:69], v[106:109], v[30:33], v[66:69]
	v_mfma_f32_16x16x32_bf16 v[70:73], v[106:109], v[62:65], v[70:73]
	v_mfma_f32_16x16x32_bf16 v[74:77], v[110:113], v[30:33], v[74:77]
	v_mfma_f32_16x16x32_bf16 v[78:81], v[110:113], v[62:65], v[78:81]
	ds_read_b64 v[106:107], v114 offset:50880
	ds_read_b64 v[108:109], v114 offset:50912
	ds_read_b64 v[110:111], v114 offset:59328
	ds_read_b64 v[112:113], v114 offset:59360
	s_waitcnt lgkmcnt(12)
	v_mfma_f32_16x16x32_bf16 v[224:227], v[82:85], v[2:5], 0
	v_mfma_f32_16x16x32_bf16 v[228:231], v[82:85], v[34:37], 0
	v_mfma_f32_16x16x32_bf16 v[232:235], v[86:89], v[2:5], 0
	v_mfma_f32_16x16x32_bf16 v[236:239], v[86:89], v[34:37], 0
	ds_read_b64 v[82:83], v114 offset:50944
	ds_read_b64 v[84:85], v114 offset:50976
	ds_read_b64 v[86:87], v114 offset:59392
	ds_read_b64 v[88:89], v114 offset:59424
	s_waitcnt lgkmcnt(12)
	v_mfma_f32_16x16x32_bf16 v[224:227], v[90:93], v[6:9], v[224:227]
	v_mfma_f32_16x16x32_bf16 v[228:231], v[90:93], v[38:41], v[228:231]
	v_mfma_f32_16x16x32_bf16 v[232:235], v[94:97], v[6:9], v[232:235]
	v_mfma_f32_16x16x32_bf16 v[236:239], v[94:97], v[38:41], v[236:239]
	ds_read_b64 v[90:91], v114 offset:51008
	ds_read_b64 v[92:93], v114 offset:51040
	ds_read_b64 v[94:95], v114 offset:59456
	ds_read_b64 v[96:97], v114 offset:59488
	s_waitcnt lgkmcnt(12)
	v_mfma_f32_16x16x32_bf16 v[224:227], v[98:101], v[10:13], v[224:227]
	v_mfma_f32_16x16x32_bf16 v[228:231], v[98:101], v[42:45], v[228:231]
	v_mfma_f32_16x16x32_bf16 v[232:235], v[102:105], v[10:13], v[232:235]
	v_mfma_f32_16x16x32_bf16 v[236:239], v[102:105], v[42:45], v[236:239]
	v_mul_f32_e32 v66, v134, v66
	v_mul_f32_e32 v67, v134, v67
	v_mul_f32_e32 v68, v134, v68
	v_mul_f32_e32 v69, v134, v69
	v_mul_f32_e32 v74, v134, v74
	v_mul_f32_e32 v75, v134, v75
	v_mul_f32_e32 v76, v134, v76
	v_mul_f32_e32 v77, v134, v77
	v_cvt_pk_bf16_f32 v116, v66, v67
	v_cvt_pk_bf16_f32 v117, v68, v69
	v_cvt_pk_bf16_f32 v118, v74, v75
	v_cvt_pk_bf16_f32 v119, v76, v77
	global_store_dwordx4 v[132:133], v[116:119], off offset:128 sc1
	v_mul_f32_e32 v70, v135, v70
	v_mul_f32_e32 v71, v135, v71
	v_mul_f32_e32 v72, v135, v72
	v_mul_f32_e32 v73, v135, v73
	v_mul_f32_e32 v78, v135, v78
	v_mul_f32_e32 v79, v135, v79
	v_mul_f32_e32 v80, v135, v80
	v_mul_f32_e32 v81, v135, v81
	v_cvt_pk_bf16_f32 v120, v70, v71
	v_cvt_pk_bf16_f32 v121, v72, v73
	v_cvt_pk_bf16_f32 v122, v78, v79
	v_cvt_pk_bf16_f32 v123, v80, v81
	global_store_dwordx4 v[246:247], v[120:123], off offset:128 sc1
	ds_read_b64 v[98:99], v114 offset:51072
	ds_read_b64 v[100:101], v114 offset:51104
	ds_read_b64 v[102:103], v114 offset:59520
	ds_read_b64 v[104:105], v114 offset:59552
	s_waitcnt lgkmcnt(12)
	v_mfma_f32_16x16x32_bf16 v[224:227], v[106:109], v[14:17], v[224:227]
	v_mfma_f32_16x16x32_bf16 v[228:231], v[106:109], v[46:49], v[228:231]
	v_mfma_f32_16x16x32_bf16 v[232:235], v[110:113], v[14:17], v[232:235]
	v_mfma_f32_16x16x32_bf16 v[236:239], v[110:113], v[46:49], v[236:239]
	ds_read_b64 v[106:107], v114 offset:51136
	ds_read_b64 v[108:109], v114 offset:51168
	ds_read_b64 v[110:111], v114 offset:59584
	ds_read_b64 v[112:113], v114 offset:59616
	s_waitcnt lgkmcnt(12)
	v_mfma_f32_16x16x32_bf16 v[224:227], v[82:85], v[18:21], v[224:227]
	v_mfma_f32_16x16x32_bf16 v[228:231], v[82:85], v[50:53], v[228:231]
	v_mfma_f32_16x16x32_bf16 v[232:235], v[86:89], v[18:21], v[232:235]
	v_mfma_f32_16x16x32_bf16 v[236:239], v[86:89], v[50:53], v[236:239]
	ds_read_b64 v[82:83], v115
	ds_read_b64 v[84:85], v115 offset:32
	ds_read_b64 v[86:87], v115 offset:8448
	ds_read_b64 v[88:89], v115 offset:8480
	s_waitcnt lgkmcnt(12)
	v_mfma_f32_16x16x32_bf16 v[224:227], v[90:93], v[22:25], v[224:227]
	v_mfma_f32_16x16x32_bf16 v[228:231], v[90:93], v[54:57], v[228:231]
	v_mfma_f32_16x16x32_bf16 v[232:235], v[94:97], v[22:25], v[232:235]
	v_mfma_f32_16x16x32_bf16 v[236:239], v[94:97], v[54:57], v[236:239]
	ds_read_b64 v[90:91], v115 offset:64
	ds_read_b64 v[92:93], v115 offset:96
	ds_read_b64 v[94:95], v115 offset:8512
	ds_read_b64 v[96:97], v115 offset:8544
	s_waitcnt lgkmcnt(12)
	v_mfma_f32_16x16x32_bf16 v[224:227], v[98:101], v[26:29], v[224:227]
	v_mfma_f32_16x16x32_bf16 v[228:231], v[98:101], v[58:61], v[228:231]
	v_mfma_f32_16x16x32_bf16 v[232:235], v[102:105], v[26:29], v[232:235]
	v_mfma_f32_16x16x32_bf16 v[236:239], v[102:105], v[58:61], v[236:239]
	ds_read_b64 v[98:99], v115 offset:128
	ds_read_b64 v[100:101], v115 offset:160
	ds_read_b64 v[102:103], v115 offset:8576
	ds_read_b64 v[104:105], v115 offset:8608
	s_waitcnt lgkmcnt(12)
	v_mfma_f32_16x16x32_bf16 v[224:227], v[106:109], v[30:33], v[224:227]
	v_mfma_f32_16x16x32_bf16 v[228:231], v[106:109], v[62:65], v[228:231]
	v_mfma_f32_16x16x32_bf16 v[232:235], v[110:113], v[30:33], v[232:235]
	v_mfma_f32_16x16x32_bf16 v[236:239], v[110:113], v[62:65], v[236:239]
	ds_read_b64 v[106:107], v115 offset:192
	ds_read_b64 v[108:109], v115 offset:224
	ds_read_b64 v[110:111], v115 offset:8640
	ds_read_b64 v[112:113], v115 offset:8672
	s_waitcnt lgkmcnt(12)
	v_mfma_f32_16x16x32_bf16 v[66:69], v[82:85], v[2:5], 0
	v_mfma_f32_16x16x32_bf16 v[70:73], v[82:85], v[34:37], 0
	v_mfma_f32_16x16x32_bf16 v[74:77], v[86:89], v[2:5], 0
	v_mfma_f32_16x16x32_bf16 v[78:81], v[86:89], v[34:37], 0
	ds_read_b64 v[82:83], v115 offset:256
	ds_read_b64 v[84:85], v115 offset:288
	ds_read_b64 v[86:87], v115 offset:8704
	ds_read_b64 v[88:89], v115 offset:8736
	s_waitcnt lgkmcnt(12)
	v_mfma_f32_16x16x32_bf16 v[66:69], v[90:93], v[6:9], v[66:69]
	v_mfma_f32_16x16x32_bf16 v[70:73], v[90:93], v[38:41], v[70:73]
	v_mfma_f32_16x16x32_bf16 v[74:77], v[94:97], v[6:9], v[74:77]
	v_mfma_f32_16x16x32_bf16 v[78:81], v[94:97], v[38:41], v[78:81]
	ds_read_b64 v[90:91], v115 offset:320
	ds_read_b64 v[92:93], v115 offset:352
	ds_read_b64 v[94:95], v115 offset:8768
	ds_read_b64 v[96:97], v115 offset:8800
	s_waitcnt lgkmcnt(12)
	v_mfma_f32_16x16x32_bf16 v[66:69], v[98:101], v[10:13], v[66:69]
	v_mfma_f32_16x16x32_bf16 v[70:73], v[98:101], v[42:45], v[70:73]
	v_mfma_f32_16x16x32_bf16 v[74:77], v[102:105], v[10:13], v[74:77]
	v_mfma_f32_16x16x32_bf16 v[78:81], v[102:105], v[42:45], v[78:81]
	v_mul_f32_e32 v224, v134, v224
	v_mul_f32_e32 v225, v134, v225
	v_mul_f32_e32 v226, v134, v226
	v_mul_f32_e32 v227, v134, v227
	v_mul_f32_e32 v232, v134, v232
	v_mul_f32_e32 v233, v134, v233
	v_mul_f32_e32 v234, v134, v234
	v_mul_f32_e32 v235, v134, v235
	v_cvt_pk_bf16_f32 v116, v224, v225
	v_cvt_pk_bf16_f32 v117, v226, v227
	v_cvt_pk_bf16_f32 v118, v232, v233
	v_cvt_pk_bf16_f32 v119, v234, v235
	global_store_dwordx4 v[132:133], v[116:119], off offset:192 sc1
	v_mul_f32_e32 v228, v135, v228
	v_mul_f32_e32 v229, v135, v229
	v_mul_f32_e32 v230, v135, v230
	v_mul_f32_e32 v231, v135, v231
	v_mul_f32_e32 v236, v135, v236
	v_mul_f32_e32 v237, v135, v237
	v_mul_f32_e32 v238, v135, v238
	v_mul_f32_e32 v239, v135, v239
	v_cvt_pk_bf16_f32 v120, v228, v229
	v_cvt_pk_bf16_f32 v121, v230, v231
	v_cvt_pk_bf16_f32 v122, v236, v237
	v_cvt_pk_bf16_f32 v123, v238, v239
	global_store_dwordx4 v[246:247], v[120:123], off offset:192 sc1
	ds_read_b64 v[98:99], v115 offset:384
	ds_read_b64 v[100:101], v115 offset:416
	ds_read_b64 v[102:103], v115 offset:8832
	ds_read_b64 v[104:105], v115 offset:8864
	s_waitcnt lgkmcnt(12)
	v_mfma_f32_16x16x32_bf16 v[66:69], v[106:109], v[14:17], v[66:69]
	v_mfma_f32_16x16x32_bf16 v[70:73], v[106:109], v[46:49], v[70:73]
	v_mfma_f32_16x16x32_bf16 v[74:77], v[110:113], v[14:17], v[74:77]
	v_mfma_f32_16x16x32_bf16 v[78:81], v[110:113], v[46:49], v[78:81]
	ds_read_b64 v[106:107], v115 offset:448
	ds_read_b64 v[108:109], v115 offset:480
	ds_read_b64 v[110:111], v115 offset:8896
	ds_read_b64 v[112:113], v115 offset:8928
	s_waitcnt lgkmcnt(12)
	v_mfma_f32_16x16x32_bf16 v[66:69], v[82:85], v[18:21], v[66:69]
	v_mfma_f32_16x16x32_bf16 v[70:73], v[82:85], v[50:53], v[70:73]
	v_mfma_f32_16x16x32_bf16 v[74:77], v[86:89], v[18:21], v[74:77]
	v_mfma_f32_16x16x32_bf16 v[78:81], v[86:89], v[50:53], v[78:81]
	ds_read_b64 v[82:83], v115 offset:16896
	ds_read_b64 v[84:85], v115 offset:16928
	ds_read_b64 v[86:87], v115 offset:25344
	ds_read_b64 v[88:89], v115 offset:25376
	s_waitcnt lgkmcnt(12)
	v_mfma_f32_16x16x32_bf16 v[66:69], v[90:93], v[22:25], v[66:69]
	v_mfma_f32_16x16x32_bf16 v[70:73], v[90:93], v[54:57], v[70:73]
	v_mfma_f32_16x16x32_bf16 v[74:77], v[94:97], v[22:25], v[74:77]
	v_mfma_f32_16x16x32_bf16 v[78:81], v[94:97], v[54:57], v[78:81]
	ds_read_b64 v[90:91], v115 offset:16960
	ds_read_b64 v[92:93], v115 offset:16992
	ds_read_b64 v[94:95], v115 offset:25408
	ds_read_b64 v[96:97], v115 offset:25440
	s_waitcnt lgkmcnt(12)
	v_mfma_f32_16x16x32_bf16 v[66:69], v[98:101], v[26:29], v[66:69]
	v_mfma_f32_16x16x32_bf16 v[70:73], v[98:101], v[58:61], v[70:73]
	v_mfma_f32_16x16x32_bf16 v[74:77], v[102:105], v[26:29], v[74:77]
	v_mfma_f32_16x16x32_bf16 v[78:81], v[102:105], v[58:61], v[78:81]
	ds_read_b64 v[98:99], v115 offset:17024
	ds_read_b64 v[100:101], v115 offset:17056
	ds_read_b64 v[102:103], v115 offset:25472
	ds_read_b64 v[104:105], v115 offset:25504
	s_waitcnt lgkmcnt(12)
	v_mfma_f32_16x16x32_bf16 v[66:69], v[106:109], v[30:33], v[66:69]
	v_mfma_f32_16x16x32_bf16 v[70:73], v[106:109], v[62:65], v[70:73]
	v_mfma_f32_16x16x32_bf16 v[74:77], v[110:113], v[30:33], v[74:77]
	v_mfma_f32_16x16x32_bf16 v[78:81], v[110:113], v[62:65], v[78:81]
	ds_read_b64 v[106:107], v115 offset:17088
	ds_read_b64 v[108:109], v115 offset:17120
	ds_read_b64 v[110:111], v115 offset:25536
	ds_read_b64 v[112:113], v115 offset:25568
	s_waitcnt lgkmcnt(12)
	v_mfma_f32_16x16x32_bf16 v[224:227], v[82:85], v[2:5], 0
	v_mfma_f32_16x16x32_bf16 v[228:231], v[82:85], v[34:37], 0
	v_mfma_f32_16x16x32_bf16 v[232:235], v[86:89], v[2:5], 0
	v_mfma_f32_16x16x32_bf16 v[236:239], v[86:89], v[34:37], 0
	ds_read_b64 v[82:83], v115 offset:17152
	ds_read_b64 v[84:85], v115 offset:17184
	ds_read_b64 v[86:87], v115 offset:25600
	ds_read_b64 v[88:89], v115 offset:25632
	s_waitcnt lgkmcnt(12)
	v_mfma_f32_16x16x32_bf16 v[224:227], v[90:93], v[6:9], v[224:227]
	v_mfma_f32_16x16x32_bf16 v[228:231], v[90:93], v[38:41], v[228:231]
	v_mfma_f32_16x16x32_bf16 v[232:235], v[94:97], v[6:9], v[232:235]
	v_mfma_f32_16x16x32_bf16 v[236:239], v[94:97], v[38:41], v[236:239]
	ds_read_b64 v[90:91], v115 offset:17216
	ds_read_b64 v[92:93], v115 offset:17248
	ds_read_b64 v[94:95], v115 offset:25664
	ds_read_b64 v[96:97], v115 offset:25696
	s_waitcnt lgkmcnt(12)
	v_mfma_f32_16x16x32_bf16 v[224:227], v[98:101], v[10:13], v[224:227]
	v_mfma_f32_16x16x32_bf16 v[228:231], v[98:101], v[42:45], v[228:231]
	v_mfma_f32_16x16x32_bf16 v[232:235], v[102:105], v[10:13], v[232:235]
	v_mfma_f32_16x16x32_bf16 v[236:239], v[102:105], v[42:45], v[236:239]
	v_mul_f32_e32 v66, v134, v66
	v_mul_f32_e32 v67, v134, v67
	v_mul_f32_e32 v68, v134, v68
	v_mul_f32_e32 v69, v134, v69
	v_mul_f32_e32 v74, v134, v74
	v_mul_f32_e32 v75, v134, v75
	v_mul_f32_e32 v76, v134, v76
	v_mul_f32_e32 v77, v134, v77
	v_cvt_pk_bf16_f32 v116, v66, v67
	v_cvt_pk_bf16_f32 v117, v68, v69
	v_cvt_pk_bf16_f32 v118, v74, v75
	v_cvt_pk_bf16_f32 v119, v76, v77
	global_store_dwordx4 v[132:133], v[116:119], off offset:256 sc1
	v_mul_f32_e32 v70, v135, v70
	v_mul_f32_e32 v71, v135, v71
	v_mul_f32_e32 v72, v135, v72
	v_mul_f32_e32 v73, v135, v73
	v_mul_f32_e32 v78, v135, v78
	v_mul_f32_e32 v79, v135, v79
	v_mul_f32_e32 v80, v135, v80
	v_mul_f32_e32 v81, v135, v81
	v_cvt_pk_bf16_f32 v120, v70, v71
	v_cvt_pk_bf16_f32 v121, v72, v73
	v_cvt_pk_bf16_f32 v122, v78, v79
	v_cvt_pk_bf16_f32 v123, v80, v81
	global_store_dwordx4 v[246:247], v[120:123], off offset:256 sc1
	ds_read_b64 v[98:99], v115 offset:17280
	ds_read_b64 v[100:101], v115 offset:17312
	ds_read_b64 v[102:103], v115 offset:25728
	ds_read_b64 v[104:105], v115 offset:25760
	s_waitcnt lgkmcnt(12)
	v_mfma_f32_16x16x32_bf16 v[224:227], v[106:109], v[14:17], v[224:227]
	v_mfma_f32_16x16x32_bf16 v[228:231], v[106:109], v[46:49], v[228:231]
	v_mfma_f32_16x16x32_bf16 v[232:235], v[110:113], v[14:17], v[232:235]
	v_mfma_f32_16x16x32_bf16 v[236:239], v[110:113], v[46:49], v[236:239]
	ds_read_b64 v[106:107], v115 offset:17344
	ds_read_b64 v[108:109], v115 offset:17376
	ds_read_b64 v[110:111], v115 offset:25792
	ds_read_b64 v[112:113], v115 offset:25824
	s_waitcnt lgkmcnt(12)
	v_mfma_f32_16x16x32_bf16 v[224:227], v[82:85], v[18:21], v[224:227]
	v_mfma_f32_16x16x32_bf16 v[228:231], v[82:85], v[50:53], v[228:231]
	v_mfma_f32_16x16x32_bf16 v[232:235], v[86:89], v[18:21], v[232:235]
	v_mfma_f32_16x16x32_bf16 v[236:239], v[86:89], v[50:53], v[236:239]
	ds_read_b64 v[82:83], v115 offset:33792
	ds_read_b64 v[84:85], v115 offset:33824
	ds_read_b64 v[86:87], v115 offset:42240
	ds_read_b64 v[88:89], v115 offset:42272
	s_waitcnt lgkmcnt(12)
	v_mfma_f32_16x16x32_bf16 v[224:227], v[90:93], v[22:25], v[224:227]
	v_mfma_f32_16x16x32_bf16 v[228:231], v[90:93], v[54:57], v[228:231]
	v_mfma_f32_16x16x32_bf16 v[232:235], v[94:97], v[22:25], v[232:235]
	v_mfma_f32_16x16x32_bf16 v[236:239], v[94:97], v[54:57], v[236:239]
	ds_read_b64 v[90:91], v115 offset:33856
	ds_read_b64 v[92:93], v115 offset:33888
	ds_read_b64 v[94:95], v115 offset:42304
	ds_read_b64 v[96:97], v115 offset:42336
	s_waitcnt lgkmcnt(12)
	v_mfma_f32_16x16x32_bf16 v[224:227], v[98:101], v[26:29], v[224:227]
	v_mfma_f32_16x16x32_bf16 v[228:231], v[98:101], v[58:61], v[228:231]
	v_mfma_f32_16x16x32_bf16 v[232:235], v[102:105], v[26:29], v[232:235]
	v_mfma_f32_16x16x32_bf16 v[236:239], v[102:105], v[58:61], v[236:239]
	ds_read_b64 v[98:99], v115 offset:33920
	ds_read_b64 v[100:101], v115 offset:33952
	ds_read_b64 v[102:103], v115 offset:42368
	ds_read_b64 v[104:105], v115 offset:42400
	s_waitcnt lgkmcnt(12)
	v_mfma_f32_16x16x32_bf16 v[224:227], v[106:109], v[30:33], v[224:227]
	v_mfma_f32_16x16x32_bf16 v[228:231], v[106:109], v[62:65], v[228:231]
	v_mfma_f32_16x16x32_bf16 v[232:235], v[110:113], v[30:33], v[232:235]
	v_mfma_f32_16x16x32_bf16 v[236:239], v[110:113], v[62:65], v[236:239]
	ds_read_b64 v[106:107], v115 offset:33984
	ds_read_b64 v[108:109], v115 offset:34016
	ds_read_b64 v[110:111], v115 offset:42432
	ds_read_b64 v[112:113], v115 offset:42464
	s_waitcnt lgkmcnt(12)
	v_mfma_f32_16x16x32_bf16 v[66:69], v[82:85], v[2:5], 0
	v_mfma_f32_16x16x32_bf16 v[70:73], v[82:85], v[34:37], 0
	v_mfma_f32_16x16x32_bf16 v[74:77], v[86:89], v[2:5], 0
	v_mfma_f32_16x16x32_bf16 v[78:81], v[86:89], v[34:37], 0
	ds_read_b64 v[82:83], v115 offset:34048
	ds_read_b64 v[84:85], v115 offset:34080
	ds_read_b64 v[86:87], v115 offset:42496
	ds_read_b64 v[88:89], v115 offset:42528
	s_waitcnt lgkmcnt(12)
	v_mfma_f32_16x16x32_bf16 v[66:69], v[90:93], v[6:9], v[66:69]
	v_mfma_f32_16x16x32_bf16 v[70:73], v[90:93], v[38:41], v[70:73]
	v_mfma_f32_16x16x32_bf16 v[74:77], v[94:97], v[6:9], v[74:77]
	v_mfma_f32_16x16x32_bf16 v[78:81], v[94:97], v[38:41], v[78:81]
	ds_read_b64 v[90:91], v115 offset:34112
	ds_read_b64 v[92:93], v115 offset:34144
	ds_read_b64 v[94:95], v115 offset:42560
	ds_read_b64 v[96:97], v115 offset:42592
	s_waitcnt lgkmcnt(12)
	v_mfma_f32_16x16x32_bf16 v[66:69], v[98:101], v[10:13], v[66:69]
	v_mfma_f32_16x16x32_bf16 v[70:73], v[98:101], v[42:45], v[70:73]
	v_mfma_f32_16x16x32_bf16 v[74:77], v[102:105], v[10:13], v[74:77]
	v_mfma_f32_16x16x32_bf16 v[78:81], v[102:105], v[42:45], v[78:81]
	v_mul_f32_e32 v224, v134, v224
	v_mul_f32_e32 v225, v134, v225
	v_mul_f32_e32 v226, v134, v226
	v_mul_f32_e32 v227, v134, v227
	v_mul_f32_e32 v232, v134, v232
	v_mul_f32_e32 v233, v134, v233
	v_mul_f32_e32 v234, v134, v234
	v_mul_f32_e32 v235, v134, v235
	v_cvt_pk_bf16_f32 v116, v224, v225
	v_cvt_pk_bf16_f32 v117, v226, v227
	v_cvt_pk_bf16_f32 v118, v232, v233
	v_cvt_pk_bf16_f32 v119, v234, v235
	global_store_dwordx4 v[132:133], v[116:119], off offset:320 sc1
	v_mul_f32_e32 v228, v135, v228
	v_mul_f32_e32 v229, v135, v229
	v_mul_f32_e32 v230, v135, v230
	v_mul_f32_e32 v231, v135, v231
	v_mul_f32_e32 v236, v135, v236
	v_mul_f32_e32 v237, v135, v237
	v_mul_f32_e32 v238, v135, v238
	v_mul_f32_e32 v239, v135, v239
	v_cvt_pk_bf16_f32 v120, v228, v229
	v_cvt_pk_bf16_f32 v121, v230, v231
	v_cvt_pk_bf16_f32 v122, v236, v237
	v_cvt_pk_bf16_f32 v123, v238, v239
	global_store_dwordx4 v[246:247], v[120:123], off offset:320 sc1
	ds_read_b64 v[98:99], v115 offset:34176
	ds_read_b64 v[100:101], v115 offset:34208
	ds_read_b64 v[102:103], v115 offset:42624
	ds_read_b64 v[104:105], v115 offset:42656
	s_waitcnt lgkmcnt(12)
	v_mfma_f32_16x16x32_bf16 v[66:69], v[106:109], v[14:17], v[66:69]
	v_mfma_f32_16x16x32_bf16 v[70:73], v[106:109], v[46:49], v[70:73]
	v_mfma_f32_16x16x32_bf16 v[74:77], v[110:113], v[14:17], v[74:77]
	v_mfma_f32_16x16x32_bf16 v[78:81], v[110:113], v[46:49], v[78:81]
	ds_read_b64 v[106:107], v115 offset:34240
	ds_read_b64 v[108:109], v115 offset:34272
	ds_read_b64 v[110:111], v115 offset:42688
	ds_read_b64 v[112:113], v115 offset:42720
	s_waitcnt lgkmcnt(12)
	v_mfma_f32_16x16x32_bf16 v[66:69], v[82:85], v[18:21], v[66:69]
	v_mfma_f32_16x16x32_bf16 v[70:73], v[82:85], v[50:53], v[70:73]
	v_mfma_f32_16x16x32_bf16 v[74:77], v[86:89], v[18:21], v[74:77]
	v_mfma_f32_16x16x32_bf16 v[78:81], v[86:89], v[50:53], v[78:81]
	ds_read_b64 v[82:83], v115 offset:50688
	ds_read_b64 v[84:85], v115 offset:50720
	ds_read_b64 v[86:87], v115 offset:59136
	ds_read_b64 v[88:89], v115 offset:59168
	s_waitcnt lgkmcnt(12)
	v_mfma_f32_16x16x32_bf16 v[66:69], v[90:93], v[22:25], v[66:69]
	v_mfma_f32_16x16x32_bf16 v[70:73], v[90:93], v[54:57], v[70:73]
	v_mfma_f32_16x16x32_bf16 v[74:77], v[94:97], v[22:25], v[74:77]
	v_mfma_f32_16x16x32_bf16 v[78:81], v[94:97], v[54:57], v[78:81]
	ds_read_b64 v[90:91], v115 offset:50752
	ds_read_b64 v[92:93], v115 offset:50784
	ds_read_b64 v[94:95], v115 offset:59200
	ds_read_b64 v[96:97], v115 offset:59232
	s_waitcnt lgkmcnt(12)
	v_mfma_f32_16x16x32_bf16 v[66:69], v[98:101], v[26:29], v[66:69]
	v_mfma_f32_16x16x32_bf16 v[70:73], v[98:101], v[58:61], v[70:73]
	v_mfma_f32_16x16x32_bf16 v[74:77], v[102:105], v[26:29], v[74:77]
	v_mfma_f32_16x16x32_bf16 v[78:81], v[102:105], v[58:61], v[78:81]
	ds_read_b64 v[98:99], v115 offset:50816
	ds_read_b64 v[100:101], v115 offset:50848
	ds_read_b64 v[102:103], v115 offset:59264
	ds_read_b64 v[104:105], v115 offset:59296
	s_waitcnt lgkmcnt(12)
	v_mfma_f32_16x16x32_bf16 v[66:69], v[106:109], v[30:33], v[66:69]
	v_mfma_f32_16x16x32_bf16 v[70:73], v[106:109], v[62:65], v[70:73]
	v_mfma_f32_16x16x32_bf16 v[74:77], v[110:113], v[30:33], v[74:77]
	v_mfma_f32_16x16x32_bf16 v[78:81], v[110:113], v[62:65], v[78:81]
	ds_read_b64 v[106:107], v115 offset:50880
	ds_read_b64 v[108:109], v115 offset:50912
	ds_read_b64 v[110:111], v115 offset:59328
	ds_read_b64 v[112:113], v115 offset:59360
	s_waitcnt lgkmcnt(12)
	v_mfma_f32_16x16x32_bf16 v[224:227], v[82:85], v[2:5], 0
	v_mfma_f32_16x16x32_bf16 v[228:231], v[82:85], v[34:37], 0
	v_mfma_f32_16x16x32_bf16 v[232:235], v[86:89], v[2:5], 0
	v_mfma_f32_16x16x32_bf16 v[236:239], v[86:89], v[34:37], 0
	ds_read_b64 v[82:83], v115 offset:50944
	ds_read_b64 v[84:85], v115 offset:50976
	ds_read_b64 v[86:87], v115 offset:59392
	ds_read_b64 v[88:89], v115 offset:59424
	s_waitcnt lgkmcnt(12)
	v_mfma_f32_16x16x32_bf16 v[224:227], v[90:93], v[6:9], v[224:227]
	v_mfma_f32_16x16x32_bf16 v[228:231], v[90:93], v[38:41], v[228:231]
	v_mfma_f32_16x16x32_bf16 v[232:235], v[94:97], v[6:9], v[232:235]
	v_mfma_f32_16x16x32_bf16 v[236:239], v[94:97], v[38:41], v[236:239]
	ds_read_b64 v[90:91], v115 offset:51008
	ds_read_b64 v[92:93], v115 offset:51040
	ds_read_b64 v[94:95], v115 offset:59456
	ds_read_b64 v[96:97], v115 offset:59488
	s_waitcnt lgkmcnt(12)
	v_mfma_f32_16x16x32_bf16 v[224:227], v[98:101], v[10:13], v[224:227]
	v_mfma_f32_16x16x32_bf16 v[228:231], v[98:101], v[42:45], v[228:231]
	v_mfma_f32_16x16x32_bf16 v[232:235], v[102:105], v[10:13], v[232:235]
	v_mfma_f32_16x16x32_bf16 v[236:239], v[102:105], v[42:45], v[236:239]
	v_mul_f32_e32 v66, v134, v66
	v_mul_f32_e32 v67, v134, v67
	v_mul_f32_e32 v68, v134, v68
	v_mul_f32_e32 v69, v134, v69
	v_mul_f32_e32 v74, v134, v74
	v_mul_f32_e32 v75, v134, v75
	v_mul_f32_e32 v76, v134, v76
	v_mul_f32_e32 v77, v134, v77
	v_cvt_pk_bf16_f32 v116, v66, v67
	v_cvt_pk_bf16_f32 v117, v68, v69
	v_cvt_pk_bf16_f32 v118, v74, v75
	v_cvt_pk_bf16_f32 v119, v76, v77
	global_store_dwordx4 v[132:133], v[116:119], off offset:384 sc1
	v_mul_f32_e32 v70, v135, v70
	v_mul_f32_e32 v71, v135, v71
	v_mul_f32_e32 v72, v135, v72
	v_mul_f32_e32 v73, v135, v73
	v_mul_f32_e32 v78, v135, v78
	v_mul_f32_e32 v79, v135, v79
	v_mul_f32_e32 v80, v135, v80
	v_mul_f32_e32 v81, v135, v81
	v_cvt_pk_bf16_f32 v120, v70, v71
	v_cvt_pk_bf16_f32 v121, v72, v73
	v_cvt_pk_bf16_f32 v122, v78, v79
	v_cvt_pk_bf16_f32 v123, v80, v81
	global_store_dwordx4 v[246:247], v[120:123], off offset:384 sc1
	ds_read_b64 v[98:99], v115 offset:51072
	ds_read_b64 v[100:101], v115 offset:51104
	ds_read_b64 v[102:103], v115 offset:59520
	ds_read_b64 v[104:105], v115 offset:59552
	s_waitcnt lgkmcnt(12)
	v_mfma_f32_16x16x32_bf16 v[224:227], v[106:109], v[14:17], v[224:227]
	v_mfma_f32_16x16x32_bf16 v[228:231], v[106:109], v[46:49], v[228:231]
	v_mfma_f32_16x16x32_bf16 v[232:235], v[110:113], v[14:17], v[232:235]
	v_mfma_f32_16x16x32_bf16 v[236:239], v[110:113], v[46:49], v[236:239]
	ds_read_b64 v[106:107], v115 offset:51136
	ds_read_b64 v[108:109], v115 offset:51168
	ds_read_b64 v[110:111], v115 offset:59584
	ds_read_b64 v[112:113], v115 offset:59616
	s_waitcnt lgkmcnt(12)
	v_mfma_f32_16x16x32_bf16 v[224:227], v[82:85], v[18:21], v[224:227]
	v_mfma_f32_16x16x32_bf16 v[228:231], v[82:85], v[50:53], v[228:231]
	v_mfma_f32_16x16x32_bf16 v[232:235], v[86:89], v[18:21], v[232:235]
	v_mfma_f32_16x16x32_bf16 v[236:239], v[86:89], v[50:53], v[236:239]
	s_waitcnt lgkmcnt(8)
	v_mfma_f32_16x16x32_bf16 v[224:227], v[90:93], v[22:25], v[224:227]
	v_mfma_f32_16x16x32_bf16 v[228:231], v[90:93], v[54:57], v[228:231]
	v_mfma_f32_16x16x32_bf16 v[232:235], v[94:97], v[22:25], v[232:235]
	v_mfma_f32_16x16x32_bf16 v[236:239], v[94:97], v[54:57], v[236:239]
	s_waitcnt lgkmcnt(4)
	v_mfma_f32_16x16x32_bf16 v[224:227], v[98:101], v[26:29], v[224:227]
	v_mfma_f32_16x16x32_bf16 v[228:231], v[98:101], v[58:61], v[228:231]
	v_mfma_f32_16x16x32_bf16 v[232:235], v[102:105], v[26:29], v[232:235]
	v_mfma_f32_16x16x32_bf16 v[236:239], v[102:105], v[58:61], v[236:239]
	s_waitcnt lgkmcnt(0)
	v_mfma_f32_16x16x32_bf16 v[224:227], v[106:109], v[30:33], v[224:227]
	v_mfma_f32_16x16x32_bf16 v[228:231], v[106:109], v[62:65], v[228:231]
	v_mfma_f32_16x16x32_bf16 v[232:235], v[110:113], v[30:33], v[232:235]
	v_mfma_f32_16x16x32_bf16 v[236:239], v[110:113], v[62:65], v[236:239]
	s_nop 7
	s_nop 1
	v_mul_f32_e32 v224, v134, v224
	v_mul_f32_e32 v225, v134, v225
	v_mul_f32_e32 v226, v134, v226
	v_mul_f32_e32 v227, v134, v227
	v_mul_f32_e32 v232, v134, v232
	v_mul_f32_e32 v233, v134, v233
	v_mul_f32_e32 v234, v134, v234
	v_mul_f32_e32 v235, v134, v235
	v_cvt_pk_bf16_f32 v116, v224, v225
	v_cvt_pk_bf16_f32 v117, v226, v227
	v_cvt_pk_bf16_f32 v118, v232, v233
	v_cvt_pk_bf16_f32 v119, v234, v235
	global_store_dwordx4 v[132:133], v[116:119], off offset:448 sc1
	v_mul_f32_e32 v228, v135, v228
	v_mul_f32_e32 v229, v135, v229
	v_mul_f32_e32 v230, v135, v230
	v_mul_f32_e32 v231, v135, v231
	v_mul_f32_e32 v236, v135, v236
	v_mul_f32_e32 v237, v135, v237
	v_mul_f32_e32 v238, v135, v238
	v_mul_f32_e32 v239, v135, v239
	v_cvt_pk_bf16_f32 v120, v228, v229
	v_cvt_pk_bf16_f32 v121, v230, v231
	v_cvt_pk_bf16_f32 v122, v236, v237
	v_cvt_pk_bf16_f32 v123, v238, v239
	global_store_dwordx4 v[246:247], v[120:123], off offset:448 sc1
	s_branch .LBB0_158

.Leg_cont:
	v_lshlrev_b64 v[144:145], 11, v[248:249]
	v_lshl_add_u64 v[144:145], s[22:23], 0, v[144:145]
	v_lshl_add_u64 v[140:141], v[246:247], 1, v[144:145]
	v_mov_b64_e32 v[142:143], v[140:141]
	s_mov_b64 s[34:35], 0x8000
	s_mov_b64 s[38:39], 0x28000
	s_cmp_gt_i32 s78, 0
	s_cselect_b64 s[6:7], -1, 0
	s_cmp_gt_i32 s78, 0
	s_cbranch_scc0 .Leg_z0
	global_load_dwordx4 v[210:213], v[138:139], off
	global_load_dwordx4 v[214:217], v[140:141], off
	global_load_dwordx4 v[218:221], v[138:139], off offset:256
	global_load_dwordx4 v[222:225], v[140:141], off offset:256
	v_lshl_add_u64 v[138:139], v[138:139], 0, s[0:1]
	v_lshl_add_u64 v[140:141], v[140:141], 0, s[34:35]
	global_load_dwordx4 v[226:229], v[138:139], off
	global_load_dwordx4 v[230:233], v[140:141], off
	global_load_dwordx4 v[234:237], v[138:139], off offset:256
	global_load_dwordx4 v[238:241], v[140:141], off offset:256
	v_lshl_add_u64 v[138:139], v[138:139], 0, s[0:1]
	v_lshl_add_u64 v[140:141], v[140:141], 0, s[34:35]
	global_load_dwordx4 v[182:185], v[138:139], off
	global_load_dwordx4 v[186:189], v[140:141], off
	global_load_dwordx4 v[190:193], v[138:139], off offset:256
	global_load_dwordx4 v[242:245], v[140:141], off offset:256
	v_lshl_add_u64 v[138:139], v[138:139], 0, s[0:1]
	v_lshl_add_u64 v[140:141], v[140:141], 0, s[34:35]
	s_waitcnt vmcnt(8)
	v_lshlrev_b32_e32 v130, 16, v210
	v_and_b32_e32 v131, 0xffff0000, v210
	v_lshlrev_b32_e32 v132, 16, v211
	v_and_b32_e32 v133, 0xffff0000, v211
	v_mul_f32_e32 v130, 0xbfb8aa3b, v130
	v_mul_f32_e32 v131, 0xbfb8aa3b, v131
	v_mul_f32_e32 v132, 0xbfb8aa3b, v132
	v_mul_f32_e32 v133, 0xbfb8aa3b, v133
	v_exp_f32_e32 v130, v130
	v_exp_f32_e32 v131, v131
	v_exp_f32_e32 v132, v132
	v_exp_f32_e32 v133, v133
	v_lshlrev_b32_e32 v134, 16, v214
	v_and_b32_e32 v135, 0xffff0000, v214
	v_lshlrev_b32_e32 v136, 16, v215
	v_and_b32_e32 v137, 0xffff0000, v215
	v_add_f32_e32 v130, 1.0, v130
	v_add_f32_e32 v131, 1.0, v131
	v_add_f32_e32 v132, 1.0, v132
	v_add_f32_e32 v133, 1.0, v133
	v_rcp_f32_e32 v130, v130
	v_rcp_f32_e32 v131, v131
	v_rcp_f32_e32 v132, v132
	v_rcp_f32_e32 v133, v133
	s_nop 0
	v_fmac_f32_e32 v134, v126, v130
	v_fmac_f32_e32 v135, v127, v131
	v_fmac_f32_e32 v136, v128, v132
	v_fmac_f32_e32 v137, v129, v133
	v_cvt_pk_bf16_f32 v126, v134, v135
	v_cvt_pk_bf16_f32 v127, v136, v137
	v_lshlrev_b32_e32 v130, 16, v212
	v_and_b32_e32 v131, 0xffff0000, v212
	v_lshlrev_b32_e32 v132, 16, v213
	v_and_b32_e32 v133, 0xffff0000, v213
	v_mul_f32_e32 v130, 0xbfb8aa3b, v130
	v_mul_f32_e32 v131, 0xbfb8aa3b, v131
	v_mul_f32_e32 v132, 0xbfb8aa3b, v132
	v_mul_f32_e32 v133, 0xbfb8aa3b, v133
	v_exp_f32_e32 v130, v130
	v_exp_f32_e32 v131, v131
	v_exp_f32_e32 v132, v132
	v_exp_f32_e32 v133, v133
	v_lshlrev_b32_e32 v134, 16, v216
	v_and_b32_e32 v135, 0xffff0000, v216
	v_lshlrev_b32_e32 v136, 16, v217
	v_and_b32_e32 v137, 0xffff0000, v217
	v_add_f32_e32 v130, 1.0, v130
	v_add_f32_e32 v131, 1.0, v131
	v_add_f32_e32 v132, 1.0, v132
	v_add_f32_e32 v133, 1.0, v133
	v_rcp_f32_e32 v130, v130
	v_rcp_f32_e32 v131, v131
	v_rcp_f32_e32 v132, v132
	v_rcp_f32_e32 v133, v133
	s_nop 0
	v_fmac_f32_e32 v134, v122, v130
	v_fmac_f32_e32 v135, v123, v131
	v_fmac_f32_e32 v136, v124, v132
	v_fmac_f32_e32 v137, v125, v133
	v_cvt_pk_bf16_f32 v128, v134, v135
	v_cvt_pk_bf16_f32 v129, v136, v137
	v_lshlrev_b32_e32 v130, 16, v218
	v_and_b32_e32 v131, 0xffff0000, v218
	v_lshlrev_b32_e32 v132, 16, v219
	v_and_b32_e32 v133, 0xffff0000, v219
	v_mul_f32_e32 v130, 0xbfb8aa3b, v130
	v_mul_f32_e32 v131, 0xbfb8aa3b, v131
	v_mul_f32_e32 v132, 0xbfb8aa3b, v132
	v_mul_f32_e32 v133, 0xbfb8aa3b, v133
	v_exp_f32_e32 v130, v130
	v_exp_f32_e32 v131, v131
	v_exp_f32_e32 v132, v132
	v_exp_f32_e32 v133, v133
	v_lshlrev_b32_e32 v134, 16, v222
	v_and_b32_e32 v135, 0xffff0000, v222
	v_lshlrev_b32_e32 v136, 16, v223
	v_and_b32_e32 v137, 0xffff0000, v223
	v_add_f32_e32 v130, 1.0, v130
	v_add_f32_e32 v131, 1.0, v131
	v_add_f32_e32 v132, 1.0, v132
	v_add_f32_e32 v133, 1.0, v133
	v_rcp_f32_e32 v130, v130
	v_rcp_f32_e32 v131, v131
	v_rcp_f32_e32 v132, v132
	v_rcp_f32_e32 v133, v133
	s_nop 0
	v_fmac_f32_e32 v134, v118, v130
	v_fmac_f32_e32 v135, v119, v131
	v_fmac_f32_e32 v136, v120, v132
	v_fmac_f32_e32 v137, v121, v133
	v_cvt_pk_bf16_f32 v118, v134, v135
	v_cvt_pk_bf16_f32 v119, v136, v137
	v_lshlrev_b32_e32 v130, 16, v220
	v_and_b32_e32 v131, 0xffff0000, v220
	v_lshlrev_b32_e32 v132, 16, v221
	v_and_b32_e32 v133, 0xffff0000, v221
	v_mul_f32_e32 v130, 0xbfb8aa3b, v130
	v_mul_f32_e32 v131, 0xbfb8aa3b, v131
	v_mul_f32_e32 v132, 0xbfb8aa3b, v132
	v_mul_f32_e32 v133, 0xbfb8aa3b, v133
	v_exp_f32_e32 v130, v130
	v_exp_f32_e32 v131, v131
	v_exp_f32_e32 v132, v132
	v_exp_f32_e32 v133, v133
	v_lshlrev_b32_e32 v134, 16, v224
	v_and_b32_e32 v135, 0xffff0000, v224
	v_lshlrev_b32_e32 v136, 16, v225
	v_and_b32_e32 v137, 0xffff0000, v225
	v_add_f32_e32 v130, 1.0, v130
	v_add_f32_e32 v131, 1.0, v131
	v_add_f32_e32 v132, 1.0, v132
	v_add_f32_e32 v133, 1.0, v133
	v_rcp_f32_e32 v130, v130
	v_rcp_f32_e32 v131, v131
	v_rcp_f32_e32 v132, v132
	v_rcp_f32_e32 v133, v133
	s_nop 0
	v_fmac_f32_e32 v134, v114, v130
	v_fmac_f32_e32 v135, v115, v131
	v_fmac_f32_e32 v136, v116, v132
	v_fmac_f32_e32 v137, v117, v133
	v_cvt_pk_bf16_f32 v120, v134, v135
	v_cvt_pk_bf16_f32 v121, v136, v137
	global_load_dwordx4 v[210:213], v[138:139], off
	global_load_dwordx4 v[214:217], v[140:141], off
	global_load_dwordx4 v[218:221], v[138:139], off offset:256
	global_load_dwordx4 v[222:225], v[140:141], off offset:256
	v_lshl_add_u64 v[138:139], v[138:139], 0, s[4:5]
	v_lshl_add_u64 v[140:141], v[140:141], 0, s[38:39]
	global_store_dwordx4 v[142:143], v[126:129], off sc1
	global_store_dwordx4 v[142:143], v[118:121], off offset:256 sc1
	v_lshl_add_u64 v[142:143], v[142:143], 0, s[34:35]
	s_waitcnt vmcnt(10)
	v_lshlrev_b32_e32 v130, 16, v226
	v_and_b32_e32 v131, 0xffff0000, v226
	v_lshlrev_b32_e32 v132, 16, v227
	v_and_b32_e32 v133, 0xffff0000, v227
	v_mul_f32_e32 v130, 0xbfb8aa3b, v130
	v_mul_f32_e32 v131, 0xbfb8aa3b, v131
	v_mul_f32_e32 v132, 0xbfb8aa3b, v132
	v_mul_f32_e32 v133, 0xbfb8aa3b, v133
	v_exp_f32_e32 v130, v130
	v_exp_f32_e32 v131, v131
	v_exp_f32_e32 v132, v132
	v_exp_f32_e32 v133, v133
	v_lshlrev_b32_e32 v134, 16, v230
	v_and_b32_e32 v135, 0xffff0000, v230
	v_lshlrev_b32_e32 v136, 16, v231
	v_and_b32_e32 v137, 0xffff0000, v231
	v_add_f32_e32 v130, 1.0, v130
	v_add_f32_e32 v131, 1.0, v131
	v_add_f32_e32 v132, 1.0, v132
	v_add_f32_e32 v133, 1.0, v133
	v_rcp_f32_e32 v130, v130
	v_rcp_f32_e32 v131, v131
	v_rcp_f32_e32 v132, v132
	v_rcp_f32_e32 v133, v133
	s_nop 0
	v_fmac_f32_e32 v134, v110, v130
	v_fmac_f32_e32 v135, v111, v131
	v_fmac_f32_e32 v136, v112, v132
	v_fmac_f32_e32 v137, v113, v133
	v_cvt_pk_bf16_f32 v110, v134, v135
	v_cvt_pk_bf16_f32 v111, v136, v137
	v_lshlrev_b32_e32 v130, 16, v228
	v_and_b32_e32 v131, 0xffff0000, v228
	v_lshlrev_b32_e32 v132, 16, v229
	v_and_b32_e32 v133, 0xffff0000, v229
	v_mul_f32_e32 v130, 0xbfb8aa3b, v130
	v_mul_f32_e32 v131, 0xbfb8aa3b, v131
	v_mul_f32_e32 v132, 0xbfb8aa3b, v132
	v_mul_f32_e32 v133, 0xbfb8aa3b, v133
	v_exp_f32_e32 v130, v130
	v_exp_f32_e32 v131, v131
	v_exp_f32_e32 v132, v132
	v_exp_f32_e32 v133, v133
	v_lshlrev_b32_e32 v134, 16, v232
	v_and_b32_e32 v135, 0xffff0000, v232
	v_lshlrev_b32_e32 v136, 16, v233
	v_and_b32_e32 v137, 0xffff0000, v233
	v_add_f32_e32 v130, 1.0, v130
	v_add_f32_e32 v131, 1.0, v131
	v_add_f32_e32 v132, 1.0, v132
	v_add_f32_e32 v133, 1.0, v133
	v_rcp_f32_e32 v130, v130
	v_rcp_f32_e32 v131, v131
	v_rcp_f32_e32 v132, v132
	v_rcp_f32_e32 v133, v133
	s_nop 0
	v_fmac_f32_e32 v134, v106, v130
	v_fmac_f32_e32 v135, v107, v131
	v_fmac_f32_e32 v136, v108, v132
	v_fmac_f32_e32 v137, v109, v133
	v_cvt_pk_bf16_f32 v112, v134, v135
	v_cvt_pk_bf16_f32 v113, v136, v137
	v_lshlrev_b32_e32 v130, 16, v234
	v_and_b32_e32 v131, 0xffff0000, v234
	v_lshlrev_b32_e32 v132, 16, v235
	v_and_b32_e32 v133, 0xffff0000, v235
	v_mul_f32_e32 v130, 0xbfb8aa3b, v130
	v_mul_f32_e32 v131, 0xbfb8aa3b, v131
	v_mul_f32_e32 v132, 0xbfb8aa3b, v132
	v_mul_f32_e32 v133, 0xbfb8aa3b, v133
	v_exp_f32_e32 v130, v130
	v_exp_f32_e32 v131, v131
	v_exp_f32_e32 v132, v132
	v_exp_f32_e32 v133, v133
	v_lshlrev_b32_e32 v134, 16, v238
	v_and_b32_e32 v135, 0xffff0000, v238
	v_lshlrev_b32_e32 v136, 16, v239
	v_and_b32_e32 v137, 0xffff0000, v239
	v_add_f32_e32 v130, 1.0, v130
	v_add_f32_e32 v131, 1.0, v131
	v_add_f32_e32 v132, 1.0, v132
	v_add_f32_e32 v133, 1.0, v133
	v_rcp_f32_e32 v130, v130
	v_rcp_f32_e32 v131, v131
	v_rcp_f32_e32 v132, v132
	v_rcp_f32_e32 v133, v133
	s_nop 0
	v_fmac_f32_e32 v134, v102, v130
	v_fmac_f32_e32 v135, v103, v131
	v_fmac_f32_e32 v136, v104, v132
	v_fmac_f32_e32 v137, v105, v133
	v_cvt_pk_bf16_f32 v102, v134, v135
	v_cvt_pk_bf16_f32 v103, v136, v137
	v_lshlrev_b32_e32 v130, 16, v236
	v_and_b32_e32 v131, 0xffff0000, v236
	v_lshlrev_b32_e32 v132, 16, v237
	v_and_b32_e32 v133, 0xffff0000, v237
	v_mul_f32_e32 v130, 0xbfb8aa3b, v130
	v_mul_f32_e32 v131, 0xbfb8aa3b, v131
	v_mul_f32_e32 v132, 0xbfb8aa3b, v132
	v_mul_f32_e32 v133, 0xbfb8aa3b, v133
	v_exp_f32_e32 v130, v130
	v_exp_f32_e32 v131, v131
	v_exp_f32_e32 v132, v132
	v_exp_f32_e32 v133, v133
	v_lshlrev_b32_e32 v134, 16, v240
	v_and_b32_e32 v135, 0xffff0000, v240
	v_lshlrev_b32_e32 v136, 16, v241
	v_and_b32_e32 v137, 0xffff0000, v241
	v_add_f32_e32 v130, 1.0, v130
	v_add_f32_e32 v131, 1.0, v131
	v_add_f32_e32 v132, 1.0, v132
	v_add_f32_e32 v133, 1.0, v133
	v_rcp_f32_e32 v130, v130
	v_rcp_f32_e32 v131, v131
	v_rcp_f32_e32 v132, v132
	v_rcp_f32_e32 v133, v133
	s_nop 0
	v_fmac_f32_e32 v134, v98, v130
	v_fmac_f32_e32 v135, v99, v131
	v_fmac_f32_e32 v136, v100, v132
	v_fmac_f32_e32 v137, v101, v133
	v_cvt_pk_bf16_f32 v104, v134, v135
	v_cvt_pk_bf16_f32 v105, v136, v137
	global_load_dwordx4 v[226:229], v[138:139], off
	global_load_dwordx4 v[230:233], v[140:141], off
	global_load_dwordx4 v[234:237], v[138:139], off offset:256
	global_load_dwordx4 v[238:241], v[140:141], off offset:256
	v_lshl_add_u64 v[138:139], v[138:139], 0, s[0:1]
	v_lshl_add_u64 v[140:141], v[140:141], 0, s[34:35]
	global_store_dwordx4 v[142:143], v[110:113], off sc1
	global_store_dwordx4 v[142:143], v[102:105], off offset:256 sc1
	v_lshl_add_u64 v[142:143], v[142:143], 0, s[34:35]
	s_waitcnt vmcnt(12)
	v_lshlrev_b32_e32 v130, 16, v182
	v_and_b32_e32 v131, 0xffff0000, v182
	v_lshlrev_b32_e32 v132, 16, v183
	v_and_b32_e32 v133, 0xffff0000, v183
	v_mul_f32_e32 v130, 0xbfb8aa3b, v130
	v_mul_f32_e32 v131, 0xbfb8aa3b, v131
	v_mul_f32_e32 v132, 0xbfb8aa3b, v132
	v_mul_f32_e32 v133, 0xbfb8aa3b, v133
	v_exp_f32_e32 v130, v130
	v_exp_f32_e32 v131, v131
	v_exp_f32_e32 v132, v132
	v_exp_f32_e32 v133, v133
	v_lshlrev_b32_e32 v134, 16, v186
	v_and_b32_e32 v135, 0xffff0000, v186
	v_lshlrev_b32_e32 v136, 16, v187
	v_and_b32_e32 v137, 0xffff0000, v187
	v_add_f32_e32 v130, 1.0, v130
	v_add_f32_e32 v131, 1.0, v131
	v_add_f32_e32 v132, 1.0, v132
	v_add_f32_e32 v133, 1.0, v133
	v_rcp_f32_e32 v130, v130
	v_rcp_f32_e32 v131, v131
	v_rcp_f32_e32 v132, v132
	v_rcp_f32_e32 v133, v133
	s_nop 0
	v_fmac_f32_e32 v134, v94, v130
	v_fmac_f32_e32 v135, v95, v131
	v_fmac_f32_e32 v136, v96, v132
	v_fmac_f32_e32 v137, v97, v133
	v_cvt_pk_bf16_f32 v94, v134, v135
	v_cvt_pk_bf16_f32 v95, v136, v137
	v_lshlrev_b32_e32 v130, 16, v184
	v_and_b32_e32 v131, 0xffff0000, v184
	v_lshlrev_b32_e32 v132, 16, v185
	v_and_b32_e32 v133, 0xffff0000, v185
	v_mul_f32_e32 v130, 0xbfb8aa3b, v130
	v_mul_f32_e32 v131, 0xbfb8aa3b, v131
	v_mul_f32_e32 v132, 0xbfb8aa3b, v132
	v_mul_f32_e32 v133, 0xbfb8aa3b, v133
	v_exp_f32_e32 v130, v130
	v_exp_f32_e32 v131, v131
	v_exp_f32_e32 v132, v132
	v_exp_f32_e32 v133, v133
	v_lshlrev_b32_e32 v134, 16, v188
	v_and_b32_e32 v135, 0xffff0000, v188
	v_lshlrev_b32_e32 v136, 16, v189
	v_and_b32_e32 v137, 0xffff0000, v189
	v_add_f32_e32 v130, 1.0, v130
	v_add_f32_e32 v131, 1.0, v131
	v_add_f32_e32 v132, 1.0, v132
	v_add_f32_e32 v133, 1.0, v133
	v_rcp_f32_e32 v130, v130
	v_rcp_f32_e32 v131, v131
	v_rcp_f32_e32 v132, v132
	v_rcp_f32_e32 v133, v133
	s_nop 0
	v_fmac_f32_e32 v134, v90, v130
	v_fmac_f32_e32 v135, v91, v131
	v_fmac_f32_e32 v136, v92, v132
	v_fmac_f32_e32 v137, v93, v133
	v_cvt_pk_bf16_f32 v96, v134, v135
	v_cvt_pk_bf16_f32 v97, v136, v137
	v_lshlrev_b32_e32 v130, 16, v190
	v_and_b32_e32 v131, 0xffff0000, v190
	v_lshlrev_b32_e32 v132, 16, v191
	v_and_b32_e32 v133, 0xffff0000, v191
	v_mul_f32_e32 v130, 0xbfb8aa3b, v130
	v_mul_f32_e32 v131, 0xbfb8aa3b, v131
	v_mul_f32_e32 v132, 0xbfb8aa3b, v132
	v_mul_f32_e32 v133, 0xbfb8aa3b, v133
	v_exp_f32_e32 v130, v130
	v_exp_f32_e32 v131, v131
	v_exp_f32_e32 v132, v132
	v_exp_f32_e32 v133, v133
	v_lshlrev_b32_e32 v134, 16, v242
	v_and_b32_e32 v135, 0xffff0000, v242
	v_lshlrev_b32_e32 v136, 16, v243
	v_and_b32_e32 v137, 0xffff0000, v243
	v_add_f32_e32 v130, 1.0, v130
	v_add_f32_e32 v131, 1.0, v131
	v_add_f32_e32 v132, 1.0, v132
	v_add_f32_e32 v133, 1.0, v133
	v_rcp_f32_e32 v130, v130
	v_rcp_f32_e32 v131, v131
	v_rcp_f32_e32 v132, v132
	v_rcp_f32_e32 v133, v133
	s_nop 0
	v_fmac_f32_e32 v134, v86, v130
	v_fmac_f32_e32 v135, v87, v131
	v_fmac_f32_e32 v136, v88, v132
	v_fmac_f32_e32 v137, v89, v133
	v_cvt_pk_bf16_f32 v86, v134, v135
	v_cvt_pk_bf16_f32 v87, v136, v137
	v_lshlrev_b32_e32 v130, 16, v192
	v_and_b32_e32 v131, 0xffff0000, v192
	v_lshlrev_b32_e32 v132, 16, v193
	v_and_b32_e32 v133, 0xffff0000, v193
	v_mul_f32_e32 v130, 0xbfb8aa3b, v130
	v_mul_f32_e32 v131, 0xbfb8aa3b, v131
	v_mul_f32_e32 v132, 0xbfb8aa3b, v132
	v_mul_f32_e32 v133, 0xbfb8aa3b, v133
	v_exp_f32_e32 v130, v130
	v_exp_f32_e32 v131, v131
	v_exp_f32_e32 v132, v132
	v_exp_f32_e32 v133, v133
	v_lshlrev_b32_e32 v134, 16, v244
	v_and_b32_e32 v135, 0xffff0000, v244
	v_lshlrev_b32_e32 v136, 16, v245
	v_and_b32_e32 v137, 0xffff0000, v245
	v_add_f32_e32 v130, 1.0, v130
	v_add_f32_e32 v131, 1.0, v131
	v_add_f32_e32 v132, 1.0, v132
	v_add_f32_e32 v133, 1.0, v133
	v_rcp_f32_e32 v130, v130
	v_rcp_f32_e32 v131, v131
	v_rcp_f32_e32 v132, v132
	v_rcp_f32_e32 v133, v133
	s_nop 0
	v_fmac_f32_e32 v134, v82, v130
	v_fmac_f32_e32 v135, v83, v131
	v_fmac_f32_e32 v136, v84, v132
	v_fmac_f32_e32 v137, v85, v133
	v_cvt_pk_bf16_f32 v88, v134, v135
	v_cvt_pk_bf16_f32 v89, v136, v137
	global_load_dwordx4 v[182:185], v[138:139], off
	global_load_dwordx4 v[186:189], v[140:141], off
	global_load_dwordx4 v[190:193], v[138:139], off offset:256
	global_load_dwordx4 v[242:245], v[140:141], off offset:256
	v_lshl_add_u64 v[138:139], v[138:139], 0, s[0:1]
	v_lshl_add_u64 v[140:141], v[140:141], 0, s[34:35]
	global_store_dwordx4 v[142:143], v[94:97], off sc1
	global_store_dwordx4 v[142:143], v[86:89], off offset:256 sc1
	v_lshl_add_u64 v[142:143], v[142:143], 0, s[34:35]
	s_waitcnt vmcnt(14)
	v_lshlrev_b32_e32 v130, 16, v210
	v_and_b32_e32 v131, 0xffff0000, v210
	v_lshlrev_b32_e32 v132, 16, v211
	v_and_b32_e32 v133, 0xffff0000, v211
	v_mul_f32_e32 v130, 0xbfb8aa3b, v130
	v_mul_f32_e32 v131, 0xbfb8aa3b, v131
	v_mul_f32_e32 v132, 0xbfb8aa3b, v132
	v_mul_f32_e32 v133, 0xbfb8aa3b, v133
	v_exp_f32_e32 v130, v130
	v_exp_f32_e32 v131, v131
	v_exp_f32_e32 v132, v132
	v_exp_f32_e32 v133, v133
	v_lshlrev_b32_e32 v134, 16, v214
	v_and_b32_e32 v135, 0xffff0000, v214
	v_lshlrev_b32_e32 v136, 16, v215
	v_and_b32_e32 v137, 0xffff0000, v215
	v_add_f32_e32 v130, 1.0, v130
	v_add_f32_e32 v131, 1.0, v131
	v_add_f32_e32 v132, 1.0, v132
	v_add_f32_e32 v133, 1.0, v133
	v_rcp_f32_e32 v130, v130
	v_rcp_f32_e32 v131, v131
	v_rcp_f32_e32 v132, v132
	v_rcp_f32_e32 v133, v133
	s_nop 0
	v_fmac_f32_e32 v134, v78, v130
	v_fmac_f32_e32 v135, v79, v131
	v_fmac_f32_e32 v136, v80, v132
	v_fmac_f32_e32 v137, v81, v133
	v_cvt_pk_bf16_f32 v78, v134, v135
	v_cvt_pk_bf16_f32 v79, v136, v137
	v_lshlrev_b32_e32 v130, 16, v212
	v_and_b32_e32 v131, 0xffff0000, v212
	v_lshlrev_b32_e32 v132, 16, v213
	v_and_b32_e32 v133, 0xffff0000, v213
	v_mul_f32_e32 v130, 0xbfb8aa3b, v130
	v_mul_f32_e32 v131, 0xbfb8aa3b, v131
	v_mul_f32_e32 v132, 0xbfb8aa3b, v132
	v_mul_f32_e32 v133, 0xbfb8aa3b, v133
	v_exp_f32_e32 v130, v130
	v_exp_f32_e32 v131, v131
	v_exp_f32_e32 v132, v132
	v_exp_f32_e32 v133, v133
	v_lshlrev_b32_e32 v134, 16, v216
	v_and_b32_e32 v135, 0xffff0000, v216
	v_lshlrev_b32_e32 v136, 16, v217
	v_and_b32_e32 v137, 0xffff0000, v217
	v_add_f32_e32 v130, 1.0, v130
	v_add_f32_e32 v131, 1.0, v131
	v_add_f32_e32 v132, 1.0, v132
	v_add_f32_e32 v133, 1.0, v133
	v_rcp_f32_e32 v130, v130
	v_rcp_f32_e32 v131, v131
	v_rcp_f32_e32 v132, v132
	v_rcp_f32_e32 v133, v133
	s_nop 0
	v_fmac_f32_e32 v134, v74, v130
	v_fmac_f32_e32 v135, v75, v131
	v_fmac_f32_e32 v136, v76, v132
	v_fmac_f32_e32 v137, v77, v133
	v_cvt_pk_bf16_f32 v80, v134, v135
	v_cvt_pk_bf16_f32 v81, v136, v137
	v_lshlrev_b32_e32 v130, 16, v218
	v_and_b32_e32 v131, 0xffff0000, v218
	v_lshlrev_b32_e32 v132, 16, v219
	v_and_b32_e32 v133, 0xffff0000, v219
	v_mul_f32_e32 v130, 0xbfb8aa3b, v130
	v_mul_f32_e32 v131, 0xbfb8aa3b, v131
	v_mul_f32_e32 v132, 0xbfb8aa3b, v132
	v_mul_f32_e32 v133, 0xbfb8aa3b, v133
	v_exp_f32_e32 v130, v130
	v_exp_f32_e32 v131, v131
	v_exp_f32_e32 v132, v132
	v_exp_f32_e32 v133, v133
	v_lshlrev_b32_e32 v134, 16, v222
	v_and_b32_e32 v135, 0xffff0000, v222
	v_lshlrev_b32_e32 v136, 16, v223
	v_and_b32_e32 v137, 0xffff0000, v223
	v_add_f32_e32 v130, 1.0, v130
	v_add_f32_e32 v131, 1.0, v131
	v_add_f32_e32 v132, 1.0, v132
	v_add_f32_e32 v133, 1.0, v133
	v_rcp_f32_e32 v130, v130
	v_rcp_f32_e32 v131, v131
	v_rcp_f32_e32 v132, v132
	v_rcp_f32_e32 v133, v133
	s_nop 0
	v_fmac_f32_e32 v134, v70, v130
	v_fmac_f32_e32 v135, v71, v131
	v_fmac_f32_e32 v136, v72, v132
	v_fmac_f32_e32 v137, v73, v133
	v_cvt_pk_bf16_f32 v70, v134, v135
	v_cvt_pk_bf16_f32 v71, v136, v137
	v_lshlrev_b32_e32 v130, 16, v220
	v_and_b32_e32 v131, 0xffff0000, v220
	v_lshlrev_b32_e32 v132, 16, v221
	v_and_b32_e32 v133, 0xffff0000, v221
	v_mul_f32_e32 v130, 0xbfb8aa3b, v130
	v_mul_f32_e32 v131, 0xbfb8aa3b, v131
	v_mul_f32_e32 v132, 0xbfb8aa3b, v132
	v_mul_f32_e32 v133, 0xbfb8aa3b, v133
	v_exp_f32_e32 v130, v130
	v_exp_f32_e32 v131, v131
	v_exp_f32_e32 v132, v132
	v_exp_f32_e32 v133, v133
	v_lshlrev_b32_e32 v134, 16, v224
	v_and_b32_e32 v135, 0xffff0000, v224
	v_lshlrev_b32_e32 v136, 16, v225
	v_and_b32_e32 v137, 0xffff0000, v225
	v_add_f32_e32 v130, 1.0, v130
	v_add_f32_e32 v131, 1.0, v131
	v_add_f32_e32 v132, 1.0, v132
	v_add_f32_e32 v133, 1.0, v133
	v_rcp_f32_e32 v130, v130
	v_rcp_f32_e32 v131, v131
	v_rcp_f32_e32 v132, v132
	v_rcp_f32_e32 v133, v133
	s_nop 0
	v_fmac_f32_e32 v134, v66, v130
	v_fmac_f32_e32 v135, v67, v131
	v_fmac_f32_e32 v136, v68, v132
	v_fmac_f32_e32 v137, v69, v133
	v_cvt_pk_bf16_f32 v72, v134, v135
	v_cvt_pk_bf16_f32 v73, v136, v137
	global_load_dwordx4 v[210:213], v[138:139], off
	global_load_dwordx4 v[214:217], v[140:141], off
	global_load_dwordx4 v[218:221], v[138:139], off offset:256
	global_load_dwordx4 v[222:225], v[140:141], off offset:256
	v_lshl_add_u64 v[138:139], v[138:139], 0, s[0:1]
	v_lshl_add_u64 v[140:141], v[140:141], 0, s[34:35]
	global_store_dwordx4 v[142:143], v[78:81], off sc1
	global_store_dwordx4 v[142:143], v[70:73], off offset:256 sc1
	v_lshl_add_u64 v[142:143], v[142:143], 0, s[38:39]
	s_waitcnt vmcnt(14)
	v_lshlrev_b32_e32 v130, 16, v226
	v_and_b32_e32 v131, 0xffff0000, v226
	v_lshlrev_b32_e32 v132, 16, v227
	v_and_b32_e32 v133, 0xffff0000, v227
	v_mul_f32_e32 v130, 0xbfb8aa3b, v130
	v_mul_f32_e32 v131, 0xbfb8aa3b, v131
	v_mul_f32_e32 v132, 0xbfb8aa3b, v132
	v_mul_f32_e32 v133, 0xbfb8aa3b, v133
	v_exp_f32_e32 v130, v130
	v_exp_f32_e32 v131, v131
	v_exp_f32_e32 v132, v132
	v_exp_f32_e32 v133, v133
	v_lshlrev_b32_e32 v134, 16, v230
	v_and_b32_e32 v135, 0xffff0000, v230
	v_lshlrev_b32_e32 v136, 16, v231
	v_and_b32_e32 v137, 0xffff0000, v231
	v_add_f32_e32 v130, 1.0, v130
	v_add_f32_e32 v131, 1.0, v131
	v_add_f32_e32 v132, 1.0, v132
	v_add_f32_e32 v133, 1.0, v133
	v_rcp_f32_e32 v130, v130
	v_rcp_f32_e32 v131, v131
	v_rcp_f32_e32 v132, v132
	v_rcp_f32_e32 v133, v133
	s_nop 0
	v_fmac_f32_e32 v134, v62, v130
	v_fmac_f32_e32 v135, v63, v131
	v_fmac_f32_e32 v136, v64, v132
	v_fmac_f32_e32 v137, v65, v133
	v_cvt_pk_bf16_f32 v62, v134, v135
	v_cvt_pk_bf16_f32 v63, v136, v137
	v_lshlrev_b32_e32 v130, 16, v228
	v_and_b32_e32 v131, 0xffff0000, v228
	v_lshlrev_b32_e32 v132, 16, v229
	v_and_b32_e32 v133, 0xffff0000, v229
	v_mul_f32_e32 v130, 0xbfb8aa3b, v130
	v_mul_f32_e32 v131, 0xbfb8aa3b, v131
	v_mul_f32_e32 v132, 0xbfb8aa3b, v132
	v_mul_f32_e32 v133, 0xbfb8aa3b, v133
	v_exp_f32_e32 v130, v130
	v_exp_f32_e32 v131, v131
	v_exp_f32_e32 v132, v132
	v_exp_f32_e32 v133, v133
	v_lshlrev_b32_e32 v134, 16, v232
	v_and_b32_e32 v135, 0xffff0000, v232
	v_lshlrev_b32_e32 v136, 16, v233
	v_and_b32_e32 v137, 0xffff0000, v233
	v_add_f32_e32 v130, 1.0, v130
	v_add_f32_e32 v131, 1.0, v131
	v_add_f32_e32 v132, 1.0, v132
	v_add_f32_e32 v133, 1.0, v133
	v_rcp_f32_e32 v130, v130
	v_rcp_f32_e32 v131, v131
	v_rcp_f32_e32 v132, v132
	v_rcp_f32_e32 v133, v133
	s_nop 0
	v_fmac_f32_e32 v134, v58, v130
	v_fmac_f32_e32 v135, v59, v131
	v_fmac_f32_e32 v136, v60, v132
	v_fmac_f32_e32 v137, v61, v133
	v_cvt_pk_bf16_f32 v64, v134, v135
	v_cvt_pk_bf16_f32 v65, v136, v137
	v_lshlrev_b32_e32 v130, 16, v234
	v_and_b32_e32 v131, 0xffff0000, v234
	v_lshlrev_b32_e32 v132, 16, v235
	v_and_b32_e32 v133, 0xffff0000, v235
	v_mul_f32_e32 v130, 0xbfb8aa3b, v130
	v_mul_f32_e32 v131, 0xbfb8aa3b, v131
	v_mul_f32_e32 v132, 0xbfb8aa3b, v132
	v_mul_f32_e32 v133, 0xbfb8aa3b, v133
	v_exp_f32_e32 v130, v130
	v_exp_f32_e32 v131, v131
	v_exp_f32_e32 v132, v132
	v_exp_f32_e32 v133, v133
	v_lshlrev_b32_e32 v134, 16, v238
	v_and_b32_e32 v135, 0xffff0000, v238
	v_lshlrev_b32_e32 v136, 16, v239
	v_and_b32_e32 v137, 0xffff0000, v239
	v_add_f32_e32 v130, 1.0, v130
	v_add_f32_e32 v131, 1.0, v131
	v_add_f32_e32 v132, 1.0, v132
	v_add_f32_e32 v133, 1.0, v133
	v_rcp_f32_e32 v130, v130
	v_rcp_f32_e32 v131, v131
	v_rcp_f32_e32 v132, v132
	v_rcp_f32_e32 v133, v133
	s_nop 0
	v_fmac_f32_e32 v134, v54, v130
	v_fmac_f32_e32 v135, v55, v131
	v_fmac_f32_e32 v136, v56, v132
	v_fmac_f32_e32 v137, v57, v133
	v_cvt_pk_bf16_f32 v54, v134, v135
	v_cvt_pk_bf16_f32 v55, v136, v137
	v_lshlrev_b32_e32 v130, 16, v236
	v_and_b32_e32 v131, 0xffff0000, v236
	v_lshlrev_b32_e32 v132, 16, v237
	v_and_b32_e32 v133, 0xffff0000, v237
	v_mul_f32_e32 v130, 0xbfb8aa3b, v130
	v_mul_f32_e32 v131, 0xbfb8aa3b, v131
	v_mul_f32_e32 v132, 0xbfb8aa3b, v132
	v_mul_f32_e32 v133, 0xbfb8aa3b, v133
	v_exp_f32_e32 v130, v130
	v_exp_f32_e32 v131, v131
	v_exp_f32_e32 v132, v132
	v_exp_f32_e32 v133, v133
	v_lshlrev_b32_e32 v134, 16, v240
	v_and_b32_e32 v135, 0xffff0000, v240
	v_lshlrev_b32_e32 v136, 16, v241
	v_and_b32_e32 v137, 0xffff0000, v241
	v_add_f32_e32 v130, 1.0, v130
	v_add_f32_e32 v131, 1.0, v131
	v_add_f32_e32 v132, 1.0, v132
	v_add_f32_e32 v133, 1.0, v133
	v_rcp_f32_e32 v130, v130
	v_rcp_f32_e32 v131, v131
	v_rcp_f32_e32 v132, v132
	v_rcp_f32_e32 v133, v133
	s_nop 0
	v_fmac_f32_e32 v134, v50, v130
	v_fmac_f32_e32 v135, v51, v131
	v_fmac_f32_e32 v136, v52, v132
	v_fmac_f32_e32 v137, v53, v133
	v_cvt_pk_bf16_f32 v56, v134, v135
	v_cvt_pk_bf16_f32 v57, v136, v137
	global_load_dwordx4 v[226:229], v[138:139], off
	global_load_dwordx4 v[230:233], v[140:141], off
	global_load_dwordx4 v[234:237], v[138:139], off offset:256
	global_load_dwordx4 v[238:241], v[140:141], off offset:256
	global_store_dwordx4 v[142:143], v[62:65], off sc1
	global_store_dwordx4 v[142:143], v[54:57], off offset:256 sc1
	v_lshl_add_u64 v[142:143], v[142:143], 0, s[34:35]
	s_waitcnt vmcnt(14)
	v_lshlrev_b32_e32 v130, 16, v182
	v_and_b32_e32 v131, 0xffff0000, v182
	v_lshlrev_b32_e32 v132, 16, v183
	v_and_b32_e32 v133, 0xffff0000, v183
	v_mul_f32_e32 v130, 0xbfb8aa3b, v130
	v_mul_f32_e32 v131, 0xbfb8aa3b, v131
	v_mul_f32_e32 v132, 0xbfb8aa3b, v132
	v_mul_f32_e32 v133, 0xbfb8aa3b, v133
	v_exp_f32_e32 v130, v130
	v_exp_f32_e32 v131, v131
	v_exp_f32_e32 v132, v132
	v_exp_f32_e32 v133, v133
	v_lshlrev_b32_e32 v134, 16, v186
	v_and_b32_e32 v135, 0xffff0000, v186
	v_lshlrev_b32_e32 v136, 16, v187
	v_and_b32_e32 v137, 0xffff0000, v187
	v_add_f32_e32 v130, 1.0, v130
	v_add_f32_e32 v131, 1.0, v131
	v_add_f32_e32 v132, 1.0, v132
	v_add_f32_e32 v133, 1.0, v133
	v_rcp_f32_e32 v130, v130
	v_rcp_f32_e32 v131, v131
	v_rcp_f32_e32 v132, v132
	v_rcp_f32_e32 v133, v133
	s_nop 0
	v_fmac_f32_e32 v134, v46, v130
	v_fmac_f32_e32 v135, v47, v131
	v_fmac_f32_e32 v136, v48, v132
	v_fmac_f32_e32 v137, v49, v133
	v_cvt_pk_bf16_f32 v46, v134, v135
	v_cvt_pk_bf16_f32 v47, v136, v137
	v_lshlrev_b32_e32 v130, 16, v184
	v_and_b32_e32 v131, 0xffff0000, v184
	v_lshlrev_b32_e32 v132, 16, v185
	v_and_b32_e32 v133, 0xffff0000, v185
	v_mul_f32_e32 v130, 0xbfb8aa3b, v130
	v_mul_f32_e32 v131, 0xbfb8aa3b, v131
	v_mul_f32_e32 v132, 0xbfb8aa3b, v132
	v_mul_f32_e32 v133, 0xbfb8aa3b, v133
	v_exp_f32_e32 v130, v130
	v_exp_f32_e32 v131, v131
	v_exp_f32_e32 v132, v132
	v_exp_f32_e32 v133, v133
	v_lshlrev_b32_e32 v134, 16, v188
	v_and_b32_e32 v135, 0xffff0000, v188
	v_lshlrev_b32_e32 v136, 16, v189
	v_and_b32_e32 v137, 0xffff0000, v189
	v_add_f32_e32 v130, 1.0, v130
	v_add_f32_e32 v131, 1.0, v131
	v_add_f32_e32 v132, 1.0, v132
	v_add_f32_e32 v133, 1.0, v133
	v_rcp_f32_e32 v130, v130
	v_rcp_f32_e32 v131, v131
	v_rcp_f32_e32 v132, v132
	v_rcp_f32_e32 v133, v133
	s_nop 0
	v_fmac_f32_e32 v134, v42, v130
	v_fmac_f32_e32 v135, v43, v131
	v_fmac_f32_e32 v136, v44, v132
	v_fmac_f32_e32 v137, v45, v133
	v_cvt_pk_bf16_f32 v48, v134, v135
	v_cvt_pk_bf16_f32 v49, v136, v137
	v_lshlrev_b32_e32 v130, 16, v190
	v_and_b32_e32 v131, 0xffff0000, v190
	v_lshlrev_b32_e32 v132, 16, v191
	v_and_b32_e32 v133, 0xffff0000, v191
	v_mul_f32_e32 v130, 0xbfb8aa3b, v130
	v_mul_f32_e32 v131, 0xbfb8aa3b, v131
	v_mul_f32_e32 v132, 0xbfb8aa3b, v132
	v_mul_f32_e32 v133, 0xbfb8aa3b, v133
	v_exp_f32_e32 v130, v130
	v_exp_f32_e32 v131, v131
	v_exp_f32_e32 v132, v132
	v_exp_f32_e32 v133, v133
	v_lshlrev_b32_e32 v134, 16, v242
	v_and_b32_e32 v135, 0xffff0000, v242
	v_lshlrev_b32_e32 v136, 16, v243
	v_and_b32_e32 v137, 0xffff0000, v243
	v_add_f32_e32 v130, 1.0, v130
	v_add_f32_e32 v131, 1.0, v131
	v_add_f32_e32 v132, 1.0, v132
	v_add_f32_e32 v133, 1.0, v133
	v_rcp_f32_e32 v130, v130
	v_rcp_f32_e32 v131, v131
	v_rcp_f32_e32 v132, v132
	v_rcp_f32_e32 v133, v133
	s_nop 0
	v_fmac_f32_e32 v134, v38, v130
	v_fmac_f32_e32 v135, v39, v131
	v_fmac_f32_e32 v136, v40, v132
	v_fmac_f32_e32 v137, v41, v133
	v_cvt_pk_bf16_f32 v38, v134, v135
	v_cvt_pk_bf16_f32 v39, v136, v137
	v_lshlrev_b32_e32 v130, 16, v192
	v_and_b32_e32 v131, 0xffff0000, v192
	v_lshlrev_b32_e32 v132, 16, v193
	v_and_b32_e32 v133, 0xffff0000, v193
	v_mul_f32_e32 v130, 0xbfb8aa3b, v130
	v_mul_f32_e32 v131, 0xbfb8aa3b, v131
	v_mul_f32_e32 v132, 0xbfb8aa3b, v132
	v_mul_f32_e32 v133, 0xbfb8aa3b, v133
	v_exp_f32_e32 v130, v130
	v_exp_f32_e32 v131, v131
	v_exp_f32_e32 v132, v132
	v_exp_f32_e32 v133, v133
	v_lshlrev_b32_e32 v134, 16, v244
	v_and_b32_e32 v135, 0xffff0000, v244
	v_lshlrev_b32_e32 v136, 16, v245
	v_and_b32_e32 v137, 0xffff0000, v245
	v_add_f32_e32 v130, 1.0, v130
	v_add_f32_e32 v131, 1.0, v131
	v_add_f32_e32 v132, 1.0, v132
	v_add_f32_e32 v133, 1.0, v133
	v_rcp_f32_e32 v130, v130
	v_rcp_f32_e32 v131, v131
	v_rcp_f32_e32 v132, v132
	v_rcp_f32_e32 v133, v133
	s_nop 0
	v_fmac_f32_e32 v134, v34, v130
	v_fmac_f32_e32 v135, v35, v131
	v_fmac_f32_e32 v136, v36, v132
	v_fmac_f32_e32 v137, v37, v133
	v_cvt_pk_bf16_f32 v40, v134, v135
	v_cvt_pk_bf16_f32 v41, v136, v137
	global_store_dwordx4 v[142:143], v[46:49], off sc1
	global_store_dwordx4 v[142:143], v[38:41], off offset:256 sc1
	v_lshl_add_u64 v[142:143], v[142:143], 0, s[34:35]
	s_waitcnt vmcnt(10)
	v_lshlrev_b32_e32 v130, 16, v210
	v_and_b32_e32 v131, 0xffff0000, v210
	v_lshlrev_b32_e32 v132, 16, v211
	v_and_b32_e32 v133, 0xffff0000, v211
	v_mul_f32_e32 v130, 0xbfb8aa3b, v130
	v_mul_f32_e32 v131, 0xbfb8aa3b, v131
	v_mul_f32_e32 v132, 0xbfb8aa3b, v132
	v_mul_f32_e32 v133, 0xbfb8aa3b, v133
	v_exp_f32_e32 v130, v130
	v_exp_f32_e32 v131, v131
	v_exp_f32_e32 v132, v132
	v_exp_f32_e32 v133, v133
	v_lshlrev_b32_e32 v134, 16, v214
	v_and_b32_e32 v135, 0xffff0000, v214
	v_lshlrev_b32_e32 v136, 16, v215
	v_and_b32_e32 v137, 0xffff0000, v215
	v_add_f32_e32 v130, 1.0, v130
	v_add_f32_e32 v131, 1.0, v131
	v_add_f32_e32 v132, 1.0, v132
	v_add_f32_e32 v133, 1.0, v133
	v_rcp_f32_e32 v130, v130
	v_rcp_f32_e32 v131, v131
	v_rcp_f32_e32 v132, v132
	v_rcp_f32_e32 v133, v133
	s_nop 0
	v_fmac_f32_e32 v134, v30, v130
	v_fmac_f32_e32 v135, v31, v131
	v_fmac_f32_e32 v136, v32, v132
	v_fmac_f32_e32 v137, v33, v133
	v_cvt_pk_bf16_f32 v30, v134, v135
	v_cvt_pk_bf16_f32 v31, v136, v137
	v_lshlrev_b32_e32 v130, 16, v212
	v_and_b32_e32 v131, 0xffff0000, v212
	v_lshlrev_b32_e32 v132, 16, v213
	v_and_b32_e32 v133, 0xffff0000, v213
	v_mul_f32_e32 v130, 0xbfb8aa3b, v130
	v_mul_f32_e32 v131, 0xbfb8aa3b, v131
	v_mul_f32_e32 v132, 0xbfb8aa3b, v132
	v_mul_f32_e32 v133, 0xbfb8aa3b, v133
	v_exp_f32_e32 v130, v130
	v_exp_f32_e32 v131, v131
	v_exp_f32_e32 v132, v132
	v_exp_f32_e32 v133, v133
	v_lshlrev_b32_e32 v134, 16, v216
	v_and_b32_e32 v135, 0xffff0000, v216
	v_lshlrev_b32_e32 v136, 16, v217
	v_and_b32_e32 v137, 0xffff0000, v217
	v_add_f32_e32 v130, 1.0, v130
	v_add_f32_e32 v131, 1.0, v131
	v_add_f32_e32 v132, 1.0, v132
	v_add_f32_e32 v133, 1.0, v133
	v_rcp_f32_e32 v130, v130
	v_rcp_f32_e32 v131, v131
	v_rcp_f32_e32 v132, v132
	v_rcp_f32_e32 v133, v133
	s_nop 0
	v_fmac_f32_e32 v134, v26, v130
	v_fmac_f32_e32 v135, v27, v131
	v_fmac_f32_e32 v136, v28, v132
	v_fmac_f32_e32 v137, v29, v133
	v_cvt_pk_bf16_f32 v32, v134, v135
	v_cvt_pk_bf16_f32 v33, v136, v137
	v_lshlrev_b32_e32 v130, 16, v218
	v_and_b32_e32 v131, 0xffff0000, v218
	v_lshlrev_b32_e32 v132, 16, v219
	v_and_b32_e32 v133, 0xffff0000, v219
	v_mul_f32_e32 v130, 0xbfb8aa3b, v130
	v_mul_f32_e32 v131, 0xbfb8aa3b, v131
	v_mul_f32_e32 v132, 0xbfb8aa3b, v132
	v_mul_f32_e32 v133, 0xbfb8aa3b, v133
	v_exp_f32_e32 v130, v130
	v_exp_f32_e32 v131, v131
	v_exp_f32_e32 v132, v132
	v_exp_f32_e32 v133, v133
	v_lshlrev_b32_e32 v134, 16, v222
	v_and_b32_e32 v135, 0xffff0000, v222
	v_lshlrev_b32_e32 v136, 16, v223
	v_and_b32_e32 v137, 0xffff0000, v223
	v_add_f32_e32 v130, 1.0, v130
	v_add_f32_e32 v131, 1.0, v131
	v_add_f32_e32 v132, 1.0, v132
	v_add_f32_e32 v133, 1.0, v133
	v_rcp_f32_e32 v130, v130
	v_rcp_f32_e32 v131, v131
	v_rcp_f32_e32 v132, v132
	v_rcp_f32_e32 v133, v133
	s_nop 0
	v_fmac_f32_e32 v134, v22, v130
	v_fmac_f32_e32 v135, v23, v131
	v_fmac_f32_e32 v136, v24, v132
	v_fmac_f32_e32 v137, v25, v133
	v_cvt_pk_bf16_f32 v22, v134, v135
	v_cvt_pk_bf16_f32 v23, v136, v137
	v_lshlrev_b32_e32 v130, 16, v220
	v_and_b32_e32 v131, 0xffff0000, v220
	v_lshlrev_b32_e32 v132, 16, v221
	v_and_b32_e32 v133, 0xffff0000, v221
	v_mul_f32_e32 v130, 0xbfb8aa3b, v130
	v_mul_f32_e32 v131, 0xbfb8aa3b, v131
	v_mul_f32_e32 v132, 0xbfb8aa3b, v132
	v_mul_f32_e32 v133, 0xbfb8aa3b, v133
	v_exp_f32_e32 v130, v130
	v_exp_f32_e32 v131, v131
	v_exp_f32_e32 v132, v132
	v_exp_f32_e32 v133, v133
	v_lshlrev_b32_e32 v134, 16, v224
	v_and_b32_e32 v135, 0xffff0000, v224
	v_lshlrev_b32_e32 v136, 16, v225
	v_and_b32_e32 v137, 0xffff0000, v225
	v_add_f32_e32 v130, 1.0, v130
	v_add_f32_e32 v131, 1.0, v131
	v_add_f32_e32 v132, 1.0, v132
	v_add_f32_e32 v133, 1.0, v133
	v_rcp_f32_e32 v130, v130
	v_rcp_f32_e32 v131, v131
	v_rcp_f32_e32 v132, v132
	v_rcp_f32_e32 v133, v133
	s_nop 0
	v_fmac_f32_e32 v134, v18, v130
	v_fmac_f32_e32 v135, v19, v131
	v_fmac_f32_e32 v136, v20, v132
	v_fmac_f32_e32 v137, v21, v133
	v_cvt_pk_bf16_f32 v24, v134, v135
	v_cvt_pk_bf16_f32 v25, v136, v137
	global_store_dwordx4 v[142:143], v[30:33], off sc1
	global_store_dwordx4 v[142:143], v[22:25], off offset:256 sc1
	v_lshl_add_u64 v[142:143], v[142:143], 0, s[34:35]
	s_waitcnt vmcnt(6)
	v_lshlrev_b32_e32 v130, 16, v226
	v_and_b32_e32 v131, 0xffff0000, v226
	v_lshlrev_b32_e32 v132, 16, v227
	v_and_b32_e32 v133, 0xffff0000, v227
	v_mul_f32_e32 v130, 0xbfb8aa3b, v130
	v_mul_f32_e32 v131, 0xbfb8aa3b, v131
	v_mul_f32_e32 v132, 0xbfb8aa3b, v132
	v_mul_f32_e32 v133, 0xbfb8aa3b, v133
	v_exp_f32_e32 v130, v130
	v_exp_f32_e32 v131, v131
	v_exp_f32_e32 v132, v132
	v_exp_f32_e32 v133, v133
	v_lshlrev_b32_e32 v134, 16, v230
	v_and_b32_e32 v135, 0xffff0000, v230
	v_lshlrev_b32_e32 v136, 16, v231
	v_and_b32_e32 v137, 0xffff0000, v231
	v_add_f32_e32 v130, 1.0, v130
	v_add_f32_e32 v131, 1.0, v131
	v_add_f32_e32 v132, 1.0, v132
	v_add_f32_e32 v133, 1.0, v133
	v_rcp_f32_e32 v130, v130
	v_rcp_f32_e32 v131, v131
	v_rcp_f32_e32 v132, v132
	v_rcp_f32_e32 v133, v133
	s_nop 0
	v_fmac_f32_e32 v134, v14, v130
	v_fmac_f32_e32 v135, v15, v131
	v_fmac_f32_e32 v136, v16, v132
	v_fmac_f32_e32 v137, v17, v133
	v_cvt_pk_bf16_f32 v14, v134, v135
	v_cvt_pk_bf16_f32 v15, v136, v137
	v_lshlrev_b32_e32 v130, 16, v228
	v_and_b32_e32 v131, 0xffff0000, v228
	v_lshlrev_b32_e32 v132, 16, v229
	v_and_b32_e32 v133, 0xffff0000, v229
	v_mul_f32_e32 v130, 0xbfb8aa3b, v130
	v_mul_f32_e32 v131, 0xbfb8aa3b, v131
	v_mul_f32_e32 v132, 0xbfb8aa3b, v132
	v_mul_f32_e32 v133, 0xbfb8aa3b, v133
	v_exp_f32_e32 v130, v130
	v_exp_f32_e32 v131, v131
	v_exp_f32_e32 v132, v132
	v_exp_f32_e32 v133, v133
	v_lshlrev_b32_e32 v134, 16, v232
	v_and_b32_e32 v135, 0xffff0000, v232
	v_lshlrev_b32_e32 v136, 16, v233
	v_and_b32_e32 v137, 0xffff0000, v233
	v_add_f32_e32 v130, 1.0, v130
	v_add_f32_e32 v131, 1.0, v131
	v_add_f32_e32 v132, 1.0, v132
	v_add_f32_e32 v133, 1.0, v133
	v_rcp_f32_e32 v130, v130
	v_rcp_f32_e32 v131, v131
	v_rcp_f32_e32 v132, v132
	v_rcp_f32_e32 v133, v133
	s_nop 0
	v_fmac_f32_e32 v134, v10, v130
	v_fmac_f32_e32 v135, v11, v131
	v_fmac_f32_e32 v136, v12, v132
	v_fmac_f32_e32 v137, v13, v133
	v_cvt_pk_bf16_f32 v16, v134, v135
	v_cvt_pk_bf16_f32 v17, v136, v137
	v_lshlrev_b32_e32 v130, 16, v234
	v_and_b32_e32 v131, 0xffff0000, v234
	v_lshlrev_b32_e32 v132, 16, v235
	v_and_b32_e32 v133, 0xffff0000, v235
	v_mul_f32_e32 v130, 0xbfb8aa3b, v130
	v_mul_f32_e32 v131, 0xbfb8aa3b, v131
	v_mul_f32_e32 v132, 0xbfb8aa3b, v132
	v_mul_f32_e32 v133, 0xbfb8aa3b, v133
	v_exp_f32_e32 v130, v130
	v_exp_f32_e32 v131, v131
	v_exp_f32_e32 v132, v132
	v_exp_f32_e32 v133, v133
	v_lshlrev_b32_e32 v134, 16, v238
	v_and_b32_e32 v135, 0xffff0000, v238
	v_lshlrev_b32_e32 v136, 16, v239
	v_and_b32_e32 v137, 0xffff0000, v239
	v_add_f32_e32 v130, 1.0, v130
	v_add_f32_e32 v131, 1.0, v131
	v_add_f32_e32 v132, 1.0, v132
	v_add_f32_e32 v133, 1.0, v133
	v_rcp_f32_e32 v130, v130
	v_rcp_f32_e32 v131, v131
	v_rcp_f32_e32 v132, v132
	v_rcp_f32_e32 v133, v133
	s_nop 0
	v_fmac_f32_e32 v134, v6, v130
	v_fmac_f32_e32 v135, v7, v131
	v_fmac_f32_e32 v136, v8, v132
	v_fmac_f32_e32 v137, v9, v133
	v_cvt_pk_bf16_f32 v6, v134, v135
	v_cvt_pk_bf16_f32 v7, v136, v137
	v_lshlrev_b32_e32 v130, 16, v236
	v_and_b32_e32 v131, 0xffff0000, v236
	v_lshlrev_b32_e32 v132, 16, v237
	v_and_b32_e32 v133, 0xffff0000, v237
	v_mul_f32_e32 v130, 0xbfb8aa3b, v130
	v_mul_f32_e32 v131, 0xbfb8aa3b, v131
	v_mul_f32_e32 v132, 0xbfb8aa3b, v132
	v_mul_f32_e32 v133, 0xbfb8aa3b, v133
	v_exp_f32_e32 v130, v130
	v_exp_f32_e32 v131, v131
	v_exp_f32_e32 v132, v132
	v_exp_f32_e32 v133, v133
	v_lshlrev_b32_e32 v134, 16, v240
	v_and_b32_e32 v135, 0xffff0000, v240
	v_lshlrev_b32_e32 v136, 16, v241
	v_and_b32_e32 v137, 0xffff0000, v241
	v_add_f32_e32 v130, 1.0, v130
	v_add_f32_e32 v131, 1.0, v131
	v_add_f32_e32 v132, 1.0, v132
	v_add_f32_e32 v133, 1.0, v133
	v_rcp_f32_e32 v130, v130
	v_rcp_f32_e32 v131, v131
	v_rcp_f32_e32 v132, v132
	v_rcp_f32_e32 v133, v133
	s_nop 0
	v_fmac_f32_e32 v134, v2, v130
	v_fmac_f32_e32 v135, v3, v131
	v_fmac_f32_e32 v136, v4, v132
	v_fmac_f32_e32 v137, v5, v133
	v_cvt_pk_bf16_f32 v8, v134, v135
	v_cvt_pk_bf16_f32 v9, v136, v137
	global_store_dwordx4 v[142:143], v[14:17], off sc1
	global_store_dwordx4 v[142:143], v[6:9], off offset:256 sc1
	s_branch .Leg_fin
.Leg_z0:
	global_load_dwordx4 v[210:213], v[138:139], off
	global_load_dwordx4 v[218:221], v[138:139], off offset:256
	v_lshl_add_u64 v[138:139], v[138:139], 0, s[0:1]
	v_lshl_add_u64 v[140:141], v[140:141], 0, s[34:35]
	global_load_dwordx4 v[226:229], v[138:139], off
	global_load_dwordx4 v[234:237], v[138:139], off offset:256
	v_lshl_add_u64 v[138:139], v[138:139], 0, s[0:1]
	v_lshl_add_u64 v[140:141], v[140:141], 0, s[34:35]
	global_load_dwordx4 v[182:185], v[138:139], off
	global_load_dwordx4 v[190:193], v[138:139], off offset:256
	v_lshl_add_u64 v[138:139], v[138:139], 0, s[0:1]
	v_lshl_add_u64 v[140:141], v[140:141], 0, s[34:35]
	s_waitcnt vmcnt(4)
	v_mov_b32_e32 v214, 0
	v_mov_b32_e32 v215, 0
	v_mov_b32_e32 v216, 0
	v_mov_b32_e32 v217, 0
	v_lshlrev_b32_e32 v130, 16, v210
	v_and_b32_e32 v131, 0xffff0000, v210
	v_lshlrev_b32_e32 v132, 16, v211
	v_and_b32_e32 v133, 0xffff0000, v211
	v_mul_f32_e32 v130, 0xbfb8aa3b, v130
	v_mul_f32_e32 v131, 0xbfb8aa3b, v131
	v_mul_f32_e32 v132, 0xbfb8aa3b, v132
	v_mul_f32_e32 v133, 0xbfb8aa3b, v133
	v_exp_f32_e32 v130, v130
	v_exp_f32_e32 v131, v131
	v_exp_f32_e32 v132, v132
	v_exp_f32_e32 v133, v133
	v_lshlrev_b32_e32 v134, 16, v214
	v_and_b32_e32 v135, 0xffff0000, v214
	v_lshlrev_b32_e32 v136, 16, v215
	v_and_b32_e32 v137, 0xffff0000, v215
	v_add_f32_e32 v130, 1.0, v130
	v_add_f32_e32 v131, 1.0, v131
	v_add_f32_e32 v132, 1.0, v132
	v_add_f32_e32 v133, 1.0, v133
	v_rcp_f32_e32 v130, v130
	v_rcp_f32_e32 v131, v131
	v_rcp_f32_e32 v132, v132
	v_rcp_f32_e32 v133, v133
	s_nop 0
	v_fmac_f32_e32 v134, v126, v130
	v_fmac_f32_e32 v135, v127, v131
	v_fmac_f32_e32 v136, v128, v132
	v_fmac_f32_e32 v137, v129, v133
	v_cvt_pk_bf16_f32 v126, v134, v135
	v_cvt_pk_bf16_f32 v127, v136, v137
	v_lshlrev_b32_e32 v130, 16, v212
	v_and_b32_e32 v131, 0xffff0000, v212
	v_lshlrev_b32_e32 v132, 16, v213
	v_and_b32_e32 v133, 0xffff0000, v213
	v_mul_f32_e32 v130, 0xbfb8aa3b, v130
	v_mul_f32_e32 v131, 0xbfb8aa3b, v131
	v_mul_f32_e32 v132, 0xbfb8aa3b, v132
	v_mul_f32_e32 v133, 0xbfb8aa3b, v133
	v_exp_f32_e32 v130, v130
	v_exp_f32_e32 v131, v131
	v_exp_f32_e32 v132, v132
	v_exp_f32_e32 v133, v133
	v_lshlrev_b32_e32 v134, 16, v216
	v_and_b32_e32 v135, 0xffff0000, v216
	v_lshlrev_b32_e32 v136, 16, v217
	v_and_b32_e32 v137, 0xffff0000, v217
	v_add_f32_e32 v130, 1.0, v130
	v_add_f32_e32 v131, 1.0, v131
	v_add_f32_e32 v132, 1.0, v132
	v_add_f32_e32 v133, 1.0, v133
	v_rcp_f32_e32 v130, v130
	v_rcp_f32_e32 v131, v131
	v_rcp_f32_e32 v132, v132
	v_rcp_f32_e32 v133, v133
	s_nop 0
	v_fmac_f32_e32 v134, v122, v130
	v_fmac_f32_e32 v135, v123, v131
	v_fmac_f32_e32 v136, v124, v132
	v_fmac_f32_e32 v137, v125, v133
	v_cvt_pk_bf16_f32 v128, v134, v135
	v_cvt_pk_bf16_f32 v129, v136, v137
	v_mov_b32_e32 v222, 0
	v_mov_b32_e32 v223, 0
	v_mov_b32_e32 v224, 0
	v_mov_b32_e32 v225, 0
	v_lshlrev_b32_e32 v130, 16, v218
	v_and_b32_e32 v131, 0xffff0000, v218
	v_lshlrev_b32_e32 v132, 16, v219
	v_and_b32_e32 v133, 0xffff0000, v219
	v_mul_f32_e32 v130, 0xbfb8aa3b, v130
	v_mul_f32_e32 v131, 0xbfb8aa3b, v131
	v_mul_f32_e32 v132, 0xbfb8aa3b, v132
	v_mul_f32_e32 v133, 0xbfb8aa3b, v133
	v_exp_f32_e32 v130, v130
	v_exp_f32_e32 v131, v131
	v_exp_f32_e32 v132, v132
	v_exp_f32_e32 v133, v133
	v_lshlrev_b32_e32 v134, 16, v222
	v_and_b32_e32 v135, 0xffff0000, v222
	v_lshlrev_b32_e32 v136, 16, v223
	v_and_b32_e32 v137, 0xffff0000, v223
	v_add_f32_e32 v130, 1.0, v130
	v_add_f32_e32 v131, 1.0, v131
	v_add_f32_e32 v132, 1.0, v132
	v_add_f32_e32 v133, 1.0, v133
	v_rcp_f32_e32 v130, v130
	v_rcp_f32_e32 v131, v131
	v_rcp_f32_e32 v132, v132
	v_rcp_f32_e32 v133, v133
	s_nop 0
	v_fmac_f32_e32 v134, v118, v130
	v_fmac_f32_e32 v135, v119, v131
	v_fmac_f32_e32 v136, v120, v132
	v_fmac_f32_e32 v137, v121, v133
	v_cvt_pk_bf16_f32 v118, v134, v135
	v_cvt_pk_bf16_f32 v119, v136, v137
	v_lshlrev_b32_e32 v130, 16, v220
	v_and_b32_e32 v131, 0xffff0000, v220
	v_lshlrev_b32_e32 v132, 16, v221
	v_and_b32_e32 v133, 0xffff0000, v221
	v_mul_f32_e32 v130, 0xbfb8aa3b, v130
	v_mul_f32_e32 v131, 0xbfb8aa3b, v131
	v_mul_f32_e32 v132, 0xbfb8aa3b, v132
	v_mul_f32_e32 v133, 0xbfb8aa3b, v133
	v_exp_f32_e32 v130, v130
	v_exp_f32_e32 v131, v131
	v_exp_f32_e32 v132, v132
	v_exp_f32_e32 v133, v133
	v_lshlrev_b32_e32 v134, 16, v224
	v_and_b32_e32 v135, 0xffff0000, v224
	v_lshlrev_b32_e32 v136, 16, v225
	v_and_b32_e32 v137, 0xffff0000, v225
	v_add_f32_e32 v130, 1.0, v130
	v_add_f32_e32 v131, 1.0, v131
	v_add_f32_e32 v132, 1.0, v132
	v_add_f32_e32 v133, 1.0, v133
	v_rcp_f32_e32 v130, v130
	v_rcp_f32_e32 v131, v131
	v_rcp_f32_e32 v132, v132
	v_rcp_f32_e32 v133, v133
	s_nop 0
	v_fmac_f32_e32 v134, v114, v130
	v_fmac_f32_e32 v135, v115, v131
	v_fmac_f32_e32 v136, v116, v132
	v_fmac_f32_e32 v137, v117, v133
	v_cvt_pk_bf16_f32 v120, v134, v135
	v_cvt_pk_bf16_f32 v121, v136, v137
	global_load_dwordx4 v[210:213], v[138:139], off
	global_load_dwordx4 v[218:221], v[138:139], off offset:256
	v_lshl_add_u64 v[138:139], v[138:139], 0, s[4:5]
	v_lshl_add_u64 v[140:141], v[140:141], 0, s[38:39]
	global_store_dwordx4 v[142:143], v[126:129], off sc1
	global_store_dwordx4 v[142:143], v[118:121], off offset:256 sc1
	v_lshl_add_u64 v[142:143], v[142:143], 0, s[34:35]
	s_waitcnt vmcnt(6)
	v_mov_b32_e32 v230, 0
	v_mov_b32_e32 v231, 0
	v_mov_b32_e32 v232, 0
	v_mov_b32_e32 v233, 0
	v_lshlrev_b32_e32 v130, 16, v226
	v_and_b32_e32 v131, 0xffff0000, v226
	v_lshlrev_b32_e32 v132, 16, v227
	v_and_b32_e32 v133, 0xffff0000, v227
	v_mul_f32_e32 v130, 0xbfb8aa3b, v130
	v_mul_f32_e32 v131, 0xbfb8aa3b, v131
	v_mul_f32_e32 v132, 0xbfb8aa3b, v132
	v_mul_f32_e32 v133, 0xbfb8aa3b, v133
	v_exp_f32_e32 v130, v130
	v_exp_f32_e32 v131, v131
	v_exp_f32_e32 v132, v132
	v_exp_f32_e32 v133, v133
	v_lshlrev_b32_e32 v134, 16, v230
	v_and_b32_e32 v135, 0xffff0000, v230
	v_lshlrev_b32_e32 v136, 16, v231
	v_and_b32_e32 v137, 0xffff0000, v231
	v_add_f32_e32 v130, 1.0, v130
	v_add_f32_e32 v131, 1.0, v131
	v_add_f32_e32 v132, 1.0, v132
	v_add_f32_e32 v133, 1.0, v133
	v_rcp_f32_e32 v130, v130
	v_rcp_f32_e32 v131, v131
	v_rcp_f32_e32 v132, v132
	v_rcp_f32_e32 v133, v133
	s_nop 0
	v_fmac_f32_e32 v134, v110, v130
	v_fmac_f32_e32 v135, v111, v131
	v_fmac_f32_e32 v136, v112, v132
	v_fmac_f32_e32 v137, v113, v133
	v_cvt_pk_bf16_f32 v110, v134, v135
	v_cvt_pk_bf16_f32 v111, v136, v137
	v_lshlrev_b32_e32 v130, 16, v228
	v_and_b32_e32 v131, 0xffff0000, v228
	v_lshlrev_b32_e32 v132, 16, v229
	v_and_b32_e32 v133, 0xffff0000, v229
	v_mul_f32_e32 v130, 0xbfb8aa3b, v130
	v_mul_f32_e32 v131, 0xbfb8aa3b, v131
	v_mul_f32_e32 v132, 0xbfb8aa3b, v132
	v_mul_f32_e32 v133, 0xbfb8aa3b, v133
	v_exp_f32_e32 v130, v130
	v_exp_f32_e32 v131, v131
	v_exp_f32_e32 v132, v132
	v_exp_f32_e32 v133, v133
	v_lshlrev_b32_e32 v134, 16, v232
	v_and_b32_e32 v135, 0xffff0000, v232
	v_lshlrev_b32_e32 v136, 16, v233
	v_and_b32_e32 v137, 0xffff0000, v233
	v_add_f32_e32 v130, 1.0, v130
	v_add_f32_e32 v131, 1.0, v131
	v_add_f32_e32 v132, 1.0, v132
	v_add_f32_e32 v133, 1.0, v133
	v_rcp_f32_e32 v130, v130
	v_rcp_f32_e32 v131, v131
	v_rcp_f32_e32 v132, v132
	v_rcp_f32_e32 v133, v133
	s_nop 0
	v_fmac_f32_e32 v134, v106, v130
	v_fmac_f32_e32 v135, v107, v131
	v_fmac_f32_e32 v136, v108, v132
	v_fmac_f32_e32 v137, v109, v133
	v_cvt_pk_bf16_f32 v112, v134, v135
	v_cvt_pk_bf16_f32 v113, v136, v137
	v_mov_b32_e32 v238, 0
	v_mov_b32_e32 v239, 0
	v_mov_b32_e32 v240, 0
	v_mov_b32_e32 v241, 0
	v_lshlrev_b32_e32 v130, 16, v234
	v_and_b32_e32 v131, 0xffff0000, v234
	v_lshlrev_b32_e32 v132, 16, v235
	v_and_b32_e32 v133, 0xffff0000, v235
	v_mul_f32_e32 v130, 0xbfb8aa3b, v130
	v_mul_f32_e32 v131, 0xbfb8aa3b, v131
	v_mul_f32_e32 v132, 0xbfb8aa3b, v132
	v_mul_f32_e32 v133, 0xbfb8aa3b, v133
	v_exp_f32_e32 v130, v130
	v_exp_f32_e32 v131, v131
	v_exp_f32_e32 v132, v132
	v_exp_f32_e32 v133, v133
	v_lshlrev_b32_e32 v134, 16, v238
	v_and_b32_e32 v135, 0xffff0000, v238
	v_lshlrev_b32_e32 v136, 16, v239
	v_and_b32_e32 v137, 0xffff0000, v239
	v_add_f32_e32 v130, 1.0, v130
	v_add_f32_e32 v131, 1.0, v131
	v_add_f32_e32 v132, 1.0, v132
	v_add_f32_e32 v133, 1.0, v133
	v_rcp_f32_e32 v130, v130
	v_rcp_f32_e32 v131, v131
	v_rcp_f32_e32 v132, v132
	v_rcp_f32_e32 v133, v133
	s_nop 0
	v_fmac_f32_e32 v134, v102, v130
	v_fmac_f32_e32 v135, v103, v131
	v_fmac_f32_e32 v136, v104, v132
	v_fmac_f32_e32 v137, v105, v133
	v_cvt_pk_bf16_f32 v102, v134, v135
	v_cvt_pk_bf16_f32 v103, v136, v137
	v_lshlrev_b32_e32 v130, 16, v236
	v_and_b32_e32 v131, 0xffff0000, v236
	v_lshlrev_b32_e32 v132, 16, v237
	v_and_b32_e32 v133, 0xffff0000, v237
	v_mul_f32_e32 v130, 0xbfb8aa3b, v130
	v_mul_f32_e32 v131, 0xbfb8aa3b, v131
	v_mul_f32_e32 v132, 0xbfb8aa3b, v132
	v_mul_f32_e32 v133, 0xbfb8aa3b, v133
	v_exp_f32_e32 v130, v130
	v_exp_f32_e32 v131, v131
	v_exp_f32_e32 v132, v132
	v_exp_f32_e32 v133, v133
	v_lshlrev_b32_e32 v134, 16, v240
	v_and_b32_e32 v135, 0xffff0000, v240
	v_lshlrev_b32_e32 v136, 16, v241
	v_and_b32_e32 v137, 0xffff0000, v241
	v_add_f32_e32 v130, 1.0, v130
	v_add_f32_e32 v131, 1.0, v131
	v_add_f32_e32 v132, 1.0, v132
	v_add_f32_e32 v133, 1.0, v133
	v_rcp_f32_e32 v130, v130
	v_rcp_f32_e32 v131, v131
	v_rcp_f32_e32 v132, v132
	v_rcp_f32_e32 v133, v133
	s_nop 0
	v_fmac_f32_e32 v134, v98, v130
	v_fmac_f32_e32 v135, v99, v131
	v_fmac_f32_e32 v136, v100, v132
	v_fmac_f32_e32 v137, v101, v133
	v_cvt_pk_bf16_f32 v104, v134, v135
	v_cvt_pk_bf16_f32 v105, v136, v137
	global_load_dwordx4 v[226:229], v[138:139], off
	global_load_dwordx4 v[234:237], v[138:139], off offset:256
	v_lshl_add_u64 v[138:139], v[138:139], 0, s[0:1]
	v_lshl_add_u64 v[140:141], v[140:141], 0, s[34:35]
	global_store_dwordx4 v[142:143], v[110:113], off sc1
	global_store_dwordx4 v[142:143], v[102:105], off offset:256 sc1
	v_lshl_add_u64 v[142:143], v[142:143], 0, s[34:35]
	s_waitcnt vmcnt(8)
	v_mov_b32_e32 v186, 0
	v_mov_b32_e32 v187, 0
	v_mov_b32_e32 v188, 0
	v_mov_b32_e32 v189, 0
	v_lshlrev_b32_e32 v130, 16, v182
	v_and_b32_e32 v131, 0xffff0000, v182
	v_lshlrev_b32_e32 v132, 16, v183
	v_and_b32_e32 v133, 0xffff0000, v183
	v_mul_f32_e32 v130, 0xbfb8aa3b, v130
	v_mul_f32_e32 v131, 0xbfb8aa3b, v131
	v_mul_f32_e32 v132, 0xbfb8aa3b, v132
	v_mul_f32_e32 v133, 0xbfb8aa3b, v133
	v_exp_f32_e32 v130, v130
	v_exp_f32_e32 v131, v131
	v_exp_f32_e32 v132, v132
	v_exp_f32_e32 v133, v133
	v_lshlrev_b32_e32 v134, 16, v186
	v_and_b32_e32 v135, 0xffff0000, v186
	v_lshlrev_b32_e32 v136, 16, v187
	v_and_b32_e32 v137, 0xffff0000, v187
	v_add_f32_e32 v130, 1.0, v130
	v_add_f32_e32 v131, 1.0, v131
	v_add_f32_e32 v132, 1.0, v132
	v_add_f32_e32 v133, 1.0, v133
	v_rcp_f32_e32 v130, v130
	v_rcp_f32_e32 v131, v131
	v_rcp_f32_e32 v132, v132
	v_rcp_f32_e32 v133, v133
	s_nop 0
	v_fmac_f32_e32 v134, v94, v130
	v_fmac_f32_e32 v135, v95, v131
	v_fmac_f32_e32 v136, v96, v132
	v_fmac_f32_e32 v137, v97, v133
	v_cvt_pk_bf16_f32 v94, v134, v135
	v_cvt_pk_bf16_f32 v95, v136, v137
	v_lshlrev_b32_e32 v130, 16, v184
	v_and_b32_e32 v131, 0xffff0000, v184
	v_lshlrev_b32_e32 v132, 16, v185
	v_and_b32_e32 v133, 0xffff0000, v185
	v_mul_f32_e32 v130, 0xbfb8aa3b, v130
	v_mul_f32_e32 v131, 0xbfb8aa3b, v131
	v_mul_f32_e32 v132, 0xbfb8aa3b, v132
	v_mul_f32_e32 v133, 0xbfb8aa3b, v133
	v_exp_f32_e32 v130, v130
	v_exp_f32_e32 v131, v131
	v_exp_f32_e32 v132, v132
	v_exp_f32_e32 v133, v133
	v_lshlrev_b32_e32 v134, 16, v188
	v_and_b32_e32 v135, 0xffff0000, v188
	v_lshlrev_b32_e32 v136, 16, v189
	v_and_b32_e32 v137, 0xffff0000, v189
	v_add_f32_e32 v130, 1.0, v130
	v_add_f32_e32 v131, 1.0, v131
	v_add_f32_e32 v132, 1.0, v132
	v_add_f32_e32 v133, 1.0, v133
	v_rcp_f32_e32 v130, v130
	v_rcp_f32_e32 v131, v131
	v_rcp_f32_e32 v132, v132
	v_rcp_f32_e32 v133, v133
	s_nop 0
	v_fmac_f32_e32 v134, v90, v130
	v_fmac_f32_e32 v135, v91, v131
	v_fmac_f32_e32 v136, v92, v132
	v_fmac_f32_e32 v137, v93, v133
	v_cvt_pk_bf16_f32 v96, v134, v135
	v_cvt_pk_bf16_f32 v97, v136, v137
	v_mov_b32_e32 v242, 0
	v_mov_b32_e32 v243, 0
	v_mov_b32_e32 v244, 0
	v_mov_b32_e32 v245, 0
	v_lshlrev_b32_e32 v130, 16, v190
	v_and_b32_e32 v131, 0xffff0000, v190
	v_lshlrev_b32_e32 v132, 16, v191
	v_and_b32_e32 v133, 0xffff0000, v191
	v_mul_f32_e32 v130, 0xbfb8aa3b, v130
	v_mul_f32_e32 v131, 0xbfb8aa3b, v131
	v_mul_f32_e32 v132, 0xbfb8aa3b, v132
	v_mul_f32_e32 v133, 0xbfb8aa3b, v133
	v_exp_f32_e32 v130, v130
	v_exp_f32_e32 v131, v131
	v_exp_f32_e32 v132, v132
	v_exp_f32_e32 v133, v133
	v_lshlrev_b32_e32 v134, 16, v242
	v_and_b32_e32 v135, 0xffff0000, v242
	v_lshlrev_b32_e32 v136, 16, v243
	v_and_b32_e32 v137, 0xffff0000, v243
	v_add_f32_e32 v130, 1.0, v130
	v_add_f32_e32 v131, 1.0, v131
	v_add_f32_e32 v132, 1.0, v132
	v_add_f32_e32 v133, 1.0, v133
	v_rcp_f32_e32 v130, v130
	v_rcp_f32_e32 v131, v131
	v_rcp_f32_e32 v132, v132
	v_rcp_f32_e32 v133, v133
	s_nop 0
	v_fmac_f32_e32 v134, v86, v130
	v_fmac_f32_e32 v135, v87, v131
	v_fmac_f32_e32 v136, v88, v132
	v_fmac_f32_e32 v137, v89, v133
	v_cvt_pk_bf16_f32 v86, v134, v135
	v_cvt_pk_bf16_f32 v87, v136, v137
	v_lshlrev_b32_e32 v130, 16, v192
	v_and_b32_e32 v131, 0xffff0000, v192
	v_lshlrev_b32_e32 v132, 16, v193
	v_and_b32_e32 v133, 0xffff0000, v193
	v_mul_f32_e32 v130, 0xbfb8aa3b, v130
	v_mul_f32_e32 v131, 0xbfb8aa3b, v131
	v_mul_f32_e32 v132, 0xbfb8aa3b, v132
	v_mul_f32_e32 v133, 0xbfb8aa3b, v133
	v_exp_f32_e32 v130, v130
	v_exp_f32_e32 v131, v131
	v_exp_f32_e32 v132, v132
	v_exp_f32_e32 v133, v133
	v_lshlrev_b32_e32 v134, 16, v244
	v_and_b32_e32 v135, 0xffff0000, v244
	v_lshlrev_b32_e32 v136, 16, v245
	v_and_b32_e32 v137, 0xffff0000, v245
	v_add_f32_e32 v130, 1.0, v130
	v_add_f32_e32 v131, 1.0, v131
	v_add_f32_e32 v132, 1.0, v132
	v_add_f32_e32 v133, 1.0, v133
	v_rcp_f32_e32 v130, v130
	v_rcp_f32_e32 v131, v131
	v_rcp_f32_e32 v132, v132
	v_rcp_f32_e32 v133, v133
	s_nop 0
	v_fmac_f32_e32 v134, v82, v130
	v_fmac_f32_e32 v135, v83, v131
	v_fmac_f32_e32 v136, v84, v132
	v_fmac_f32_e32 v137, v85, v133
	v_cvt_pk_bf16_f32 v88, v134, v135
	v_cvt_pk_bf16_f32 v89, v136, v137
	global_load_dwordx4 v[182:185], v[138:139], off
	global_load_dwordx4 v[190:193], v[138:139], off offset:256
	v_lshl_add_u64 v[138:139], v[138:139], 0, s[0:1]
	v_lshl_add_u64 v[140:141], v[140:141], 0, s[34:35]
	global_store_dwordx4 v[142:143], v[94:97], off sc1
	global_store_dwordx4 v[142:143], v[86:89], off offset:256 sc1
	v_lshl_add_u64 v[142:143], v[142:143], 0, s[34:35]
	s_waitcnt vmcnt(10)
	v_mov_b32_e32 v214, 0
	v_mov_b32_e32 v215, 0
	v_mov_b32_e32 v216, 0
	v_mov_b32_e32 v217, 0
	v_lshlrev_b32_e32 v130, 16, v210
	v_and_b32_e32 v131, 0xffff0000, v210
	v_lshlrev_b32_e32 v132, 16, v211
	v_and_b32_e32 v133, 0xffff0000, v211
	v_mul_f32_e32 v130, 0xbfb8aa3b, v130
	v_mul_f32_e32 v131, 0xbfb8aa3b, v131
	v_mul_f32_e32 v132, 0xbfb8aa3b, v132
	v_mul_f32_e32 v133, 0xbfb8aa3b, v133
	v_exp_f32_e32 v130, v130
	v_exp_f32_e32 v131, v131
	v_exp_f32_e32 v132, v132
	v_exp_f32_e32 v133, v133
	v_lshlrev_b32_e32 v134, 16, v214
	v_and_b32_e32 v135, 0xffff0000, v214
	v_lshlrev_b32_e32 v136, 16, v215
	v_and_b32_e32 v137, 0xffff0000, v215
	v_add_f32_e32 v130, 1.0, v130
	v_add_f32_e32 v131, 1.0, v131
	v_add_f32_e32 v132, 1.0, v132
	v_add_f32_e32 v133, 1.0, v133
	v_rcp_f32_e32 v130, v130
	v_rcp_f32_e32 v131, v131
	v_rcp_f32_e32 v132, v132
	v_rcp_f32_e32 v133, v133
	s_nop 0
	v_fmac_f32_e32 v134, v78, v130
	v_fmac_f32_e32 v135, v79, v131
	v_fmac_f32_e32 v136, v80, v132
	v_fmac_f32_e32 v137, v81, v133
	v_cvt_pk_bf16_f32 v78, v134, v135
	v_cvt_pk_bf16_f32 v79, v136, v137
	v_lshlrev_b32_e32 v130, 16, v212
	v_and_b32_e32 v131, 0xffff0000, v212
	v_lshlrev_b32_e32 v132, 16, v213
	v_and_b32_e32 v133, 0xffff0000, v213
	v_mul_f32_e32 v130, 0xbfb8aa3b, v130
	v_mul_f32_e32 v131, 0xbfb8aa3b, v131
	v_mul_f32_e32 v132, 0xbfb8aa3b, v132
	v_mul_f32_e32 v133, 0xbfb8aa3b, v133
	v_exp_f32_e32 v130, v130
	v_exp_f32_e32 v131, v131
	v_exp_f32_e32 v132, v132
	v_exp_f32_e32 v133, v133
	v_lshlrev_b32_e32 v134, 16, v216
	v_and_b32_e32 v135, 0xffff0000, v216
	v_lshlrev_b32_e32 v136, 16, v217
	v_and_b32_e32 v137, 0xffff0000, v217
	v_add_f32_e32 v130, 1.0, v130
	v_add_f32_e32 v131, 1.0, v131
	v_add_f32_e32 v132, 1.0, v132
	v_add_f32_e32 v133, 1.0, v133
	v_rcp_f32_e32 v130, v130
	v_rcp_f32_e32 v131, v131
	v_rcp_f32_e32 v132, v132
	v_rcp_f32_e32 v133, v133
	s_nop 0
	v_fmac_f32_e32 v134, v74, v130
	v_fmac_f32_e32 v135, v75, v131
	v_fmac_f32_e32 v136, v76, v132
	v_fmac_f32_e32 v137, v77, v133
	v_cvt_pk_bf16_f32 v80, v134, v135
	v_cvt_pk_bf16_f32 v81, v136, v137
	v_mov_b32_e32 v222, 0
	v_mov_b32_e32 v223, 0
	v_mov_b32_e32 v224, 0
	v_mov_b32_e32 v225, 0
	v_lshlrev_b32_e32 v130, 16, v218
	v_and_b32_e32 v131, 0xffff0000, v218
	v_lshlrev_b32_e32 v132, 16, v219
	v_and_b32_e32 v133, 0xffff0000, v219
	v_mul_f32_e32 v130, 0xbfb8aa3b, v130
	v_mul_f32_e32 v131, 0xbfb8aa3b, v131
	v_mul_f32_e32 v132, 0xbfb8aa3b, v132
	v_mul_f32_e32 v133, 0xbfb8aa3b, v133
	v_exp_f32_e32 v130, v130
	v_exp_f32_e32 v131, v131
	v_exp_f32_e32 v132, v132
	v_exp_f32_e32 v133, v133
	v_lshlrev_b32_e32 v134, 16, v222
	v_and_b32_e32 v135, 0xffff0000, v222
	v_lshlrev_b32_e32 v136, 16, v223
	v_and_b32_e32 v137, 0xffff0000, v223
	v_add_f32_e32 v130, 1.0, v130
	v_add_f32_e32 v131, 1.0, v131
	v_add_f32_e32 v132, 1.0, v132
	v_add_f32_e32 v133, 1.0, v133
	v_rcp_f32_e32 v130, v130
	v_rcp_f32_e32 v131, v131
	v_rcp_f32_e32 v132, v132
	v_rcp_f32_e32 v133, v133
	s_nop 0
	v_fmac_f32_e32 v134, v70, v130
	v_fmac_f32_e32 v135, v71, v131
	v_fmac_f32_e32 v136, v72, v132
	v_fmac_f32_e32 v137, v73, v133
	v_cvt_pk_bf16_f32 v70, v134, v135
	v_cvt_pk_bf16_f32 v71, v136, v137
	v_lshlrev_b32_e32 v130, 16, v220
	v_and_b32_e32 v131, 0xffff0000, v220
	v_lshlrev_b32_e32 v132, 16, v221
	v_and_b32_e32 v133, 0xffff0000, v221
	v_mul_f32_e32 v130, 0xbfb8aa3b, v130
	v_mul_f32_e32 v131, 0xbfb8aa3b, v131
	v_mul_f32_e32 v132, 0xbfb8aa3b, v132
	v_mul_f32_e32 v133, 0xbfb8aa3b, v133
	v_exp_f32_e32 v130, v130
	v_exp_f32_e32 v131, v131
	v_exp_f32_e32 v132, v132
	v_exp_f32_e32 v133, v133
	v_lshlrev_b32_e32 v134, 16, v224
	v_and_b32_e32 v135, 0xffff0000, v224
	v_lshlrev_b32_e32 v136, 16, v225
	v_and_b32_e32 v137, 0xffff0000, v225
	v_add_f32_e32 v130, 1.0, v130
	v_add_f32_e32 v131, 1.0, v131
	v_add_f32_e32 v132, 1.0, v132
	v_add_f32_e32 v133, 1.0, v133
	v_rcp_f32_e32 v130, v130
	v_rcp_f32_e32 v131, v131
	v_rcp_f32_e32 v132, v132
	v_rcp_f32_e32 v133, v133
	s_nop 0
	v_fmac_f32_e32 v134, v66, v130
	v_fmac_f32_e32 v135, v67, v131
	v_fmac_f32_e32 v136, v68, v132
	v_fmac_f32_e32 v137, v69, v133
	v_cvt_pk_bf16_f32 v72, v134, v135
	v_cvt_pk_bf16_f32 v73, v136, v137
	global_load_dwordx4 v[210:213], v[138:139], off
	global_load_dwordx4 v[218:221], v[138:139], off offset:256
	v_lshl_add_u64 v[138:139], v[138:139], 0, s[0:1]
	v_lshl_add_u64 v[140:141], v[140:141], 0, s[34:35]
	global_store_dwordx4 v[142:143], v[78:81], off sc1
	global_store_dwordx4 v[142:143], v[70:73], off offset:256 sc1
	v_lshl_add_u64 v[142:143], v[142:143], 0, s[38:39]
	s_waitcnt vmcnt(10)
	v_mov_b32_e32 v230, 0
	v_mov_b32_e32 v231, 0
	v_mov_b32_e32 v232, 0
	v_mov_b32_e32 v233, 0
	v_lshlrev_b32_e32 v130, 16, v226
	v_and_b32_e32 v131, 0xffff0000, v226
	v_lshlrev_b32_e32 v132, 16, v227
	v_and_b32_e32 v133, 0xffff0000, v227
	v_mul_f32_e32 v130, 0xbfb8aa3b, v130
	v_mul_f32_e32 v131, 0xbfb8aa3b, v131
	v_mul_f32_e32 v132, 0xbfb8aa3b, v132
	v_mul_f32_e32 v133, 0xbfb8aa3b, v133
	v_exp_f32_e32 v130, v130
	v_exp_f32_e32 v131, v131
	v_exp_f32_e32 v132, v132
	v_exp_f32_e32 v133, v133
	v_lshlrev_b32_e32 v134, 16, v230
	v_and_b32_e32 v135, 0xffff0000, v230
	v_lshlrev_b32_e32 v136, 16, v231
	v_and_b32_e32 v137, 0xffff0000, v231
	v_add_f32_e32 v130, 1.0, v130
	v_add_f32_e32 v131, 1.0, v131
	v_add_f32_e32 v132, 1.0, v132
	v_add_f32_e32 v133, 1.0, v133
	v_rcp_f32_e32 v130, v130
	v_rcp_f32_e32 v131, v131
	v_rcp_f32_e32 v132, v132
	v_rcp_f32_e32 v133, v133
	s_nop 0
	v_fmac_f32_e32 v134, v62, v130
	v_fmac_f32_e32 v135, v63, v131
	v_fmac_f32_e32 v136, v64, v132
	v_fmac_f32_e32 v137, v65, v133
	v_cvt_pk_bf16_f32 v62, v134, v135
	v_cvt_pk_bf16_f32 v63, v136, v137
	v_lshlrev_b32_e32 v130, 16, v228
	v_and_b32_e32 v131, 0xffff0000, v228
	v_lshlrev_b32_e32 v132, 16, v229
	v_and_b32_e32 v133, 0xffff0000, v229
	v_mul_f32_e32 v130, 0xbfb8aa3b, v130
	v_mul_f32_e32 v131, 0xbfb8aa3b, v131
	v_mul_f32_e32 v132, 0xbfb8aa3b, v132
	v_mul_f32_e32 v133, 0xbfb8aa3b, v133
	v_exp_f32_e32 v130, v130
	v_exp_f32_e32 v131, v131
	v_exp_f32_e32 v132, v132
	v_exp_f32_e32 v133, v133
	v_lshlrev_b32_e32 v134, 16, v232
	v_and_b32_e32 v135, 0xffff0000, v232
	v_lshlrev_b32_e32 v136, 16, v233
	v_and_b32_e32 v137, 0xffff0000, v233
	v_add_f32_e32 v130, 1.0, v130
	v_add_f32_e32 v131, 1.0, v131
	v_add_f32_e32 v132, 1.0, v132
	v_add_f32_e32 v133, 1.0, v133
	v_rcp_f32_e32 v130, v130
	v_rcp_f32_e32 v131, v131
	v_rcp_f32_e32 v132, v132
	v_rcp_f32_e32 v133, v133
	s_nop 0
	v_fmac_f32_e32 v134, v58, v130
	v_fmac_f32_e32 v135, v59, v131
	v_fmac_f32_e32 v136, v60, v132
	v_fmac_f32_e32 v137, v61, v133
	v_cvt_pk_bf16_f32 v64, v134, v135
	v_cvt_pk_bf16_f32 v65, v136, v137
	v_mov_b32_e32 v238, 0
	v_mov_b32_e32 v239, 0
	v_mov_b32_e32 v240, 0
	v_mov_b32_e32 v241, 0
	v_lshlrev_b32_e32 v130, 16, v234
	v_and_b32_e32 v131, 0xffff0000, v234
	v_lshlrev_b32_e32 v132, 16, v235
	v_and_b32_e32 v133, 0xffff0000, v235
	v_mul_f32_e32 v130, 0xbfb8aa3b, v130
	v_mul_f32_e32 v131, 0xbfb8aa3b, v131
	v_mul_f32_e32 v132, 0xbfb8aa3b, v132
	v_mul_f32_e32 v133, 0xbfb8aa3b, v133
	v_exp_f32_e32 v130, v130
	v_exp_f32_e32 v131, v131
	v_exp_f32_e32 v132, v132
	v_exp_f32_e32 v133, v133
	v_lshlrev_b32_e32 v134, 16, v238
	v_and_b32_e32 v135, 0xffff0000, v238
	v_lshlrev_b32_e32 v136, 16, v239
	v_and_b32_e32 v137, 0xffff0000, v239
	v_add_f32_e32 v130, 1.0, v130
	v_add_f32_e32 v131, 1.0, v131
	v_add_f32_e32 v132, 1.0, v132
	v_add_f32_e32 v133, 1.0, v133
	v_rcp_f32_e32 v130, v130
	v_rcp_f32_e32 v131, v131
	v_rcp_f32_e32 v132, v132
	v_rcp_f32_e32 v133, v133
	s_nop 0
	v_fmac_f32_e32 v134, v54, v130
	v_fmac_f32_e32 v135, v55, v131
	v_fmac_f32_e32 v136, v56, v132
	v_fmac_f32_e32 v137, v57, v133
	v_cvt_pk_bf16_f32 v54, v134, v135
	v_cvt_pk_bf16_f32 v55, v136, v137
	v_lshlrev_b32_e32 v130, 16, v236
	v_and_b32_e32 v131, 0xffff0000, v236
	v_lshlrev_b32_e32 v132, 16, v237
	v_and_b32_e32 v133, 0xffff0000, v237
	v_mul_f32_e32 v130, 0xbfb8aa3b, v130
	v_mul_f32_e32 v131, 0xbfb8aa3b, v131
	v_mul_f32_e32 v132, 0xbfb8aa3b, v132
	v_mul_f32_e32 v133, 0xbfb8aa3b, v133
	v_exp_f32_e32 v130, v130
	v_exp_f32_e32 v131, v131
	v_exp_f32_e32 v132, v132
	v_exp_f32_e32 v133, v133
	v_lshlrev_b32_e32 v134, 16, v240
	v_and_b32_e32 v135, 0xffff0000, v240
	v_lshlrev_b32_e32 v136, 16, v241
	v_and_b32_e32 v137, 0xffff0000, v241
	v_add_f32_e32 v130, 1.0, v130
	v_add_f32_e32 v131, 1.0, v131
	v_add_f32_e32 v132, 1.0, v132
	v_add_f32_e32 v133, 1.0, v133
	v_rcp_f32_e32 v130, v130
	v_rcp_f32_e32 v131, v131
	v_rcp_f32_e32 v132, v132
	v_rcp_f32_e32 v133, v133
	s_nop 0
	v_fmac_f32_e32 v134, v50, v130
	v_fmac_f32_e32 v135, v51, v131
	v_fmac_f32_e32 v136, v52, v132
	v_fmac_f32_e32 v137, v53, v133
	v_cvt_pk_bf16_f32 v56, v134, v135
	v_cvt_pk_bf16_f32 v57, v136, v137
	global_load_dwordx4 v[226:229], v[138:139], off
	global_load_dwordx4 v[234:237], v[138:139], off offset:256
	global_store_dwordx4 v[142:143], v[62:65], off sc1
	global_store_dwordx4 v[142:143], v[54:57], off offset:256 sc1
	v_lshl_add_u64 v[142:143], v[142:143], 0, s[34:35]
	s_waitcnt vmcnt(10)
	v_mov_b32_e32 v186, 0
	v_mov_b32_e32 v187, 0
	v_mov_b32_e32 v188, 0
	v_mov_b32_e32 v189, 0
	v_lshlrev_b32_e32 v130, 16, v182
	v_and_b32_e32 v131, 0xffff0000, v182
	v_lshlrev_b32_e32 v132, 16, v183
	v_and_b32_e32 v133, 0xffff0000, v183
	v_mul_f32_e32 v130, 0xbfb8aa3b, v130
	v_mul_f32_e32 v131, 0xbfb8aa3b, v131
	v_mul_f32_e32 v132, 0xbfb8aa3b, v132
	v_mul_f32_e32 v133, 0xbfb8aa3b, v133
	v_exp_f32_e32 v130, v130
	v_exp_f32_e32 v131, v131
	v_exp_f32_e32 v132, v132
	v_exp_f32_e32 v133, v133
	v_lshlrev_b32_e32 v134, 16, v186
	v_and_b32_e32 v135, 0xffff0000, v186
	v_lshlrev_b32_e32 v136, 16, v187
	v_and_b32_e32 v137, 0xffff0000, v187
	v_add_f32_e32 v130, 1.0, v130
	v_add_f32_e32 v131, 1.0, v131
	v_add_f32_e32 v132, 1.0, v132
	v_add_f32_e32 v133, 1.0, v133
	v_rcp_f32_e32 v130, v130
	v_rcp_f32_e32 v131, v131
	v_rcp_f32_e32 v132, v132
	v_rcp_f32_e32 v133, v133
	s_nop 0
	v_fmac_f32_e32 v134, v46, v130
	v_fmac_f32_e32 v135, v47, v131
	v_fmac_f32_e32 v136, v48, v132
	v_fmac_f32_e32 v137, v49, v133
	v_cvt_pk_bf16_f32 v46, v134, v135
	v_cvt_pk_bf16_f32 v47, v136, v137
	v_lshlrev_b32_e32 v130, 16, v184
	v_and_b32_e32 v131, 0xffff0000, v184
	v_lshlrev_b32_e32 v132, 16, v185
	v_and_b32_e32 v133, 0xffff0000, v185
	v_mul_f32_e32 v130, 0xbfb8aa3b, v130
	v_mul_f32_e32 v131, 0xbfb8aa3b, v131
	v_mul_f32_e32 v132, 0xbfb8aa3b, v132
	v_mul_f32_e32 v133, 0xbfb8aa3b, v133
	v_exp_f32_e32 v130, v130
	v_exp_f32_e32 v131, v131
	v_exp_f32_e32 v132, v132
	v_exp_f32_e32 v133, v133
	v_lshlrev_b32_e32 v134, 16, v188
	v_and_b32_e32 v135, 0xffff0000, v188
	v_lshlrev_b32_e32 v136, 16, v189
	v_and_b32_e32 v137, 0xffff0000, v189
	v_add_f32_e32 v130, 1.0, v130
	v_add_f32_e32 v131, 1.0, v131
	v_add_f32_e32 v132, 1.0, v132
	v_add_f32_e32 v133, 1.0, v133
	v_rcp_f32_e32 v130, v130
	v_rcp_f32_e32 v131, v131
	v_rcp_f32_e32 v132, v132
	v_rcp_f32_e32 v133, v133
	s_nop 0
	v_fmac_f32_e32 v134, v42, v130
	v_fmac_f32_e32 v135, v43, v131
	v_fmac_f32_e32 v136, v44, v132
	v_fmac_f32_e32 v137, v45, v133
	v_cvt_pk_bf16_f32 v48, v134, v135
	v_cvt_pk_bf16_f32 v49, v136, v137
	v_mov_b32_e32 v242, 0
	v_mov_b32_e32 v243, 0
	v_mov_b32_e32 v244, 0
	v_mov_b32_e32 v245, 0
	v_lshlrev_b32_e32 v130, 16, v190
	v_and_b32_e32 v131, 0xffff0000, v190
	v_lshlrev_b32_e32 v132, 16, v191
	v_and_b32_e32 v133, 0xffff0000, v191
	v_mul_f32_e32 v130, 0xbfb8aa3b, v130
	v_mul_f32_e32 v131, 0xbfb8aa3b, v131
	v_mul_f32_e32 v132, 0xbfb8aa3b, v132
	v_mul_f32_e32 v133, 0xbfb8aa3b, v133
	v_exp_f32_e32 v130, v130
	v_exp_f32_e32 v131, v131
	v_exp_f32_e32 v132, v132
	v_exp_f32_e32 v133, v133
	v_lshlrev_b32_e32 v134, 16, v242
	v_and_b32_e32 v135, 0xffff0000, v242
	v_lshlrev_b32_e32 v136, 16, v243
	v_and_b32_e32 v137, 0xffff0000, v243
	v_add_f32_e32 v130, 1.0, v130
	v_add_f32_e32 v131, 1.0, v131
	v_add_f32_e32 v132, 1.0, v132
	v_add_f32_e32 v133, 1.0, v133
	v_rcp_f32_e32 v130, v130
	v_rcp_f32_e32 v131, v131
	v_rcp_f32_e32 v132, v132
	v_rcp_f32_e32 v133, v133
	s_nop 0
	v_fmac_f32_e32 v134, v38, v130
	v_fmac_f32_e32 v135, v39, v131
	v_fmac_f32_e32 v136, v40, v132
	v_fmac_f32_e32 v137, v41, v133
	v_cvt_pk_bf16_f32 v38, v134, v135
	v_cvt_pk_bf16_f32 v39, v136, v137
	v_lshlrev_b32_e32 v130, 16, v192
	v_and_b32_e32 v131, 0xffff0000, v192
	v_lshlrev_b32_e32 v132, 16, v193
	v_and_b32_e32 v133, 0xffff0000, v193
	v_mul_f32_e32 v130, 0xbfb8aa3b, v130
	v_mul_f32_e32 v131, 0xbfb8aa3b, v131
	v_mul_f32_e32 v132, 0xbfb8aa3b, v132
	v_mul_f32_e32 v133, 0xbfb8aa3b, v133
	v_exp_f32_e32 v130, v130
	v_exp_f32_e32 v131, v131
	v_exp_f32_e32 v132, v132
	v_exp_f32_e32 v133, v133
	v_lshlrev_b32_e32 v134, 16, v244
	v_and_b32_e32 v135, 0xffff0000, v244
	v_lshlrev_b32_e32 v136, 16, v245
	v_and_b32_e32 v137, 0xffff0000, v245
	v_add_f32_e32 v130, 1.0, v130
	v_add_f32_e32 v131, 1.0, v131
	v_add_f32_e32 v132, 1.0, v132
	v_add_f32_e32 v133, 1.0, v133
	v_rcp_f32_e32 v130, v130
	v_rcp_f32_e32 v131, v131
	v_rcp_f32_e32 v132, v132
	v_rcp_f32_e32 v133, v133
	s_nop 0
	v_fmac_f32_e32 v134, v34, v130
	v_fmac_f32_e32 v135, v35, v131
	v_fmac_f32_e32 v136, v36, v132
	v_fmac_f32_e32 v137, v37, v133
	v_cvt_pk_bf16_f32 v40, v134, v135
	v_cvt_pk_bf16_f32 v41, v136, v137
	global_store_dwordx4 v[142:143], v[46:49], off sc1
	global_store_dwordx4 v[142:143], v[38:41], off offset:256 sc1
	v_lshl_add_u64 v[142:143], v[142:143], 0, s[34:35]
	s_waitcnt vmcnt(8)
	v_mov_b32_e32 v214, 0
	v_mov_b32_e32 v215, 0
	v_mov_b32_e32 v216, 0
	v_mov_b32_e32 v217, 0
	v_lshlrev_b32_e32 v130, 16, v210
	v_and_b32_e32 v131, 0xffff0000, v210
	v_lshlrev_b32_e32 v132, 16, v211
	v_and_b32_e32 v133, 0xffff0000, v211
	v_mul_f32_e32 v130, 0xbfb8aa3b, v130
	v_mul_f32_e32 v131, 0xbfb8aa3b, v131
	v_mul_f32_e32 v132, 0xbfb8aa3b, v132
	v_mul_f32_e32 v133, 0xbfb8aa3b, v133
	v_exp_f32_e32 v130, v130
	v_exp_f32_e32 v131, v131
	v_exp_f32_e32 v132, v132
	v_exp_f32_e32 v133, v133
	v_lshlrev_b32_e32 v134, 16, v214
	v_and_b32_e32 v135, 0xffff0000, v214
	v_lshlrev_b32_e32 v136, 16, v215
	v_and_b32_e32 v137, 0xffff0000, v215
	v_add_f32_e32 v130, 1.0, v130
	v_add_f32_e32 v131, 1.0, v131
	v_add_f32_e32 v132, 1.0, v132
	v_add_f32_e32 v133, 1.0, v133
	v_rcp_f32_e32 v130, v130
	v_rcp_f32_e32 v131, v131
	v_rcp_f32_e32 v132, v132
	v_rcp_f32_e32 v133, v133
	s_nop 0
	v_fmac_f32_e32 v134, v30, v130
	v_fmac_f32_e32 v135, v31, v131
	v_fmac_f32_e32 v136, v32, v132
	v_fmac_f32_e32 v137, v33, v133
	v_cvt_pk_bf16_f32 v30, v134, v135
	v_cvt_pk_bf16_f32 v31, v136, v137
	v_lshlrev_b32_e32 v130, 16, v212
	v_and_b32_e32 v131, 0xffff0000, v212
	v_lshlrev_b32_e32 v132, 16, v213
	v_and_b32_e32 v133, 0xffff0000, v213
	v_mul_f32_e32 v130, 0xbfb8aa3b, v130
	v_mul_f32_e32 v131, 0xbfb8aa3b, v131
	v_mul_f32_e32 v132, 0xbfb8aa3b, v132
	v_mul_f32_e32 v133, 0xbfb8aa3b, v133
	v_exp_f32_e32 v130, v130
	v_exp_f32_e32 v131, v131
	v_exp_f32_e32 v132, v132
	v_exp_f32_e32 v133, v133
	v_lshlrev_b32_e32 v134, 16, v216
	v_and_b32_e32 v135, 0xffff0000, v216
	v_lshlrev_b32_e32 v136, 16, v217
	v_and_b32_e32 v137, 0xffff0000, v217
	v_add_f32_e32 v130, 1.0, v130
	v_add_f32_e32 v131, 1.0, v131
	v_add_f32_e32 v132, 1.0, v132
	v_add_f32_e32 v133, 1.0, v133
	v_rcp_f32_e32 v130, v130
	v_rcp_f32_e32 v131, v131
	v_rcp_f32_e32 v132, v132
	v_rcp_f32_e32 v133, v133
	s_nop 0
	v_fmac_f32_e32 v134, v26, v130
	v_fmac_f32_e32 v135, v27, v131
	v_fmac_f32_e32 v136, v28, v132
	v_fmac_f32_e32 v137, v29, v133
	v_cvt_pk_bf16_f32 v32, v134, v135
	v_cvt_pk_bf16_f32 v33, v136, v137
	v_mov_b32_e32 v222, 0
	v_mov_b32_e32 v223, 0
	v_mov_b32_e32 v224, 0
	v_mov_b32_e32 v225, 0
	v_lshlrev_b32_e32 v130, 16, v218
	v_and_b32_e32 v131, 0xffff0000, v218
	v_lshlrev_b32_e32 v132, 16, v219
	v_and_b32_e32 v133, 0xffff0000, v219
	v_mul_f32_e32 v130, 0xbfb8aa3b, v130
	v_mul_f32_e32 v131, 0xbfb8aa3b, v131
	v_mul_f32_e32 v132, 0xbfb8aa3b, v132
	v_mul_f32_e32 v133, 0xbfb8aa3b, v133
	v_exp_f32_e32 v130, v130
	v_exp_f32_e32 v131, v131
	v_exp_f32_e32 v132, v132
	v_exp_f32_e32 v133, v133
	v_lshlrev_b32_e32 v134, 16, v222
	v_and_b32_e32 v135, 0xffff0000, v222
	v_lshlrev_b32_e32 v136, 16, v223
	v_and_b32_e32 v137, 0xffff0000, v223
	v_add_f32_e32 v130, 1.0, v130
	v_add_f32_e32 v131, 1.0, v131
	v_add_f32_e32 v132, 1.0, v132
	v_add_f32_e32 v133, 1.0, v133
	v_rcp_f32_e32 v130, v130
	v_rcp_f32_e32 v131, v131
	v_rcp_f32_e32 v132, v132
	v_rcp_f32_e32 v133, v133
	s_nop 0
	v_fmac_f32_e32 v134, v22, v130
	v_fmac_f32_e32 v135, v23, v131
	v_fmac_f32_e32 v136, v24, v132
	v_fmac_f32_e32 v137, v25, v133
	v_cvt_pk_bf16_f32 v22, v134, v135
	v_cvt_pk_bf16_f32 v23, v136, v137
	v_lshlrev_b32_e32 v130, 16, v220
	v_and_b32_e32 v131, 0xffff0000, v220
	v_lshlrev_b32_e32 v132, 16, v221
	v_and_b32_e32 v133, 0xffff0000, v221
	v_mul_f32_e32 v130, 0xbfb8aa3b, v130
	v_mul_f32_e32 v131, 0xbfb8aa3b, v131
	v_mul_f32_e32 v132, 0xbfb8aa3b, v132
	v_mul_f32_e32 v133, 0xbfb8aa3b, v133
	v_exp_f32_e32 v130, v130
	v_exp_f32_e32 v131, v131
	v_exp_f32_e32 v132, v132
	v_exp_f32_e32 v133, v133
	v_lshlrev_b32_e32 v134, 16, v224
	v_and_b32_e32 v135, 0xffff0000, v224
	v_lshlrev_b32_e32 v136, 16, v225
	v_and_b32_e32 v137, 0xffff0000, v225
	v_add_f32_e32 v130, 1.0, v130
	v_add_f32_e32 v131, 1.0, v131
	v_add_f32_e32 v132, 1.0, v132
	v_add_f32_e32 v133, 1.0, v133
	v_rcp_f32_e32 v130, v130
	v_rcp_f32_e32 v131, v131
	v_rcp_f32_e32 v132, v132
	v_rcp_f32_e32 v133, v133
	s_nop 0
	v_fmac_f32_e32 v134, v18, v130
	v_fmac_f32_e32 v135, v19, v131
	v_fmac_f32_e32 v136, v20, v132
	v_fmac_f32_e32 v137, v21, v133
	v_cvt_pk_bf16_f32 v24, v134, v135
	v_cvt_pk_bf16_f32 v25, v136, v137
	global_store_dwordx4 v[142:143], v[30:33], off sc1
	global_store_dwordx4 v[142:143], v[22:25], off offset:256 sc1
	v_lshl_add_u64 v[142:143], v[142:143], 0, s[34:35]
	s_waitcnt vmcnt(6)
	v_mov_b32_e32 v230, 0
	v_mov_b32_e32 v231, 0
	v_mov_b32_e32 v232, 0
	v_mov_b32_e32 v233, 0
	v_lshlrev_b32_e32 v130, 16, v226
	v_and_b32_e32 v131, 0xffff0000, v226
	v_lshlrev_b32_e32 v132, 16, v227
	v_and_b32_e32 v133, 0xffff0000, v227
	v_mul_f32_e32 v130, 0xbfb8aa3b, v130
	v_mul_f32_e32 v131, 0xbfb8aa3b, v131
	v_mul_f32_e32 v132, 0xbfb8aa3b, v132
	v_mul_f32_e32 v133, 0xbfb8aa3b, v133
	v_exp_f32_e32 v130, v130
	v_exp_f32_e32 v131, v131
	v_exp_f32_e32 v132, v132
	v_exp_f32_e32 v133, v133
	v_lshlrev_b32_e32 v134, 16, v230
	v_and_b32_e32 v135, 0xffff0000, v230
	v_lshlrev_b32_e32 v136, 16, v231
	v_and_b32_e32 v137, 0xffff0000, v231
	v_add_f32_e32 v130, 1.0, v130
	v_add_f32_e32 v131, 1.0, v131
	v_add_f32_e32 v132, 1.0, v132
	v_add_f32_e32 v133, 1.0, v133
	v_rcp_f32_e32 v130, v130
	v_rcp_f32_e32 v131, v131
	v_rcp_f32_e32 v132, v132
	v_rcp_f32_e32 v133, v133
	s_nop 0
	v_fmac_f32_e32 v134, v14, v130
	v_fmac_f32_e32 v135, v15, v131
	v_fmac_f32_e32 v136, v16, v132
	v_fmac_f32_e32 v137, v17, v133
	v_cvt_pk_bf16_f32 v14, v134, v135
	v_cvt_pk_bf16_f32 v15, v136, v137
	v_lshlrev_b32_e32 v130, 16, v228
	v_and_b32_e32 v131, 0xffff0000, v228
	v_lshlrev_b32_e32 v132, 16, v229
	v_and_b32_e32 v133, 0xffff0000, v229
	v_mul_f32_e32 v130, 0xbfb8aa3b, v130
	v_mul_f32_e32 v131, 0xbfb8aa3b, v131
	v_mul_f32_e32 v132, 0xbfb8aa3b, v132
	v_mul_f32_e32 v133, 0xbfb8aa3b, v133
	v_exp_f32_e32 v130, v130
	v_exp_f32_e32 v131, v131
	v_exp_f32_e32 v132, v132
	v_exp_f32_e32 v133, v133
	v_lshlrev_b32_e32 v134, 16, v232
	v_and_b32_e32 v135, 0xffff0000, v232
	v_lshlrev_b32_e32 v136, 16, v233
	v_and_b32_e32 v137, 0xffff0000, v233
	v_add_f32_e32 v130, 1.0, v130
	v_add_f32_e32 v131, 1.0, v131
	v_add_f32_e32 v132, 1.0, v132
	v_add_f32_e32 v133, 1.0, v133
	v_rcp_f32_e32 v130, v130
	v_rcp_f32_e32 v131, v131
	v_rcp_f32_e32 v132, v132
	v_rcp_f32_e32 v133, v133
	s_nop 0
	v_fmac_f32_e32 v134, v10, v130
	v_fmac_f32_e32 v135, v11, v131
	v_fmac_f32_e32 v136, v12, v132
	v_fmac_f32_e32 v137, v13, v133
	v_cvt_pk_bf16_f32 v16, v134, v135
	v_cvt_pk_bf16_f32 v17, v136, v137
	v_mov_b32_e32 v238, 0
	v_mov_b32_e32 v239, 0
	v_mov_b32_e32 v240, 0
	v_mov_b32_e32 v241, 0
	v_lshlrev_b32_e32 v130, 16, v234
	v_and_b32_e32 v131, 0xffff0000, v234
	v_lshlrev_b32_e32 v132, 16, v235
	v_and_b32_e32 v133, 0xffff0000, v235
	v_mul_f32_e32 v130, 0xbfb8aa3b, v130
	v_mul_f32_e32 v131, 0xbfb8aa3b, v131
	v_mul_f32_e32 v132, 0xbfb8aa3b, v132
	v_mul_f32_e32 v133, 0xbfb8aa3b, v133
	v_exp_f32_e32 v130, v130
	v_exp_f32_e32 v131, v131
	v_exp_f32_e32 v132, v132
	v_exp_f32_e32 v133, v133
	v_lshlrev_b32_e32 v134, 16, v238
	v_and_b32_e32 v135, 0xffff0000, v238
	v_lshlrev_b32_e32 v136, 16, v239
	v_and_b32_e32 v137, 0xffff0000, v239
	v_add_f32_e32 v130, 1.0, v130
	v_add_f32_e32 v131, 1.0, v131
	v_add_f32_e32 v132, 1.0, v132
	v_add_f32_e32 v133, 1.0, v133
	v_rcp_f32_e32 v130, v130
	v_rcp_f32_e32 v131, v131
	v_rcp_f32_e32 v132, v132
	v_rcp_f32_e32 v133, v133
	s_nop 0
	v_fmac_f32_e32 v134, v6, v130
	v_fmac_f32_e32 v135, v7, v131
	v_fmac_f32_e32 v136, v8, v132
	v_fmac_f32_e32 v137, v9, v133
	v_cvt_pk_bf16_f32 v6, v134, v135
	v_cvt_pk_bf16_f32 v7, v136, v137
	v_lshlrev_b32_e32 v130, 16, v236
	v_and_b32_e32 v131, 0xffff0000, v236
	v_lshlrev_b32_e32 v132, 16, v237
	v_and_b32_e32 v133, 0xffff0000, v237
	v_mul_f32_e32 v130, 0xbfb8aa3b, v130
	v_mul_f32_e32 v131, 0xbfb8aa3b, v131
	v_mul_f32_e32 v132, 0xbfb8aa3b, v132
	v_mul_f32_e32 v133, 0xbfb8aa3b, v133
	v_exp_f32_e32 v130, v130
	v_exp_f32_e32 v131, v131
	v_exp_f32_e32 v132, v132
	v_exp_f32_e32 v133, v133
	v_lshlrev_b32_e32 v134, 16, v240
	v_and_b32_e32 v135, 0xffff0000, v240
	v_lshlrev_b32_e32 v136, 16, v241
	v_and_b32_e32 v137, 0xffff0000, v241
	v_add_f32_e32 v130, 1.0, v130
	v_add_f32_e32 v131, 1.0, v131
	v_add_f32_e32 v132, 1.0, v132
	v_add_f32_e32 v133, 1.0, v133
	v_rcp_f32_e32 v130, v130
	v_rcp_f32_e32 v131, v131
	v_rcp_f32_e32 v132, v132
	v_rcp_f32_e32 v133, v133
	s_nop 0
	v_fmac_f32_e32 v134, v2, v130
	v_fmac_f32_e32 v135, v3, v131
	v_fmac_f32_e32 v136, v4, v132
	v_fmac_f32_e32 v137, v5, v133
	v_cvt_pk_bf16_f32 v8, v134, v135
	v_cvt_pk_bf16_f32 v9, v136, v137
	global_store_dwordx4 v[142:143], v[14:17], off sc1
	global_store_dwordx4 v[142:143], v[6:9], off offset:256 sc1

.LBB0_376:
	s_add_u32 s8, s75, 0x40080
	s_addc_u32 s9, s23, 0
	s_mov_b32 m0, s69
	s_nop 0
	global_load_lds_dwordx4 v136, s[8:9]
	v_lshl_add_u32 v147, s74, 10, v143
	s_mov_b32 m0, s70
	s_nop 0
	global_load_lds_dwordx4 v138, s[8:9]
	ds_read_b32 v148, v147
	v_lshl_or_b32 v132, s36, 8, v144
	v_lshl_add_u32 v149, s38, 8, v142
	v_ashrrev_i32_e32 v133, 31, v132
	v_mov_b64_e32 v[130:131], s[26:27]
	v_mad_i64_i32 v[150:151], s[8:9], v149, s83, v[130:131]
	v_lshlrev_b64 v[132:133], 1, v[132:133]
	v_lshl_add_u64 v[150:151], v[150:151], 0, v[132:133]
	s_waitcnt lgkmcnt(0)
	v_pk_mul_f32 v[128:129], v[128:129], v[148:149] op_sel_hi:[1,0]
	v_pk_mul_f32 v[126:127], v[126:127], v[148:149] op_sel_hi:[1,0]
	v_pk_mul_f32 v[152:153], v[124:125], v[148:149] op_sel_hi:[1,0]
	v_pk_mul_f32 v[124:125], v[122:123], v[148:149] op_sel_hi:[1,0]
	v_cvt_pk_bf16_f32 v122, v126, v127
	v_cvt_pk_bf16_f32 v123, v128, v129
	v_pk_mul_f32 v[118:119], v[118:119], v[148:149] op_sel_hi:[1,0]
	v_cvt_pk_bf16_f32 v124, v124, v125
	v_cvt_pk_bf16_f32 v125, v152, v153
	global_store_dwordx4 v[150:151], v[122:125], off sc1
	v_pk_mul_f32 v[120:121], v[120:121], v[148:149] op_sel_hi:[1,0]
	s_andn2_b64 vcc, exec, s[4:5]
	v_pk_mul_f32 v[122:123], v[116:117], v[148:149] op_sel_hi:[1,0]
	v_pk_mul_f32 v[116:117], v[114:115], v[148:149] op_sel_hi:[1,0]
	v_cvt_pk_bf16_f32 v114, v118, v119
	v_cvt_pk_bf16_f32 v115, v120, v121
	s_mov_b64 s[4:5], -1
	v_cvt_pk_bf16_f32 v116, v116, v117
	v_cvt_pk_bf16_f32 v117, v122, v123
	global_store_dwordx4 v[150:151], v[114:117], off offset:256 sc1
	ds_read_b32 v114, v147 offset:64
	s_nop 0
	v_or_b32_e32 v115, 16, v149
	v_mad_i64_i32 v[116:117], s[8:9], v115, s83, v[130:131]
	v_lshl_add_u64 v[116:117], v[116:117], 0, v[132:133]
	s_waitcnt lgkmcnt(0)
	v_pk_mul_f32 v[112:113], v[112:113], v[114:115] op_sel_hi:[1,0]
	v_pk_mul_f32 v[110:111], v[110:111], v[114:115] op_sel_hi:[1,0]
	v_pk_mul_f32 v[118:119], v[108:109], v[114:115] op_sel_hi:[1,0]
	v_pk_mul_f32 v[108:109], v[106:107], v[114:115] op_sel_hi:[1,0]
	v_cvt_pk_bf16_f32 v106, v110, v111
	v_cvt_pk_bf16_f32 v107, v112, v113
	v_pk_mul_f32 v[102:103], v[102:103], v[114:115] op_sel_hi:[1,0]
	v_cvt_pk_bf16_f32 v108, v108, v109
	v_cvt_pk_bf16_f32 v109, v118, v119
	global_store_dwordx4 v[116:117], v[106:109], off sc1
	v_pk_mul_f32 v[104:105], v[104:105], v[114:115] op_sel_hi:[1,0]
	s_nop 0
	v_pk_mul_f32 v[106:107], v[100:101], v[114:115] op_sel_hi:[1,0]
	v_pk_mul_f32 v[100:101], v[98:99], v[114:115] op_sel_hi:[1,0]
	v_cvt_pk_bf16_f32 v98, v102, v103
	v_cvt_pk_bf16_f32 v99, v104, v105
	s_nop 0
	v_cvt_pk_bf16_f32 v100, v100, v101
	v_cvt_pk_bf16_f32 v101, v106, v107
	global_store_dwordx4 v[116:117], v[98:101], off offset:256 sc1
	ds_read_b32 v98, v147 offset:128
	s_nop 0
	v_or_b32_e32 v99, 32, v149
	v_mad_i64_i32 v[100:101], s[8:9], v99, s83, v[130:131]
	v_lshl_add_u64 v[100:101], v[100:101], 0, v[132:133]
	s_waitcnt lgkmcnt(0)
	v_pk_mul_f32 v[96:97], v[96:97], v[98:99] op_sel_hi:[1,0]
	v_pk_mul_f32 v[94:95], v[94:95], v[98:99] op_sel_hi:[1,0]
	v_pk_mul_f32 v[102:103], v[92:93], v[98:99] op_sel_hi:[1,0]
	v_pk_mul_f32 v[92:93], v[90:91], v[98:99] op_sel_hi:[1,0]
	v_cvt_pk_bf16_f32 v90, v94, v95
	v_cvt_pk_bf16_f32 v91, v96, v97
	v_pk_mul_f32 v[86:87], v[86:87], v[98:99] op_sel_hi:[1,0]
	v_cvt_pk_bf16_f32 v92, v92, v93
	v_cvt_pk_bf16_f32 v93, v102, v103
	global_store_dwordx4 v[100:101], v[90:93], off sc1
	v_pk_mul_f32 v[88:89], v[88:89], v[98:99] op_sel_hi:[1,0]
	s_nop 0
	v_pk_mul_f32 v[90:91], v[84:85], v[98:99] op_sel_hi:[1,0]
	v_pk_mul_f32 v[84:85], v[82:83], v[98:99] op_sel_hi:[1,0]
	v_cvt_pk_bf16_f32 v82, v86, v87
	v_cvt_pk_bf16_f32 v83, v88, v89
	s_nop 0
	v_cvt_pk_bf16_f32 v84, v84, v85
	v_cvt_pk_bf16_f32 v85, v90, v91
	global_store_dwordx4 v[100:101], v[82:85], off offset:256 sc1
	ds_read_b32 v82, v147 offset:192
	s_nop 0
	v_or_b32_e32 v83, 48, v149
	v_mad_i64_i32 v[84:85], s[8:9], v83, s83, v[130:131]
	v_lshl_add_u64 v[84:85], v[84:85], 0, v[132:133]
	s_waitcnt lgkmcnt(0)
	v_pk_mul_f32 v[80:81], v[80:81], v[82:83] op_sel_hi:[1,0]
	v_pk_mul_f32 v[78:79], v[78:79], v[82:83] op_sel_hi:[1,0]
	v_pk_mul_f32 v[86:87], v[76:77], v[82:83] op_sel_hi:[1,0]
	v_pk_mul_f32 v[76:77], v[74:75], v[82:83] op_sel_hi:[1,0]
	v_cvt_pk_bf16_f32 v74, v78, v79
	v_cvt_pk_bf16_f32 v75, v80, v81
	v_pk_mul_f32 v[70:71], v[70:71], v[82:83] op_sel_hi:[1,0]
	v_cvt_pk_bf16_f32 v76, v76, v77
	v_cvt_pk_bf16_f32 v77, v86, v87
	global_store_dwordx4 v[84:85], v[74:77], off sc1
	v_pk_mul_f32 v[72:73], v[72:73], v[82:83] op_sel_hi:[1,0]
	s_nop 0
	v_pk_mul_f32 v[74:75], v[68:69], v[82:83] op_sel_hi:[1,0]
	v_pk_mul_f32 v[68:69], v[66:67], v[82:83] op_sel_hi:[1,0]
	v_cvt_pk_bf16_f32 v66, v70, v71
	v_cvt_pk_bf16_f32 v67, v72, v73
	s_nop 0
	v_cvt_pk_bf16_f32 v68, v68, v69
	v_cvt_pk_bf16_f32 v69, v74, v75
	global_store_dwordx4 v[84:85], v[66:69], off offset:256 sc1
	ds_read_b32 v66, v147 offset:512
	s_nop 0
	v_add_u32_e32 v67, 0x80, v149
	v_mad_i64_i32 v[68:69], s[8:9], v67, s83, v[130:131]
	v_lshl_add_u64 v[68:69], v[68:69], 0, v[132:133]
	s_waitcnt lgkmcnt(0)
	v_pk_mul_f32 v[64:65], v[64:65], v[66:67] op_sel_hi:[1,0]
	v_pk_mul_f32 v[62:63], v[62:63], v[66:67] op_sel_hi:[1,0]
	v_pk_mul_f32 v[70:71], v[60:61], v[66:67] op_sel_hi:[1,0]
	v_pk_mul_f32 v[60:61], v[58:59], v[66:67] op_sel_hi:[1,0]
	v_cvt_pk_bf16_f32 v58, v62, v63
	v_cvt_pk_bf16_f32 v59, v64, v65
	v_pk_mul_f32 v[54:55], v[54:55], v[66:67] op_sel_hi:[1,0]
	v_cvt_pk_bf16_f32 v60, v60, v61
	v_cvt_pk_bf16_f32 v61, v70, v71
	global_store_dwordx4 v[68:69], v[58:61], off sc1
	v_pk_mul_f32 v[56:57], v[56:57], v[66:67] op_sel_hi:[1,0]
	s_nop 0
	v_pk_mul_f32 v[58:59], v[52:53], v[66:67] op_sel_hi:[1,0]
	v_pk_mul_f32 v[52:53], v[50:51], v[66:67] op_sel_hi:[1,0]
	v_cvt_pk_bf16_f32 v50, v54, v55
	v_cvt_pk_bf16_f32 v51, v56, v57
	s_nop 0
	v_cvt_pk_bf16_f32 v52, v52, v53
	v_cvt_pk_bf16_f32 v53, v58, v59
	global_store_dwordx4 v[68:69], v[50:53], off offset:256 sc1
	ds_read_b32 v50, v147 offset:576
	s_nop 0
	v_add_u32_e32 v51, 0x90, v149
	v_mad_i64_i32 v[52:53], s[8:9], v51, s83, v[130:131]
	v_lshl_add_u64 v[52:53], v[52:53], 0, v[132:133]
	s_waitcnt lgkmcnt(0)
	v_pk_mul_f32 v[48:49], v[48:49], v[50:51] op_sel_hi:[1,0]
	v_pk_mul_f32 v[46:47], v[46:47], v[50:51] op_sel_hi:[1,0]
	v_pk_mul_f32 v[54:55], v[44:45], v[50:51] op_sel_hi:[1,0]
	v_pk_mul_f32 v[44:45], v[42:43], v[50:51] op_sel_hi:[1,0]
	v_cvt_pk_bf16_f32 v42, v46, v47
	v_cvt_pk_bf16_f32 v43, v48, v49
	v_pk_mul_f32 v[38:39], v[38:39], v[50:51] op_sel_hi:[1,0]
	v_cvt_pk_bf16_f32 v44, v44, v45
	v_cvt_pk_bf16_f32 v45, v54, v55
	global_store_dwordx4 v[52:53], v[42:45], off sc1
	v_pk_mul_f32 v[40:41], v[40:41], v[50:51] op_sel_hi:[1,0]
	s_nop 0
	v_pk_mul_f32 v[42:43], v[36:37], v[50:51] op_sel_hi:[1,0]
	v_pk_mul_f32 v[36:37], v[34:35], v[50:51] op_sel_hi:[1,0]
	v_cvt_pk_bf16_f32 v34, v38, v39
	v_cvt_pk_bf16_f32 v35, v40, v41
	s_nop 0
	v_cvt_pk_bf16_f32 v36, v36, v37
	v_cvt_pk_bf16_f32 v37, v42, v43
	global_store_dwordx4 v[52:53], v[34:37], off offset:256 sc1
	ds_read_b32 v34, v147 offset:640
	s_nop 0
	v_add_u32_e32 v35, 0xa0, v149
	v_mad_i64_i32 v[36:37], s[8:9], v35, s83, v[130:131]
	v_lshl_add_u64 v[36:37], v[36:37], 0, v[132:133]
	s_waitcnt lgkmcnt(0)
	v_pk_mul_f32 v[32:33], v[32:33], v[34:35] op_sel_hi:[1,0]
	v_pk_mul_f32 v[30:31], v[30:31], v[34:35] op_sel_hi:[1,0]
	v_pk_mul_f32 v[38:39], v[28:29], v[34:35] op_sel_hi:[1,0]
	v_pk_mul_f32 v[28:29], v[26:27], v[34:35] op_sel_hi:[1,0]
	v_cvt_pk_bf16_f32 v26, v30, v31
	v_cvt_pk_bf16_f32 v27, v32, v33
	v_pk_mul_f32 v[22:23], v[22:23], v[34:35] op_sel_hi:[1,0]
	v_cvt_pk_bf16_f32 v28, v28, v29
	v_cvt_pk_bf16_f32 v29, v38, v39
	global_store_dwordx4 v[36:37], v[26:29], off sc1
	v_pk_mul_f32 v[24:25], v[24:25], v[34:35] op_sel_hi:[1,0]
	s_nop 0
	v_pk_mul_f32 v[26:27], v[20:21], v[34:35] op_sel_hi:[1,0]
	v_pk_mul_f32 v[20:21], v[18:19], v[34:35] op_sel_hi:[1,0]
	v_cvt_pk_bf16_f32 v18, v22, v23
	v_cvt_pk_bf16_f32 v19, v24, v25
	s_nop 0
	v_cvt_pk_bf16_f32 v20, v20, v21
	v_cvt_pk_bf16_f32 v21, v26, v27
	global_store_dwordx4 v[36:37], v[18:21], off offset:256 sc1
	ds_read_b32 v18, v147 offset:704
	s_nop 0
	v_add_u32_e32 v19, 0xb0, v149
	v_mad_i64_i32 v[20:21], s[8:9], v19, s83, v[130:131]
	v_lshl_add_u64 v[20:21], v[20:21], 0, v[132:133]
	s_waitcnt lgkmcnt(0)
	v_pk_mul_f32 v[16:17], v[16:17], v[18:19] op_sel_hi:[1,0]
	v_pk_mul_f32 v[14:15], v[14:15], v[18:19] op_sel_hi:[1,0]
	v_pk_mul_f32 v[22:23], v[12:13], v[18:19] op_sel_hi:[1,0]
	v_pk_mul_f32 v[12:13], v[10:11], v[18:19] op_sel_hi:[1,0]
	v_cvt_pk_bf16_f32 v10, v14, v15
	v_cvt_pk_bf16_f32 v11, v16, v17
	v_pk_mul_f32 v[8:9], v[8:9], v[18:19] op_sel_hi:[1,0]
	v_cvt_pk_bf16_f32 v12, v12, v13
	v_cvt_pk_bf16_f32 v13, v22, v23
	global_store_dwordx4 v[20:21], v[10:13], off sc1
	v_pk_mul_f32 v[6:7], v[6:7], v[18:19] op_sel_hi:[1,0]
	s_nop 0
	v_pk_mul_f32 v[10:11], v[4:5], v[18:19] op_sel_hi:[1,0]
	v_pk_mul_f32 v[4:5], v[2:3], v[18:19] op_sel_hi:[1,0]
	v_cvt_pk_bf16_f32 v2, v6, v7
	v_cvt_pk_bf16_f32 v3, v8, v9
	s_nop 0
	v_cvt_pk_bf16_f32 v4, v4, v5
	v_cvt_pk_bf16_f32 v5, v10, v11
	global_store_dwordx4 v[20:21], v[2:5], off offset:256 sc1
	s_cbranch_vccnz .LBB0_365
	s_andn2_b64 vcc, exec, s[6:7]
	v_mov_b64 v[126:127], 0
	v_mov_b64 v[128:129], 0
	v_mov_b64 v[122:123], 0
	v_mov_b64 v[124:125], 0
	v_mov_b64 v[110:111], 0
	v_mov_b64 v[112:113], 0
	v_mov_b64 v[106:107], 0
	v_mov_b64 v[108:109], 0
	v_mov_b64 v[94:95], 0
	v_mov_b64 v[96:97], 0
	v_mov_b64 v[90:91], 0
	v_mov_b64 v[92:93], 0
	v_mov_b64 v[78:79], 0
	v_mov_b64 v[80:81], 0
	v_mov_b64 v[74:75], 0
	v_mov_b64 v[76:77], 0
	v_mov_b64 v[118:119], 0
	v_mov_b64 v[120:121], 0
	v_mov_b64 v[114:115], 0
	v_mov_b64 v[116:117], 0
	v_mov_b64 v[102:103], 0
	v_mov_b64 v[104:105], 0
	v_mov_b64 v[98:99], 0
	v_mov_b64 v[100:101], 0
	v_mov_b64 v[86:87], 0
	v_mov_b64 v[88:89], 0
	v_mov_b64 v[82:83], 0
	v_mov_b64 v[84:85], 0
	v_mov_b64 v[70:71], 0
	v_mov_b64 v[72:73], 0
	v_mov_b64 v[66:67], 0
	v_mov_b64 v[68:69], 0
	v_mov_b64 v[62:63], 0
	v_mov_b64 v[64:65], 0
	v_mov_b64 v[58:59], 0
	v_mov_b64 v[60:61], 0
	v_mov_b64 v[46:47], 0
	v_mov_b64 v[48:49], 0
	v_mov_b64 v[42:43], 0
	v_mov_b64 v[44:45], 0
	v_mov_b64 v[30:31], 0
	v_mov_b64 v[32:33], 0
	v_mov_b64 v[26:27], 0
	v_mov_b64 v[28:29], 0
	v_mov_b64 v[14:15], 0
	v_mov_b64 v[16:17], 0
	v_mov_b64 v[10:11], 0
	v_mov_b64 v[12:13], 0
	v_mov_b64 v[54:55], 0
	v_mov_b64 v[56:57], 0
	v_mov_b64 v[50:51], 0
	v_mov_b64 v[52:53], 0
	v_mov_b64 v[38:39], 0
	v_mov_b64 v[40:41], 0
	v_mov_b64 v[34:35], 0
	v_mov_b64 v[36:37], 0
	v_mov_b64 v[22:23], 0
	v_mov_b64 v[24:25], 0
	v_mov_b64 v[18:19], 0
	v_mov_b64 v[20:21], 0
	v_mov_b64 v[6:7], 0
	v_mov_b64 v[8:9], 0
	v_mov_b64 v[2:3], 0
	v_mov_b64 v[4:5], 0
	s_cbranch_vccnz .LBB0_364
	s_barrier
	s_branch .LBB0_364

.LBB0_462:
	s_add_u32 s8, s71, 0x40080
	s_addc_u32 s9, s27, 0
	s_mov_b32 m0, s66
	s_nop 0
	global_load_lds_dwordx4 v136, s[8:9]
	v_lshl_add_u32 v147, s70, 10, v133
	s_mov_b32 m0, s67
	s_nop 0
	global_load_lds_dwordx4 v138, s[8:9]
	ds_read_b32 v146, v147
	v_lshl_add_u32 v144, s38, 8, v132
	v_lshl_or_b32 v130, s69, 8, v141
	v_ashrrev_i32_e32 v145, 31, v144
	v_ashrrev_i32_e32 v131, 31, v130
	v_lshlrev_b64 v[148:149], 9, v[144:145]
	v_lshl_add_u64 v[148:149], s[20:21], 0, v[148:149]
	v_lshlrev_b64 v[150:151], 1, v[130:131]
	v_lshl_add_u64 v[130:131], v[148:149], 0, v[150:151]
	s_waitcnt lgkmcnt(0)
	v_pk_mul_f32 v[128:129], v[128:129], v[146:147] op_sel_hi:[1,0]
	v_pk_mul_f32 v[126:127], v[126:127], v[146:147] op_sel_hi:[1,0]
	v_pk_mul_f32 v[148:149], v[124:125], v[146:147] op_sel_hi:[1,0]
	v_pk_mul_f32 v[124:125], v[122:123], v[146:147] op_sel_hi:[1,0]
	v_cvt_pk_bf16_f32 v122, v126, v127
	v_cvt_pk_bf16_f32 v123, v128, v129
	v_pk_mul_f32 v[120:121], v[120:121], v[146:147] op_sel_hi:[1,0]
	v_cvt_pk_bf16_f32 v124, v124, v125
	v_cvt_pk_bf16_f32 v125, v148, v149
	global_store_dwordx4 v[130:131], v[122:125], off sc1
	v_pk_mul_f32 v[118:119], v[118:119], v[146:147] op_sel_hi:[1,0]
	s_mov_b64 s[8:9], 0x10000
	v_pk_mul_f32 v[122:123], v[116:117], v[146:147] op_sel_hi:[1,0]
	v_pk_mul_f32 v[116:117], v[114:115], v[146:147] op_sel_hi:[1,0]
	v_cvt_pk_bf16_f32 v114, v118, v119
	v_cvt_pk_bf16_f32 v115, v120, v121
	s_mov_b32 s2, 0x14000
	v_cvt_pk_bf16_f32 v116, v116, v117
	v_cvt_pk_bf16_f32 v117, v122, v123
	global_store_dwordx4 v[130:131], v[114:117], off offset:256 sc1
	ds_read_b32 v116, v147 offset:64
	s_waitcnt lgkmcnt(0)
	v_pk_mul_f32 v[112:113], v[112:113], v[116:117] op_sel_hi:[1,0]
	v_or_b32_e32 v114, 16, v144
	v_ashrrev_i32_e32 v115, 31, v114
	v_lshlrev_b64 v[114:115], 9, v[114:115]
	v_lshl_add_u64 v[114:115], s[20:21], 0, v[114:115]
	v_lshl_add_u64 v[114:115], v[114:115], 0, v[150:151]
	v_pk_mul_f32 v[110:111], v[110:111], v[116:117] op_sel_hi:[1,0]
	v_pk_mul_f32 v[118:119], v[108:109], v[116:117] op_sel_hi:[1,0]
	v_pk_mul_f32 v[108:109], v[106:107], v[116:117] op_sel_hi:[1,0]
	v_cvt_pk_bf16_f32 v106, v110, v111
	v_cvt_pk_bf16_f32 v107, v112, v113
	v_pk_mul_f32 v[104:105], v[104:105], v[116:117] op_sel_hi:[1,0]
	v_cvt_pk_bf16_f32 v108, v108, v109
	v_cvt_pk_bf16_f32 v109, v118, v119
	global_store_dwordx4 v[114:115], v[106:109], off sc1
	v_pk_mul_f32 v[102:103], v[102:103], v[116:117] op_sel_hi:[1,0]
	s_nop 0
	v_pk_mul_f32 v[106:107], v[100:101], v[116:117] op_sel_hi:[1,0]
	v_pk_mul_f32 v[100:101], v[98:99], v[116:117] op_sel_hi:[1,0]
	v_cvt_pk_bf16_f32 v98, v102, v103
	v_cvt_pk_bf16_f32 v99, v104, v105
	s_nop 0
	v_cvt_pk_bf16_f32 v100, v100, v101
	v_cvt_pk_bf16_f32 v101, v106, v107
	global_store_dwordx4 v[114:115], v[98:101], off offset:256 sc1
	ds_read_b32 v100, v147 offset:128
	s_waitcnt lgkmcnt(0)
	v_pk_mul_f32 v[96:97], v[96:97], v[100:101] op_sel_hi:[1,0]
	v_or_b32_e32 v98, 32, v144
	v_ashrrev_i32_e32 v99, 31, v98
	v_lshlrev_b64 v[98:99], 9, v[98:99]
	v_lshl_add_u64 v[98:99], s[20:21], 0, v[98:99]
	v_lshl_add_u64 v[98:99], v[98:99], 0, v[150:151]
	v_pk_mul_f32 v[94:95], v[94:95], v[100:101] op_sel_hi:[1,0]
	v_pk_mul_f32 v[102:103], v[92:93], v[100:101] op_sel_hi:[1,0]
	v_pk_mul_f32 v[92:93], v[90:91], v[100:101] op_sel_hi:[1,0]
	v_cvt_pk_bf16_f32 v90, v94, v95
	v_cvt_pk_bf16_f32 v91, v96, v97
	v_pk_mul_f32 v[88:89], v[88:89], v[100:101] op_sel_hi:[1,0]
	v_cvt_pk_bf16_f32 v92, v92, v93
	v_cvt_pk_bf16_f32 v93, v102, v103
	global_store_dwordx4 v[98:99], v[90:93], off sc1
	v_pk_mul_f32 v[86:87], v[86:87], v[100:101] op_sel_hi:[1,0]
	s_nop 0
	v_pk_mul_f32 v[90:91], v[84:85], v[100:101] op_sel_hi:[1,0]
	v_pk_mul_f32 v[84:85], v[82:83], v[100:101] op_sel_hi:[1,0]
	v_cvt_pk_bf16_f32 v82, v86, v87
	v_cvt_pk_bf16_f32 v83, v88, v89
	s_nop 0
	v_cvt_pk_bf16_f32 v84, v84, v85
	v_cvt_pk_bf16_f32 v85, v90, v91
	global_store_dwordx4 v[98:99], v[82:85], off offset:256 sc1
	ds_read_b32 v84, v147 offset:192
	s_waitcnt lgkmcnt(0)
	v_pk_mul_f32 v[80:81], v[80:81], v[84:85] op_sel_hi:[1,0]
	v_or_b32_e32 v82, 48, v144
	v_ashrrev_i32_e32 v83, 31, v82
	v_lshlrev_b64 v[82:83], 9, v[82:83]
	v_lshl_add_u64 v[82:83], s[20:21], 0, v[82:83]
	v_lshl_add_u64 v[82:83], v[82:83], 0, v[150:151]
	v_pk_mul_f32 v[78:79], v[78:79], v[84:85] op_sel_hi:[1,0]
	v_pk_mul_f32 v[86:87], v[76:77], v[84:85] op_sel_hi:[1,0]
	v_pk_mul_f32 v[76:77], v[74:75], v[84:85] op_sel_hi:[1,0]
	v_cvt_pk_bf16_f32 v74, v78, v79
	v_cvt_pk_bf16_f32 v75, v80, v81
	v_pk_mul_f32 v[70:71], v[70:71], v[84:85] op_sel_hi:[1,0]
	v_cvt_pk_bf16_f32 v76, v76, v77
	v_cvt_pk_bf16_f32 v77, v86, v87
	global_store_dwordx4 v[82:83], v[74:77], off sc1
	v_pk_mul_f32 v[72:73], v[72:73], v[84:85] op_sel_hi:[1,0]
	s_nop 0
	v_pk_mul_f32 v[74:75], v[68:69], v[84:85] op_sel_hi:[1,0]
	v_pk_mul_f32 v[68:69], v[66:67], v[84:85] op_sel_hi:[1,0]
	v_cvt_pk_bf16_f32 v66, v70, v71
	v_cvt_pk_bf16_f32 v67, v72, v73
	s_nop 0
	v_cvt_pk_bf16_f32 v68, v68, v69
	v_cvt_pk_bf16_f32 v69, v74, v75
	ds_read_b32 v70, v147 offset:512
	global_store_dwordx4 v[82:83], v[66:69], off offset:256 sc1
	s_waitcnt lgkmcnt(0)
	v_pk_mul_f32 v[62:63], v[62:63], v[70:71] op_sel_hi:[1,0]
	v_pk_mul_f32 v[66:67], v[60:61], v[70:71] op_sel_hi:[1,0]
	v_pk_mul_f32 v[60:61], v[58:59], v[70:71] op_sel_hi:[1,0]
	v_cvt_pk_bf16_f32 v58, v62, v63
	v_add_co_u32_e32 v62, vcc, s33, v130
	v_pk_mul_f32 v[64:65], v[64:65], v[70:71] op_sel_hi:[1,0]
	s_nop 0
	v_addc_co_u32_e32 v63, vcc, 0, v131, vcc
	v_cvt_pk_bf16_f32 v59, v64, v65
	v_cvt_pk_bf16_f32 v60, v60, v61
	v_cvt_pk_bf16_f32 v61, v66, v67
	global_store_dwordx4 v[62:63], v[58:61], off sc1
	v_pk_mul_f32 v[54:55], v[54:55], v[70:71] op_sel_hi:[1,0]
	v_pk_mul_f32 v[56:57], v[56:57], v[70:71] op_sel_hi:[1,0]
	v_pk_mul_f32 v[58:59], v[52:53], v[70:71] op_sel_hi:[1,0]
	v_pk_mul_f32 v[52:53], v[50:51], v[70:71] op_sel_hi:[1,0]
	v_cvt_pk_bf16_f32 v50, v54, v55
	v_cvt_pk_bf16_f32 v51, v56, v57
	v_lshl_add_u64 v[56:57], v[130:131], 0, s[8:9]
	v_cvt_pk_bf16_f32 v52, v52, v53
	v_cvt_pk_bf16_f32 v53, v58, v59
	ds_read_b32 v54, v147 offset:576
	global_store_dwordx4 v[56:57], v[50:53], off offset:256 sc1
	s_mov_b64 s[8:9], 0x12000
	s_waitcnt lgkmcnt(0)
	v_pk_mul_f32 v[46:47], v[46:47], v[54:55] op_sel_hi:[1,0]
	v_pk_mul_f32 v[50:51], v[44:45], v[54:55] op_sel_hi:[1,0]
	v_pk_mul_f32 v[44:45], v[42:43], v[54:55] op_sel_hi:[1,0]
	v_cvt_pk_bf16_f32 v42, v46, v47
	v_add_co_u32_e32 v46, vcc, s3, v130
	v_pk_mul_f32 v[48:49], v[48:49], v[54:55] op_sel_hi:[1,0]
	s_nop 0
	v_addc_co_u32_e32 v47, vcc, 0, v131, vcc
	v_cvt_pk_bf16_f32 v43, v48, v49
	v_cvt_pk_bf16_f32 v44, v44, v45
	v_cvt_pk_bf16_f32 v45, v50, v51
	global_store_dwordx4 v[46:47], v[42:45], off sc1
	v_pk_mul_f32 v[38:39], v[38:39], v[54:55] op_sel_hi:[1,0]
	v_pk_mul_f32 v[40:41], v[40:41], v[54:55] op_sel_hi:[1,0]
	v_pk_mul_f32 v[42:43], v[36:37], v[54:55] op_sel_hi:[1,0]
	v_pk_mul_f32 v[36:37], v[34:35], v[54:55] op_sel_hi:[1,0]
	v_cvt_pk_bf16_f32 v34, v38, v39
	v_cvt_pk_bf16_f32 v35, v40, v41
	v_lshl_add_u64 v[40:41], v[130:131], 0, s[8:9]
	v_cvt_pk_bf16_f32 v36, v36, v37
	v_cvt_pk_bf16_f32 v37, v42, v43
	ds_read_b32 v38, v147 offset:640
	global_store_dwordx4 v[40:41], v[34:37], off offset:256 sc1
	s_mov_b64 s[8:9], 0x14000
	s_waitcnt lgkmcnt(0)
	v_pk_mul_f32 v[30:31], v[30:31], v[38:39] op_sel_hi:[1,0]
	v_pk_mul_f32 v[34:35], v[28:29], v[38:39] op_sel_hi:[1,0]
	v_pk_mul_f32 v[28:29], v[26:27], v[38:39] op_sel_hi:[1,0]
	v_cvt_pk_bf16_f32 v26, v30, v31
	v_add_co_u32_e32 v30, vcc, s2, v130
	v_pk_mul_f32 v[32:33], v[32:33], v[38:39] op_sel_hi:[1,0]
	s_nop 0
	v_addc_co_u32_e32 v31, vcc, 0, v131, vcc
	v_cvt_pk_bf16_f32 v27, v32, v33
	v_cvt_pk_bf16_f32 v28, v28, v29
	v_cvt_pk_bf16_f32 v29, v34, v35
	global_store_dwordx4 v[30:31], v[26:29], off sc1
	v_pk_mul_f32 v[22:23], v[22:23], v[38:39] op_sel_hi:[1,0]
	v_pk_mul_f32 v[24:25], v[24:25], v[38:39] op_sel_hi:[1,0]
	v_pk_mul_f32 v[26:27], v[20:21], v[38:39] op_sel_hi:[1,0]
	v_pk_mul_f32 v[20:21], v[18:19], v[38:39] op_sel_hi:[1,0]
	v_cvt_pk_bf16_f32 v18, v22, v23
	v_cvt_pk_bf16_f32 v19, v24, v25
	v_lshl_add_u64 v[24:25], v[130:131], 0, s[8:9]
	v_cvt_pk_bf16_f32 v20, v20, v21
	v_cvt_pk_bf16_f32 v21, v26, v27
	ds_read_b32 v22, v147 offset:704
	global_store_dwordx4 v[24:25], v[18:21], off offset:256 sc1
	s_mov_b64 s[8:9], 0x16000
	s_waitcnt lgkmcnt(0)
	v_pk_mul_f32 v[14:15], v[14:15], v[22:23] op_sel_hi:[1,0]
	v_pk_mul_f32 v[20:21], v[12:13], v[22:23] op_sel_hi:[1,0]
	v_pk_mul_f32 v[12:13], v[10:11], v[22:23] op_sel_hi:[1,0]
	v_cvt_pk_bf16_f32 v10, v14, v15
	v_add_co_u32_e32 v14, vcc, s80, v130
	v_pk_mul_f32 v[16:17], v[16:17], v[22:23] op_sel_hi:[1,0]
	s_nop 0
	v_addc_co_u32_e32 v15, vcc, 0, v131, vcc
	v_cvt_pk_bf16_f32 v11, v16, v17
	v_cvt_pk_bf16_f32 v12, v12, v13
	v_cvt_pk_bf16_f32 v13, v20, v21
	global_store_dwordx4 v[14:15], v[10:13], off sc1
	v_lshl_add_u64 v[18:19], v[130:131], 0, s[8:9]
	v_pk_mul_f32 v[8:9], v[8:9], v[22:23] op_sel_hi:[1,0]
	v_pk_mul_f32 v[10:11], v[4:5], v[22:23] op_sel_hi:[1,0]
	v_pk_mul_f32 v[4:5], v[2:3], v[22:23] op_sel_hi:[1,0]
	v_pk_mul_f32 v[6:7], v[6:7], v[22:23] op_sel_hi:[1,0]
	s_andn2_b64 vcc, exec, s[0:1]
	v_cvt_pk_bf16_f32 v2, v6, v7
	v_cvt_pk_bf16_f32 v3, v8, v9
	v_cvt_pk_bf16_f32 v4, v4, v5
	v_cvt_pk_bf16_f32 v5, v10, v11
	s_mov_b64 s[0:1], -1
	global_store_dwordx4 v[18:19], v[2:5], off offset:256 sc1
	s_cbranch_vccnz .LBB0_451
	s_andn2_b64 vcc, exec, s[6:7]
	v_mov_b64 v[126:127], 0
	v_mov_b64 v[128:129], 0
	v_mov_b64 v[122:123], 0
	v_mov_b64 v[124:125], 0
	v_mov_b64 v[110:111], 0
	v_mov_b64 v[112:113], 0
	v_mov_b64 v[106:107], 0
	v_mov_b64 v[108:109], 0
	v_mov_b64 v[94:95], 0
	v_mov_b64 v[96:97], 0
	v_mov_b64 v[90:91], 0
	v_mov_b64 v[92:93], 0
	v_mov_b64 v[78:79], 0
	v_mov_b64 v[80:81], 0
	v_mov_b64 v[74:75], 0
	v_mov_b64 v[76:77], 0
	v_mov_b64 v[118:119], 0
	v_mov_b64 v[120:121], 0
	v_mov_b64 v[114:115], 0
	v_mov_b64 v[116:117], 0
	v_mov_b64 v[102:103], 0
	v_mov_b64 v[104:105], 0
	v_mov_b64 v[98:99], 0
	v_mov_b64 v[100:101], 0
	v_mov_b64 v[86:87], 0
	v_mov_b64 v[88:89], 0
	v_mov_b64 v[82:83], 0
	v_mov_b64 v[84:85], 0
	v_mov_b64 v[70:71], 0
	v_mov_b64 v[72:73], 0
	v_mov_b64 v[66:67], 0
	v_mov_b64 v[68:69], 0
	v_mov_b64 v[62:63], 0
	v_mov_b64 v[64:65], 0
	v_mov_b64 v[58:59], 0
	v_mov_b64 v[60:61], 0
	v_mov_b64 v[46:47], 0
	v_mov_b64 v[48:49], 0
	v_mov_b64 v[42:43], 0
	v_mov_b64 v[44:45], 0
	v_mov_b64 v[30:31], 0
	v_mov_b64 v[32:33], 0
	v_mov_b64 v[26:27], 0
	v_mov_b64 v[28:29], 0
	v_mov_b64 v[14:15], 0
	v_mov_b64 v[16:17], 0
	v_mov_b64 v[10:11], 0
	v_mov_b64 v[12:13], 0
	v_mov_b64 v[54:55], 0
	v_mov_b64 v[56:57], 0
	v_mov_b64 v[50:51], 0
	v_mov_b64 v[52:53], 0
	v_mov_b64 v[38:39], 0
	v_mov_b64 v[40:41], 0
	v_mov_b64 v[34:35], 0
	v_mov_b64 v[36:37], 0
	v_mov_b64 v[22:23], 0
	v_mov_b64 v[24:25], 0
	v_mov_b64 v[18:19], 0
	v_mov_b64 v[20:21], 0
	v_mov_b64 v[6:7], 0
	v_mov_b64 v[8:9], 0
	v_mov_b64 v[2:3], 0
	v_mov_b64 v[4:5], 0
	s_cbranch_vccnz .LBB0_450
	s_barrier
	s_branch .LBB0_450

.LBB0_494:
	v_or_b32_e32 v132, s8, v140
	v_ashrrev_i32_e32 v133, 31, v132
	v_lshlrev_b64 v[134:135], 11, v[132:133]
	s_andn2_b64 vcc, exec, s[0:1]
	v_lshl_add_u64 v[134:135], s[6:7], 0, v[134:135]
	s_cbranch_vccnz .LBB0_496
	v_cvt_pk_bf16_f32 v126, v126, v127
	v_cvt_pk_bf16_f32 v127, v128, v129
	v_cvt_pk_bf16_f32 v128, v122, v123
	v_lshl_add_u64 v[122:123], v[130:131], 1, v[134:135]
	v_cvt_pk_bf16_f32 v129, v124, v125
	global_store_dwordx4 v[122:123], v[126:129], off sc1

.LBB0_498:
	s_andn2_b64 vcc, exec, s[42:43]
	s_cbranch_vccnz .LBB0_500
	v_cvt_pk_bf16_f32 v118, v118, v119
	v_cvt_pk_bf16_f32 v119, v120, v121
	v_cvt_pk_bf16_f32 v120, v114, v115
	v_lshl_add_u64 v[114:115], v[130:131], 1, v[134:135]
	v_cvt_pk_bf16_f32 v121, v116, v117
	global_store_dwordx4 v[114:115], v[118:121], off offset:256 sc1

.LBB0_502:
	v_or_b32_e32 v114, 16, v132
	v_ashrrev_i32_e32 v115, 31, v114
	v_lshlrev_b64 v[114:115], 11, v[114:115]
	s_andn2_b64 vcc, exec, s[42:43]
	v_lshl_add_u64 v[114:115], s[6:7], 0, v[114:115]
	s_cbranch_vccnz .LBB0_545
	v_cvt_pk_bf16_f32 v110, v110, v111
	v_cvt_pk_bf16_f32 v111, v112, v113
	v_cvt_pk_bf16_f32 v112, v106, v107
	v_lshl_add_u64 v[106:107], v[130:131], 1, v[114:115]
	v_cvt_pk_bf16_f32 v113, v108, v109
	global_store_dwordx4 v[106:107], v[110:113], off sc1
	s_and_b64 vcc, exec, s[0:1]
	s_mov_b64 s[42:43], -1
	s_cbranch_vccz .LBB0_546

.LBB0_505:
	v_cvt_pk_bf16_f32 v102, v102, v103
	v_cvt_pk_bf16_f32 v103, v104, v105
	v_cvt_pk_bf16_f32 v104, v98, v99
	v_lshl_add_u64 v[98:99], v[130:131], 1, v[114:115]
	v_cvt_pk_bf16_f32 v105, v100, v101
	global_store_dwordx4 v[98:99], v[102:105], off offset:256 sc1

.LBB0_508:
	v_or_b32_e32 v98, 32, v132
	v_ashrrev_i32_e32 v99, 31, v98
	v_lshlrev_b64 v[98:99], 11, v[98:99]
	s_andn2_b64 vcc, exec, s[42:43]
	v_lshl_add_u64 v[98:99], s[6:7], 0, v[98:99]
	s_cbranch_vccnz .LBB0_547
	v_cvt_pk_bf16_f32 v94, v94, v95
	v_cvt_pk_bf16_f32 v95, v96, v97
	v_cvt_pk_bf16_f32 v96, v90, v91
	v_lshl_add_u64 v[90:91], v[130:131], 1, v[98:99]
	v_cvt_pk_bf16_f32 v97, v92, v93
	global_store_dwordx4 v[90:91], v[94:97], off sc1
	s_and_b64 vcc, exec, s[0:1]
	s_mov_b64 s[42:43], -1
	s_cbranch_vccz .LBB0_548

.LBB0_511:
	v_cvt_pk_bf16_f32 v86, v86, v87
	v_cvt_pk_bf16_f32 v87, v88, v89
	v_cvt_pk_bf16_f32 v88, v82, v83
	v_lshl_add_u64 v[82:83], v[130:131], 1, v[98:99]
	v_cvt_pk_bf16_f32 v89, v84, v85
	global_store_dwordx4 v[82:83], v[86:89], off offset:256 sc1

.LBB0_514:
	v_or_b32_e32 v82, 48, v132
	v_ashrrev_i32_e32 v83, 31, v82
	v_lshlrev_b64 v[82:83], 11, v[82:83]
	s_andn2_b64 vcc, exec, s[42:43]
	v_lshl_add_u64 v[82:83], s[6:7], 0, v[82:83]
	s_cbranch_vccnz .LBB0_549
	v_cvt_pk_bf16_f32 v78, v78, v79
	v_cvt_pk_bf16_f32 v79, v80, v81
	v_cvt_pk_bf16_f32 v80, v74, v75
	v_lshl_add_u64 v[74:75], v[130:131], 1, v[82:83]
	v_cvt_pk_bf16_f32 v81, v76, v77
	global_store_dwordx4 v[74:75], v[78:81], off sc1
	s_and_b64 vcc, exec, s[0:1]
	s_mov_b64 s[42:43], -1
	s_cbranch_vccz .LBB0_550

.LBB0_517:
	v_cvt_pk_bf16_f32 v70, v70, v71
	v_cvt_pk_bf16_f32 v71, v72, v73
	v_cvt_pk_bf16_f32 v72, v66, v67
	v_lshl_add_u64 v[66:67], v[130:131], 1, v[82:83]
	v_cvt_pk_bf16_f32 v73, v68, v69
	global_store_dwordx4 v[66:67], v[70:73], off offset:256 sc1

.LBB0_520:
	v_ashrrev_i32_e32 v69, 31, v68
	v_lshlrev_b64 v[68:69], 11, v[68:69]
	s_andn2_b64 vcc, exec, s[34:35]
	v_lshl_add_u64 v[68:69], s[6:7], 0, v[68:69]
	s_cbranch_vccnz .LBB0_551
	v_cvt_pk_bf16_f32 v62, v62, v63
	v_cvt_pk_bf16_f32 v63, v64, v65
	v_cvt_pk_bf16_f32 v64, v58, v59
	v_lshl_add_u64 v[58:59], v[130:131], 1, v[68:69]
	v_cvt_pk_bf16_f32 v65, v60, v61
	global_store_dwordx4 v[58:59], v[62:65], off sc1
	s_and_b64 vcc, exec, s[0:1]
	s_mov_b64 s[34:35], -1
	s_cbranch_vccz .LBB0_552

.LBB0_523:
	v_cvt_pk_bf16_f32 v54, v54, v55
	v_cvt_pk_bf16_f32 v55, v56, v57
	v_cvt_pk_bf16_f32 v56, v50, v51
	v_lshl_add_u64 v[50:51], v[130:131], 1, v[68:69]
	v_cvt_pk_bf16_f32 v57, v52, v53
	global_store_dwordx4 v[50:51], v[54:57], off offset:256 sc1

.LBB0_526:
	v_ashrrev_i32_e32 v51, 31, v50
	v_lshlrev_b64 v[50:51], 11, v[50:51]
	s_andn2_b64 vcc, exec, s[34:35]
	v_lshl_add_u64 v[50:51], s[6:7], 0, v[50:51]
	s_cbranch_vccnz .LBB0_553
	v_cvt_pk_bf16_f32 v46, v46, v47
	v_cvt_pk_bf16_f32 v47, v48, v49
	v_cvt_pk_bf16_f32 v48, v42, v43
	v_lshl_add_u64 v[42:43], v[130:131], 1, v[50:51]
	v_cvt_pk_bf16_f32 v49, v44, v45
	global_store_dwordx4 v[42:43], v[46:49], off sc1
	s_and_b64 vcc, exec, s[0:1]
	s_mov_b64 s[34:35], -1
	s_cbranch_vccz .LBB0_554

.LBB0_529:
	v_cvt_pk_bf16_f32 v38, v38, v39
	v_cvt_pk_bf16_f32 v39, v40, v41
	v_cvt_pk_bf16_f32 v40, v34, v35
	v_lshl_add_u64 v[34:35], v[130:131], 1, v[50:51]
	v_cvt_pk_bf16_f32 v41, v36, v37
	global_store_dwordx4 v[34:35], v[38:41], off offset:256 sc1

.LBB0_532:
	v_ashrrev_i32_e32 v35, 31, v34
	v_lshlrev_b64 v[34:35], 11, v[34:35]
	s_andn2_b64 vcc, exec, s[34:35]
	v_lshl_add_u64 v[34:35], s[6:7], 0, v[34:35]
	s_cbranch_vccnz .LBB0_555
	v_cvt_pk_bf16_f32 v30, v30, v31
	v_cvt_pk_bf16_f32 v31, v32, v33
	v_cvt_pk_bf16_f32 v32, v26, v27
	v_lshl_add_u64 v[26:27], v[130:131], 1, v[34:35]
	v_cvt_pk_bf16_f32 v33, v28, v29
	global_store_dwordx4 v[26:27], v[30:33], off sc1
	s_and_b64 vcc, exec, s[0:1]
	s_mov_b64 s[34:35], -1
	s_cbranch_vccz .LBB0_556

.LBB0_535:
	v_cvt_pk_bf16_f32 v22, v22, v23
	v_cvt_pk_bf16_f32 v23, v24, v25
	v_cvt_pk_bf16_f32 v24, v18, v19
	v_lshl_add_u64 v[18:19], v[130:131], 1, v[34:35]
	v_cvt_pk_bf16_f32 v25, v20, v21
	global_store_dwordx4 v[18:19], v[22:25], off offset:256 sc1

.LBB0_538:
	v_ashrrev_i32_e32 v19, 31, v18
	v_lshlrev_b64 v[18:19], 11, v[18:19]
	s_andn2_b64 vcc, exec, s[34:35]
	v_lshl_add_u64 v[18:19], s[6:7], 0, v[18:19]
	s_cbranch_vccnz .LBB0_557
	v_cvt_pk_bf16_f32 v14, v14, v15
	v_cvt_pk_bf16_f32 v15, v16, v17
	v_cvt_pk_bf16_f32 v16, v10, v11
	v_lshl_add_u64 v[10:11], v[130:131], 1, v[18:19]
	v_cvt_pk_bf16_f32 v17, v12, v13
	global_store_dwordx4 v[10:11], v[14:17], off sc1
	s_and_b64 vcc, exec, s[0:1]
	s_mov_b64 s[0:1], -1
	s_cbranch_vccz .LBB0_558

.LBB0_541:
	v_cvt_pk_bf16_f32 v6, v6, v7
	v_cvt_pk_bf16_f32 v7, v8, v9
	v_cvt_pk_bf16_f32 v8, v2, v3
	v_lshl_add_u64 v[2:3], v[130:131], 1, v[18:19]
	v_cvt_pk_bf16_f32 v9, v4, v5
	global_store_dwordx4 v[2:3], v[6:9], off offset:256 sc1

.LBB0_609:
	s_add_u32 s8, s70, 0x40080
	s_addc_u32 s9, s25, 0
	s_mov_b32 m0, s65
	s_nop 0
	global_load_lds_dwordx4 v0, s[8:9]
	v_lshl_add_u32 v141, s69, 10, v136
	s_mov_b32 m0, s66
	s_nop 0
	global_load_lds_dwordx4 v133, s[8:9]
	ds_read_b32 v145, v141
	v_mul_f32_e32 v126, v122, v126
	v_mul_f32_e32 v127, v123, v127
	v_mul_f32_e32 v118, v114, v118
	v_mul_f32_e32 v128, v124, v128
	s_waitcnt lgkmcnt(0)
	v_mul_f32_e32 v144, 0xbfb8aa3b, v145
	v_pk_mul_f32 v[148:149], v[122:123], v[144:145] op_sel_hi:[1,0]
	v_pk_mul_f32 v[150:151], v[124:125], v[144:145] op_sel_hi:[1,0]
	v_exp_f32_e32 v122, v149
	v_exp_f32_e32 v123, v150
	v_mul_f32_e32 v129, v125, v129
	v_pk_mul_f32 v[124:125], v[116:117], v[144:145] op_sel_hi:[1,0]
	v_add_f32_e32 v122, 1.0, v122
	v_rcp_f32_e32 v149, v122
	v_exp_f32_e32 v122, v151
	v_add_f32_e32 v123, 1.0, v123
	v_rcp_f32_e32 v150, v123
	v_mul_f32_e32 v119, v115, v119
	v_add_f32_e32 v122, 1.0, v122
	v_rcp_f32_e32 v151, v122
	v_pk_mul_f32 v[122:123], v[114:115], v[144:145] op_sel_hi:[1,0]
	v_mov_b32_e32 v144, v116
	v_exp_f32_e32 v114, v123
	v_exp_f32_e32 v122, v122
	v_mov_b32_e32 v115, v145
	v_exp_f32_e32 v148, v148
	v_add_f32_e32 v114, 1.0, v114
	v_rcp_f32_e32 v123, v114
	v_mov_b32_e32 v114, v120
	v_pk_mul_f32 v[114:115], v[144:145], v[114:115]
	v_add_f32_e32 v122, 1.0, v122
	v_mul_f32_e32 v120, v127, v115
	v_rcp_f32_e32 v122, v122
	v_mul_f32_e32 v116, v126, v115
	v_mul_f32_e32 v126, v120, v149
	v_mul_f32_e32 v120, v128, v115
	v_mul_f32_e32 v127, v120, v150
	v_mul_f32_e32 v120, v129, v115
	v_mul_f32_e32 v128, v120, v151
	v_exp_f32_e32 v120, v124
	v_mul_f32_e32 v118, v118, v115
	v_mul_f32_e32 v118, v118, v122
	v_exp_f32_e32 v122, v125
	v_add_f32_e32 v120, 1.0, v120
	v_add_f32_e32 v148, 1.0, v148
	v_rcp_f32_e32 v120, v120
	v_rcp_f32_e32 v148, v148
	v_add_f32_e32 v122, 1.0, v122
	v_rcp_f32_e32 v122, v122
	v_mul_f32_e32 v119, v119, v115
	v_mul_f32_e32 v114, v114, v115
	v_mul_f32_e32 v119, v119, v123
	v_mul_f32_e32 v123, v114, v120
	v_mul_f32_e32 v114, v117, v121
	v_mul_f32_e32 v116, v116, v148
	v_mul_f32_e32 v114, v114, v115
	v_mul_f32_e32 v122, v114, v122
	v_cvt_pk_bf16_f32 v116, v116, v126
	v_cvt_pk_bf16_f32 v117, v127, v128
	v_cvt_pk_bf16_f32 v118, v118, v119
	v_cvt_pk_bf16_f32 v119, v123, v122
	ds_read_b32 v123, v141 offset:64
	v_lshl_or_b32 v142, s68, 7, v137
	v_lshl_add_u32 v140, s34, 8, v135
	v_ashrrev_i32_e32 v143, 31, v142
	v_mov_b64_e32 v[130:131], s[6:7]
	v_mad_i64_i32 v[146:147], s[8:9], v140, s87, v[130:131]
	v_lshlrev_b64 v[114:115], 1, v[142:143]
	v_lshl_add_u64 v[120:121], v[146:147], 0, v[114:115]
	global_store_dwordx4 v[120:121], v[116:119], off sc1
	v_mul_f32_e32 v110, v106, v110
	v_mul_f32_e32 v111, v107, v111
	s_waitcnt lgkmcnt(0)
	v_mul_f32_e32 v118, 0xbfb8aa3b, v123
	v_pk_mul_f32 v[120:121], v[106:107], v[118:119] op_sel_hi:[1,0]
	v_mul_f32_e32 v102, v98, v102
	v_exp_f32_e32 v119, v120
	v_exp_f32_e32 v106, v121
	v_mul_f32_e32 v103, v99, v103
	v_mov_b32_e32 v122, v100
	v_pk_mul_f32 v[124:125], v[108:109], v[118:119] op_sel_hi:[1,0]
	v_add_f32_e32 v106, 1.0, v106
	v_add_f32_e32 v119, 1.0, v119
	v_exp_f32_e32 v107, v124
	v_rcp_f32_e32 v120, v106
	v_exp_f32_e32 v106, v125
	v_rcp_f32_e32 v119, v119
	v_add_f32_e32 v107, 1.0, v107
	v_rcp_f32_e32 v121, v107
	v_add_f32_e32 v106, 1.0, v106
	v_rcp_f32_e32 v124, v106
	v_pk_mul_f32 v[106:107], v[98:99], v[118:119] op_sel_hi:[1,0]
	v_mov_b32_e32 v99, v123
	v_exp_f32_e32 v106, v106
	v_exp_f32_e32 v98, v107
	v_mul_f32_e32 v112, v108, v112
	v_mul_f32_e32 v113, v109, v113
	v_add_f32_e32 v106, 1.0, v106
	v_rcp_f32_e32 v106, v106
	v_add_f32_e32 v98, 1.0, v98
	v_rcp_f32_e32 v107, v98
	v_mov_b32_e32 v98, v104
	v_pk_mul_f32 v[98:99], v[122:123], v[98:99]
	v_pk_mul_f32 v[108:109], v[100:101], v[118:119] op_sel_hi:[1,0]
	v_mul_f32_e32 v102, v102, v99
	v_mul_f32_e32 v106, v102, v106
	v_exp_f32_e32 v102, v108
	v_mul_f32_e32 v103, v103, v99
	v_mul_f32_e32 v107, v103, v107
	v_exp_f32_e32 v103, v109
	v_add_f32_e32 v102, 1.0, v102
	v_rcp_f32_e32 v102, v102
	v_mul_f32_e32 v98, v98, v99
	v_add_f32_e32 v103, 1.0, v103
	v_rcp_f32_e32 v103, v103
	v_mul_f32_e32 v108, v98, v102
	v_mul_f32_e32 v98, v101, v105
	v_mul_f32_e32 v100, v110, v99
	v_mul_f32_e32 v98, v98, v99
	v_mul_f32_e32 v100, v100, v119
	v_mul_f32_e32 v104, v111, v99
	v_mul_f32_e32 v110, v112, v99
	v_mul_f32_e32 v111, v113, v99
	v_mul_f32_e32 v101, v98, v103
	v_mul_f32_e32 v104, v104, v120
	v_mul_f32_e32 v110, v110, v121
	v_mul_f32_e32 v111, v111, v124
	v_cvt_pk_bf16_f32 v98, v100, v104
	v_cvt_pk_bf16_f32 v99, v110, v111
	v_cvt_pk_bf16_f32 v100, v106, v107
	v_cvt_pk_bf16_f32 v101, v108, v101
	ds_read_b32 v105, v141 offset:128
	v_or_b32_e32 v116, 16, v140
	v_mad_i64_i32 v[116:117], s[8:9], v116, s87, v[130:131]
	v_lshl_add_u64 v[102:103], v[116:117], 0, v[114:115]
	global_store_dwordx4 v[102:103], v[98:101], off sc1
	v_mul_f32_e32 v94, v90, v94
	v_mul_f32_e32 v95, v91, v95
	s_waitcnt lgkmcnt(0)
	v_mul_f32_e32 v100, 0xbfb8aa3b, v105
	v_pk_mul_f32 v[102:103], v[90:91], v[100:101] op_sel_hi:[1,0]
	v_mul_f32_e32 v86, v82, v86
	v_exp_f32_e32 v101, v102
	v_exp_f32_e32 v90, v103
	v_mul_f32_e32 v87, v83, v87
	v_mov_b32_e32 v104, v84
	v_pk_mul_f32 v[106:107], v[92:93], v[100:101] op_sel_hi:[1,0]
	v_add_f32_e32 v90, 1.0, v90
	v_add_f32_e32 v101, 1.0, v101
	v_exp_f32_e32 v91, v106
	v_rcp_f32_e32 v102, v90
	v_exp_f32_e32 v90, v107
	v_rcp_f32_e32 v101, v101
	v_add_f32_e32 v91, 1.0, v91
	v_rcp_f32_e32 v103, v91
	v_add_f32_e32 v90, 1.0, v90
	v_rcp_f32_e32 v106, v90
	v_pk_mul_f32 v[90:91], v[82:83], v[100:101] op_sel_hi:[1,0]
	v_mov_b32_e32 v83, v105
	v_exp_f32_e32 v90, v90
	v_exp_f32_e32 v82, v91
	v_mul_f32_e32 v96, v92, v96
	v_mul_f32_e32 v97, v93, v97
	v_add_f32_e32 v90, 1.0, v90
	v_rcp_f32_e32 v90, v90
	v_add_f32_e32 v82, 1.0, v82
	v_rcp_f32_e32 v91, v82
	v_mov_b32_e32 v82, v88
	v_pk_mul_f32 v[82:83], v[104:105], v[82:83]
	v_pk_mul_f32 v[92:93], v[84:85], v[100:101] op_sel_hi:[1,0]
	v_mul_f32_e32 v86, v86, v83
	v_mul_f32_e32 v90, v86, v90
	v_exp_f32_e32 v86, v92
	v_mul_f32_e32 v87, v87, v83
	v_mul_f32_e32 v91, v87, v91
	v_exp_f32_e32 v87, v93
	v_add_f32_e32 v86, 1.0, v86
	v_rcp_f32_e32 v86, v86
	v_mul_f32_e32 v82, v82, v83
	v_add_f32_e32 v87, 1.0, v87
	v_rcp_f32_e32 v87, v87
	v_mul_f32_e32 v92, v82, v86
	v_mul_f32_e32 v82, v85, v89
	v_mul_f32_e32 v84, v94, v83
	v_mul_f32_e32 v82, v82, v83
	v_mul_f32_e32 v84, v84, v101
	v_mul_f32_e32 v88, v95, v83
	v_mul_f32_e32 v94, v96, v83
	v_mul_f32_e32 v95, v97, v83
	v_mul_f32_e32 v85, v82, v87
	v_mul_f32_e32 v88, v88, v102
	v_mul_f32_e32 v94, v94, v103
	v_mul_f32_e32 v95, v95, v106
	v_cvt_pk_bf16_f32 v82, v84, v88
	v_cvt_pk_bf16_f32 v83, v94, v95
	v_cvt_pk_bf16_f32 v84, v90, v91
	v_cvt_pk_bf16_f32 v85, v92, v85
	ds_read_b32 v89, v141 offset:192
	v_or_b32_e32 v98, 32, v140
	v_mad_i64_i32 v[98:99], s[8:9], v98, s87, v[130:131]
	v_lshl_add_u64 v[86:87], v[98:99], 0, v[114:115]
	global_store_dwordx4 v[86:87], v[82:85], off sc1
	v_mul_f32_e32 v78, v74, v78
	v_mul_f32_e32 v79, v75, v79
	s_waitcnt lgkmcnt(0)
	v_mul_f32_e32 v84, 0xbfb8aa3b, v89
	v_pk_mul_f32 v[86:87], v[74:75], v[84:85] op_sel_hi:[1,0]
	v_mul_f32_e32 v70, v66, v70
	v_exp_f32_e32 v85, v86
	v_exp_f32_e32 v74, v87
	v_mul_f32_e32 v71, v67, v71
	v_mov_b32_e32 v88, v68
	v_pk_mul_f32 v[90:91], v[76:77], v[84:85] op_sel_hi:[1,0]
	v_add_f32_e32 v74, 1.0, v74
	v_add_f32_e32 v85, 1.0, v85
	v_exp_f32_e32 v75, v90
	v_rcp_f32_e32 v86, v74
	v_exp_f32_e32 v74, v91
	v_rcp_f32_e32 v85, v85
	v_add_f32_e32 v75, 1.0, v75
	v_rcp_f32_e32 v87, v75
	v_add_f32_e32 v74, 1.0, v74
	v_rcp_f32_e32 v90, v74
	v_pk_mul_f32 v[74:75], v[66:67], v[84:85] op_sel_hi:[1,0]
	v_mov_b32_e32 v67, v89
	v_exp_f32_e32 v74, v74
	v_exp_f32_e32 v66, v75
	v_mul_f32_e32 v80, v76, v80
	v_mul_f32_e32 v81, v77, v81
	v_add_f32_e32 v74, 1.0, v74
	v_rcp_f32_e32 v74, v74
	v_add_f32_e32 v66, 1.0, v66
	v_rcp_f32_e32 v75, v66
	v_mov_b32_e32 v66, v72
	v_pk_mul_f32 v[66:67], v[88:89], v[66:67]
	v_pk_mul_f32 v[76:77], v[68:69], v[84:85] op_sel_hi:[1,0]
	v_mul_f32_e32 v70, v70, v67
	v_mul_f32_e32 v74, v70, v74
	v_exp_f32_e32 v70, v76
	v_mul_f32_e32 v71, v71, v67
	v_mul_f32_e32 v75, v71, v75
	v_exp_f32_e32 v71, v77
	v_add_f32_e32 v70, 1.0, v70
	v_rcp_f32_e32 v70, v70
	v_mul_f32_e32 v66, v66, v67
	v_add_f32_e32 v71, 1.0, v71
	v_rcp_f32_e32 v71, v71
	v_mul_f32_e32 v76, v66, v70
	v_mul_f32_e32 v66, v69, v73
	v_mul_f32_e32 v68, v78, v67
	v_mul_f32_e32 v66, v66, v67
	v_mul_f32_e32 v68, v68, v85
	v_mul_f32_e32 v72, v79, v67
	v_mul_f32_e32 v78, v80, v67
	v_mul_f32_e32 v79, v81, v67
	v_mul_f32_e32 v69, v66, v71
	v_mul_f32_e32 v72, v72, v86
	v_mul_f32_e32 v78, v78, v87
	v_mul_f32_e32 v79, v79, v90
	v_cvt_pk_bf16_f32 v66, v68, v72
	v_cvt_pk_bf16_f32 v67, v78, v79
	v_cvt_pk_bf16_f32 v68, v74, v75
	v_cvt_pk_bf16_f32 v69, v76, v69
	ds_read_b32 v73, v141 offset:512
	v_or_b32_e32 v82, 48, v140
	v_mad_i64_i32 v[82:83], s[8:9], v82, s87, v[130:131]
	v_lshl_add_u64 v[70:71], v[82:83], 0, v[114:115]
	global_store_dwordx4 v[70:71], v[66:69], off sc1
	v_mul_f32_e32 v62, v58, v62
	v_mul_f32_e32 v63, v59, v63
	s_waitcnt lgkmcnt(0)
	v_mul_f32_e32 v68, 0xbfb8aa3b, v73
	v_pk_mul_f32 v[70:71], v[58:59], v[68:69] op_sel_hi:[1,0]
	v_mul_f32_e32 v54, v50, v54
	v_exp_f32_e32 v69, v70
	v_exp_f32_e32 v58, v71
	v_mul_f32_e32 v55, v51, v55
	v_mov_b32_e32 v72, v52
	v_pk_mul_f32 v[74:75], v[60:61], v[68:69] op_sel_hi:[1,0]
	v_add_f32_e32 v58, 1.0, v58
	v_add_f32_e32 v69, 1.0, v69
	v_exp_f32_e32 v59, v74
	v_rcp_f32_e32 v70, v58
	v_exp_f32_e32 v58, v75
	v_rcp_f32_e32 v69, v69
	v_add_f32_e32 v59, 1.0, v59
	v_rcp_f32_e32 v71, v59
	v_add_f32_e32 v58, 1.0, v58
	v_rcp_f32_e32 v74, v58
	v_pk_mul_f32 v[58:59], v[50:51], v[68:69] op_sel_hi:[1,0]
	v_mov_b32_e32 v51, v73
	v_exp_f32_e32 v58, v58
	v_exp_f32_e32 v50, v59
	v_mul_f32_e32 v64, v60, v64
	v_mul_f32_e32 v65, v61, v65
	v_add_f32_e32 v58, 1.0, v58
	v_rcp_f32_e32 v58, v58
	v_add_f32_e32 v50, 1.0, v50
	v_rcp_f32_e32 v59, v50
	v_mov_b32_e32 v50, v56
	v_pk_mul_f32 v[50:51], v[72:73], v[50:51]
	v_pk_mul_f32 v[60:61], v[52:53], v[68:69] op_sel_hi:[1,0]
	v_mul_f32_e32 v54, v54, v51
	v_mul_f32_e32 v58, v54, v58
	v_exp_f32_e32 v54, v60
	v_mul_f32_e32 v55, v55, v51
	v_mul_f32_e32 v59, v55, v59
	v_exp_f32_e32 v55, v61
	v_add_f32_e32 v54, 1.0, v54
	v_rcp_f32_e32 v54, v54
	v_mul_f32_e32 v50, v50, v51
	v_add_f32_e32 v55, 1.0, v55
	v_rcp_f32_e32 v55, v55
	v_mul_f32_e32 v60, v50, v54
	v_mul_f32_e32 v50, v53, v57
	v_mul_f32_e32 v52, v62, v51
	v_mul_f32_e32 v50, v50, v51
	v_mul_f32_e32 v52, v52, v69
	v_mul_f32_e32 v56, v63, v51
	v_mul_f32_e32 v62, v64, v51
	v_mul_f32_e32 v63, v65, v51
	v_mul_f32_e32 v53, v50, v55
	v_mul_f32_e32 v56, v56, v70
	v_mul_f32_e32 v62, v62, v71
	v_mul_f32_e32 v63, v63, v74
	v_cvt_pk_bf16_f32 v50, v52, v56
	v_cvt_pk_bf16_f32 v51, v62, v63
	v_cvt_pk_bf16_f32 v52, v58, v59
	v_cvt_pk_bf16_f32 v53, v60, v53
	ds_read_b32 v57, v141 offset:576
	v_add_u32_e32 v66, 0x80, v140
	v_mad_i64_i32 v[66:67], s[8:9], v66, s87, v[130:131]
	v_lshl_add_u64 v[54:55], v[66:67], 0, v[114:115]
	global_store_dwordx4 v[54:55], v[50:53], off sc1
	v_mul_f32_e32 v46, v42, v46
	v_mul_f32_e32 v47, v43, v47
	s_waitcnt lgkmcnt(0)
	v_mul_f32_e32 v52, 0xbfb8aa3b, v57
	v_pk_mul_f32 v[54:55], v[42:43], v[52:53] op_sel_hi:[1,0]
	v_mul_f32_e32 v38, v34, v38
	v_exp_f32_e32 v53, v54
	v_exp_f32_e32 v42, v55
	v_mul_f32_e32 v39, v35, v39
	v_mov_b32_e32 v56, v36
	v_pk_mul_f32 v[58:59], v[44:45], v[52:53] op_sel_hi:[1,0]
	v_add_f32_e32 v42, 1.0, v42
	v_add_f32_e32 v53, 1.0, v53
	v_exp_f32_e32 v43, v58
	v_rcp_f32_e32 v54, v42
	v_exp_f32_e32 v42, v59
	v_rcp_f32_e32 v53, v53
	v_add_f32_e32 v43, 1.0, v43
	v_rcp_f32_e32 v55, v43
	v_add_f32_e32 v42, 1.0, v42
	v_rcp_f32_e32 v58, v42
	v_pk_mul_f32 v[42:43], v[34:35], v[52:53] op_sel_hi:[1,0]
	v_mov_b32_e32 v35, v57
	v_exp_f32_e32 v42, v42
	v_exp_f32_e32 v34, v43
	v_mul_f32_e32 v48, v44, v48
	v_mul_f32_e32 v49, v45, v49
	v_add_f32_e32 v42, 1.0, v42
	v_rcp_f32_e32 v42, v42
	v_add_f32_e32 v34, 1.0, v34
	v_rcp_f32_e32 v43, v34
	v_mov_b32_e32 v34, v40
	v_pk_mul_f32 v[34:35], v[56:57], v[34:35]
	v_pk_mul_f32 v[44:45], v[36:37], v[52:53] op_sel_hi:[1,0]
	v_mul_f32_e32 v38, v38, v35
	v_mul_f32_e32 v42, v38, v42
	v_exp_f32_e32 v38, v44
	v_mul_f32_e32 v39, v39, v35
	v_mul_f32_e32 v43, v39, v43
	v_exp_f32_e32 v39, v45
	v_add_f32_e32 v38, 1.0, v38
	v_rcp_f32_e32 v38, v38
	v_mul_f32_e32 v34, v34, v35
	v_add_f32_e32 v39, 1.0, v39
	v_rcp_f32_e32 v39, v39
	v_mul_f32_e32 v44, v34, v38
	v_mul_f32_e32 v34, v37, v41
	v_mul_f32_e32 v36, v46, v35
	v_mul_f32_e32 v34, v34, v35
	v_mul_f32_e32 v36, v36, v53
	v_mul_f32_e32 v40, v47, v35
	v_mul_f32_e32 v46, v48, v35
	v_mul_f32_e32 v47, v49, v35
	v_mul_f32_e32 v37, v34, v39
	v_mul_f32_e32 v40, v40, v54
	v_mul_f32_e32 v46, v46, v55
	v_mul_f32_e32 v47, v47, v58
	v_cvt_pk_bf16_f32 v34, v36, v40
	v_cvt_pk_bf16_f32 v35, v46, v47
	v_cvt_pk_bf16_f32 v36, v42, v43
	v_cvt_pk_bf16_f32 v37, v44, v37
	ds_read_b32 v41, v141 offset:640
	v_add_u32_e32 v50, 0x90, v140
	v_mad_i64_i32 v[50:51], s[8:9], v50, s87, v[130:131]
	v_lshl_add_u64 v[38:39], v[50:51], 0, v[114:115]
	global_store_dwordx4 v[38:39], v[34:37], off sc1
	v_mul_f32_e32 v30, v26, v30
	v_mul_f32_e32 v31, v27, v31
	s_waitcnt lgkmcnt(0)
	v_mul_f32_e32 v36, 0xbfb8aa3b, v41
	v_pk_mul_f32 v[38:39], v[26:27], v[36:37] op_sel_hi:[1,0]
	v_mul_f32_e32 v22, v18, v22
	v_exp_f32_e32 v37, v38
	v_exp_f32_e32 v26, v39
	v_mul_f32_e32 v23, v19, v23
	v_mov_b32_e32 v40, v20
	v_pk_mul_f32 v[42:43], v[28:29], v[36:37] op_sel_hi:[1,0]
	v_add_f32_e32 v26, 1.0, v26
	v_add_f32_e32 v37, 1.0, v37
	v_exp_f32_e32 v27, v42
	v_rcp_f32_e32 v38, v26
	v_exp_f32_e32 v26, v43
	v_rcp_f32_e32 v37, v37
	v_add_f32_e32 v27, 1.0, v27
	v_rcp_f32_e32 v39, v27
	v_add_f32_e32 v26, 1.0, v26
	v_rcp_f32_e32 v42, v26
	v_pk_mul_f32 v[26:27], v[18:19], v[36:37] op_sel_hi:[1,0]
	v_mov_b32_e32 v19, v41
	v_exp_f32_e32 v26, v26
	v_exp_f32_e32 v18, v27
	v_mul_f32_e32 v32, v28, v32
	v_mul_f32_e32 v33, v29, v33
	v_add_f32_e32 v26, 1.0, v26
	v_rcp_f32_e32 v26, v26
	v_add_f32_e32 v18, 1.0, v18
	v_rcp_f32_e32 v27, v18
	v_mov_b32_e32 v18, v24
	v_pk_mul_f32 v[18:19], v[40:41], v[18:19]
	v_pk_mul_f32 v[28:29], v[20:21], v[36:37] op_sel_hi:[1,0]
	v_mul_f32_e32 v22, v22, v19
	v_mul_f32_e32 v26, v22, v26
	v_exp_f32_e32 v22, v28
	v_mul_f32_e32 v23, v23, v19
	v_mul_f32_e32 v27, v23, v27
	v_exp_f32_e32 v23, v29
	v_add_f32_e32 v22, 1.0, v22
	v_rcp_f32_e32 v22, v22
	v_mul_f32_e32 v18, v18, v19
	v_add_f32_e32 v23, 1.0, v23
	v_rcp_f32_e32 v23, v23
	v_mul_f32_e32 v28, v18, v22
	v_mul_f32_e32 v18, v21, v25
	v_mul_f32_e32 v20, v30, v19
	v_mul_f32_e32 v18, v18, v19
	v_mul_f32_e32 v20, v20, v37
	v_mul_f32_e32 v24, v31, v19
	v_mul_f32_e32 v30, v32, v19
	v_mul_f32_e32 v31, v33, v19
	v_mul_f32_e32 v21, v18, v23
	v_mul_f32_e32 v24, v24, v38
	v_mul_f32_e32 v30, v30, v39
	v_mul_f32_e32 v31, v31, v42
	v_cvt_pk_bf16_f32 v18, v20, v24
	v_cvt_pk_bf16_f32 v19, v30, v31
	v_cvt_pk_bf16_f32 v20, v26, v27
	v_cvt_pk_bf16_f32 v21, v28, v21
	ds_read_b32 v25, v141 offset:704
	v_add_u32_e32 v34, 0xa0, v140
	v_mad_i64_i32 v[34:35], s[8:9], v34, s87, v[130:131]
	v_lshl_add_u64 v[22:23], v[34:35], 0, v[114:115]
	global_store_dwordx4 v[22:23], v[18:21], off sc1
	v_mul_f32_e32 v14, v10, v14
	v_mul_f32_e32 v15, v11, v15
	s_waitcnt lgkmcnt(0)
	v_mul_f32_e32 v20, 0xbfb8aa3b, v25
	v_pk_mul_f32 v[22:23], v[10:11], v[20:21] op_sel_hi:[1,0]
	v_mul_f32_e32 v6, v2, v6
	v_exp_f32_e32 v21, v22
	v_exp_f32_e32 v10, v23
	v_mul_f32_e32 v7, v3, v7
	v_mov_b32_e32 v24, v4
	v_pk_mul_f32 v[26:27], v[12:13], v[20:21] op_sel_hi:[1,0]
	v_add_f32_e32 v10, 1.0, v10
	v_add_f32_e32 v21, 1.0, v21
	v_exp_f32_e32 v11, v26
	v_rcp_f32_e32 v22, v10
	v_exp_f32_e32 v10, v27
	v_rcp_f32_e32 v21, v21
	v_add_f32_e32 v11, 1.0, v11
	v_rcp_f32_e32 v23, v11
	v_add_f32_e32 v10, 1.0, v10
	v_rcp_f32_e32 v26, v10
	v_pk_mul_f32 v[10:11], v[2:3], v[20:21] op_sel_hi:[1,0]
	v_mov_b32_e32 v3, v25
	v_exp_f32_e32 v10, v10
	v_exp_f32_e32 v2, v11
	v_mul_f32_e32 v16, v12, v16
	v_mul_f32_e32 v17, v13, v17
	v_add_f32_e32 v10, 1.0, v10
	v_rcp_f32_e32 v10, v10
	v_add_f32_e32 v2, 1.0, v2
	v_rcp_f32_e32 v11, v2
	v_mov_b32_e32 v2, v8
	v_pk_mul_f32 v[2:3], v[24:25], v[2:3]
	v_pk_mul_f32 v[12:13], v[4:5], v[20:21] op_sel_hi:[1,0]
	v_mul_f32_e32 v6, v6, v3
	v_mul_f32_e32 v10, v6, v10
	v_exp_f32_e32 v6, v12
	v_mul_f32_e32 v7, v7, v3
	v_mul_f32_e32 v11, v7, v11
	v_exp_f32_e32 v7, v13
	v_add_f32_e32 v6, 1.0, v6
	v_rcp_f32_e32 v6, v6
	v_mul_f32_e32 v2, v2, v3
	v_add_f32_e32 v7, 1.0, v7
	v_rcp_f32_e32 v7, v7
	v_mul_f32_e32 v12, v2, v6
	v_mul_f32_e32 v2, v5, v9
	v_add_u32_e32 v18, 0xb0, v140
	v_mul_f32_e32 v4, v14, v3
	v_mul_f32_e32 v2, v2, v3
	v_mad_i64_i32 v[18:19], s[8:9], v18, s87, v[130:131]
	v_mul_f32_e32 v4, v4, v21
	v_mul_f32_e32 v8, v15, v3
	v_mul_f32_e32 v14, v16, v3
	v_mul_f32_e32 v15, v17, v3
	v_mul_f32_e32 v5, v2, v7
	v_mul_f32_e32 v8, v8, v22
	v_mul_f32_e32 v14, v14, v23
	v_mul_f32_e32 v15, v15, v26
	v_lshl_add_u64 v[6:7], v[18:19], 0, v[114:115]
	v_cvt_pk_bf16_f32 v2, v4, v8
	v_cvt_pk_bf16_f32 v3, v14, v15
	v_cvt_pk_bf16_f32 v4, v10, v11
	v_cvt_pk_bf16_f32 v5, v12, v5
	s_andn2_b64 vcc, exec, s[0:1]
	s_mov_b64 s[0:1], -1
	global_store_dwordx4 v[6:7], v[2:5], off sc1
	s_cbranch_vccnz .LBB0_602
	s_andn2_b64 vcc, exec, s[4:5]
	v_mov_b64 v[122:123], 0
	v_mov_b64 v[124:125], 0
	v_mov_b64 v[114:115], 0
	v_mov_b64 v[116:117], 0
	v_mov_b64 v[106:107], 0
	v_mov_b64 v[108:109], 0
	v_mov_b64 v[98:99], 0
	v_mov_b64 v[100:101], 0
	v_mov_b64 v[90:91], 0
	v_mov_b64 v[92:93], 0
	v_mov_b64 v[82:83], 0
	v_mov_b64 v[84:85], 0
	v_mov_b64 v[74:75], 0
	v_mov_b64 v[76:77], 0
	v_mov_b64 v[66:67], 0
	v_mov_b64 v[68:69], 0
	v_mov_b64 v[126:127], 0
	v_mov_b64 v[128:129], 0
	v_mov_b64 v[118:119], 0
	v_mov_b64 v[120:121], 0
	v_mov_b64 v[110:111], 0
	v_mov_b64 v[112:113], 0
	v_mov_b64 v[102:103], 0
	v_mov_b64 v[104:105], 0
	v_mov_b64 v[94:95], 0
	v_mov_b64 v[96:97], 0
	v_mov_b64 v[86:87], 0
	v_mov_b64 v[88:89], 0
	v_mov_b64 v[78:79], 0
	v_mov_b64 v[80:81], 0
	v_mov_b64 v[70:71], 0
	v_mov_b64 v[72:73], 0
	v_mov_b64 v[58:59], 0
	v_mov_b64 v[60:61], 0
	v_mov_b64 v[50:51], 0
	v_mov_b64 v[52:53], 0
	v_mov_b64 v[42:43], 0
	v_mov_b64 v[44:45], 0
	v_mov_b64 v[34:35], 0
	v_mov_b64 v[36:37], 0
	v_mov_b64 v[26:27], 0
	v_mov_b64 v[28:29], 0
	v_mov_b64 v[18:19], 0
	v_mov_b64 v[20:21], 0
	v_mov_b64 v[10:11], 0
	v_mov_b64 v[12:13], 0
	v_mov_b64 v[2:3], 0
	v_mov_b64 v[4:5], 0
	v_mov_b64 v[62:63], 0
	v_mov_b64 v[64:65], 0
	v_mov_b64 v[54:55], 0
	v_mov_b64 v[56:57], 0
	v_mov_b64 v[46:47], 0
	v_mov_b64 v[48:49], 0
	v_mov_b64 v[38:39], 0
	v_mov_b64 v[40:41], 0
	v_mov_b64 v[30:31], 0
	v_mov_b64 v[32:33], 0
	v_mov_b64 v[22:23], 0
	v_mov_b64 v[24:25], 0
	v_mov_b64 v[14:15], 0
	v_mov_b64 v[16:17], 0
	v_mov_b64 v[6:7], 0
	v_mov_b64 v[8:9], 0
	s_cbranch_vccnz .LBB0_601
	s_barrier
	s_branch .LBB0_601

.LBB0_618:
	ds_read2_b32 v[100:101], v79 offset1:65
	s_movk_i32 s0, 0xffd4
	v_mad_u64_u32 v[104:105], s[0:1], v0, s0, v[74:75]
	v_lshlrev_b32_e32 v0, 6, v104
	s_waitcnt vmcnt(0) lgkmcnt(0)
	v_mul_f32_e32 v39, v6, v100
	v_mul_f32_e32 v43, v7, v101
	v_cvt_pk_bf16_f32 v100, v39, v43
	ds_read2_b32 v[102:103], v79 offset0:130 offset1:195
	v_add_u32_e32 v39, 0x400, v79
	v_and_b32_e32 v0, 64, v0
	v_lshl_add_u64 v[76:77], v[76:77], 1, v[10:11]
	s_waitcnt lgkmcnt(0)
	v_mul_f32_e32 v43, v8, v102
	v_mul_f32_e32 v47, v9, v103
	v_cvt_pk_bf16_f32 v101, v43, v47
	ds_read2_b32 v[102:103], v39 offset0:4 offset1:69
	s_waitcnt lgkmcnt(0)
	v_mul_f32_e32 v43, v2, v102
	v_mul_f32_e32 v47, v3, v103
	v_cvt_pk_bf16_f32 v102, v43, v47
	v_lshlrev_b32_e32 v43, 7, v104
	ds_read2_b32 v[106:107], v39 offset0:134 offset1:199
	v_and_or_b32 v0, v43, s15, v0
	v_or_b32_e32 v104, v0, v78
	v_ashrrev_i32_e32 v105, 31, v104
	v_lshlrev_b64 v[104:105], 11, v[104:105]
	v_lshl_add_u64 v[104:105], v[76:77], 0, v[104:105]
	s_waitcnt lgkmcnt(0)
	v_mul_f32_e32 v43, v4, v106
	v_mul_f32_e32 v47, v5, v107
	v_cvt_pk_bf16_f32 v103, v43, v47
	flat_store_dwordx4 v[104:105], v[100:103] sc1
	ds_read2_b32 v[100:101], v79 offset0:8 offset1:73
	v_or_b32_e32 v106, v0, v80
	v_ashrrev_i32_e32 v107, 31, v106
	v_lshlrev_b64 v[106:107], 11, v[106:107]
	v_lshl_add_u64 v[106:107], v[76:77], 0, v[106:107]
	s_waitcnt lgkmcnt(0)
	v_mul_f32_e32 v43, v6, v100
	v_mul_f32_e32 v47, v7, v101
	v_cvt_pk_bf16_f32 v100, v43, v47
	ds_read2_b32 v[102:103], v79 offset0:138 offset1:203
	s_waitcnt lgkmcnt(0)
	v_mul_f32_e32 v43, v8, v102
	v_mul_f32_e32 v47, v9, v103
	v_cvt_pk_bf16_f32 v101, v43, v47
	ds_read2_b32 v[102:103], v39 offset0:12 offset1:77
	s_waitcnt lgkmcnt(0)
	v_mul_f32_e32 v43, v2, v102
	v_mul_f32_e32 v47, v3, v103
	v_cvt_pk_bf16_f32 v102, v43, v47
	ds_read2_b32 v[104:105], v39 offset0:142 offset1:207
	s_waitcnt lgkmcnt(0)
	v_mul_f32_e32 v43, v4, v104
	v_mul_f32_e32 v47, v5, v105
	v_cvt_pk_bf16_f32 v103, v43, v47
	flat_store_dwordx4 v[106:107], v[100:103] sc1
	ds_read2_b32 v[100:101], v79 offset0:16 offset1:81
	v_or_b32_e32 v106, v0, v81
	v_ashrrev_i32_e32 v107, 31, v106
	v_lshlrev_b64 v[106:107], 11, v[106:107]
	v_lshl_add_u64 v[106:107], v[76:77], 0, v[106:107]
	s_waitcnt lgkmcnt(0)
	v_mul_f32_e32 v43, v6, v100
	v_mul_f32_e32 v47, v7, v101
	v_cvt_pk_bf16_f32 v100, v43, v47
	ds_read2_b32 v[102:103], v79 offset0:146 offset1:211
	s_waitcnt lgkmcnt(0)
	v_mul_f32_e32 v43, v8, v102
	v_mul_f32_e32 v47, v9, v103
	v_cvt_pk_bf16_f32 v101, v43, v47
	ds_read2_b32 v[102:103], v39 offset0:20 offset1:85
	s_waitcnt lgkmcnt(0)
	v_mul_f32_e32 v43, v2, v102
	v_mul_f32_e32 v47, v3, v103
	v_cvt_pk_bf16_f32 v102, v43, v47
	ds_read2_b32 v[104:105], v39 offset0:150 offset1:215
	s_waitcnt lgkmcnt(0)
	v_mul_f32_e32 v43, v4, v104
	v_mul_f32_e32 v47, v5, v105
	v_cvt_pk_bf16_f32 v103, v43, v47
	flat_store_dwordx4 v[106:107], v[100:103] sc1
	ds_read2_b32 v[100:101], v79 offset0:24 offset1:89
	v_or_b32_e32 v106, v0, v82
	v_ashrrev_i32_e32 v107, 31, v106
	v_lshlrev_b64 v[106:107], 11, v[106:107]
	v_lshl_add_u64 v[106:107], v[76:77], 0, v[106:107]
	s_waitcnt lgkmcnt(0)
	v_mul_f32_e32 v43, v6, v100
	v_mul_f32_e32 v47, v7, v101
	v_cvt_pk_bf16_f32 v100, v43, v47
	ds_read2_b32 v[102:103], v79 offset0:154 offset1:219
	s_waitcnt lgkmcnt(0)
	v_mul_f32_e32 v43, v8, v102
	v_mul_f32_e32 v47, v9, v103
	v_cvt_pk_bf16_f32 v101, v43, v47
	ds_read2_b32 v[102:103], v39 offset0:28 offset1:93
	s_waitcnt lgkmcnt(0)
	v_mul_f32_e32 v43, v2, v102
	v_mul_f32_e32 v47, v3, v103
	v_cvt_pk_bf16_f32 v102, v43, v47
	ds_read2_b32 v[104:105], v39 offset0:158 offset1:223
	s_waitcnt lgkmcnt(0)
	v_mul_f32_e32 v43, v4, v104
	v_mul_f32_e32 v47, v5, v105
	v_cvt_pk_bf16_f32 v103, v43, v47
	flat_store_dwordx4 v[106:107], v[100:103] sc1
	ds_read2_b32 v[100:101], v79 offset0:32 offset1:97
	v_or_b32_e32 v106, v0, v83
	v_ashrrev_i32_e32 v107, 31, v106
	v_lshlrev_b64 v[106:107], 11, v[106:107]
	v_lshl_add_u64 v[106:107], v[76:77], 0, v[106:107]
	s_waitcnt lgkmcnt(0)
	v_mul_f32_e32 v43, v6, v100
	v_mul_f32_e32 v47, v7, v101
	v_cvt_pk_bf16_f32 v100, v43, v47
	ds_read2_b32 v[102:103], v79 offset0:162 offset1:227
	s_waitcnt lgkmcnt(0)
	v_mul_f32_e32 v43, v8, v102
	v_mul_f32_e32 v47, v9, v103
	v_cvt_pk_bf16_f32 v101, v43, v47
	ds_read2_b32 v[102:103], v39 offset0:36 offset1:101
	s_waitcnt lgkmcnt(0)
	v_mul_f32_e32 v43, v2, v102
	v_mul_f32_e32 v47, v3, v103
	v_cvt_pk_bf16_f32 v102, v43, v47
	ds_read2_b32 v[104:105], v39 offset0:166 offset1:231
	s_waitcnt lgkmcnt(0)
	v_mul_f32_e32 v43, v4, v104
	v_mul_f32_e32 v47, v5, v105
	v_cvt_pk_bf16_f32 v103, v43, v47
	flat_store_dwordx4 v[106:107], v[100:103] sc1
	ds_read2_b32 v[100:101], v79 offset0:40 offset1:105
	v_or_b32_e32 v106, v0, v84
	v_ashrrev_i32_e32 v107, 31, v106
	v_lshlrev_b64 v[106:107], 11, v[106:107]
	v_lshl_add_u64 v[106:107], v[76:77], 0, v[106:107]
	s_waitcnt lgkmcnt(0)
	v_mul_f32_e32 v43, v6, v100
	v_mul_f32_e32 v47, v7, v101
	v_cvt_pk_bf16_f32 v100, v43, v47
	ds_read2_b32 v[102:103], v79 offset0:170 offset1:235
	s_waitcnt lgkmcnt(0)
	v_mul_f32_e32 v43, v8, v102
	v_mul_f32_e32 v47, v9, v103
	v_cvt_pk_bf16_f32 v101, v43, v47
	ds_read2_b32 v[102:103], v39 offset0:44 offset1:109
	s_waitcnt lgkmcnt(0)
	v_mul_f32_e32 v43, v2, v102
	v_mul_f32_e32 v47, v3, v103
	v_cvt_pk_bf16_f32 v102, v43, v47
	ds_read2_b32 v[104:105], v39 offset0:174 offset1:239
	s_waitcnt lgkmcnt(0)
	v_mul_f32_e32 v43, v4, v104
	v_mul_f32_e32 v47, v5, v105
	v_cvt_pk_bf16_f32 v103, v43, v47
	flat_store_dwordx4 v[106:107], v[100:103] sc1
	ds_read2_b32 v[100:101], v79 offset0:48 offset1:113
	v_or_b32_e32 v106, v0, v85
	v_ashrrev_i32_e32 v107, 31, v106
	v_lshlrev_b64 v[106:107], 11, v[106:107]
	v_lshl_add_u64 v[106:107], v[76:77], 0, v[106:107]
	s_waitcnt lgkmcnt(0)
	v_mul_f32_e32 v43, v6, v100
	v_mul_f32_e32 v47, v7, v101
	v_cvt_pk_bf16_f32 v100, v43, v47
	ds_read2_b32 v[102:103], v79 offset0:178 offset1:243
	s_waitcnt lgkmcnt(0)
	v_mul_f32_e32 v43, v8, v102
	v_mul_f32_e32 v47, v9, v103
	v_cvt_pk_bf16_f32 v101, v43, v47
	ds_read2_b32 v[102:103], v39 offset0:52 offset1:117
	s_waitcnt lgkmcnt(0)
	v_mul_f32_e32 v43, v2, v102
	v_mul_f32_e32 v47, v3, v103
	v_cvt_pk_bf16_f32 v102, v43, v47
	ds_read2_b32 v[104:105], v39 offset0:182 offset1:247
	s_waitcnt lgkmcnt(0)
	v_mul_f32_e32 v43, v4, v104
	v_mul_f32_e32 v47, v5, v105
	v_cvt_pk_bf16_f32 v103, v43, v47
	flat_store_dwordx4 v[106:107], v[100:103] sc1
	ds_read2_b32 v[100:101], v79 offset0:56 offset1:121
	s_waitcnt lgkmcnt(0)
	v_mul_f32_e32 v6, v6, v100
	v_mul_f32_e32 v7, v7, v101
	v_cvt_pk_bf16_f32 v6, v6, v7
	ds_read2_b32 v[100:101], v79 offset0:186 offset1:251
	s_waitcnt lgkmcnt(0)
	v_mul_f32_e32 v7, v8, v100
	v_mul_f32_e32 v8, v9, v101
	v_cvt_pk_bf16_f32 v7, v7, v8
	ds_read2_b32 v[8:9], v39 offset0:60 offset1:125
	v_or_b32_e32 v100, v0, v86
	v_ashrrev_i32_e32 v101, 31, v100
	v_lshlrev_b64 v[100:101], 11, v[100:101]
	s_waitcnt lgkmcnt(0)
	v_mul_f32_e32 v2, v2, v8
	v_mul_f32_e32 v3, v3, v9
	v_cvt_pk_bf16_f32 v8, v2, v3
	ds_read2_b32 v[2:3], v39 offset0:190 offset1:255
	s_waitcnt lgkmcnt(0)
	v_mul_f32_e32 v0, v4, v2
	v_mul_f32_e32 v2, v5, v3
	v_cvt_pk_bf16_f32 v9, v0, v2
	v_lshl_add_u64 v[2:3], v[76:77], 0, v[100:101]
	flat_store_dwordx4 v[2:3], v[6:9] sc1
	s_waitcnt lgkmcnt(0)

.LBB0_632:
	v_lshl_add_u64 v[4:5], v[2:3], 0, s[48:49]
	v_add_co_u32_e32 v6, vcc, 0x1000, v4
	s_mov_b64 s[0:1], vcc
	v_add_co_u32_e32 v8, vcc, 0x2000, v4
	v_addc_co_u32_e64 v7, s[0:1], 0, v5, s[0:1]
	s_mov_b64 s[0:1], vcc
	v_add_co_u32_e32 v76, vcc, 0x3000, v4
	v_addc_co_u32_e64 v9, s[0:1], 0, v5, s[0:1]
	s_mov_b64 s[0:1], vcc
	s_nop 0
	v_addc_co_u32_e64 v77, s[0:1], 0, v5, s[0:1]
	global_load_dword v39, v[4:5], off nt
	global_load_dword v43, v[6:7], off nt
	global_load_dword v47, v[8:9], off nt
	global_load_dword v51, v[76:77], off nt
	v_add_co_u32_e32 v6, vcc, 0x4000, v4
	s_mov_b64 s[0:1], vcc
	v_add_co_u32_e32 v8, vcc, 0x5000, v4
	v_addc_co_u32_e64 v7, s[0:1], 0, v5, s[0:1]
	s_mov_b64 s[0:1], vcc
	v_add_co_u32_e32 v76, vcc, 0x6000, v4
	v_addc_co_u32_e64 v9, s[0:1], 0, v5, s[0:1]
	s_mov_b64 s[0:1], vcc
	s_nop 0
	v_addc_co_u32_e64 v77, s[0:1], 0, v5, s[0:1]
	global_load_dword v55, v[6:7], off nt
	global_load_dword v61, v[8:9], off nt
	global_load_dword v73, v[76:77], off nt
	v_add_co_u32_e32 v6, vcc, 0x7000, v4
	s_mov_b64 s[0:1], vcc
	v_add_co_u32_e32 v8, vcc, 0x8000, v4
	v_addc_co_u32_e64 v7, s[0:1], 0, v5, s[0:1]
	s_mov_b64 s[0:1], vcc
	v_add_co_u32_e32 v76, vcc, 0x9000, v4
	v_addc_co_u32_e64 v9, s[0:1], 0, v5, s[0:1]
	s_mov_b64 s[0:1], vcc
	s_nop 0
	v_addc_co_u32_e64 v77, s[0:1], 0, v5, s[0:1]
	global_load_dword v99, v[6:7], off nt
	global_load_dword v100, v[8:9], off nt
	global_load_dword v101, v[76:77], off nt
	v_add_co_u32_e32 v6, vcc, 0xa000, v4
	s_mov_b64 s[0:1], vcc
	v_add_co_u32_e32 v8, vcc, 0xb000, v4
	v_addc_co_u32_e64 v7, s[0:1], 0, v5, s[0:1]
	s_mov_b64 s[0:1], vcc
	v_add_co_u32_e32 v76, vcc, 0xc000, v4
	v_addc_co_u32_e64 v9, s[0:1], 0, v5, s[0:1]
	s_mov_b64 s[0:1], vcc
	global_load_dword v102, v[6:7], off nt
	global_load_dword v103, v[8:9], off nt
	v_add_co_u32_e32 v6, vcc, 0xd000, v4
	v_addc_co_u32_e64 v77, s[0:1], 0, v5, s[0:1]
	s_mov_b64 s[0:1], vcc
	v_add_co_u32_e32 v8, vcc, 0xe000, v4
	v_addc_co_u32_e64 v7, s[0:1], 0, v5, s[0:1]
	s_mov_b64 s[0:1], vcc
	v_add_co_u32_e32 v4, vcc, 0xf000, v4
	v_addc_co_u32_e64 v9, s[0:1], 0, v5, s[0:1]
	global_load_dword v76, v[76:77], off nt
	v_addc_co_u32_e32 v5, vcc, 0, v5, vcc
	global_load_dword v6, v[6:7], off nt
	s_nop 0
	global_load_dword v7, v[8:9], off nt
	s_nop 0
	global_load_dword v4, v[4:5], off nt
	s_add_u32 s48, s48, 0x10000
	s_addc_u32 s49, s49, 0
	v_add_u32_e32 v5, 0x400, v0
	v_add_u32_e32 v8, 0x800, v0
	v_add_u32_e32 v9, 0xc00, v0
	s_cmp_lg_u32 s48, 0x40000
	s_waitcnt vmcnt(0)
	ds_write2_b32 v0, v39, v43 offset1:65
	ds_write2_b32 v0, v47, v51 offset0:130 offset1:195
	v_add_u32_e32 v0, 0x1040, v0
	ds_write2_b32 v5, v55, v61 offset0:4 offset1:69
	ds_write2_b32 v5, v73, v99 offset0:134 offset1:199
	ds_write2_b32 v8, v100, v101 offset0:8 offset1:73
	ds_write2_b32 v8, v102, v103 offset0:138 offset1:203
	ds_write2_b32 v9, v76, v6 offset0:12 offset1:77
	ds_write2_b32 v9, v7, v4 offset0:142 offset1:207
	s_cbranch_scc1 .LBB0_632
	v_add_u32_e32 v0, 0xffffe240, v74
	v_lshrrev_b32_e32 v6, 4, v0
	v_lshlrev_b32_e32 v7, 6, v0
	v_lshlrev_b32_e32 v8, 10, v6
	v_sub_u32_e32 v43, v7, v8
	s_waitcnt lgkmcnt(0)
	v_or_b32_e32 v76, v43, v78
	ds_read2_b32 v[2:3], v79 offset1:65
	v_lshlrev_b32_e32 v0, 7, v6
	v_ashrrev_i32_e32 v77, 31, v76
	s_waitcnt lgkmcnt(0)
	v_cvt_pk_bf16_f32 v2, v2, v3
	ds_read2_b32 v[4:5], v79 offset0:130 offset1:195
	v_add_u32_e32 v39, 0x400, v79
	v_lshl_add_u64 v[6:7], v[12:13], 0, v[0:1]
	v_lshlrev_b64 v[76:77], 11, v[76:77]
	s_waitcnt lgkmcnt(0)
	v_cvt_pk_bf16_f32 v3, v4, v5
	ds_read2_b32 v[4:5], v39 offset0:4 offset1:69
	v_lshl_add_u64 v[76:77], v[6:7], 0, v[76:77]
	s_waitcnt lgkmcnt(0)
	v_cvt_pk_bf16_f32 v4, v4, v5
	ds_read2_b32 v[8:9], v39 offset0:134 offset1:199
	s_waitcnt lgkmcnt(0)
	v_cvt_pk_bf16_f32 v5, v8, v9
	flat_store_dwordx4 v[76:77], v[2:5] sc1
	v_or_b32_e32 v76, v43, v80
	ds_read2_b32 v[2:3], v79 offset0:8 offset1:73
	v_ashrrev_i32_e32 v77, 31, v76
	s_waitcnt lgkmcnt(0)
	v_cvt_pk_bf16_f32 v2, v2, v3
	ds_read2_b32 v[4:5], v79 offset0:138 offset1:203
	v_lshlrev_b64 v[76:77], 11, v[76:77]
	s_waitcnt lgkmcnt(0)
	v_cvt_pk_bf16_f32 v3, v4, v5
	ds_read2_b32 v[4:5], v39 offset0:12 offset1:77
	v_lshl_add_u64 v[76:77], v[6:7], 0, v[76:77]
	s_waitcnt lgkmcnt(0)
	v_cvt_pk_bf16_f32 v4, v4, v5
	ds_read2_b32 v[8:9], v39 offset0:142 offset1:207
	s_waitcnt lgkmcnt(0)
	v_cvt_pk_bf16_f32 v5, v8, v9
	flat_store_dwordx4 v[76:77], v[2:5] sc1
	v_or_b32_e32 v76, v43, v81
	ds_read2_b32 v[2:3], v79 offset0:16 offset1:81
	v_ashrrev_i32_e32 v77, 31, v76
	s_waitcnt lgkmcnt(0)
	v_cvt_pk_bf16_f32 v2, v2, v3
	ds_read2_b32 v[4:5], v79 offset0:146 offset1:211
	v_lshlrev_b64 v[76:77], 11, v[76:77]
	s_waitcnt lgkmcnt(0)
	v_cvt_pk_bf16_f32 v3, v4, v5
	ds_read2_b32 v[4:5], v39 offset0:20 offset1:85
	v_lshl_add_u64 v[76:77], v[6:7], 0, v[76:77]
	s_waitcnt lgkmcnt(0)
	v_cvt_pk_bf16_f32 v4, v4, v5
	ds_read2_b32 v[8:9], v39 offset0:150 offset1:215
	s_waitcnt lgkmcnt(0)
	v_cvt_pk_bf16_f32 v5, v8, v9
	flat_store_dwordx4 v[76:77], v[2:5] sc1
	v_or_b32_e32 v76, v43, v82
	ds_read2_b32 v[2:3], v79 offset0:24 offset1:89
	v_ashrrev_i32_e32 v77, 31, v76
	s_waitcnt lgkmcnt(0)
	v_cvt_pk_bf16_f32 v2, v2, v3
	ds_read2_b32 v[4:5], v79 offset0:154 offset1:219
	v_lshlrev_b64 v[76:77], 11, v[76:77]
	s_waitcnt lgkmcnt(0)
	v_cvt_pk_bf16_f32 v3, v4, v5
	ds_read2_b32 v[4:5], v39 offset0:28 offset1:93
	v_lshl_add_u64 v[76:77], v[6:7], 0, v[76:77]
	s_waitcnt lgkmcnt(0)
	v_cvt_pk_bf16_f32 v4, v4, v5
	ds_read2_b32 v[8:9], v39 offset0:158 offset1:223
	s_waitcnt lgkmcnt(0)
	v_cvt_pk_bf16_f32 v5, v8, v9
	flat_store_dwordx4 v[76:77], v[2:5] sc1
	v_or_b32_e32 v76, v43, v83
	ds_read2_b32 v[2:3], v79 offset0:32 offset1:97
	v_ashrrev_i32_e32 v77, 31, v76
	s_waitcnt lgkmcnt(0)
	v_cvt_pk_bf16_f32 v2, v2, v3
	ds_read2_b32 v[4:5], v79 offset0:162 offset1:227
	v_lshlrev_b64 v[76:77], 11, v[76:77]
	s_waitcnt lgkmcnt(0)
	v_cvt_pk_bf16_f32 v3, v4, v5
	ds_read2_b32 v[4:5], v39 offset0:36 offset1:101
	v_lshl_add_u64 v[76:77], v[6:7], 0, v[76:77]
	s_waitcnt lgkmcnt(0)
	v_cvt_pk_bf16_f32 v4, v4, v5
	ds_read2_b32 v[8:9], v39 offset0:166 offset1:231
	s_waitcnt lgkmcnt(0)
	v_cvt_pk_bf16_f32 v5, v8, v9
	flat_store_dwordx4 v[76:77], v[2:5] sc1
	v_or_b32_e32 v76, v43, v84
	ds_read2_b32 v[2:3], v79 offset0:40 offset1:105
	v_ashrrev_i32_e32 v77, 31, v76
	s_waitcnt lgkmcnt(0)
	v_cvt_pk_bf16_f32 v2, v2, v3
	ds_read2_b32 v[4:5], v79 offset0:170 offset1:235
	v_lshlrev_b64 v[76:77], 11, v[76:77]
	s_waitcnt lgkmcnt(0)
	v_cvt_pk_bf16_f32 v3, v4, v5
	ds_read2_b32 v[4:5], v39 offset0:44 offset1:109
	v_lshl_add_u64 v[76:77], v[6:7], 0, v[76:77]
	s_waitcnt lgkmcnt(0)
	v_cvt_pk_bf16_f32 v4, v4, v5
	ds_read2_b32 v[8:9], v39 offset0:174 offset1:239
	s_waitcnt lgkmcnt(0)
	v_cvt_pk_bf16_f32 v5, v8, v9
	flat_store_dwordx4 v[76:77], v[2:5] sc1
	v_or_b32_e32 v76, v43, v85
	ds_read2_b32 v[2:3], v79 offset0:48 offset1:113
	v_ashrrev_i32_e32 v77, 31, v76
	s_waitcnt lgkmcnt(0)
	v_cvt_pk_bf16_f32 v2, v2, v3
	ds_read2_b32 v[4:5], v79 offset0:178 offset1:243
	v_lshlrev_b64 v[76:77], 11, v[76:77]
	s_waitcnt lgkmcnt(0)
	v_cvt_pk_bf16_f32 v3, v4, v5
	ds_read2_b32 v[4:5], v39 offset0:52 offset1:117
	v_lshl_add_u64 v[76:77], v[6:7], 0, v[76:77]
	s_waitcnt lgkmcnt(0)
	v_cvt_pk_bf16_f32 v4, v4, v5
	ds_read2_b32 v[8:9], v39 offset0:182 offset1:247
	s_waitcnt lgkmcnt(0)
	v_cvt_pk_bf16_f32 v5, v8, v9
	flat_store_dwordx4 v[76:77], v[2:5] sc1
	v_or_b32_e32 v76, v43, v86
	ds_read2_b32 v[2:3], v79 offset0:56 offset1:121
	v_ashrrev_i32_e32 v77, 31, v76
	s_waitcnt lgkmcnt(0)
	v_cvt_pk_bf16_f32 v2, v2, v3
	ds_read2_b32 v[4:5], v79 offset0:186 offset1:251
	v_lshlrev_b64 v[76:77], 11, v[76:77]
	s_waitcnt lgkmcnt(0)
	v_cvt_pk_bf16_f32 v3, v4, v5
	ds_read2_b32 v[4:5], v39 offset0:60 offset1:125
	v_lshl_add_u64 v[6:7], v[6:7], 0, v[76:77]
	s_waitcnt lgkmcnt(0)
	v_cvt_pk_bf16_f32 v4, v4, v5
	ds_read2_b32 v[8:9], v39 offset0:190 offset1:255
	s_waitcnt lgkmcnt(0)
	v_cvt_pk_bf16_f32 v5, v8, v9
	flat_store_dwordx4 v[6:7], v[2:5] sc1
	s_waitcnt lgkmcnt(0)

.LBB0_636:
	v_lshl_add_u64 v[4:5], v[2:3], 0, s[48:49]
	v_add_co_u32_e32 v6, vcc, 0x1000, v4
	s_mov_b64 s[0:1], vcc
	v_add_co_u32_e32 v8, vcc, 0x2000, v4
	v_addc_co_u32_e64 v7, s[0:1], 0, v5, s[0:1]
	s_mov_b64 s[0:1], vcc
	v_add_co_u32_e32 v76, vcc, 0x3000, v4
	v_addc_co_u32_e64 v9, s[0:1], 0, v5, s[0:1]
	s_mov_b64 s[0:1], vcc
	s_nop 0
	v_addc_co_u32_e64 v77, s[0:1], 0, v5, s[0:1]
	global_load_dword v39, v[4:5], off nt
	global_load_dword v43, v[6:7], off nt
	global_load_dword v47, v[8:9], off nt
	global_load_dword v51, v[76:77], off nt
	v_add_co_u32_e32 v6, vcc, 0x4000, v4
	s_mov_b64 s[0:1], vcc
	v_add_co_u32_e32 v8, vcc, 0x5000, v4
	v_addc_co_u32_e64 v7, s[0:1], 0, v5, s[0:1]
	s_mov_b64 s[0:1], vcc
	v_add_co_u32_e32 v76, vcc, 0x6000, v4
	v_addc_co_u32_e64 v9, s[0:1], 0, v5, s[0:1]
	s_mov_b64 s[0:1], vcc
	s_nop 0
	v_addc_co_u32_e64 v77, s[0:1], 0, v5, s[0:1]
	global_load_dword v55, v[6:7], off nt
	global_load_dword v61, v[8:9], off nt
	global_load_dword v73, v[76:77], off nt
	v_add_co_u32_e32 v6, vcc, 0x7000, v4
	s_mov_b64 s[0:1], vcc
	v_add_co_u32_e32 v8, vcc, 0x8000, v4
	v_addc_co_u32_e64 v7, s[0:1], 0, v5, s[0:1]
	s_mov_b64 s[0:1], vcc
	v_add_co_u32_e32 v76, vcc, 0x9000, v4
	v_addc_co_u32_e64 v9, s[0:1], 0, v5, s[0:1]
	s_mov_b64 s[0:1], vcc
	s_nop 0
	v_addc_co_u32_e64 v77, s[0:1], 0, v5, s[0:1]
	global_load_dword v99, v[6:7], off nt
	global_load_dword v100, v[8:9], off nt
	global_load_dword v101, v[76:77], off nt
	v_add_co_u32_e32 v6, vcc, 0xa000, v4
	s_mov_b64 s[0:1], vcc
	v_add_co_u32_e32 v8, vcc, 0xb000, v4
	v_addc_co_u32_e64 v7, s[0:1], 0, v5, s[0:1]
	s_mov_b64 s[0:1], vcc
	v_add_co_u32_e32 v76, vcc, 0xc000, v4
	v_addc_co_u32_e64 v9, s[0:1], 0, v5, s[0:1]
	s_mov_b64 s[0:1], vcc
	global_load_dword v102, v[6:7], off nt
	global_load_dword v103, v[8:9], off nt
	v_add_co_u32_e32 v6, vcc, 0xd000, v4
	v_addc_co_u32_e64 v77, s[0:1], 0, v5, s[0:1]
	s_mov_b64 s[0:1], vcc
	v_add_co_u32_e32 v8, vcc, 0xe000, v4
	v_addc_co_u32_e64 v7, s[0:1], 0, v5, s[0:1]
	s_mov_b64 s[0:1], vcc
	v_add_co_u32_e32 v4, vcc, 0xf000, v4
	v_addc_co_u32_e64 v9, s[0:1], 0, v5, s[0:1]
	global_load_dword v76, v[76:77], off nt
	v_addc_co_u32_e32 v5, vcc, 0, v5, vcc
	global_load_dword v6, v[6:7], off nt
	s_nop 0
	global_load_dword v7, v[8:9], off nt
	s_nop 0
	global_load_dword v4, v[4:5], off nt
	s_add_u32 s48, s48, 0x10000
	s_addc_u32 s49, s49, 0
	v_add_u32_e32 v5, 0x400, v0
	v_add_u32_e32 v8, 0x800, v0
	v_add_u32_e32 v9, 0xc00, v0
	s_cmp_lg_u32 s48, 0x40000
	s_waitcnt vmcnt(0)
	ds_write2_b32 v0, v39, v43 offset1:65
	ds_write2_b32 v0, v47, v51 offset0:130 offset1:195
	v_add_u32_e32 v0, 0x1040, v0
	ds_write2_b32 v5, v55, v61 offset0:4 offset1:69
	ds_write2_b32 v5, v73, v99 offset0:134 offset1:199
	ds_write2_b32 v8, v100, v101 offset0:8 offset1:73
	ds_write2_b32 v8, v102, v103 offset0:138 offset1:203
	ds_write2_b32 v9, v76, v6 offset0:12 offset1:77
	ds_write2_b32 v9, v7, v4 offset0:142 offset1:207
	s_cbranch_scc1 .LBB0_636
	v_add_u32_e32 v0, 0xffffe340, v74
	v_lshrrev_b32_e32 v6, 4, v0
	v_lshlrev_b32_e32 v7, 6, v0
	v_lshlrev_b32_e32 v8, 10, v6
	v_sub_u32_e32 v43, v7, v8
	s_waitcnt lgkmcnt(0)
	v_or_b32_e32 v76, v43, v78
	ds_read2_b32 v[2:3], v79 offset1:65
	v_lshlrev_b32_e32 v0, 7, v6
	v_ashrrev_i32_e32 v77, 31, v76
	s_waitcnt lgkmcnt(0)
	v_cvt_pk_bf16_f32 v2, v2, v3
	ds_read2_b32 v[4:5], v79 offset0:130 offset1:195
	v_add_u32_e32 v39, 0x400, v79
	v_lshl_add_u64 v[6:7], v[14:15], 0, v[0:1]
	v_lshlrev_b64 v[76:77], 11, v[76:77]
	s_waitcnt lgkmcnt(0)
	v_cvt_pk_bf16_f32 v3, v4, v5
	ds_read2_b32 v[4:5], v39 offset0:4 offset1:69
	v_lshl_add_u64 v[76:77], v[6:7], 0, v[76:77]
	s_waitcnt lgkmcnt(0)
	v_cvt_pk_bf16_f32 v4, v4, v5
	ds_read2_b32 v[8:9], v39 offset0:134 offset1:199
	s_waitcnt lgkmcnt(0)
	v_cvt_pk_bf16_f32 v5, v8, v9
	flat_store_dwordx4 v[76:77], v[2:5] sc1
	v_or_b32_e32 v76, v43, v80
	ds_read2_b32 v[2:3], v79 offset0:8 offset1:73
	v_ashrrev_i32_e32 v77, 31, v76
	s_waitcnt lgkmcnt(0)
	v_cvt_pk_bf16_f32 v2, v2, v3
	ds_read2_b32 v[4:5], v79 offset0:138 offset1:203
	v_lshlrev_b64 v[76:77], 11, v[76:77]
	s_waitcnt lgkmcnt(0)
	v_cvt_pk_bf16_f32 v3, v4, v5
	ds_read2_b32 v[4:5], v39 offset0:12 offset1:77
	v_lshl_add_u64 v[76:77], v[6:7], 0, v[76:77]
	s_waitcnt lgkmcnt(0)
	v_cvt_pk_bf16_f32 v4, v4, v5
	ds_read2_b32 v[8:9], v39 offset0:142 offset1:207
	s_waitcnt lgkmcnt(0)
	v_cvt_pk_bf16_f32 v5, v8, v9
	flat_store_dwordx4 v[76:77], v[2:5] sc1
	v_or_b32_e32 v76, v43, v81
	ds_read2_b32 v[2:3], v79 offset0:16 offset1:81
	v_ashrrev_i32_e32 v77, 31, v76
	s_waitcnt lgkmcnt(0)
	v_cvt_pk_bf16_f32 v2, v2, v3
	ds_read2_b32 v[4:5], v79 offset0:146 offset1:211
	v_lshlrev_b64 v[76:77], 11, v[76:77]
	s_waitcnt lgkmcnt(0)
	v_cvt_pk_bf16_f32 v3, v4, v5
	ds_read2_b32 v[4:5], v39 offset0:20 offset1:85
	v_lshl_add_u64 v[76:77], v[6:7], 0, v[76:77]
	s_waitcnt lgkmcnt(0)
	v_cvt_pk_bf16_f32 v4, v4, v5
	ds_read2_b32 v[8:9], v39 offset0:150 offset1:215
	s_waitcnt lgkmcnt(0)
	v_cvt_pk_bf16_f32 v5, v8, v9
	flat_store_dwordx4 v[76:77], v[2:5] sc1
	v_or_b32_e32 v76, v43, v82
	ds_read2_b32 v[2:3], v79 offset0:24 offset1:89
	v_ashrrev_i32_e32 v77, 31, v76
	s_waitcnt lgkmcnt(0)
	v_cvt_pk_bf16_f32 v2, v2, v3
	ds_read2_b32 v[4:5], v79 offset0:154 offset1:219
	v_lshlrev_b64 v[76:77], 11, v[76:77]
	s_waitcnt lgkmcnt(0)
	v_cvt_pk_bf16_f32 v3, v4, v5
	ds_read2_b32 v[4:5], v39 offset0:28 offset1:93
	v_lshl_add_u64 v[76:77], v[6:7], 0, v[76:77]
	s_waitcnt lgkmcnt(0)
	v_cvt_pk_bf16_f32 v4, v4, v5
	ds_read2_b32 v[8:9], v39 offset0:158 offset1:223
	s_waitcnt lgkmcnt(0)
	v_cvt_pk_bf16_f32 v5, v8, v9
	flat_store_dwordx4 v[76:77], v[2:5] sc1
	v_or_b32_e32 v76, v43, v83
	ds_read2_b32 v[2:3], v79 offset0:32 offset1:97
	v_ashrrev_i32_e32 v77, 31, v76
	s_waitcnt lgkmcnt(0)
	v_cvt_pk_bf16_f32 v2, v2, v3
	ds_read2_b32 v[4:5], v79 offset0:162 offset1:227
	v_lshlrev_b64 v[76:77], 11, v[76:77]
	s_waitcnt lgkmcnt(0)
	v_cvt_pk_bf16_f32 v3, v4, v5
	ds_read2_b32 v[4:5], v39 offset0:36 offset1:101
	v_lshl_add_u64 v[76:77], v[6:7], 0, v[76:77]
	s_waitcnt lgkmcnt(0)
	v_cvt_pk_bf16_f32 v4, v4, v5
	ds_read2_b32 v[8:9], v39 offset0:166 offset1:231
	s_waitcnt lgkmcnt(0)
	v_cvt_pk_bf16_f32 v5, v8, v9
	flat_store_dwordx4 v[76:77], v[2:5] sc1
	v_or_b32_e32 v76, v43, v84
	ds_read2_b32 v[2:3], v79 offset0:40 offset1:105
	v_ashrrev_i32_e32 v77, 31, v76
	s_waitcnt lgkmcnt(0)
	v_cvt_pk_bf16_f32 v2, v2, v3
	ds_read2_b32 v[4:5], v79 offset0:170 offset1:235
	v_lshlrev_b64 v[76:77], 11, v[76:77]
	s_waitcnt lgkmcnt(0)
	v_cvt_pk_bf16_f32 v3, v4, v5
	ds_read2_b32 v[4:5], v39 offset0:44 offset1:109
	v_lshl_add_u64 v[76:77], v[6:7], 0, v[76:77]
	s_waitcnt lgkmcnt(0)
	v_cvt_pk_bf16_f32 v4, v4, v5
	ds_read2_b32 v[8:9], v39 offset0:174 offset1:239
	s_waitcnt lgkmcnt(0)
	v_cvt_pk_bf16_f32 v5, v8, v9
	flat_store_dwordx4 v[76:77], v[2:5] sc1
	v_or_b32_e32 v76, v43, v85
	ds_read2_b32 v[2:3], v79 offset0:48 offset1:113
	v_ashrrev_i32_e32 v77, 31, v76
	s_waitcnt lgkmcnt(0)
	v_cvt_pk_bf16_f32 v2, v2, v3
	ds_read2_b32 v[4:5], v79 offset0:178 offset1:243
	v_lshlrev_b64 v[76:77], 11, v[76:77]
	s_waitcnt lgkmcnt(0)
	v_cvt_pk_bf16_f32 v3, v4, v5
	ds_read2_b32 v[4:5], v39 offset0:52 offset1:117
	v_lshl_add_u64 v[76:77], v[6:7], 0, v[76:77]
	s_waitcnt lgkmcnt(0)
	v_cvt_pk_bf16_f32 v4, v4, v5
	ds_read2_b32 v[8:9], v39 offset0:182 offset1:247
	s_waitcnt lgkmcnt(0)
	v_cvt_pk_bf16_f32 v5, v8, v9
	flat_store_dwordx4 v[76:77], v[2:5] sc1
	v_or_b32_e32 v76, v43, v86
	ds_read2_b32 v[2:3], v79 offset0:56 offset1:121
	v_ashrrev_i32_e32 v77, 31, v76
	s_waitcnt lgkmcnt(0)
	v_cvt_pk_bf16_f32 v2, v2, v3
	ds_read2_b32 v[4:5], v79 offset0:186 offset1:251
	v_lshlrev_b64 v[76:77], 11, v[76:77]
	s_waitcnt lgkmcnt(0)
	v_cvt_pk_bf16_f32 v3, v4, v5
	ds_read2_b32 v[4:5], v39 offset0:60 offset1:125
	v_lshl_add_u64 v[6:7], v[6:7], 0, v[76:77]
	s_waitcnt lgkmcnt(0)
	v_cvt_pk_bf16_f32 v4, v4, v5
	ds_read2_b32 v[8:9], v39 offset0:190 offset1:255
	s_waitcnt lgkmcnt(0)
	v_cvt_pk_bf16_f32 v5, v8, v9
	flat_store_dwordx4 v[6:7], v[2:5] sc1
	s_waitcnt lgkmcnt(0)

.LBB0_641:
	v_lshl_add_u64 v[4:5], v[2:3], 0, s[46:47]
	v_add_co_u32_e32 v6, vcc, 0x1000, v4
	s_mov_b64 s[0:1], vcc
	v_add_co_u32_e32 v8, vcc, 0x2000, v4
	v_addc_co_u32_e64 v7, s[0:1], 0, v5, s[0:1]
	s_mov_b64 s[0:1], vcc
	v_add_co_u32_e32 v76, vcc, 0x3000, v4
	v_addc_co_u32_e64 v9, s[0:1], 0, v5, s[0:1]
	s_mov_b64 s[0:1], vcc
	s_nop 0
	v_addc_co_u32_e64 v77, s[0:1], 0, v5, s[0:1]
	global_load_dword v39, v[4:5], off nt
	global_load_dword v43, v[6:7], off nt
	global_load_dword v47, v[8:9], off nt
	global_load_dword v51, v[76:77], off nt
	v_add_co_u32_e32 v6, vcc, 0x4000, v4
	s_mov_b64 s[0:1], vcc
	v_add_co_u32_e32 v8, vcc, 0x5000, v4
	v_addc_co_u32_e64 v7, s[0:1], 0, v5, s[0:1]
	s_mov_b64 s[0:1], vcc
	v_add_co_u32_e32 v76, vcc, 0x6000, v4
	v_addc_co_u32_e64 v9, s[0:1], 0, v5, s[0:1]
	s_mov_b64 s[0:1], vcc
	s_nop 0
	v_addc_co_u32_e64 v77, s[0:1], 0, v5, s[0:1]
	global_load_dword v55, v[6:7], off nt
	global_load_dword v61, v[8:9], off nt
	global_load_dword v73, v[76:77], off nt
	v_add_co_u32_e32 v6, vcc, 0x7000, v4
	s_mov_b64 s[0:1], vcc
	v_add_co_u32_e32 v8, vcc, 0x8000, v4
	v_addc_co_u32_e64 v7, s[0:1], 0, v5, s[0:1]
	s_mov_b64 s[0:1], vcc
	v_add_co_u32_e32 v76, vcc, 0x9000, v4
	v_addc_co_u32_e64 v9, s[0:1], 0, v5, s[0:1]
	s_mov_b64 s[0:1], vcc
	s_nop 0
	v_addc_co_u32_e64 v77, s[0:1], 0, v5, s[0:1]
	global_load_dword v99, v[6:7], off nt
	global_load_dword v100, v[8:9], off nt
	global_load_dword v101, v[76:77], off nt
	v_add_co_u32_e32 v6, vcc, 0xa000, v4
	s_mov_b64 s[0:1], vcc
	v_add_co_u32_e32 v8, vcc, 0xb000, v4
	v_addc_co_u32_e64 v7, s[0:1], 0, v5, s[0:1]
	s_mov_b64 s[0:1], vcc
	v_add_co_u32_e32 v76, vcc, 0xc000, v4
	v_addc_co_u32_e64 v9, s[0:1], 0, v5, s[0:1]
	s_mov_b64 s[0:1], vcc
	global_load_dword v102, v[6:7], off nt
	global_load_dword v103, v[8:9], off nt
	v_add_co_u32_e32 v6, vcc, 0xd000, v4
	v_addc_co_u32_e64 v77, s[0:1], 0, v5, s[0:1]
	s_mov_b64 s[0:1], vcc
	v_add_co_u32_e32 v8, vcc, 0xe000, v4
	v_addc_co_u32_e64 v7, s[0:1], 0, v5, s[0:1]
	s_mov_b64 s[0:1], vcc
	v_add_co_u32_e32 v4, vcc, 0xf000, v4
	v_addc_co_u32_e64 v9, s[0:1], 0, v5, s[0:1]
	global_load_dword v76, v[76:77], off nt
	v_addc_co_u32_e32 v5, vcc, 0, v5, vcc
	global_load_dword v6, v[6:7], off nt
	s_nop 0
	global_load_dword v7, v[8:9], off nt
	s_nop 0
	global_load_dword v4, v[4:5], off nt
	s_add_u32 s46, s46, 0x10000
	s_addc_u32 s47, s47, 0
	v_add_u32_e32 v5, 0x400, v0
	v_add_u32_e32 v8, 0x800, v0
	v_add_u32_e32 v9, 0xc00, v0
	s_cmp_lg_u32 s46, 0x40000
	s_waitcnt vmcnt(0)
	ds_write2_b32 v0, v39, v43 offset1:65
	ds_write2_b32 v0, v47, v51 offset0:130 offset1:195
	v_add_u32_e32 v0, 0x1040, v0
	ds_write2_b32 v5, v55, v61 offset0:4 offset1:69
	ds_write2_b32 v5, v73, v99 offset0:134 offset1:199
	ds_write2_b32 v8, v100, v101 offset0:8 offset1:73
	ds_write2_b32 v8, v102, v103 offset0:138 offset1:203
	ds_write2_b32 v9, v76, v6 offset0:12 offset1:77
	ds_write2_b32 v9, v7, v4 offset0:142 offset1:207
	s_cbranch_scc1 .LBB0_641
	v_add_u32_e32 v0, 0xffffe440, v74
	v_lshrrev_b32_e32 v6, 4, v0
	v_lshlrev_b32_e32 v7, 6, v0
	v_lshlrev_b32_e32 v8, 10, v6
	v_sub_u32_e32 v43, v7, v8
	s_waitcnt lgkmcnt(0)
	v_or_b32_e32 v76, v43, v78
	ds_read2_b32 v[2:3], v79 offset1:65
	v_lshlrev_b32_e32 v0, 7, v6
	v_ashrrev_i32_e32 v77, 31, v76
	s_waitcnt lgkmcnt(0)
	v_cvt_pk_bf16_f32 v2, v2, v3
	ds_read2_b32 v[4:5], v79 offset0:130 offset1:195
	v_add_u32_e32 v39, 0x400, v79
	v_lshl_add_u64 v[6:7], v[16:17], 0, v[0:1]
	v_lshlrev_b64 v[76:77], 11, v[76:77]
	s_waitcnt lgkmcnt(0)
	v_cvt_pk_bf16_f32 v3, v4, v5
	ds_read2_b32 v[4:5], v39 offset0:4 offset1:69
	v_lshl_add_u64 v[76:77], v[6:7], 0, v[76:77]
	s_waitcnt lgkmcnt(0)
	v_cvt_pk_bf16_f32 v4, v4, v5
	ds_read2_b32 v[8:9], v39 offset0:134 offset1:199
	s_waitcnt lgkmcnt(0)
	v_cvt_pk_bf16_f32 v5, v8, v9
	flat_store_dwordx4 v[76:77], v[2:5] sc1
	v_or_b32_e32 v76, v43, v80
	ds_read2_b32 v[2:3], v79 offset0:8 offset1:73
	v_ashrrev_i32_e32 v77, 31, v76
	s_waitcnt lgkmcnt(0)
	v_cvt_pk_bf16_f32 v2, v2, v3
	ds_read2_b32 v[4:5], v79 offset0:138 offset1:203
	v_lshlrev_b64 v[76:77], 11, v[76:77]
	s_waitcnt lgkmcnt(0)
	v_cvt_pk_bf16_f32 v3, v4, v5
	ds_read2_b32 v[4:5], v39 offset0:12 offset1:77
	v_lshl_add_u64 v[76:77], v[6:7], 0, v[76:77]
	s_waitcnt lgkmcnt(0)
	v_cvt_pk_bf16_f32 v4, v4, v5
	ds_read2_b32 v[8:9], v39 offset0:142 offset1:207
	s_waitcnt lgkmcnt(0)
	v_cvt_pk_bf16_f32 v5, v8, v9
	flat_store_dwordx4 v[76:77], v[2:5] sc1
	v_or_b32_e32 v76, v43, v81
	ds_read2_b32 v[2:3], v79 offset0:16 offset1:81
	v_ashrrev_i32_e32 v77, 31, v76
	s_waitcnt lgkmcnt(0)
	v_cvt_pk_bf16_f32 v2, v2, v3
	ds_read2_b32 v[4:5], v79 offset0:146 offset1:211
	v_lshlrev_b64 v[76:77], 11, v[76:77]
	s_waitcnt lgkmcnt(0)
	v_cvt_pk_bf16_f32 v3, v4, v5
	ds_read2_b32 v[4:5], v39 offset0:20 offset1:85
	v_lshl_add_u64 v[76:77], v[6:7], 0, v[76:77]
	s_waitcnt lgkmcnt(0)
	v_cvt_pk_bf16_f32 v4, v4, v5
	ds_read2_b32 v[8:9], v39 offset0:150 offset1:215
	s_waitcnt lgkmcnt(0)
	v_cvt_pk_bf16_f32 v5, v8, v9
	flat_store_dwordx4 v[76:77], v[2:5] sc1
	v_or_b32_e32 v76, v43, v82
	ds_read2_b32 v[2:3], v79 offset0:24 offset1:89
	v_ashrrev_i32_e32 v77, 31, v76
	s_waitcnt lgkmcnt(0)
	v_cvt_pk_bf16_f32 v2, v2, v3
	ds_read2_b32 v[4:5], v79 offset0:154 offset1:219
	v_lshlrev_b64 v[76:77], 11, v[76:77]
	s_waitcnt lgkmcnt(0)
	v_cvt_pk_bf16_f32 v3, v4, v5
	ds_read2_b32 v[4:5], v39 offset0:28 offset1:93
	v_lshl_add_u64 v[76:77], v[6:7], 0, v[76:77]
	s_waitcnt lgkmcnt(0)
	v_cvt_pk_bf16_f32 v4, v4, v5
	ds_read2_b32 v[8:9], v39 offset0:158 offset1:223
	s_waitcnt lgkmcnt(0)
	v_cvt_pk_bf16_f32 v5, v8, v9
	flat_store_dwordx4 v[76:77], v[2:5] sc1
	v_or_b32_e32 v76, v43, v83
	ds_read2_b32 v[2:3], v79 offset0:32 offset1:97
	v_ashrrev_i32_e32 v77, 31, v76
	s_waitcnt lgkmcnt(0)
	v_cvt_pk_bf16_f32 v2, v2, v3
	ds_read2_b32 v[4:5], v79 offset0:162 offset1:227
	v_lshlrev_b64 v[76:77], 11, v[76:77]
	s_waitcnt lgkmcnt(0)
	v_cvt_pk_bf16_f32 v3, v4, v5
	ds_read2_b32 v[4:5], v39 offset0:36 offset1:101
	v_lshl_add_u64 v[76:77], v[6:7], 0, v[76:77]
	s_waitcnt lgkmcnt(0)
	v_cvt_pk_bf16_f32 v4, v4, v5
	ds_read2_b32 v[8:9], v39 offset0:166 offset1:231
	s_waitcnt lgkmcnt(0)
	v_cvt_pk_bf16_f32 v5, v8, v9
	flat_store_dwordx4 v[76:77], v[2:5] sc1
	v_or_b32_e32 v76, v43, v84
	ds_read2_b32 v[2:3], v79 offset0:40 offset1:105
	v_ashrrev_i32_e32 v77, 31, v76
	s_waitcnt lgkmcnt(0)
	v_cvt_pk_bf16_f32 v2, v2, v3
	ds_read2_b32 v[4:5], v79 offset0:170 offset1:235
	v_lshlrev_b64 v[76:77], 11, v[76:77]
	s_waitcnt lgkmcnt(0)
	v_cvt_pk_bf16_f32 v3, v4, v5
	ds_read2_b32 v[4:5], v39 offset0:44 offset1:109
	v_lshl_add_u64 v[76:77], v[6:7], 0, v[76:77]
	s_waitcnt lgkmcnt(0)
	v_cvt_pk_bf16_f32 v4, v4, v5
	ds_read2_b32 v[8:9], v39 offset0:174 offset1:239
	s_waitcnt lgkmcnt(0)
	v_cvt_pk_bf16_f32 v5, v8, v9
	flat_store_dwordx4 v[76:77], v[2:5] sc1
	v_or_b32_e32 v76, v43, v85
	ds_read2_b32 v[2:3], v79 offset0:48 offset1:113
	v_ashrrev_i32_e32 v77, 31, v76
	s_waitcnt lgkmcnt(0)
	v_cvt_pk_bf16_f32 v2, v2, v3
	ds_read2_b32 v[4:5], v79 offset0:178 offset1:243
	v_lshlrev_b64 v[76:77], 11, v[76:77]
	s_waitcnt lgkmcnt(0)
	v_cvt_pk_bf16_f32 v3, v4, v5
	ds_read2_b32 v[4:5], v39 offset0:52 offset1:117
	v_lshl_add_u64 v[76:77], v[6:7], 0, v[76:77]
	s_waitcnt lgkmcnt(0)
	v_cvt_pk_bf16_f32 v4, v4, v5
	ds_read2_b32 v[8:9], v39 offset0:182 offset1:247
	s_waitcnt lgkmcnt(0)
	v_cvt_pk_bf16_f32 v5, v8, v9
	flat_store_dwordx4 v[76:77], v[2:5] sc1
	v_or_b32_e32 v76, v43, v86
	ds_read2_b32 v[2:3], v79 offset0:56 offset1:121
	v_ashrrev_i32_e32 v77, 31, v76
	s_waitcnt lgkmcnt(0)
	v_cvt_pk_bf16_f32 v2, v2, v3
	ds_read2_b32 v[4:5], v79 offset0:186 offset1:251
	v_lshlrev_b64 v[76:77], 11, v[76:77]
	s_waitcnt lgkmcnt(0)
	v_cvt_pk_bf16_f32 v3, v4, v5
	ds_read2_b32 v[4:5], v39 offset0:60 offset1:125
	v_lshl_add_u64 v[6:7], v[6:7], 0, v[76:77]
	s_waitcnt lgkmcnt(0)
	v_cvt_pk_bf16_f32 v4, v4, v5
	ds_read2_b32 v[8:9], v39 offset0:190 offset1:255
	s_waitcnt lgkmcnt(0)
	v_cvt_pk_bf16_f32 v5, v8, v9
	flat_store_dwordx4 v[6:7], v[2:5] sc1
	s_waitcnt lgkmcnt(0)

.LBB0_646:
	v_lshl_add_u64 v[4:5], v[2:3], 0, s[44:45]
	v_add_co_u32_e32 v6, vcc, 0x1000, v4
	s_mov_b64 s[0:1], vcc
	v_add_co_u32_e32 v8, vcc, 0x2000, v4
	v_addc_co_u32_e64 v7, s[0:1], 0, v5, s[0:1]
	s_mov_b64 s[0:1], vcc
	v_add_co_u32_e32 v76, vcc, 0x3000, v4
	v_addc_co_u32_e64 v9, s[0:1], 0, v5, s[0:1]
	s_mov_b64 s[0:1], vcc
	s_nop 0
	v_addc_co_u32_e64 v77, s[0:1], 0, v5, s[0:1]
	global_load_dword v39, v[4:5], off nt
	global_load_dword v43, v[6:7], off nt
	global_load_dword v47, v[8:9], off nt
	global_load_dword v51, v[76:77], off nt
	v_add_co_u32_e32 v6, vcc, 0x4000, v4
	s_mov_b64 s[0:1], vcc
	v_add_co_u32_e32 v8, vcc, 0x5000, v4
	v_addc_co_u32_e64 v7, s[0:1], 0, v5, s[0:1]
	s_mov_b64 s[0:1], vcc
	v_add_co_u32_e32 v76, vcc, 0x6000, v4
	v_addc_co_u32_e64 v9, s[0:1], 0, v5, s[0:1]
	s_mov_b64 s[0:1], vcc
	s_nop 0
	v_addc_co_u32_e64 v77, s[0:1], 0, v5, s[0:1]
	global_load_dword v55, v[6:7], off nt
	global_load_dword v61, v[8:9], off nt
	global_load_dword v73, v[76:77], off nt
	v_add_co_u32_e32 v6, vcc, 0x7000, v4
	s_mov_b64 s[0:1], vcc
	v_add_co_u32_e32 v8, vcc, 0x8000, v4
	v_addc_co_u32_e64 v7, s[0:1], 0, v5, s[0:1]
	s_mov_b64 s[0:1], vcc
	v_add_co_u32_e32 v76, vcc, 0x9000, v4
	v_addc_co_u32_e64 v9, s[0:1], 0, v5, s[0:1]
	s_mov_b64 s[0:1], vcc
	s_nop 0
	v_addc_co_u32_e64 v77, s[0:1], 0, v5, s[0:1]
	global_load_dword v99, v[6:7], off nt
	global_load_dword v100, v[8:9], off nt
	global_load_dword v101, v[76:77], off nt
	v_add_co_u32_e32 v6, vcc, 0xa000, v4
	s_mov_b64 s[0:1], vcc
	v_add_co_u32_e32 v8, vcc, 0xb000, v4
	v_addc_co_u32_e64 v7, s[0:1], 0, v5, s[0:1]
	s_mov_b64 s[0:1], vcc
	v_add_co_u32_e32 v76, vcc, 0xc000, v4
	v_addc_co_u32_e64 v9, s[0:1], 0, v5, s[0:1]
	s_mov_b64 s[0:1], vcc
	global_load_dword v102, v[6:7], off nt
	global_load_dword v103, v[8:9], off nt
	v_add_co_u32_e32 v6, vcc, 0xd000, v4
	v_addc_co_u32_e64 v77, s[0:1], 0, v5, s[0:1]
	s_mov_b64 s[0:1], vcc
	v_add_co_u32_e32 v8, vcc, 0xe000, v4
	v_addc_co_u32_e64 v7, s[0:1], 0, v5, s[0:1]
	s_mov_b64 s[0:1], vcc
	v_add_co_u32_e32 v4, vcc, 0xf000, v4
	v_addc_co_u32_e64 v9, s[0:1], 0, v5, s[0:1]
	global_load_dword v76, v[76:77], off nt
	v_addc_co_u32_e32 v5, vcc, 0, v5, vcc
	global_load_dword v6, v[6:7], off nt
	s_nop 0
	global_load_dword v7, v[8:9], off nt
	s_nop 0
	global_load_dword v4, v[4:5], off nt
	s_add_u32 s44, s44, 0x10000
	s_addc_u32 s45, s45, 0
	v_add_u32_e32 v5, 0x400, v0
	v_add_u32_e32 v8, 0x800, v0
	v_add_u32_e32 v9, 0xc00, v0
	s_cmp_lg_u32 s44, 0x40000
	s_waitcnt vmcnt(0)
	ds_write2_b32 v0, v39, v43 offset1:65
	ds_write2_b32 v0, v47, v51 offset0:130 offset1:195
	v_add_u32_e32 v0, 0x1040, v0
	ds_write2_b32 v5, v55, v61 offset0:4 offset1:69
	ds_write2_b32 v5, v73, v99 offset0:134 offset1:199
	ds_write2_b32 v8, v100, v101 offset0:8 offset1:73
	ds_write2_b32 v8, v102, v103 offset0:138 offset1:203
	ds_write2_b32 v9, v76, v6 offset0:12 offset1:77
	ds_write2_b32 v9, v7, v4 offset0:142 offset1:207
	s_cbranch_scc1 .LBB0_646
	v_add_u32_e32 v0, 0xffffe540, v74
	v_lshrrev_b32_e32 v6, 4, v0
	v_lshlrev_b32_e32 v7, 6, v0
	v_lshlrev_b32_e32 v8, 10, v6
	v_sub_u32_e32 v43, v7, v8
	s_waitcnt lgkmcnt(0)
	v_or_b32_e32 v76, v43, v78
	ds_read2_b32 v[2:3], v79 offset1:65
	v_lshlrev_b32_e32 v0, 7, v6
	v_ashrrev_i32_e32 v77, 31, v76
	s_waitcnt lgkmcnt(0)
	v_cvt_pk_bf16_f32 v2, v2, v3
	ds_read2_b32 v[4:5], v79 offset0:130 offset1:195
	v_add_u32_e32 v39, 0x400, v79
	v_lshl_add_u64 v[6:7], v[18:19], 0, v[0:1]
	v_lshlrev_b64 v[76:77], 11, v[76:77]
	s_waitcnt lgkmcnt(0)
	v_cvt_pk_bf16_f32 v3, v4, v5
	ds_read2_b32 v[4:5], v39 offset0:4 offset1:69
	v_lshl_add_u64 v[76:77], v[6:7], 0, v[76:77]
	s_waitcnt lgkmcnt(0)
	v_cvt_pk_bf16_f32 v4, v4, v5
	ds_read2_b32 v[8:9], v39 offset0:134 offset1:199
	s_waitcnt lgkmcnt(0)
	v_cvt_pk_bf16_f32 v5, v8, v9
	flat_store_dwordx4 v[76:77], v[2:5] sc1
	v_or_b32_e32 v76, v43, v80
	ds_read2_b32 v[2:3], v79 offset0:8 offset1:73
	v_ashrrev_i32_e32 v77, 31, v76
	s_waitcnt lgkmcnt(0)
	v_cvt_pk_bf16_f32 v2, v2, v3
	ds_read2_b32 v[4:5], v79 offset0:138 offset1:203
	v_lshlrev_b64 v[76:77], 11, v[76:77]
	s_waitcnt lgkmcnt(0)
	v_cvt_pk_bf16_f32 v3, v4, v5
	ds_read2_b32 v[4:5], v39 offset0:12 offset1:77
	v_lshl_add_u64 v[76:77], v[6:7], 0, v[76:77]
	s_waitcnt lgkmcnt(0)
	v_cvt_pk_bf16_f32 v4, v4, v5
	ds_read2_b32 v[8:9], v39 offset0:142 offset1:207
	s_waitcnt lgkmcnt(0)
	v_cvt_pk_bf16_f32 v5, v8, v9
	flat_store_dwordx4 v[76:77], v[2:5] sc1
	v_or_b32_e32 v76, v43, v81
	ds_read2_b32 v[2:3], v79 offset0:16 offset1:81
	v_ashrrev_i32_e32 v77, 31, v76
	s_waitcnt lgkmcnt(0)
	v_cvt_pk_bf16_f32 v2, v2, v3
	ds_read2_b32 v[4:5], v79 offset0:146 offset1:211
	v_lshlrev_b64 v[76:77], 11, v[76:77]
	s_waitcnt lgkmcnt(0)
	v_cvt_pk_bf16_f32 v3, v4, v5
	ds_read2_b32 v[4:5], v39 offset0:20 offset1:85
	v_lshl_add_u64 v[76:77], v[6:7], 0, v[76:77]
	s_waitcnt lgkmcnt(0)
	v_cvt_pk_bf16_f32 v4, v4, v5
	ds_read2_b32 v[8:9], v39 offset0:150 offset1:215
	s_waitcnt lgkmcnt(0)
	v_cvt_pk_bf16_f32 v5, v8, v9
	flat_store_dwordx4 v[76:77], v[2:5] sc1
	v_or_b32_e32 v76, v43, v82
	ds_read2_b32 v[2:3], v79 offset0:24 offset1:89
	v_ashrrev_i32_e32 v77, 31, v76
	s_waitcnt lgkmcnt(0)
	v_cvt_pk_bf16_f32 v2, v2, v3
	ds_read2_b32 v[4:5], v79 offset0:154 offset1:219
	v_lshlrev_b64 v[76:77], 11, v[76:77]
	s_waitcnt lgkmcnt(0)
	v_cvt_pk_bf16_f32 v3, v4, v5
	ds_read2_b32 v[4:5], v39 offset0:28 offset1:93
	v_lshl_add_u64 v[76:77], v[6:7], 0, v[76:77]
	s_waitcnt lgkmcnt(0)
	v_cvt_pk_bf16_f32 v4, v4, v5
	ds_read2_b32 v[8:9], v39 offset0:158 offset1:223
	s_waitcnt lgkmcnt(0)
	v_cvt_pk_bf16_f32 v5, v8, v9
	flat_store_dwordx4 v[76:77], v[2:5] sc1
	v_or_b32_e32 v76, v43, v83
	ds_read2_b32 v[2:3], v79 offset0:32 offset1:97
	v_ashrrev_i32_e32 v77, 31, v76
	s_waitcnt lgkmcnt(0)
	v_cvt_pk_bf16_f32 v2, v2, v3
	ds_read2_b32 v[4:5], v79 offset0:162 offset1:227
	v_lshlrev_b64 v[76:77], 11, v[76:77]
	s_waitcnt lgkmcnt(0)
	v_cvt_pk_bf16_f32 v3, v4, v5
	ds_read2_b32 v[4:5], v39 offset0:36 offset1:101
	v_lshl_add_u64 v[76:77], v[6:7], 0, v[76:77]
	s_waitcnt lgkmcnt(0)
	v_cvt_pk_bf16_f32 v4, v4, v5
	ds_read2_b32 v[8:9], v39 offset0:166 offset1:231
	s_waitcnt lgkmcnt(0)
	v_cvt_pk_bf16_f32 v5, v8, v9
	flat_store_dwordx4 v[76:77], v[2:5] sc1
	v_or_b32_e32 v76, v43, v84
	ds_read2_b32 v[2:3], v79 offset0:40 offset1:105
	v_ashrrev_i32_e32 v77, 31, v76
	s_waitcnt lgkmcnt(0)
	v_cvt_pk_bf16_f32 v2, v2, v3
	ds_read2_b32 v[4:5], v79 offset0:170 offset1:235
	v_lshlrev_b64 v[76:77], 11, v[76:77]
	s_waitcnt lgkmcnt(0)
	v_cvt_pk_bf16_f32 v3, v4, v5
	ds_read2_b32 v[4:5], v39 offset0:44 offset1:109
	v_lshl_add_u64 v[76:77], v[6:7], 0, v[76:77]
	s_waitcnt lgkmcnt(0)
	v_cvt_pk_bf16_f32 v4, v4, v5
	ds_read2_b32 v[8:9], v39 offset0:174 offset1:239
	s_waitcnt lgkmcnt(0)
	v_cvt_pk_bf16_f32 v5, v8, v9
	flat_store_dwordx4 v[76:77], v[2:5] sc1
	v_or_b32_e32 v76, v43, v85
	ds_read2_b32 v[2:3], v79 offset0:48 offset1:113
	v_ashrrev_i32_e32 v77, 31, v76
	s_waitcnt lgkmcnt(0)
	v_cvt_pk_bf16_f32 v2, v2, v3
	ds_read2_b32 v[4:5], v79 offset0:178 offset1:243
	v_lshlrev_b64 v[76:77], 11, v[76:77]
	s_waitcnt lgkmcnt(0)
	v_cvt_pk_bf16_f32 v3, v4, v5
	ds_read2_b32 v[4:5], v39 offset0:52 offset1:117
	v_lshl_add_u64 v[76:77], v[6:7], 0, v[76:77]
	s_waitcnt lgkmcnt(0)
	v_cvt_pk_bf16_f32 v4, v4, v5
	ds_read2_b32 v[8:9], v39 offset0:182 offset1:247
	s_waitcnt lgkmcnt(0)
	v_cvt_pk_bf16_f32 v5, v8, v9
	flat_store_dwordx4 v[76:77], v[2:5] sc1
	v_or_b32_e32 v76, v43, v86
	ds_read2_b32 v[2:3], v79 offset0:56 offset1:121
	v_ashrrev_i32_e32 v77, 31, v76
	s_waitcnt lgkmcnt(0)
	v_cvt_pk_bf16_f32 v2, v2, v3
	ds_read2_b32 v[4:5], v79 offset0:186 offset1:251
	v_lshlrev_b64 v[76:77], 11, v[76:77]
	s_waitcnt lgkmcnt(0)
	v_cvt_pk_bf16_f32 v3, v4, v5
	ds_read2_b32 v[4:5], v39 offset0:60 offset1:125
	v_lshl_add_u64 v[6:7], v[6:7], 0, v[76:77]
	s_waitcnt lgkmcnt(0)
	v_cvt_pk_bf16_f32 v4, v4, v5
	ds_read2_b32 v[8:9], v39 offset0:190 offset1:255
	s_waitcnt lgkmcnt(0)
	v_cvt_pk_bf16_f32 v5, v8, v9
	flat_store_dwordx4 v[6:7], v[2:5] sc1
	s_waitcnt lgkmcnt(0)

.LBB0_651:
	v_lshl_add_u64 v[4:5], v[2:3], 0, s[42:43]
	v_add_co_u32_e32 v6, vcc, 0x2000, v4
	s_mov_b64 s[0:1], vcc
	v_add_co_u32_e32 v8, vcc, 0x4000, v4
	v_addc_co_u32_e64 v7, s[0:1], 0, v5, s[0:1]
	s_mov_b64 s[0:1], vcc
	v_add_co_u32_e32 v76, vcc, 0x6000, v4
	v_addc_co_u32_e64 v9, s[0:1], 0, v5, s[0:1]
	s_mov_b64 s[0:1], vcc
	s_nop 0
	v_addc_co_u32_e64 v77, s[0:1], 0, v5, s[0:1]
	global_load_dword v39, v[4:5], off nt
	global_load_dword v43, v[6:7], off nt
	global_load_dword v47, v[8:9], off nt
	global_load_dword v51, v[76:77], off nt
	v_add_co_u32_e32 v6, vcc, 0x8000, v4
	s_mov_b64 s[0:1], vcc
	v_add_co_u32_e32 v8, vcc, 0xa000, v4
	v_addc_co_u32_e64 v7, s[0:1], 0, v5, s[0:1]
	s_mov_b64 s[0:1], vcc
	v_add_co_u32_e32 v76, vcc, 0xc000, v4
	v_addc_co_u32_e64 v9, s[0:1], 0, v5, s[0:1]
	s_mov_b64 s[0:1], vcc
	s_nop 0
	v_addc_co_u32_e64 v77, s[0:1], 0, v5, s[0:1]
	global_load_dword v55, v[6:7], off nt
	global_load_dword v61, v[8:9], off nt
	global_load_dword v73, v[76:77], off nt
	v_add_co_u32_e32 v6, vcc, 0xe000, v4
	s_mov_b64 s[0:1], vcc
	v_add_co_u32_e32 v8, vcc, s33, v4
	v_addc_co_u32_e64 v7, s[0:1], 0, v5, s[0:1]
	s_mov_b64 s[0:1], vcc
	v_add_co_u32_e32 v76, vcc, s2, v4
	v_addc_co_u32_e64 v9, s[0:1], 0, v5, s[0:1]
	s_mov_b64 s[0:1], vcc
	s_nop 0
	v_addc_co_u32_e64 v77, s[0:1], 0, v5, s[0:1]
	global_load_dword v99, v[6:7], off nt
	global_load_dword v100, v[8:9], off nt
	global_load_dword v101, v[76:77], off nt
	v_add_co_u32_e32 v6, vcc, s3, v4
	s_mov_b64 s[0:1], vcc
	v_add_co_u32_e32 v8, vcc, s80, v4
	v_addc_co_u32_e64 v7, s[0:1], 0, v5, s[0:1]
	s_mov_b64 s[0:1], vcc
	v_add_co_u32_e32 v76, vcc, s81, v4
	v_addc_co_u32_e64 v9, s[0:1], 0, v5, s[0:1]
	s_mov_b64 s[0:1], vcc
	s_mov_b32 s8, 0x1a000
	global_load_dword v102, v[6:7], off nt
	global_load_dword v103, v[8:9], off nt
	v_add_co_u32_e32 v6, vcc, s8, v4
	v_addc_co_u32_e64 v77, s[0:1], 0, v5, s[0:1]
	s_mov_b64 s[0:1], vcc
	s_mov_b32 s8, 0x1c000
	v_add_co_u32_e32 v8, vcc, s8, v4
	v_addc_co_u32_e64 v7, s[0:1], 0, v5, s[0:1]
	s_mov_b64 s[0:1], vcc
	v_add_co_u32_e32 v4, vcc, s82, v4
	v_addc_co_u32_e64 v9, s[0:1], 0, v5, s[0:1]
	global_load_dword v76, v[76:77], off nt
	v_addc_co_u32_e32 v5, vcc, 0, v5, vcc
	global_load_dword v6, v[6:7], off nt
	s_nop 0
	global_load_dword v7, v[8:9], off nt
	s_nop 0
	global_load_dword v4, v[4:5], off nt
	s_add_u32 s42, s42, 0x20000
	s_addc_u32 s43, s43, 0
	v_add_u32_e32 v5, 0x400, v0
	v_add_u32_e32 v8, 0x800, v0
	v_add_u32_e32 v9, 0xc00, v0
	s_cmp_lg_u32 s42, 0x80000
	s_waitcnt vmcnt(0)
	ds_write2_b32 v0, v39, v43 offset1:65
	ds_write2_b32 v0, v47, v51 offset0:130 offset1:195
	v_add_u32_e32 v0, 0x1040, v0
	ds_write2_b32 v5, v55, v61 offset0:4 offset1:69
	ds_write2_b32 v5, v73, v99 offset0:134 offset1:199
	ds_write2_b32 v8, v100, v101 offset0:8 offset1:73
	ds_write2_b32 v8, v102, v103 offset0:138 offset1:203
	ds_write2_b32 v9, v76, v6 offset0:12 offset1:77
	ds_write2_b32 v9, v7, v4 offset0:142 offset1:207
	s_cbranch_scc1 .LBB0_651
	v_add_u32_e32 v0, 0xffffe740, v74
	v_lshrrev_b32_e32 v6, 5, v0
	v_lshlrev_b32_e32 v7, 6, v0
	v_lshlrev_b32_e32 v8, 11, v6
	v_sub_u32_e32 v43, v7, v8
	s_waitcnt lgkmcnt(0)
	v_or_b32_e32 v76, v43, v78
	ds_read2_b32 v[2:3], v79 offset1:65
	v_lshlrev_b32_e32 v0, 7, v6
	v_ashrrev_i32_e32 v77, 31, v76
	s_waitcnt lgkmcnt(0)
	v_cvt_pk_bf16_f32 v2, v2, v3
	ds_read2_b32 v[4:5], v79 offset0:130 offset1:195
	v_add_u32_e32 v39, 0x400, v79
	v_lshl_add_u64 v[6:7], v[20:21], 0, v[0:1]
	v_lshlrev_b64 v[76:77], 11, v[76:77]
	s_waitcnt lgkmcnt(0)
	v_cvt_pk_bf16_f32 v3, v4, v5
	ds_read2_b32 v[4:5], v39 offset0:4 offset1:69
	v_lshl_add_u64 v[76:77], v[6:7], 0, v[76:77]
	s_waitcnt lgkmcnt(0)
	v_cvt_pk_bf16_f32 v4, v4, v5
	ds_read2_b32 v[8:9], v39 offset0:134 offset1:199
	s_waitcnt lgkmcnt(0)
	v_cvt_pk_bf16_f32 v5, v8, v9
	flat_store_dwordx4 v[76:77], v[2:5] sc1
	v_or_b32_e32 v76, v43, v80
	ds_read2_b32 v[2:3], v79 offset0:8 offset1:73
	v_ashrrev_i32_e32 v77, 31, v76
	s_waitcnt lgkmcnt(0)
	v_cvt_pk_bf16_f32 v2, v2, v3
	ds_read2_b32 v[4:5], v79 offset0:138 offset1:203
	v_lshlrev_b64 v[76:77], 11, v[76:77]
	s_waitcnt lgkmcnt(0)
	v_cvt_pk_bf16_f32 v3, v4, v5
	ds_read2_b32 v[4:5], v39 offset0:12 offset1:77
	v_lshl_add_u64 v[76:77], v[6:7], 0, v[76:77]
	s_waitcnt lgkmcnt(0)
	v_cvt_pk_bf16_f32 v4, v4, v5
	ds_read2_b32 v[8:9], v39 offset0:142 offset1:207
	s_waitcnt lgkmcnt(0)
	v_cvt_pk_bf16_f32 v5, v8, v9
	flat_store_dwordx4 v[76:77], v[2:5] sc1
	v_or_b32_e32 v76, v43, v81
	ds_read2_b32 v[2:3], v79 offset0:16 offset1:81
	v_ashrrev_i32_e32 v77, 31, v76
	s_waitcnt lgkmcnt(0)
	v_cvt_pk_bf16_f32 v2, v2, v3
	ds_read2_b32 v[4:5], v79 offset0:146 offset1:211
	v_lshlrev_b64 v[76:77], 11, v[76:77]
	s_waitcnt lgkmcnt(0)
	v_cvt_pk_bf16_f32 v3, v4, v5
	ds_read2_b32 v[4:5], v39 offset0:20 offset1:85
	v_lshl_add_u64 v[76:77], v[6:7], 0, v[76:77]
	s_waitcnt lgkmcnt(0)
	v_cvt_pk_bf16_f32 v4, v4, v5
	ds_read2_b32 v[8:9], v39 offset0:150 offset1:215
	s_waitcnt lgkmcnt(0)
	v_cvt_pk_bf16_f32 v5, v8, v9
	flat_store_dwordx4 v[76:77], v[2:5] sc1
	v_or_b32_e32 v76, v43, v82
	ds_read2_b32 v[2:3], v79 offset0:24 offset1:89
	v_ashrrev_i32_e32 v77, 31, v76
	s_waitcnt lgkmcnt(0)
	v_cvt_pk_bf16_f32 v2, v2, v3
	ds_read2_b32 v[4:5], v79 offset0:154 offset1:219
	v_lshlrev_b64 v[76:77], 11, v[76:77]
	s_waitcnt lgkmcnt(0)
	v_cvt_pk_bf16_f32 v3, v4, v5
	ds_read2_b32 v[4:5], v39 offset0:28 offset1:93
	v_lshl_add_u64 v[76:77], v[6:7], 0, v[76:77]
	s_waitcnt lgkmcnt(0)
	v_cvt_pk_bf16_f32 v4, v4, v5
	ds_read2_b32 v[8:9], v39 offset0:158 offset1:223
	s_waitcnt lgkmcnt(0)
	v_cvt_pk_bf16_f32 v5, v8, v9
	flat_store_dwordx4 v[76:77], v[2:5] sc1
	v_or_b32_e32 v76, v43, v83
	ds_read2_b32 v[2:3], v79 offset0:32 offset1:97
	v_ashrrev_i32_e32 v77, 31, v76
	s_waitcnt lgkmcnt(0)
	v_cvt_pk_bf16_f32 v2, v2, v3
	ds_read2_b32 v[4:5], v79 offset0:162 offset1:227
	v_lshlrev_b64 v[76:77], 11, v[76:77]
	s_waitcnt lgkmcnt(0)
	v_cvt_pk_bf16_f32 v3, v4, v5
	ds_read2_b32 v[4:5], v39 offset0:36 offset1:101
	v_lshl_add_u64 v[76:77], v[6:7], 0, v[76:77]
	s_waitcnt lgkmcnt(0)
	v_cvt_pk_bf16_f32 v4, v4, v5
	ds_read2_b32 v[8:9], v39 offset0:166 offset1:231
	s_waitcnt lgkmcnt(0)
	v_cvt_pk_bf16_f32 v5, v8, v9
	flat_store_dwordx4 v[76:77], v[2:5] sc1
	v_or_b32_e32 v76, v43, v84
	ds_read2_b32 v[2:3], v79 offset0:40 offset1:105
	v_ashrrev_i32_e32 v77, 31, v76
	s_waitcnt lgkmcnt(0)
	v_cvt_pk_bf16_f32 v2, v2, v3
	ds_read2_b32 v[4:5], v79 offset0:170 offset1:235
	v_lshlrev_b64 v[76:77], 11, v[76:77]
	s_waitcnt lgkmcnt(0)
	v_cvt_pk_bf16_f32 v3, v4, v5
	ds_read2_b32 v[4:5], v39 offset0:44 offset1:109
	v_lshl_add_u64 v[76:77], v[6:7], 0, v[76:77]
	s_waitcnt lgkmcnt(0)
	v_cvt_pk_bf16_f32 v4, v4, v5
	ds_read2_b32 v[8:9], v39 offset0:174 offset1:239
	s_waitcnt lgkmcnt(0)
	v_cvt_pk_bf16_f32 v5, v8, v9
	flat_store_dwordx4 v[76:77], v[2:5] sc1
	v_or_b32_e32 v76, v43, v85
	ds_read2_b32 v[2:3], v79 offset0:48 offset1:113
	v_ashrrev_i32_e32 v77, 31, v76
	s_waitcnt lgkmcnt(0)
	v_cvt_pk_bf16_f32 v2, v2, v3
	ds_read2_b32 v[4:5], v79 offset0:178 offset1:243
	v_lshlrev_b64 v[76:77], 11, v[76:77]
	s_waitcnt lgkmcnt(0)
	v_cvt_pk_bf16_f32 v3, v4, v5
	ds_read2_b32 v[4:5], v39 offset0:52 offset1:117
	v_lshl_add_u64 v[76:77], v[6:7], 0, v[76:77]
	s_waitcnt lgkmcnt(0)
	v_cvt_pk_bf16_f32 v4, v4, v5
	ds_read2_b32 v[8:9], v39 offset0:182 offset1:247
	s_waitcnt lgkmcnt(0)
	v_cvt_pk_bf16_f32 v5, v8, v9
	flat_store_dwordx4 v[76:77], v[2:5] sc1
	v_or_b32_e32 v76, v43, v86
	ds_read2_b32 v[2:3], v79 offset0:56 offset1:121
	v_ashrrev_i32_e32 v77, 31, v76
	s_waitcnt lgkmcnt(0)
	v_cvt_pk_bf16_f32 v2, v2, v3
	ds_read2_b32 v[4:5], v79 offset0:186 offset1:251
	v_lshlrev_b64 v[76:77], 11, v[76:77]
	s_waitcnt lgkmcnt(0)
	v_cvt_pk_bf16_f32 v3, v4, v5
	ds_read2_b32 v[4:5], v39 offset0:60 offset1:125
	v_lshl_add_u64 v[6:7], v[6:7], 0, v[76:77]
	s_waitcnt lgkmcnt(0)
	v_cvt_pk_bf16_f32 v4, v4, v5
	ds_read2_b32 v[8:9], v39 offset0:190 offset1:255
	s_waitcnt lgkmcnt(0)
	v_cvt_pk_bf16_f32 v5, v8, v9
	flat_store_dwordx4 v[6:7], v[2:5] sc1
	s_waitcnt lgkmcnt(0)

.LBB0_660:
	ds_read2_b32 v[76:77], v79 offset1:65
	v_add_lshl_u32 v39, v43, v39, 6
	v_or_b32_e32 v106, v39, v78
	v_ashrrev_i32_e32 v107, 31, v106
	v_lshlrev_b64 v[106:107], 11, v[106:107]
	s_waitcnt vmcnt(0) lgkmcnt(0)
	v_mul_f32_e32 v0, v6, v76
	v_mul_f32_e32 v51, v7, v77
	v_cvt_pk_bf16_f32 v100, v0, v51
	ds_read2_b32 v[76:77], v79 offset0:130 offset1:195
	v_add_u32_e32 v51, 0x400, v79
	s_waitcnt lgkmcnt(0)
	v_mul_f32_e32 v0, v8, v76
	v_mul_f32_e32 v55, v9, v77
	v_cvt_pk_bf16_f32 v101, v0, v55
	ds_read2_b32 v[76:77], v51 offset0:4 offset1:69
	v_lshlrev_b32_e32 v0, 1, v47
	v_lshl_add_u64 v[104:105], v[32:33], 0, v[0:1]
	v_lshl_add_u64 v[106:107], v[104:105], 0, v[106:107]
	s_waitcnt lgkmcnt(0)
	v_mul_f32_e32 v0, v2, v76
	v_mul_f32_e32 v43, v3, v77
	v_cvt_pk_bf16_f32 v102, v0, v43
	ds_read2_b32 v[76:77], v51 offset0:134 offset1:199
	s_waitcnt lgkmcnt(0)
	v_mul_f32_e32 v0, v4, v76
	v_mul_f32_e32 v43, v5, v77
	v_cvt_pk_bf16_f32 v103, v0, v43
	flat_store_dwordx4 v[106:107], v[100:103] sc1
	ds_read2_b32 v[76:77], v79 offset0:8 offset1:73
	v_or_b32_e32 v106, v39, v80
	v_ashrrev_i32_e32 v107, 31, v106
	v_lshlrev_b64 v[106:107], 11, v[106:107]
	v_lshl_add_u64 v[106:107], v[104:105], 0, v[106:107]
	s_waitcnt lgkmcnt(0)
	v_mul_f32_e32 v0, v6, v76
	v_mul_f32_e32 v43, v7, v77
	v_cvt_pk_bf16_f32 v100, v0, v43
	ds_read2_b32 v[76:77], v79 offset0:138 offset1:203
	s_waitcnt lgkmcnt(0)
	v_mul_f32_e32 v0, v8, v76
	v_mul_f32_e32 v43, v9, v77
	v_cvt_pk_bf16_f32 v101, v0, v43
	ds_read2_b32 v[76:77], v51 offset0:12 offset1:77
	s_waitcnt lgkmcnt(0)
	v_mul_f32_e32 v0, v2, v76
	v_mul_f32_e32 v43, v3, v77
	v_cvt_pk_bf16_f32 v102, v0, v43
	ds_read2_b32 v[76:77], v51 offset0:142 offset1:207
	s_waitcnt lgkmcnt(0)
	v_mul_f32_e32 v0, v4, v76
	v_mul_f32_e32 v43, v5, v77
	v_cvt_pk_bf16_f32 v103, v0, v43
	flat_store_dwordx4 v[106:107], v[100:103] sc1
	ds_read2_b32 v[76:77], v79 offset0:16 offset1:81
	v_or_b32_e32 v106, v39, v81
	v_ashrrev_i32_e32 v107, 31, v106
	v_lshlrev_b64 v[106:107], 11, v[106:107]
	v_lshl_add_u64 v[106:107], v[104:105], 0, v[106:107]
	s_waitcnt lgkmcnt(0)
	v_mul_f32_e32 v0, v6, v76
	v_mul_f32_e32 v43, v7, v77
	v_cvt_pk_bf16_f32 v100, v0, v43
	ds_read2_b32 v[76:77], v79 offset0:146 offset1:211
	s_waitcnt lgkmcnt(0)
	v_mul_f32_e32 v0, v8, v76
	v_mul_f32_e32 v43, v9, v77
	v_cvt_pk_bf16_f32 v101, v0, v43
	ds_read2_b32 v[76:77], v51 offset0:20 offset1:85
	s_waitcnt lgkmcnt(0)
	v_mul_f32_e32 v0, v2, v76
	v_mul_f32_e32 v43, v3, v77
	v_cvt_pk_bf16_f32 v102, v0, v43
	ds_read2_b32 v[76:77], v51 offset0:150 offset1:215
	s_waitcnt lgkmcnt(0)
	v_mul_f32_e32 v0, v4, v76
	v_mul_f32_e32 v43, v5, v77
	v_cvt_pk_bf16_f32 v103, v0, v43
	flat_store_dwordx4 v[106:107], v[100:103] sc1
	ds_read2_b32 v[76:77], v79 offset0:24 offset1:89
	v_or_b32_e32 v106, v39, v82
	v_ashrrev_i32_e32 v107, 31, v106
	v_lshlrev_b64 v[106:107], 11, v[106:107]
	v_lshl_add_u64 v[106:107], v[104:105], 0, v[106:107]
	s_waitcnt lgkmcnt(0)
	v_mul_f32_e32 v0, v6, v76
	v_mul_f32_e32 v43, v7, v77
	v_cvt_pk_bf16_f32 v100, v0, v43
	ds_read2_b32 v[76:77], v79 offset0:154 offset1:219
	s_waitcnt lgkmcnt(0)
	v_mul_f32_e32 v0, v8, v76
	v_mul_f32_e32 v43, v9, v77
	v_cvt_pk_bf16_f32 v101, v0, v43
	ds_read2_b32 v[76:77], v51 offset0:28 offset1:93
	s_waitcnt lgkmcnt(0)
	v_mul_f32_e32 v0, v2, v76
	v_mul_f32_e32 v43, v3, v77
	v_cvt_pk_bf16_f32 v102, v0, v43
	ds_read2_b32 v[76:77], v51 offset0:158 offset1:223
	s_waitcnt lgkmcnt(0)
	v_mul_f32_e32 v0, v4, v76
	v_mul_f32_e32 v43, v5, v77
	v_cvt_pk_bf16_f32 v103, v0, v43
	flat_store_dwordx4 v[106:107], v[100:103] sc1
	ds_read2_b32 v[76:77], v79 offset0:32 offset1:97
	v_or_b32_e32 v106, v39, v83
	v_ashrrev_i32_e32 v107, 31, v106
	v_lshlrev_b64 v[106:107], 11, v[106:107]
	v_lshl_add_u64 v[106:107], v[104:105], 0, v[106:107]
	s_waitcnt lgkmcnt(0)
	v_mul_f32_e32 v0, v6, v76
	v_mul_f32_e32 v43, v7, v77
	v_cvt_pk_bf16_f32 v100, v0, v43
	ds_read2_b32 v[76:77], v79 offset0:162 offset1:227
	s_waitcnt lgkmcnt(0)
	v_mul_f32_e32 v0, v8, v76
	v_mul_f32_e32 v43, v9, v77
	v_cvt_pk_bf16_f32 v101, v0, v43
	ds_read2_b32 v[76:77], v51 offset0:36 offset1:101
	s_waitcnt lgkmcnt(0)
	v_mul_f32_e32 v0, v2, v76
	v_mul_f32_e32 v43, v3, v77
	v_cvt_pk_bf16_f32 v102, v0, v43
	ds_read2_b32 v[76:77], v51 offset0:166 offset1:231
	s_waitcnt lgkmcnt(0)
	v_mul_f32_e32 v0, v4, v76
	v_mul_f32_e32 v43, v5, v77
	v_cvt_pk_bf16_f32 v103, v0, v43
	flat_store_dwordx4 v[106:107], v[100:103] sc1
	ds_read2_b32 v[76:77], v79 offset0:40 offset1:105
	v_or_b32_e32 v106, v39, v84
	v_ashrrev_i32_e32 v107, 31, v106
	v_lshlrev_b64 v[106:107], 11, v[106:107]
	v_lshl_add_u64 v[106:107], v[104:105], 0, v[106:107]
	s_waitcnt lgkmcnt(0)
	v_mul_f32_e32 v0, v6, v76
	v_mul_f32_e32 v43, v7, v77
	v_cvt_pk_bf16_f32 v100, v0, v43
	ds_read2_b32 v[76:77], v79 offset0:170 offset1:235
	s_waitcnt lgkmcnt(0)
	v_mul_f32_e32 v0, v8, v76
	v_mul_f32_e32 v43, v9, v77
	v_cvt_pk_bf16_f32 v101, v0, v43
	ds_read2_b32 v[76:77], v51 offset0:44 offset1:109
	s_waitcnt lgkmcnt(0)
	v_mul_f32_e32 v0, v2, v76
	v_mul_f32_e32 v43, v3, v77
	v_cvt_pk_bf16_f32 v102, v0, v43
	ds_read2_b32 v[76:77], v51 offset0:174 offset1:239
	s_waitcnt lgkmcnt(0)
	v_mul_f32_e32 v0, v4, v76
	v_mul_f32_e32 v43, v5, v77
	v_cvt_pk_bf16_f32 v103, v0, v43
	flat_store_dwordx4 v[106:107], v[100:103] sc1
	ds_read2_b32 v[76:77], v79 offset0:48 offset1:113
	v_or_b32_e32 v106, v39, v85
	v_ashrrev_i32_e32 v107, 31, v106
	v_lshlrev_b64 v[106:107], 11, v[106:107]
	v_lshl_add_u64 v[106:107], v[104:105], 0, v[106:107]
	s_waitcnt lgkmcnt(0)
	v_mul_f32_e32 v0, v6, v76
	v_mul_f32_e32 v43, v7, v77
	v_cvt_pk_bf16_f32 v100, v0, v43
	ds_read2_b32 v[76:77], v79 offset0:178 offset1:243
	s_waitcnt lgkmcnt(0)
	v_mul_f32_e32 v0, v8, v76
	v_mul_f32_e32 v43, v9, v77
	v_cvt_pk_bf16_f32 v101, v0, v43
	ds_read2_b32 v[76:77], v51 offset0:52 offset1:117
	s_waitcnt lgkmcnt(0)
	v_mul_f32_e32 v0, v2, v76
	v_mul_f32_e32 v43, v3, v77
	v_cvt_pk_bf16_f32 v102, v0, v43
	ds_read2_b32 v[76:77], v51 offset0:182 offset1:247
	s_waitcnt lgkmcnt(0)
	v_mul_f32_e32 v0, v4, v76
	v_mul_f32_e32 v43, v5, v77
	v_cvt_pk_bf16_f32 v103, v0, v43
	flat_store_dwordx4 v[106:107], v[100:103] sc1
	ds_read2_b32 v[76:77], v79 offset0:56 offset1:121
	s_waitcnt lgkmcnt(0)
	v_mul_f32_e32 v0, v6, v76
	v_mul_f32_e32 v6, v7, v77
	v_cvt_pk_bf16_f32 v6, v0, v6
	ds_read2_b32 v[76:77], v79 offset0:186 offset1:251
	s_waitcnt lgkmcnt(0)
	v_mul_f32_e32 v7, v9, v77
	v_mul_f32_e32 v0, v8, v76
	v_cvt_pk_bf16_f32 v7, v0, v7
	ds_read2_b32 v[8:9], v51 offset0:60 offset1:125
	v_or_b32_e32 v76, v39, v86
	v_ashrrev_i32_e32 v77, 31, v76
	v_lshlrev_b64 v[76:77], 11, v[76:77]
	s_waitcnt lgkmcnt(0)
	v_mul_f32_e32 v0, v2, v8
	v_mul_f32_e32 v2, v3, v9
	v_cvt_pk_bf16_f32 v8, v0, v2
	ds_read2_b32 v[2:3], v51 offset0:190 offset1:255
	s_waitcnt lgkmcnt(0)
	v_mul_f32_e32 v0, v4, v2
	v_mul_f32_e32 v2, v5, v3
	v_cvt_pk_bf16_f32 v9, v0, v2
	v_lshl_add_u64 v[2:3], v[104:105], 0, v[76:77]
	flat_store_dwordx4 v[2:3], v[6:9] sc1
	s_waitcnt lgkmcnt(0)

.LBB0_664:
	v_lshl_add_u64 v[4:5], v[2:3], 0, s[38:39]
	v_add_co_u32_e32 v6, vcc, 0x1000, v4
	s_mov_b64 s[0:1], vcc
	v_add_co_u32_e32 v8, vcc, 0x2000, v4
	v_addc_co_u32_e64 v7, s[0:1], 0, v5, s[0:1]
	s_mov_b64 s[0:1], vcc
	v_add_co_u32_e32 v76, vcc, 0x3000, v4
	v_addc_co_u32_e64 v9, s[0:1], 0, v5, s[0:1]
	s_mov_b64 s[0:1], vcc
	s_nop 0
	v_addc_co_u32_e64 v77, s[0:1], 0, v5, s[0:1]
	global_load_dword v39, v[4:5], off nt
	global_load_dword v43, v[6:7], off nt
	global_load_dword v47, v[8:9], off nt
	global_load_dword v51, v[76:77], off nt
	v_add_co_u32_e32 v6, vcc, 0x4000, v4
	s_mov_b64 s[0:1], vcc
	v_add_co_u32_e32 v8, vcc, 0x5000, v4
	v_addc_co_u32_e64 v7, s[0:1], 0, v5, s[0:1]
	s_mov_b64 s[0:1], vcc
	v_add_co_u32_e32 v76, vcc, 0x6000, v4
	v_addc_co_u32_e64 v9, s[0:1], 0, v5, s[0:1]
	s_mov_b64 s[0:1], vcc
	s_nop 0
	v_addc_co_u32_e64 v77, s[0:1], 0, v5, s[0:1]
	global_load_dword v55, v[6:7], off nt
	global_load_dword v61, v[8:9], off nt
	global_load_dword v73, v[76:77], off nt
	v_add_co_u32_e32 v6, vcc, 0x7000, v4
	s_mov_b64 s[0:1], vcc
	v_add_co_u32_e32 v8, vcc, 0x8000, v4
	v_addc_co_u32_e64 v7, s[0:1], 0, v5, s[0:1]
	s_mov_b64 s[0:1], vcc
	v_add_co_u32_e32 v76, vcc, 0x9000, v4
	v_addc_co_u32_e64 v9, s[0:1], 0, v5, s[0:1]
	s_mov_b64 s[0:1], vcc
	s_nop 0
	v_addc_co_u32_e64 v77, s[0:1], 0, v5, s[0:1]
	global_load_dword v99, v[6:7], off nt
	global_load_dword v100, v[8:9], off nt
	global_load_dword v101, v[76:77], off nt
	v_add_co_u32_e32 v6, vcc, 0xa000, v4
	s_mov_b64 s[0:1], vcc
	v_add_co_u32_e32 v8, vcc, 0xb000, v4
	v_addc_co_u32_e64 v7, s[0:1], 0, v5, s[0:1]
	s_mov_b64 s[0:1], vcc
	v_add_co_u32_e32 v76, vcc, 0xc000, v4
	v_addc_co_u32_e64 v9, s[0:1], 0, v5, s[0:1]
	s_mov_b64 s[0:1], vcc
	global_load_dword v102, v[6:7], off nt
	global_load_dword v103, v[8:9], off nt
	v_add_co_u32_e32 v6, vcc, 0xd000, v4
	v_addc_co_u32_e64 v77, s[0:1], 0, v5, s[0:1]
	s_mov_b64 s[0:1], vcc
	v_add_co_u32_e32 v8, vcc, 0xe000, v4
	v_addc_co_u32_e64 v7, s[0:1], 0, v5, s[0:1]
	s_mov_b64 s[0:1], vcc
	v_add_co_u32_e32 v4, vcc, 0xf000, v4
	v_addc_co_u32_e64 v9, s[0:1], 0, v5, s[0:1]
	global_load_dword v76, v[76:77], off nt
	v_addc_co_u32_e32 v5, vcc, 0, v5, vcc
	global_load_dword v6, v[6:7], off nt
	s_nop 0
	global_load_dword v7, v[8:9], off nt
	s_nop 0
	global_load_dword v4, v[4:5], off nt
	s_add_u32 s38, s38, 0x10000
	s_addc_u32 s39, s39, 0
	v_add_u32_e32 v5, 0x400, v0
	v_add_u32_e32 v8, 0x800, v0
	v_add_u32_e32 v9, 0xc00, v0
	s_cmp_lg_u32 s38, 0x40000
	s_waitcnt vmcnt(0)
	ds_write2_b32 v0, v39, v43 offset1:65
	ds_write2_b32 v0, v47, v51 offset0:130 offset1:195
	v_add_u32_e32 v0, 0x1040, v0
	ds_write2_b32 v5, v55, v61 offset0:4 offset1:69
	ds_write2_b32 v5, v73, v99 offset0:134 offset1:199
	ds_write2_b32 v8, v100, v101 offset0:8 offset1:73
	ds_write2_b32 v8, v102, v103 offset0:138 offset1:203
	ds_write2_b32 v9, v76, v6 offset0:12 offset1:77
	ds_write2_b32 v9, v7, v4 offset0:142 offset1:207
	s_cbranch_scc1 .LBB0_664
	v_add_u32_e32 v0, 0xfffff240, v74
	v_lshrrev_b32_e32 v6, 4, v0
	s_waitcnt lgkmcnt(0)
	v_lshlrev_b32_e32 v7, 6, v0
	v_lshlrev_b32_e32 v8, 10, v6
	ds_read2_b32 v[2:3], v79 offset1:65
	v_lshlrev_b32_e32 v0, 7, v6
	v_sub_u32_e32 v43, v7, v8
	s_waitcnt lgkmcnt(0)
	v_cvt_pk_bf16_f32 v2, v2, v3
	ds_read2_b32 v[4:5], v79 offset0:130 offset1:195
	v_add_u32_e32 v39, 0x400, v79
	v_lshl_add_u64 v[8:9], v[24:25], 0, v[0:1]
	v_or_b32_e32 v0, v43, v78
	s_waitcnt lgkmcnt(0)
	v_cvt_pk_bf16_f32 v3, v4, v5
	ds_read2_b32 v[4:5], v39 offset0:4 offset1:69
	v_mad_i64_i32 v[76:77], s[0:1], v0, s87, v[8:9]
	s_waitcnt lgkmcnt(0)
	v_cvt_pk_bf16_f32 v4, v4, v5
	ds_read2_b32 v[6:7], v39 offset0:134 offset1:199
	s_waitcnt lgkmcnt(0)
	v_cvt_pk_bf16_f32 v5, v6, v7
	flat_store_dwordx4 v[76:77], v[2:5] sc1
	ds_read2_b32 v[2:3], v79 offset0:8 offset1:73
	v_or_b32_e32 v0, v43, v80
	s_waitcnt lgkmcnt(0)
	v_cvt_pk_bf16_f32 v2, v2, v3
	ds_read2_b32 v[4:5], v79 offset0:138 offset1:203
	s_waitcnt lgkmcnt(0)
	v_cvt_pk_bf16_f32 v3, v4, v5
	ds_read2_b32 v[4:5], v39 offset0:12 offset1:77
	v_mad_i64_i32 v[76:77], s[0:1], v0, s87, v[8:9]
	s_waitcnt lgkmcnt(0)
	v_cvt_pk_bf16_f32 v4, v4, v5
	ds_read2_b32 v[6:7], v39 offset0:142 offset1:207
	s_waitcnt lgkmcnt(0)
	v_cvt_pk_bf16_f32 v5, v6, v7
	flat_store_dwordx4 v[76:77], v[2:5] sc1
	ds_read2_b32 v[2:3], v79 offset0:16 offset1:81
	v_or_b32_e32 v0, v43, v81
	s_waitcnt lgkmcnt(0)
	v_cvt_pk_bf16_f32 v2, v2, v3
	ds_read2_b32 v[4:5], v79 offset0:146 offset1:211
	s_waitcnt lgkmcnt(0)
	v_cvt_pk_bf16_f32 v3, v4, v5
	ds_read2_b32 v[4:5], v39 offset0:20 offset1:85
	v_mad_i64_i32 v[76:77], s[0:1], v0, s87, v[8:9]
	s_waitcnt lgkmcnt(0)
	v_cvt_pk_bf16_f32 v4, v4, v5
	ds_read2_b32 v[6:7], v39 offset0:150 offset1:215
	s_waitcnt lgkmcnt(0)
	v_cvt_pk_bf16_f32 v5, v6, v7
	flat_store_dwordx4 v[76:77], v[2:5] sc1
	ds_read2_b32 v[2:3], v79 offset0:24 offset1:89
	v_or_b32_e32 v0, v43, v82
	s_waitcnt lgkmcnt(0)
	v_cvt_pk_bf16_f32 v2, v2, v3
	ds_read2_b32 v[4:5], v79 offset0:154 offset1:219
	s_waitcnt lgkmcnt(0)
	v_cvt_pk_bf16_f32 v3, v4, v5
	ds_read2_b32 v[4:5], v39 offset0:28 offset1:93
	v_mad_i64_i32 v[76:77], s[0:1], v0, s87, v[8:9]
	s_waitcnt lgkmcnt(0)
	v_cvt_pk_bf16_f32 v4, v4, v5
	ds_read2_b32 v[6:7], v39 offset0:158 offset1:223
	s_waitcnt lgkmcnt(0)
	v_cvt_pk_bf16_f32 v5, v6, v7
	flat_store_dwordx4 v[76:77], v[2:5] sc1
	ds_read2_b32 v[2:3], v79 offset0:32 offset1:97
	v_or_b32_e32 v0, v43, v83
	s_waitcnt lgkmcnt(0)
	v_cvt_pk_bf16_f32 v2, v2, v3
	ds_read2_b32 v[4:5], v79 offset0:162 offset1:227
	s_waitcnt lgkmcnt(0)
	v_cvt_pk_bf16_f32 v3, v4, v5
	ds_read2_b32 v[4:5], v39 offset0:36 offset1:101
	v_mad_i64_i32 v[76:77], s[0:1], v0, s87, v[8:9]
	s_waitcnt lgkmcnt(0)
	v_cvt_pk_bf16_f32 v4, v4, v5
	ds_read2_b32 v[6:7], v39 offset0:166 offset1:231
	s_waitcnt lgkmcnt(0)
	v_cvt_pk_bf16_f32 v5, v6, v7
	flat_store_dwordx4 v[76:77], v[2:5] sc1
	ds_read2_b32 v[2:3], v79 offset0:40 offset1:105
	v_or_b32_e32 v0, v43, v84
	s_waitcnt lgkmcnt(0)
	v_cvt_pk_bf16_f32 v2, v2, v3
	ds_read2_b32 v[4:5], v79 offset0:170 offset1:235
	s_waitcnt lgkmcnt(0)
	v_cvt_pk_bf16_f32 v3, v4, v5
	ds_read2_b32 v[4:5], v39 offset0:44 offset1:109
	v_mad_i64_i32 v[76:77], s[0:1], v0, s87, v[8:9]
	s_waitcnt lgkmcnt(0)
	v_cvt_pk_bf16_f32 v4, v4, v5
	ds_read2_b32 v[6:7], v39 offset0:174 offset1:239
	s_waitcnt lgkmcnt(0)
	v_cvt_pk_bf16_f32 v5, v6, v7
	flat_store_dwordx4 v[76:77], v[2:5] sc1
	ds_read2_b32 v[2:3], v79 offset0:48 offset1:113
	v_or_b32_e32 v0, v43, v85
	s_waitcnt lgkmcnt(0)
	v_cvt_pk_bf16_f32 v2, v2, v3
	ds_read2_b32 v[4:5], v79 offset0:178 offset1:243
	s_waitcnt lgkmcnt(0)
	v_cvt_pk_bf16_f32 v3, v4, v5
	ds_read2_b32 v[4:5], v39 offset0:52 offset1:117
	v_mad_i64_i32 v[76:77], s[0:1], v0, s87, v[8:9]
	s_waitcnt lgkmcnt(0)
	v_cvt_pk_bf16_f32 v4, v4, v5
	ds_read2_b32 v[6:7], v39 offset0:182 offset1:247
	s_waitcnt lgkmcnt(0)
	v_cvt_pk_bf16_f32 v5, v6, v7
	flat_store_dwordx4 v[76:77], v[2:5] sc1
	ds_read2_b32 v[2:3], v79 offset0:56 offset1:121
	v_or_b32_e32 v0, v43, v86
	s_waitcnt lgkmcnt(0)
	v_cvt_pk_bf16_f32 v2, v2, v3
	ds_read2_b32 v[4:5], v79 offset0:186 offset1:251
	s_waitcnt lgkmcnt(0)
	v_cvt_pk_bf16_f32 v3, v4, v5
	ds_read2_b32 v[4:5], v39 offset0:60 offset1:125
	s_waitcnt lgkmcnt(0)
	v_cvt_pk_bf16_f32 v4, v4, v5
	ds_read2_b32 v[6:7], v39 offset0:190 offset1:255
	s_waitcnt lgkmcnt(0)
	v_cvt_pk_bf16_f32 v5, v6, v7
	v_mad_i64_i32 v[6:7], s[0:1], v0, s87, v[8:9]
	flat_store_dwordx4 v[6:7], v[2:5] sc1
	s_waitcnt lgkmcnt(0)

.LBB0_673:
	ds_read2_b32 v[76:77], v79 offset1:65
	v_add_u32_e32 v39, v43, v39
	v_lshlrev_b32_e32 v43, 6, v39
	v_lshlrev_b32_e32 v39, 7, v39
	s_movk_i32 s0, 0x80
	s_waitcnt vmcnt(0) lgkmcnt(0)
	v_mul_f32_e32 v0, v6, v76
	v_mul_f32_e32 v51, v7, v77
	v_cvt_pk_bf16_f32 v100, v0, v51
	ds_read2_b32 v[76:77], v79 offset0:130 offset1:195
	v_add_u32_e32 v51, 0x400, v79
	s_waitcnt lgkmcnt(0)
	v_mul_f32_e32 v0, v8, v76
	v_mul_f32_e32 v55, v9, v77
	v_cvt_pk_bf16_f32 v101, v0, v55
	ds_read2_b32 v[76:77], v51 offset0:4 offset1:69
	v_lshlrev_b32_e32 v0, 1, v47
	v_lshl_add_u64 v[104:105], v[34:35], 0, v[0:1]
	v_and_b32_e32 v0, 64, v43
	v_or3_b32 v0, v39, v0, s0
	s_waitcnt lgkmcnt(0)
	v_mul_f32_e32 v47, v2, v76
	v_mul_f32_e32 v55, v3, v77
	v_cvt_pk_bf16_f32 v102, v47, v55
	ds_read2_b32 v[76:77], v51 offset0:134 offset1:199
	v_or_b32_e32 v106, v0, v78
	v_ashrrev_i32_e32 v107, 31, v106
	s_waitcnt lgkmcnt(0)
	v_mul_f32_e32 v39, v4, v76
	v_mul_f32_e32 v43, v5, v77
	v_lshlrev_b64 v[76:77], 11, v[106:107]
	v_lshl_add_u64 v[76:77], v[104:105], 0, v[76:77]
	v_cvt_pk_bf16_f32 v103, v39, v43
	flat_store_dwordx4 v[76:77], v[100:103] sc1
	ds_read2_b32 v[76:77], v79 offset0:8 offset1:73
	v_or_b32_e32 v106, v0, v80
	v_ashrrev_i32_e32 v107, 31, v106
	v_lshlrev_b64 v[106:107], 11, v[106:107]
	v_lshl_add_u64 v[106:107], v[104:105], 0, v[106:107]
	s_waitcnt lgkmcnt(0)
	v_mul_f32_e32 v39, v6, v76
	v_mul_f32_e32 v43, v7, v77
	v_cvt_pk_bf16_f32 v100, v39, v43
	ds_read2_b32 v[76:77], v79 offset0:138 offset1:203
	s_waitcnt lgkmcnt(0)
	v_mul_f32_e32 v39, v8, v76
	v_mul_f32_e32 v43, v9, v77
	v_cvt_pk_bf16_f32 v101, v39, v43
	ds_read2_b32 v[76:77], v51 offset0:12 offset1:77
	s_waitcnt lgkmcnt(0)
	v_mul_f32_e32 v39, v2, v76
	v_mul_f32_e32 v43, v3, v77
	v_cvt_pk_bf16_f32 v102, v39, v43
	ds_read2_b32 v[76:77], v51 offset0:142 offset1:207
	s_waitcnt lgkmcnt(0)
	v_mul_f32_e32 v39, v4, v76
	v_mul_f32_e32 v43, v5, v77
	v_cvt_pk_bf16_f32 v103, v39, v43
	flat_store_dwordx4 v[106:107], v[100:103] sc1
	ds_read2_b32 v[76:77], v79 offset0:16 offset1:81
	v_or_b32_e32 v106, v0, v81
	v_ashrrev_i32_e32 v107, 31, v106
	v_lshlrev_b64 v[106:107], 11, v[106:107]
	v_lshl_add_u64 v[106:107], v[104:105], 0, v[106:107]
	s_waitcnt lgkmcnt(0)
	v_mul_f32_e32 v39, v6, v76
	v_mul_f32_e32 v43, v7, v77
	v_cvt_pk_bf16_f32 v100, v39, v43
	ds_read2_b32 v[76:77], v79 offset0:146 offset1:211
	s_waitcnt lgkmcnt(0)
	v_mul_f32_e32 v39, v8, v76
	v_mul_f32_e32 v43, v9, v77
	v_cvt_pk_bf16_f32 v101, v39, v43
	ds_read2_b32 v[76:77], v51 offset0:20 offset1:85
	s_waitcnt lgkmcnt(0)
	v_mul_f32_e32 v39, v2, v76
	v_mul_f32_e32 v43, v3, v77
	v_cvt_pk_bf16_f32 v102, v39, v43
	ds_read2_b32 v[76:77], v51 offset0:150 offset1:215
	s_waitcnt lgkmcnt(0)
	v_mul_f32_e32 v39, v4, v76
	v_mul_f32_e32 v43, v5, v77
	v_cvt_pk_bf16_f32 v103, v39, v43
	flat_store_dwordx4 v[106:107], v[100:103] sc1
	ds_read2_b32 v[76:77], v79 offset0:24 offset1:89
	v_or_b32_e32 v106, v0, v82
	v_ashrrev_i32_e32 v107, 31, v106
	v_lshlrev_b64 v[106:107], 11, v[106:107]
	v_lshl_add_u64 v[106:107], v[104:105], 0, v[106:107]
	s_waitcnt lgkmcnt(0)
	v_mul_f32_e32 v39, v6, v76
	v_mul_f32_e32 v43, v7, v77
	v_cvt_pk_bf16_f32 v100, v39, v43
	ds_read2_b32 v[76:77], v79 offset0:154 offset1:219
	s_waitcnt lgkmcnt(0)
	v_mul_f32_e32 v39, v8, v76
	v_mul_f32_e32 v43, v9, v77
	v_cvt_pk_bf16_f32 v101, v39, v43
	ds_read2_b32 v[76:77], v51 offset0:28 offset1:93
	s_waitcnt lgkmcnt(0)
	v_mul_f32_e32 v39, v2, v76
	v_mul_f32_e32 v43, v3, v77
	v_cvt_pk_bf16_f32 v102, v39, v43
	ds_read2_b32 v[76:77], v51 offset0:158 offset1:223
	s_waitcnt lgkmcnt(0)
	v_mul_f32_e32 v39, v4, v76
	v_mul_f32_e32 v43, v5, v77
	v_cvt_pk_bf16_f32 v103, v39, v43
	flat_store_dwordx4 v[106:107], v[100:103] sc1
	ds_read2_b32 v[76:77], v79 offset0:32 offset1:97
	v_or_b32_e32 v106, v0, v83
	v_ashrrev_i32_e32 v107, 31, v106
	v_lshlrev_b64 v[106:107], 11, v[106:107]
	v_lshl_add_u64 v[106:107], v[104:105], 0, v[106:107]
	s_waitcnt lgkmcnt(0)
	v_mul_f32_e32 v39, v6, v76
	v_mul_f32_e32 v43, v7, v77
	v_cvt_pk_bf16_f32 v100, v39, v43
	ds_read2_b32 v[76:77], v79 offset0:162 offset1:227
	s_waitcnt lgkmcnt(0)
	v_mul_f32_e32 v39, v8, v76
	v_mul_f32_e32 v43, v9, v77
	v_cvt_pk_bf16_f32 v101, v39, v43
	ds_read2_b32 v[76:77], v51 offset0:36 offset1:101
	s_waitcnt lgkmcnt(0)
	v_mul_f32_e32 v39, v2, v76
	v_mul_f32_e32 v43, v3, v77
	v_cvt_pk_bf16_f32 v102, v39, v43
	ds_read2_b32 v[76:77], v51 offset0:166 offset1:231
	s_waitcnt lgkmcnt(0)
	v_mul_f32_e32 v39, v4, v76
	v_mul_f32_e32 v43, v5, v77
	v_cvt_pk_bf16_f32 v103, v39, v43
	flat_store_dwordx4 v[106:107], v[100:103] sc1
	ds_read2_b32 v[76:77], v79 offset0:40 offset1:105
	v_or_b32_e32 v106, v0, v84
	v_ashrrev_i32_e32 v107, 31, v106
	v_lshlrev_b64 v[106:107], 11, v[106:107]
	v_lshl_add_u64 v[106:107], v[104:105], 0, v[106:107]
	s_waitcnt lgkmcnt(0)
	v_mul_f32_e32 v39, v6, v76
	v_mul_f32_e32 v43, v7, v77
	v_cvt_pk_bf16_f32 v100, v39, v43
	ds_read2_b32 v[76:77], v79 offset0:170 offset1:235
	s_waitcnt lgkmcnt(0)
	v_mul_f32_e32 v39, v8, v76
	v_mul_f32_e32 v43, v9, v77
	v_cvt_pk_bf16_f32 v101, v39, v43
	ds_read2_b32 v[76:77], v51 offset0:44 offset1:109
	s_waitcnt lgkmcnt(0)
	v_mul_f32_e32 v39, v2, v76
	v_mul_f32_e32 v43, v3, v77
	v_cvt_pk_bf16_f32 v102, v39, v43
	ds_read2_b32 v[76:77], v51 offset0:174 offset1:239
	s_waitcnt lgkmcnt(0)
	v_mul_f32_e32 v39, v4, v76
	v_mul_f32_e32 v43, v5, v77
	v_cvt_pk_bf16_f32 v103, v39, v43
	flat_store_dwordx4 v[106:107], v[100:103] sc1
	ds_read2_b32 v[76:77], v79 offset0:48 offset1:113
	v_or_b32_e32 v106, v0, v85
	v_ashrrev_i32_e32 v107, 31, v106
	v_lshlrev_b64 v[106:107], 11, v[106:107]
	v_lshl_add_u64 v[106:107], v[104:105], 0, v[106:107]
	s_waitcnt lgkmcnt(0)
	v_mul_f32_e32 v39, v6, v76
	v_mul_f32_e32 v43, v7, v77
	v_cvt_pk_bf16_f32 v100, v39, v43
	ds_read2_b32 v[76:77], v79 offset0:178 offset1:243
	s_waitcnt lgkmcnt(0)
	v_mul_f32_e32 v39, v8, v76
	v_mul_f32_e32 v43, v9, v77
	v_cvt_pk_bf16_f32 v101, v39, v43
	ds_read2_b32 v[76:77], v51 offset0:52 offset1:117
	s_waitcnt lgkmcnt(0)
	v_mul_f32_e32 v39, v2, v76
	v_mul_f32_e32 v43, v3, v77
	v_cvt_pk_bf16_f32 v102, v39, v43
	ds_read2_b32 v[76:77], v51 offset0:182 offset1:247
	s_waitcnt lgkmcnt(0)
	v_mul_f32_e32 v39, v4, v76
	v_mul_f32_e32 v43, v5, v77
	v_cvt_pk_bf16_f32 v103, v39, v43
	flat_store_dwordx4 v[106:107], v[100:103] sc1
	ds_read2_b32 v[76:77], v79 offset0:56 offset1:121
	s_waitcnt lgkmcnt(0)
	v_mul_f32_e32 v6, v6, v76
	v_mul_f32_e32 v7, v7, v77
	v_cvt_pk_bf16_f32 v6, v6, v7
	ds_read2_b32 v[76:77], v79 offset0:186 offset1:251
	s_waitcnt lgkmcnt(0)
	v_mul_f32_e32 v7, v8, v76
	v_mul_f32_e32 v8, v9, v77
	v_cvt_pk_bf16_f32 v7, v7, v8
	ds_read2_b32 v[8:9], v51 offset0:60 offset1:125
	v_or_b32_e32 v76, v0, v86
	v_ashrrev_i32_e32 v77, 31, v76
	v_lshlrev_b64 v[76:77], 11, v[76:77]
	s_waitcnt lgkmcnt(0)
	v_mul_f32_e32 v2, v2, v8
	v_mul_f32_e32 v3, v3, v9
	v_cvt_pk_bf16_f32 v8, v2, v3
	ds_read2_b32 v[2:3], v51 offset0:190 offset1:255
	s_waitcnt lgkmcnt(0)
	v_mul_f32_e32 v0, v4, v2
	v_mul_f32_e32 v2, v5, v3
	v_cvt_pk_bf16_f32 v9, v0, v2
	v_lshl_add_u64 v[2:3], v[104:105], 0, v[76:77]
	flat_store_dwordx4 v[2:3], v[6:9] sc1
	s_waitcnt lgkmcnt(0)

.LBB0_681:
	ds_read2_b32 v[76:77], v79 offset1:65
	v_add_u32_e32 v39, v43, v39
	v_lshlrev_b32_e32 v43, 6, v39
	v_lshlrev_b32_e32 v39, 7, v39
	s_waitcnt vmcnt(0) lgkmcnt(0)
	v_mul_f32_e32 v0, v6, v76
	v_mul_f32_e32 v51, v7, v77
	v_cvt_pk_bf16_f32 v100, v0, v51
	ds_read2_b32 v[76:77], v79 offset0:130 offset1:195
	v_add_u32_e32 v51, 0x400, v79
	s_waitcnt lgkmcnt(0)
	v_mul_f32_e32 v0, v8, v76
	v_mul_f32_e32 v55, v9, v77
	v_cvt_pk_bf16_f32 v101, v0, v55
	ds_read2_b32 v[76:77], v51 offset0:4 offset1:69
	v_lshlrev_b32_e32 v0, 1, v47
	v_lshl_add_u64 v[104:105], v[34:35], 0, v[0:1]
	v_and_b32_e32 v0, 64, v43
	v_and_or_b32 v0, v39, s15, v0
	s_waitcnt lgkmcnt(0)
	v_mul_f32_e32 v47, v2, v76
	v_mul_f32_e32 v55, v3, v77
	v_cvt_pk_bf16_f32 v102, v47, v55
	ds_read2_b32 v[76:77], v51 offset0:134 offset1:199
	v_or_b32_e32 v106, v0, v78
	v_ashrrev_i32_e32 v107, 31, v106
	s_waitcnt lgkmcnt(0)
	v_mul_f32_e32 v39, v4, v76
	v_mul_f32_e32 v43, v5, v77
	v_lshlrev_b64 v[76:77], 11, v[106:107]
	v_lshl_add_u64 v[76:77], v[104:105], 0, v[76:77]
	v_cvt_pk_bf16_f32 v103, v39, v43
	flat_store_dwordx4 v[76:77], v[100:103] sc1
	ds_read2_b32 v[76:77], v79 offset0:8 offset1:73
	v_or_b32_e32 v106, v0, v80
	v_ashrrev_i32_e32 v107, 31, v106
	v_lshlrev_b64 v[106:107], 11, v[106:107]
	v_lshl_add_u64 v[106:107], v[104:105], 0, v[106:107]
	s_waitcnt lgkmcnt(0)
	v_mul_f32_e32 v39, v6, v76
	v_mul_f32_e32 v43, v7, v77
	v_cvt_pk_bf16_f32 v100, v39, v43
	ds_read2_b32 v[76:77], v79 offset0:138 offset1:203
	s_waitcnt lgkmcnt(0)
	v_mul_f32_e32 v39, v8, v76
	v_mul_f32_e32 v43, v9, v77
	v_cvt_pk_bf16_f32 v101, v39, v43
	ds_read2_b32 v[76:77], v51 offset0:12 offset1:77
	s_waitcnt lgkmcnt(0)
	v_mul_f32_e32 v39, v2, v76
	v_mul_f32_e32 v43, v3, v77
	v_cvt_pk_bf16_f32 v102, v39, v43
	ds_read2_b32 v[76:77], v51 offset0:142 offset1:207
	s_waitcnt lgkmcnt(0)
	v_mul_f32_e32 v39, v4, v76
	v_mul_f32_e32 v43, v5, v77
	v_cvt_pk_bf16_f32 v103, v39, v43
	flat_store_dwordx4 v[106:107], v[100:103] sc1
	ds_read2_b32 v[76:77], v79 offset0:16 offset1:81
	v_or_b32_e32 v106, v0, v81
	v_ashrrev_i32_e32 v107, 31, v106
	v_lshlrev_b64 v[106:107], 11, v[106:107]
	v_lshl_add_u64 v[106:107], v[104:105], 0, v[106:107]
	s_waitcnt lgkmcnt(0)
	v_mul_f32_e32 v39, v6, v76
	v_mul_f32_e32 v43, v7, v77
	v_cvt_pk_bf16_f32 v100, v39, v43
	ds_read2_b32 v[76:77], v79 offset0:146 offset1:211
	s_waitcnt lgkmcnt(0)
	v_mul_f32_e32 v39, v8, v76
	v_mul_f32_e32 v43, v9, v77
	v_cvt_pk_bf16_f32 v101, v39, v43
	ds_read2_b32 v[76:77], v51 offset0:20 offset1:85
	s_waitcnt lgkmcnt(0)
	v_mul_f32_e32 v39, v2, v76
	v_mul_f32_e32 v43, v3, v77
	v_cvt_pk_bf16_f32 v102, v39, v43
	ds_read2_b32 v[76:77], v51 offset0:150 offset1:215
	s_waitcnt lgkmcnt(0)
	v_mul_f32_e32 v39, v4, v76
	v_mul_f32_e32 v43, v5, v77
	v_cvt_pk_bf16_f32 v103, v39, v43
	flat_store_dwordx4 v[106:107], v[100:103] sc1
	ds_read2_b32 v[76:77], v79 offset0:24 offset1:89
	v_or_b32_e32 v106, v0, v82
	v_ashrrev_i32_e32 v107, 31, v106
	v_lshlrev_b64 v[106:107], 11, v[106:107]
	v_lshl_add_u64 v[106:107], v[104:105], 0, v[106:107]
	s_waitcnt lgkmcnt(0)
	v_mul_f32_e32 v39, v6, v76
	v_mul_f32_e32 v43, v7, v77
	v_cvt_pk_bf16_f32 v100, v39, v43
	ds_read2_b32 v[76:77], v79 offset0:154 offset1:219
	s_waitcnt lgkmcnt(0)
	v_mul_f32_e32 v39, v8, v76
	v_mul_f32_e32 v43, v9, v77
	v_cvt_pk_bf16_f32 v101, v39, v43
	ds_read2_b32 v[76:77], v51 offset0:28 offset1:93
	s_waitcnt lgkmcnt(0)
	v_mul_f32_e32 v39, v2, v76
	v_mul_f32_e32 v43, v3, v77
	v_cvt_pk_bf16_f32 v102, v39, v43
	ds_read2_b32 v[76:77], v51 offset0:158 offset1:223
	s_waitcnt lgkmcnt(0)
	v_mul_f32_e32 v39, v4, v76
	v_mul_f32_e32 v43, v5, v77
	v_cvt_pk_bf16_f32 v103, v39, v43
	flat_store_dwordx4 v[106:107], v[100:103] sc1
	ds_read2_b32 v[76:77], v79 offset0:32 offset1:97
	v_or_b32_e32 v106, v0, v83
	v_ashrrev_i32_e32 v107, 31, v106
	v_lshlrev_b64 v[106:107], 11, v[106:107]
	v_lshl_add_u64 v[106:107], v[104:105], 0, v[106:107]
	s_waitcnt lgkmcnt(0)
	v_mul_f32_e32 v39, v6, v76
	v_mul_f32_e32 v43, v7, v77
	v_cvt_pk_bf16_f32 v100, v39, v43
	ds_read2_b32 v[76:77], v79 offset0:162 offset1:227
	s_waitcnt lgkmcnt(0)
	v_mul_f32_e32 v39, v8, v76
	v_mul_f32_e32 v43, v9, v77
	v_cvt_pk_bf16_f32 v101, v39, v43
	ds_read2_b32 v[76:77], v51 offset0:36 offset1:101
	s_waitcnt lgkmcnt(0)
	v_mul_f32_e32 v39, v2, v76
	v_mul_f32_e32 v43, v3, v77
	v_cvt_pk_bf16_f32 v102, v39, v43
	ds_read2_b32 v[76:77], v51 offset0:166 offset1:231
	s_waitcnt lgkmcnt(0)
	v_mul_f32_e32 v39, v4, v76
	v_mul_f32_e32 v43, v5, v77
	v_cvt_pk_bf16_f32 v103, v39, v43
	flat_store_dwordx4 v[106:107], v[100:103] sc1
	ds_read2_b32 v[76:77], v79 offset0:40 offset1:105
	v_or_b32_e32 v106, v0, v84
	v_ashrrev_i32_e32 v107, 31, v106
	v_lshlrev_b64 v[106:107], 11, v[106:107]
	v_lshl_add_u64 v[106:107], v[104:105], 0, v[106:107]
	s_waitcnt lgkmcnt(0)
	v_mul_f32_e32 v39, v6, v76
	v_mul_f32_e32 v43, v7, v77
	v_cvt_pk_bf16_f32 v100, v39, v43
	ds_read2_b32 v[76:77], v79 offset0:170 offset1:235
	s_waitcnt lgkmcnt(0)
	v_mul_f32_e32 v39, v8, v76
	v_mul_f32_e32 v43, v9, v77
	v_cvt_pk_bf16_f32 v101, v39, v43
	ds_read2_b32 v[76:77], v51 offset0:44 offset1:109
	s_waitcnt lgkmcnt(0)
	v_mul_f32_e32 v39, v2, v76
	v_mul_f32_e32 v43, v3, v77
	v_cvt_pk_bf16_f32 v102, v39, v43
	ds_read2_b32 v[76:77], v51 offset0:174 offset1:239
	s_waitcnt lgkmcnt(0)
	v_mul_f32_e32 v39, v4, v76
	v_mul_f32_e32 v43, v5, v77
	v_cvt_pk_bf16_f32 v103, v39, v43
	flat_store_dwordx4 v[106:107], v[100:103] sc1
	ds_read2_b32 v[76:77], v79 offset0:48 offset1:113
	v_or_b32_e32 v106, v0, v85
	v_ashrrev_i32_e32 v107, 31, v106
	v_lshlrev_b64 v[106:107], 11, v[106:107]
	v_lshl_add_u64 v[106:107], v[104:105], 0, v[106:107]
	s_waitcnt lgkmcnt(0)
	v_mul_f32_e32 v39, v6, v76
	v_mul_f32_e32 v43, v7, v77
	v_cvt_pk_bf16_f32 v100, v39, v43
	ds_read2_b32 v[76:77], v79 offset0:178 offset1:243
	s_waitcnt lgkmcnt(0)
	v_mul_f32_e32 v39, v8, v76
	v_mul_f32_e32 v43, v9, v77
	v_cvt_pk_bf16_f32 v101, v39, v43
	ds_read2_b32 v[76:77], v51 offset0:52 offset1:117
	s_waitcnt lgkmcnt(0)
	v_mul_f32_e32 v39, v2, v76
	v_mul_f32_e32 v43, v3, v77
	v_cvt_pk_bf16_f32 v102, v39, v43
	ds_read2_b32 v[76:77], v51 offset0:182 offset1:247
	s_waitcnt lgkmcnt(0)
	v_mul_f32_e32 v39, v4, v76
	v_mul_f32_e32 v43, v5, v77
	v_cvt_pk_bf16_f32 v103, v39, v43
	flat_store_dwordx4 v[106:107], v[100:103] sc1
	ds_read2_b32 v[76:77], v79 offset0:56 offset1:121
	s_waitcnt lgkmcnt(0)
	v_mul_f32_e32 v6, v6, v76
	v_mul_f32_e32 v7, v7, v77
	v_cvt_pk_bf16_f32 v6, v6, v7
	ds_read2_b32 v[76:77], v79 offset0:186 offset1:251
	s_waitcnt lgkmcnt(0)
	v_mul_f32_e32 v7, v8, v76
	v_mul_f32_e32 v8, v9, v77
	v_cvt_pk_bf16_f32 v7, v7, v8
	ds_read2_b32 v[8:9], v51 offset0:60 offset1:125
	v_or_b32_e32 v76, v0, v86
	v_ashrrev_i32_e32 v77, 31, v76
	v_lshlrev_b64 v[76:77], 11, v[76:77]
	s_waitcnt lgkmcnt(0)
	v_mul_f32_e32 v2, v2, v8
	v_mul_f32_e32 v3, v3, v9
	v_cvt_pk_bf16_f32 v8, v2, v3
	ds_read2_b32 v[2:3], v51 offset0:190 offset1:255
	s_waitcnt lgkmcnt(0)
	v_mul_f32_e32 v0, v4, v2
	v_mul_f32_e32 v2, v5, v3
	v_cvt_pk_bf16_f32 v9, v0, v2
	v_lshl_add_u64 v[2:3], v[104:105], 0, v[76:77]
	flat_store_dwordx4 v[2:3], v[6:9] sc1
	s_waitcnt lgkmcnt(0)

.LBB0_685:
	v_lshl_add_u64 v[4:5], v[2:3], 0, s[26:27]
	v_add_co_u32_e32 v6, vcc, 0x1000, v4
	s_mov_b64 s[0:1], vcc
	v_add_co_u32_e32 v8, vcc, 0x2000, v4
	v_addc_co_u32_e64 v7, s[0:1], 0, v5, s[0:1]
	s_mov_b64 s[0:1], vcc
	v_add_co_u32_e32 v76, vcc, 0x3000, v4
	v_addc_co_u32_e64 v9, s[0:1], 0, v5, s[0:1]
	s_mov_b64 s[0:1], vcc
	s_nop 0
	v_addc_co_u32_e64 v77, s[0:1], 0, v5, s[0:1]
	global_load_dword v39, v[4:5], off nt
	global_load_dword v43, v[6:7], off nt
	global_load_dword v47, v[8:9], off nt
	global_load_dword v51, v[76:77], off nt
	v_add_co_u32_e32 v6, vcc, 0x4000, v4
	s_mov_b64 s[0:1], vcc
	v_add_co_u32_e32 v8, vcc, 0x5000, v4
	v_addc_co_u32_e64 v7, s[0:1], 0, v5, s[0:1]
	s_mov_b64 s[0:1], vcc
	v_add_co_u32_e32 v76, vcc, 0x6000, v4
	v_addc_co_u32_e64 v9, s[0:1], 0, v5, s[0:1]
	s_mov_b64 s[0:1], vcc
	s_nop 0
	v_addc_co_u32_e64 v77, s[0:1], 0, v5, s[0:1]
	global_load_dword v55, v[6:7], off nt
	global_load_dword v61, v[8:9], off nt
	global_load_dword v73, v[76:77], off nt
	v_add_co_u32_e32 v6, vcc, 0x7000, v4
	s_mov_b64 s[0:1], vcc
	v_add_co_u32_e32 v8, vcc, 0x8000, v4
	v_addc_co_u32_e64 v7, s[0:1], 0, v5, s[0:1]
	s_mov_b64 s[0:1], vcc
	v_add_co_u32_e32 v76, vcc, 0x9000, v4
	v_addc_co_u32_e64 v9, s[0:1], 0, v5, s[0:1]
	s_mov_b64 s[0:1], vcc
	s_nop 0
	v_addc_co_u32_e64 v77, s[0:1], 0, v5, s[0:1]
	global_load_dword v99, v[6:7], off nt
	global_load_dword v100, v[8:9], off nt
	global_load_dword v101, v[76:77], off nt
	v_add_co_u32_e32 v6, vcc, 0xa000, v4
	s_mov_b64 s[0:1], vcc
	v_add_co_u32_e32 v8, vcc, 0xb000, v4
	v_addc_co_u32_e64 v7, s[0:1], 0, v5, s[0:1]
	s_mov_b64 s[0:1], vcc
	v_add_co_u32_e32 v76, vcc, 0xc000, v4
	v_addc_co_u32_e64 v9, s[0:1], 0, v5, s[0:1]
	s_mov_b64 s[0:1], vcc
	global_load_dword v102, v[6:7], off nt
	global_load_dword v103, v[8:9], off nt
	v_add_co_u32_e32 v6, vcc, 0xd000, v4
	v_addc_co_u32_e64 v77, s[0:1], 0, v5, s[0:1]
	s_mov_b64 s[0:1], vcc
	v_add_co_u32_e32 v8, vcc, 0xe000, v4
	v_addc_co_u32_e64 v7, s[0:1], 0, v5, s[0:1]
	s_mov_b64 s[0:1], vcc
	v_add_co_u32_e32 v4, vcc, 0xf000, v4
	v_addc_co_u32_e64 v9, s[0:1], 0, v5, s[0:1]
	global_load_dword v76, v[76:77], off nt
	v_addc_co_u32_e32 v5, vcc, 0, v5, vcc
	global_load_dword v6, v[6:7], off nt
	s_nop 0
	global_load_dword v7, v[8:9], off nt
	s_nop 0
	global_load_dword v4, v[4:5], off nt
	s_add_u32 s26, s26, 0x10000
	s_addc_u32 s27, s27, 0
	v_add_u32_e32 v5, 0x400, v0
	v_add_u32_e32 v8, 0x800, v0
	v_add_u32_e32 v9, 0xc00, v0
	s_cmp_lg_u32 s26, 0x40000
	s_waitcnt vmcnt(0)
	ds_write2_b32 v0, v39, v43 offset1:65
	ds_write2_b32 v0, v47, v51 offset0:130 offset1:195
	v_add_u32_e32 v0, 0x1040, v0
	ds_write2_b32 v5, v55, v61 offset0:4 offset1:69
	ds_write2_b32 v5, v73, v99 offset0:134 offset1:199
	ds_write2_b32 v8, v100, v101 offset0:8 offset1:73
	ds_write2_b32 v8, v102, v103 offset0:138 offset1:203
	ds_write2_b32 v9, v76, v6 offset0:12 offset1:77
	ds_write2_b32 v9, v7, v4 offset0:142 offset1:207
	s_cbranch_scc1 .LBB0_685
	v_add_u32_e32 v0, 0xfffffa80, v74
	v_lshrrev_b32_e32 v6, 4, v0
	s_waitcnt lgkmcnt(0)
	v_lshlrev_b32_e32 v7, 6, v0
	v_lshlrev_b32_e32 v8, 10, v6
	ds_read2_b32 v[2:3], v79 offset1:65
	v_lshlrev_b32_e32 v0, 7, v6
	v_sub_u32_e32 v43, v7, v8
	s_waitcnt lgkmcnt(0)
	v_cvt_pk_bf16_f32 v2, v2, v3
	ds_read2_b32 v[4:5], v79 offset0:130 offset1:195
	v_add_u32_e32 v39, 0x400, v79
	v_lshl_add_u64 v[8:9], v[28:29], 0, v[0:1]
	v_or_b32_e32 v0, v43, v78
	s_waitcnt lgkmcnt(0)
	v_cvt_pk_bf16_f32 v3, v4, v5
	ds_read2_b32 v[4:5], v39 offset0:4 offset1:69
	v_mad_i64_i32 v[76:77], s[0:1], v0, s87, v[8:9]
	s_waitcnt lgkmcnt(0)
	v_cvt_pk_bf16_f32 v4, v4, v5
	ds_read2_b32 v[6:7], v39 offset0:134 offset1:199
	s_waitcnt lgkmcnt(0)
	v_cvt_pk_bf16_f32 v5, v6, v7
	flat_store_dwordx4 v[76:77], v[2:5] sc1
	ds_read2_b32 v[2:3], v79 offset0:8 offset1:73
	v_or_b32_e32 v0, v43, v80
	s_waitcnt lgkmcnt(0)
	v_cvt_pk_bf16_f32 v2, v2, v3
	ds_read2_b32 v[4:5], v79 offset0:138 offset1:203
	s_waitcnt lgkmcnt(0)
	v_cvt_pk_bf16_f32 v3, v4, v5
	ds_read2_b32 v[4:5], v39 offset0:12 offset1:77
	v_mad_i64_i32 v[76:77], s[0:1], v0, s87, v[8:9]
	s_waitcnt lgkmcnt(0)
	v_cvt_pk_bf16_f32 v4, v4, v5
	ds_read2_b32 v[6:7], v39 offset0:142 offset1:207
	s_waitcnt lgkmcnt(0)
	v_cvt_pk_bf16_f32 v5, v6, v7
	flat_store_dwordx4 v[76:77], v[2:5] sc1
	ds_read2_b32 v[2:3], v79 offset0:16 offset1:81
	v_or_b32_e32 v0, v43, v81
	s_waitcnt lgkmcnt(0)
	v_cvt_pk_bf16_f32 v2, v2, v3
	ds_read2_b32 v[4:5], v79 offset0:146 offset1:211
	s_waitcnt lgkmcnt(0)
	v_cvt_pk_bf16_f32 v3, v4, v5
	ds_read2_b32 v[4:5], v39 offset0:20 offset1:85
	v_mad_i64_i32 v[76:77], s[0:1], v0, s87, v[8:9]
	s_waitcnt lgkmcnt(0)
	v_cvt_pk_bf16_f32 v4, v4, v5
	ds_read2_b32 v[6:7], v39 offset0:150 offset1:215
	s_waitcnt lgkmcnt(0)
	v_cvt_pk_bf16_f32 v5, v6, v7
	flat_store_dwordx4 v[76:77], v[2:5] sc1
	ds_read2_b32 v[2:3], v79 offset0:24 offset1:89
	v_or_b32_e32 v0, v43, v82
	s_waitcnt lgkmcnt(0)
	v_cvt_pk_bf16_f32 v2, v2, v3
	ds_read2_b32 v[4:5], v79 offset0:154 offset1:219
	s_waitcnt lgkmcnt(0)
	v_cvt_pk_bf16_f32 v3, v4, v5
	ds_read2_b32 v[4:5], v39 offset0:28 offset1:93
	v_mad_i64_i32 v[76:77], s[0:1], v0, s87, v[8:9]
	s_waitcnt lgkmcnt(0)
	v_cvt_pk_bf16_f32 v4, v4, v5
	ds_read2_b32 v[6:7], v39 offset0:158 offset1:223
	s_waitcnt lgkmcnt(0)
	v_cvt_pk_bf16_f32 v5, v6, v7
	flat_store_dwordx4 v[76:77], v[2:5] sc1
	ds_read2_b32 v[2:3], v79 offset0:32 offset1:97
	v_or_b32_e32 v0, v43, v83
	s_waitcnt lgkmcnt(0)
	v_cvt_pk_bf16_f32 v2, v2, v3
	ds_read2_b32 v[4:5], v79 offset0:162 offset1:227
	s_waitcnt lgkmcnt(0)
	v_cvt_pk_bf16_f32 v3, v4, v5
	ds_read2_b32 v[4:5], v39 offset0:36 offset1:101
	v_mad_i64_i32 v[76:77], s[0:1], v0, s87, v[8:9]
	s_waitcnt lgkmcnt(0)
	v_cvt_pk_bf16_f32 v4, v4, v5
	ds_read2_b32 v[6:7], v39 offset0:166 offset1:231
	s_waitcnt lgkmcnt(0)
	v_cvt_pk_bf16_f32 v5, v6, v7
	flat_store_dwordx4 v[76:77], v[2:5] sc1
	ds_read2_b32 v[2:3], v79 offset0:40 offset1:105
	v_or_b32_e32 v0, v43, v84
	s_waitcnt lgkmcnt(0)
	v_cvt_pk_bf16_f32 v2, v2, v3
	ds_read2_b32 v[4:5], v79 offset0:170 offset1:235
	s_waitcnt lgkmcnt(0)
	v_cvt_pk_bf16_f32 v3, v4, v5
	ds_read2_b32 v[4:5], v39 offset0:44 offset1:109
	v_mad_i64_i32 v[76:77], s[0:1], v0, s87, v[8:9]
	s_waitcnt lgkmcnt(0)
	v_cvt_pk_bf16_f32 v4, v4, v5
	ds_read2_b32 v[6:7], v39 offset0:174 offset1:239
	s_waitcnt lgkmcnt(0)
	v_cvt_pk_bf16_f32 v5, v6, v7
	flat_store_dwordx4 v[76:77], v[2:5] sc1
	ds_read2_b32 v[2:3], v79 offset0:48 offset1:113
	v_or_b32_e32 v0, v43, v85
	s_waitcnt lgkmcnt(0)
	v_cvt_pk_bf16_f32 v2, v2, v3
	ds_read2_b32 v[4:5], v79 offset0:178 offset1:243
	s_waitcnt lgkmcnt(0)
	v_cvt_pk_bf16_f32 v3, v4, v5
	ds_read2_b32 v[4:5], v39 offset0:52 offset1:117
	v_mad_i64_i32 v[76:77], s[0:1], v0, s87, v[8:9]
	s_waitcnt lgkmcnt(0)
	v_cvt_pk_bf16_f32 v4, v4, v5
	ds_read2_b32 v[6:7], v39 offset0:182 offset1:247
	s_waitcnt lgkmcnt(0)
	v_cvt_pk_bf16_f32 v5, v6, v7
	flat_store_dwordx4 v[76:77], v[2:5] sc1
	ds_read2_b32 v[2:3], v79 offset0:56 offset1:121
	v_or_b32_e32 v0, v43, v86
	s_waitcnt lgkmcnt(0)
	v_cvt_pk_bf16_f32 v2, v2, v3
	ds_read2_b32 v[4:5], v79 offset0:186 offset1:251
	s_waitcnt lgkmcnt(0)
	v_cvt_pk_bf16_f32 v3, v4, v5
	ds_read2_b32 v[4:5], v39 offset0:60 offset1:125
	s_waitcnt lgkmcnt(0)
	v_cvt_pk_bf16_f32 v4, v4, v5
	ds_read2_b32 v[6:7], v39 offset0:190 offset1:255
	s_waitcnt lgkmcnt(0)
	v_cvt_pk_bf16_f32 v5, v6, v7
	v_mad_i64_i32 v[6:7], s[0:1], v0, s87, v[8:9]
	flat_store_dwordx4 v[6:7], v[2:5] sc1
	s_waitcnt lgkmcnt(0)

.LBB0_694:
	ds_read2_b32 v[76:77], v79 offset1:65
	v_add_u32_e32 v39, v43, v39
	v_lshlrev_b32_e32 v43, 6, v39
	v_lshlrev_b32_e32 v39, 7, v39
	s_movk_i32 s0, 0x80
	s_waitcnt vmcnt(0) lgkmcnt(0)
	v_mul_f32_e32 v0, v6, v76
	v_mul_f32_e32 v51, v7, v77
	v_cvt_pk_bf16_f32 v100, v0, v51
	ds_read2_b32 v[76:77], v79 offset0:130 offset1:195
	v_add_u32_e32 v51, 0x400, v79
	s_waitcnt lgkmcnt(0)
	v_mul_f32_e32 v0, v8, v76
	v_mul_f32_e32 v55, v9, v77
	v_cvt_pk_bf16_f32 v101, v0, v55
	ds_read2_b32 v[76:77], v51 offset0:4 offset1:69
	v_lshlrev_b32_e32 v0, 1, v47
	v_lshl_add_u64 v[104:105], v[10:11], 0, v[0:1]
	v_and_b32_e32 v0, 64, v43
	v_or3_b32 v0, v39, v0, s0
	s_waitcnt lgkmcnt(0)
	v_mul_f32_e32 v47, v2, v76
	v_mul_f32_e32 v55, v3, v77
	v_cvt_pk_bf16_f32 v102, v47, v55
	ds_read2_b32 v[76:77], v51 offset0:134 offset1:199
	v_or_b32_e32 v106, v0, v78
	v_ashrrev_i32_e32 v107, 31, v106
	s_waitcnt lgkmcnt(0)
	v_mul_f32_e32 v39, v4, v76
	v_mul_f32_e32 v43, v5, v77
	v_lshlrev_b64 v[76:77], 11, v[106:107]
	v_lshl_add_u64 v[76:77], v[104:105], 0, v[76:77]
	v_cvt_pk_bf16_f32 v103, v39, v43
	flat_store_dwordx4 v[76:77], v[100:103] sc1
	ds_read2_b32 v[76:77], v79 offset0:8 offset1:73
	v_or_b32_e32 v106, v0, v80
	v_ashrrev_i32_e32 v107, 31, v106
	v_lshlrev_b64 v[106:107], 11, v[106:107]
	v_lshl_add_u64 v[106:107], v[104:105], 0, v[106:107]
	s_waitcnt lgkmcnt(0)
	v_mul_f32_e32 v39, v6, v76
	v_mul_f32_e32 v43, v7, v77
	v_cvt_pk_bf16_f32 v100, v39, v43
	ds_read2_b32 v[76:77], v79 offset0:138 offset1:203
	s_waitcnt lgkmcnt(0)
	v_mul_f32_e32 v39, v8, v76
	v_mul_f32_e32 v43, v9, v77
	v_cvt_pk_bf16_f32 v101, v39, v43
	ds_read2_b32 v[76:77], v51 offset0:12 offset1:77
	s_waitcnt lgkmcnt(0)
	v_mul_f32_e32 v39, v2, v76
	v_mul_f32_e32 v43, v3, v77
	v_cvt_pk_bf16_f32 v102, v39, v43
	ds_read2_b32 v[76:77], v51 offset0:142 offset1:207
	s_waitcnt lgkmcnt(0)
	v_mul_f32_e32 v39, v4, v76
	v_mul_f32_e32 v43, v5, v77
	v_cvt_pk_bf16_f32 v103, v39, v43
	flat_store_dwordx4 v[106:107], v[100:103] sc1
	ds_read2_b32 v[76:77], v79 offset0:16 offset1:81
	v_or_b32_e32 v106, v0, v81
	v_ashrrev_i32_e32 v107, 31, v106
	v_lshlrev_b64 v[106:107], 11, v[106:107]
	v_lshl_add_u64 v[106:107], v[104:105], 0, v[106:107]
	s_waitcnt lgkmcnt(0)
	v_mul_f32_e32 v39, v6, v76
	v_mul_f32_e32 v43, v7, v77
	v_cvt_pk_bf16_f32 v100, v39, v43
	ds_read2_b32 v[76:77], v79 offset0:146 offset1:211
	s_waitcnt lgkmcnt(0)
	v_mul_f32_e32 v39, v8, v76
	v_mul_f32_e32 v43, v9, v77
	v_cvt_pk_bf16_f32 v101, v39, v43
	ds_read2_b32 v[76:77], v51 offset0:20 offset1:85
	s_waitcnt lgkmcnt(0)
	v_mul_f32_e32 v39, v2, v76
	v_mul_f32_e32 v43, v3, v77
	v_cvt_pk_bf16_f32 v102, v39, v43
	ds_read2_b32 v[76:77], v51 offset0:150 offset1:215
	s_waitcnt lgkmcnt(0)
	v_mul_f32_e32 v39, v4, v76
	v_mul_f32_e32 v43, v5, v77
	v_cvt_pk_bf16_f32 v103, v39, v43
	flat_store_dwordx4 v[106:107], v[100:103] sc1
	ds_read2_b32 v[76:77], v79 offset0:24 offset1:89
	v_or_b32_e32 v106, v0, v82
	v_ashrrev_i32_e32 v107, 31, v106
	v_lshlrev_b64 v[106:107], 11, v[106:107]
	v_lshl_add_u64 v[106:107], v[104:105], 0, v[106:107]
	s_waitcnt lgkmcnt(0)
	v_mul_f32_e32 v39, v6, v76
	v_mul_f32_e32 v43, v7, v77
	v_cvt_pk_bf16_f32 v100, v39, v43
	ds_read2_b32 v[76:77], v79 offset0:154 offset1:219
	s_waitcnt lgkmcnt(0)
	v_mul_f32_e32 v39, v8, v76
	v_mul_f32_e32 v43, v9, v77
	v_cvt_pk_bf16_f32 v101, v39, v43
	ds_read2_b32 v[76:77], v51 offset0:28 offset1:93
	s_waitcnt lgkmcnt(0)
	v_mul_f32_e32 v39, v2, v76
	v_mul_f32_e32 v43, v3, v77
	v_cvt_pk_bf16_f32 v102, v39, v43
	ds_read2_b32 v[76:77], v51 offset0:158 offset1:223
	s_waitcnt lgkmcnt(0)
	v_mul_f32_e32 v39, v4, v76
	v_mul_f32_e32 v43, v5, v77
	v_cvt_pk_bf16_f32 v103, v39, v43
	flat_store_dwordx4 v[106:107], v[100:103] sc1
	ds_read2_b32 v[76:77], v79 offset0:32 offset1:97
	v_or_b32_e32 v106, v0, v83
	v_ashrrev_i32_e32 v107, 31, v106
	v_lshlrev_b64 v[106:107], 11, v[106:107]
	v_lshl_add_u64 v[106:107], v[104:105], 0, v[106:107]
	s_waitcnt lgkmcnt(0)
	v_mul_f32_e32 v39, v6, v76
	v_mul_f32_e32 v43, v7, v77
	v_cvt_pk_bf16_f32 v100, v39, v43
	ds_read2_b32 v[76:77], v79 offset0:162 offset1:227
	s_waitcnt lgkmcnt(0)
	v_mul_f32_e32 v39, v8, v76
	v_mul_f32_e32 v43, v9, v77
	v_cvt_pk_bf16_f32 v101, v39, v43
	ds_read2_b32 v[76:77], v51 offset0:36 offset1:101
	s_waitcnt lgkmcnt(0)
	v_mul_f32_e32 v39, v2, v76
	v_mul_f32_e32 v43, v3, v77
	v_cvt_pk_bf16_f32 v102, v39, v43
	ds_read2_b32 v[76:77], v51 offset0:166 offset1:231
	s_waitcnt lgkmcnt(0)
	v_mul_f32_e32 v39, v4, v76
	v_mul_f32_e32 v43, v5, v77
	v_cvt_pk_bf16_f32 v103, v39, v43
	flat_store_dwordx4 v[106:107], v[100:103] sc1
	ds_read2_b32 v[76:77], v79 offset0:40 offset1:105
	v_or_b32_e32 v106, v0, v84
	v_ashrrev_i32_e32 v107, 31, v106
	v_lshlrev_b64 v[106:107], 11, v[106:107]
	v_lshl_add_u64 v[106:107], v[104:105], 0, v[106:107]
	s_waitcnt lgkmcnt(0)
	v_mul_f32_e32 v39, v6, v76
	v_mul_f32_e32 v43, v7, v77
	v_cvt_pk_bf16_f32 v100, v39, v43
	ds_read2_b32 v[76:77], v79 offset0:170 offset1:235
	s_waitcnt lgkmcnt(0)
	v_mul_f32_e32 v39, v8, v76
	v_mul_f32_e32 v43, v9, v77
	v_cvt_pk_bf16_f32 v101, v39, v43
	ds_read2_b32 v[76:77], v51 offset0:44 offset1:109
	s_waitcnt lgkmcnt(0)
	v_mul_f32_e32 v39, v2, v76
	v_mul_f32_e32 v43, v3, v77
	v_cvt_pk_bf16_f32 v102, v39, v43
	ds_read2_b32 v[76:77], v51 offset0:174 offset1:239
	s_waitcnt lgkmcnt(0)
	v_mul_f32_e32 v39, v4, v76
	v_mul_f32_e32 v43, v5, v77
	v_cvt_pk_bf16_f32 v103, v39, v43
	flat_store_dwordx4 v[106:107], v[100:103] sc1
	ds_read2_b32 v[76:77], v79 offset0:48 offset1:113
	v_or_b32_e32 v106, v0, v85
	v_ashrrev_i32_e32 v107, 31, v106
	v_lshlrev_b64 v[106:107], 11, v[106:107]
	v_lshl_add_u64 v[106:107], v[104:105], 0, v[106:107]
	s_waitcnt lgkmcnt(0)
	v_mul_f32_e32 v39, v6, v76
	v_mul_f32_e32 v43, v7, v77
	v_cvt_pk_bf16_f32 v100, v39, v43
	ds_read2_b32 v[76:77], v79 offset0:178 offset1:243
	s_waitcnt lgkmcnt(0)
	v_mul_f32_e32 v39, v8, v76
	v_mul_f32_e32 v43, v9, v77
	v_cvt_pk_bf16_f32 v101, v39, v43
	ds_read2_b32 v[76:77], v51 offset0:52 offset1:117
	s_waitcnt lgkmcnt(0)
	v_mul_f32_e32 v39, v2, v76
	v_mul_f32_e32 v43, v3, v77
	v_cvt_pk_bf16_f32 v102, v39, v43
	ds_read2_b32 v[76:77], v51 offset0:182 offset1:247
	s_waitcnt lgkmcnt(0)
	v_mul_f32_e32 v39, v4, v76
	v_mul_f32_e32 v43, v5, v77
	v_cvt_pk_bf16_f32 v103, v39, v43
	flat_store_dwordx4 v[106:107], v[100:103] sc1
	ds_read2_b32 v[76:77], v79 offset0:56 offset1:121
	s_waitcnt lgkmcnt(0)
	v_mul_f32_e32 v6, v6, v76
	v_mul_f32_e32 v7, v7, v77
	v_cvt_pk_bf16_f32 v6, v6, v7
	ds_read2_b32 v[76:77], v79 offset0:186 offset1:251
	s_waitcnt lgkmcnt(0)
	v_mul_f32_e32 v7, v8, v76
	v_mul_f32_e32 v8, v9, v77
	v_cvt_pk_bf16_f32 v7, v7, v8
	ds_read2_b32 v[8:9], v51 offset0:60 offset1:125
	v_or_b32_e32 v76, v0, v86
	v_ashrrev_i32_e32 v77, 31, v76
	v_lshlrev_b64 v[76:77], 11, v[76:77]
	s_waitcnt lgkmcnt(0)
	v_mul_f32_e32 v2, v2, v8
	v_mul_f32_e32 v3, v3, v9
	v_cvt_pk_bf16_f32 v8, v2, v3
	ds_read2_b32 v[2:3], v51 offset0:190 offset1:255
	s_waitcnt lgkmcnt(0)
	v_mul_f32_e32 v0, v4, v2
	v_mul_f32_e32 v2, v5, v3
	v_cvt_pk_bf16_f32 v9, v0, v2
	v_lshl_add_u64 v[2:3], v[104:105], 0, v[76:77]
	flat_store_dwordx4 v[2:3], v[6:9] sc1
	s_waitcnt lgkmcnt(0)

.LBB0_708:
	flat_load_dwordx4 v[12:15], v[6:7] nt
	s_waitcnt vmcnt(0) lgkmcnt(0)
	v_cvt_pk_bf16_f32 v2, v12, v13
	v_cvt_pk_bf16_f32 v3, v14, v15
	flat_store_dwordx2 v[8:9], v[2:3]
	flat_load_dwordx4 v[16:19], v[6:7] offset:1024 nt
	s_waitcnt vmcnt(0) lgkmcnt(0)
	v_cvt_pk_bf16_f32 v2, v16, v17
	v_cvt_pk_bf16_f32 v3, v18, v19
	flat_store_dwordx2 v[8:9], v[2:3] offset:512
	flat_load_dwordx4 v[20:23], v[6:7] offset:2048 nt
	s_waitcnt vmcnt(0) lgkmcnt(0)
	v_cvt_pk_bf16_f32 v2, v20, v21
	v_cvt_pk_bf16_f32 v3, v22, v23
	flat_store_dwordx2 v[8:9], v[2:3] offset:1024
	flat_load_dwordx4 v[24:27], v[6:7] offset:3072 nt
	v_and_b32_e32 v0, 64, v195
	v_xor_b32_e32 v2, 1, v195
	v_add_u32_e32 v0, 64, v0
	v_cmp_lt_i32_e64 s[0:1], v2, v0
	v_mul_f32_e32 v3, v13, v13
	v_mul_f32_e32 v11, v15, v15
	v_fmac_f32_e32 v3, v12, v12
	v_fmac_f32_e32 v11, v14, v14
	v_add_f32_e32 v3, v3, v11
	v_mul_f32_e32 v11, v17, v17
	v_mul_f32_e32 v12, v19, v19
	v_fmac_f32_e32 v11, v16, v16
	v_fmac_f32_e32 v12, v18, v18
	v_add_f32_e32 v11, v11, v12
	v_add_f32_e32 v3, v3, v11
	v_mul_f32_e32 v11, v21, v21
	v_mul_f32_e32 v12, v23, v23
	v_fmac_f32_e32 v11, v20, v20
	v_fmac_f32_e32 v12, v22, v22
	v_add_f32_e32 v11, v11, v12
	v_add_f32_e32 v3, v3, v11
	s_waitcnt vmcnt(0) lgkmcnt(0)
	v_mul_f32_e32 v11, v25, v25
	v_mul_f32_e32 v12, v27, v27
	v_fmac_f32_e32 v11, v24, v24
	v_fmac_f32_e32 v12, v26, v26
	v_cndmask_b32_e64 v2, v195, v2, s[0:1]
	v_add_f32_e32 v11, v11, v12
	v_lshlrev_b32_e32 v2, 2, v2
	v_add_f32_e32 v3, v3, v11
	ds_bpermute_b32 v2, v2, v3
	v_xor_b32_e32 v11, 2, v195
	v_cmp_lt_i32_e64 s[0:1], v11, v0
	v_cvt_pk_bf16_f32 v12, v24, v25
	v_cvt_pk_bf16_f32 v13, v26, v27
	s_waitcnt lgkmcnt(0)
	v_add_f32_e32 v2, v3, v2
	flat_store_dwordx2 v[8:9], v[12:13] offset:1536
	v_cndmask_b32_e64 v11, v195, v11, s[0:1]
	v_lshlrev_b32_e32 v11, 2, v11
	ds_bpermute_b32 v3, v11, v2
	v_xor_b32_e32 v11, 4, v195
	v_cmp_lt_i32_e64 s[0:1], v11, v0
	s_waitcnt lgkmcnt(0)
	v_add_f32_e32 v2, v2, v3
	v_cndmask_b32_e64 v11, v195, v11, s[0:1]
	v_lshlrev_b32_e32 v11, 2, v11
	ds_bpermute_b32 v3, v11, v2
	v_xor_b32_e32 v11, 8, v195
	v_cmp_lt_i32_e64 s[0:1], v11, v0
	s_waitcnt lgkmcnt(0)
	v_add_f32_e32 v2, v2, v3
	v_cndmask_b32_e64 v11, v195, v11, s[0:1]
	v_lshlrev_b32_e32 v11, 2, v11
	ds_bpermute_b32 v3, v11, v2
	v_xor_b32_e32 v11, 16, v195
	v_cmp_lt_i32_e64 s[0:1], v11, v0
	s_waitcnt lgkmcnt(0)
	v_add_f32_e32 v2, v2, v3
	v_cndmask_b32_e64 v11, v195, v11, s[0:1]
	v_lshlrev_b32_e32 v11, 2, v11
	ds_bpermute_b32 v3, v11, v2
	v_xor_b32_e32 v11, 32, v195
	v_cmp_lt_i32_e64 s[0:1], v11, v0
	s_waitcnt lgkmcnt(0)
	v_add_f32_e32 v0, v2, v3
	v_cndmask_b32_e64 v11, v195, v11, s[0:1]
	v_lshlrev_b32_e32 v2, 2, v11
	ds_bpermute_b32 v2, v2, v0
	s_and_saveexec_b64 s[0:1], vcc
	s_cbranch_execz .LBB0_707
	s_waitcnt lgkmcnt(0)
	v_add_f32_e32 v0, v0, v2
	v_mov_b32_e32 v2, v1
	v_mov_b32_e32 v3, v1
	flat_store_dwordx4 v[4:5], v[0:3] sc1
	s_branch .LBB0_707
